# GEMM mainloops: one static s_setprio 1 for the wave half that takes the stagger barrier (younger half), per-MFMA-cluster priority flips deleted
# speedup vs baseline: 1.0098x; 1.0098x over previous
.LBB0_152:
	s_andn2_b64 vcc, exec, s[4:5]
	s_cbranch_vccnz .LBB0_194
	v_ashrrev_i32_e32 v2, 31, v0
	v_lshrrev_b32_e32 v2, 26, v2
	v_lshlrev_b32_e32 v1, 4, v0
	v_add_u32_e32 v2, v0, v2
	v_bfe_i32 v0, v0, 27, 1
	v_lshrrev_b32_e32 v0, 22, v0
	v_add_u32_e32 v0, v1, v0
	v_and_b32_e32 v0, 0xfffffc00, v0
	v_sub_u32_e32 v0, v1, v0
	v_ashrrev_i32_e32 v9, 6, v2
	v_lshrrev_b32_e32 v2, 4, v0
	v_bitop3_b32 v0, v2, v0, 32 bitop3:0x6c
	v_ashrrev_i32_e32 v3, 31, v0
	v_lshrrev_b32_e32 v3, 26, v3
	v_add_u32_e32 v3, v0, v3
	v_lshlrev_b32_e32 v2, 3, v9
	v_ashrrev_i32_e32 v10, 6, v3
	v_and_b32_e32 v3, 0xc0, v3
	v_and_b32_e32 v2, -16, v2
	v_sub_u32_e32 v0, v0, v3
	v_mov_b32_e32 v3, 1
	v_add_u32_e32 v2, v10, v2
	v_ashrrev_i16_sdwa v0, v3, sext(v0) dst_sel:DWORD dst_unused:UNUSED_PAD src0_sel:DWORD src1_sel:BYTE_0
	v_lshlrev_b32_e32 v4, 5, v9
	v_bfe_i32 v11, v0, 0, 16
	v_lshlrev_b32_e32 v0, 1, v2
	v_lshrrev_b32_e32 v5, 2, v2
	v_and_b32_e32 v6, 3, v10
	s_mov_b32 s3, 0x1fffe0
	v_and_b32_e32 v4, 32, v4
	v_and_b32_e32 v0, 24, v0
	v_and_b32_e32 v5, 4, v5
	v_and_or_b32 v6, v2, s3, v6
	v_or3_b32 v0, v6, v5, v0
	v_add_lshl_u32 v4, v4, v11, 1
	v_lshl_add_u32 v130, v0, 11, v4
	v_add_u32_e32 v0, 0x2000, v1
	v_ashrrev_i32_e32 v1, 31, v0
	v_lshrrev_b32_e32 v1, 22, v1
	v_add_u32_e32 v1, v0, v1
	v_ashrrev_i32_e32 v12, 10, v1
	v_mul_i32_i24_e32 v1, 0x400, v12
	v_sub_u32_e32 v0, v0, v1
	v_lshrrev_b32_e32 v1, 4, v0
	v_bitop3_b32 v0, v1, v0, 32 bitop3:0x6c
	v_lshl_add_u32 v128, v2, 11, v4
	v_ashrrev_i32_e32 v2, 31, v0
	v_lshrrev_b32_e32 v2, 26, v2
	v_add_u32_e32 v2, v0, v2
	v_lshlrev_b32_e32 v1, 3, v12
	v_ashrrev_i32_e32 v13, 6, v2
	v_and_b32_e32 v2, 0xc0, v2
	v_and_b32_e32 v1, -16, v1
	v_sub_u32_e32 v0, v0, v2
	s_ashr_i32 s2, s6, 6
	v_add_u32_e32 v1, v13, v1
	v_ashrrev_i16_sdwa v0, v3, sext(v0) dst_sel:DWORD dst_unused:UNUSED_PAD src0_sel:DWORD src1_sel:BYTE_0
	v_and_b32_e32 v3, 3, v13
	v_and_or_b32 v3, v1, s3, v3
	s_ashr_i32 s3, s6, 8
	s_lshl_b32 s36, s2, 10
	s_add_u32 s37, s70, 0x400000
	s_addc_u32 s38, s71, 0
	s_ashr_i32 s27, s26, 31
	s_ashr_i32 s25, s24, 31
	s_lshl_b64 s[4:5], s[26:27], 19
	s_lshl_b64 s[8:9], s[24:25], 19
	s_add_u32 s30, s37, s8
	v_lshlrev_b32_e32 v4, 5, v12
	v_bfe_i32 v14, v0, 0, 16
	v_lshlrev_b32_e32 v0, 1, v1
	v_lshrrev_b32_e32 v2, 2, v1
	s_addc_u32 s31, s38, s9
	s_add_i32 s39, s36, 0
	v_and_b32_e32 v4, 32, v4
	v_and_b32_e32 v0, 24, v0
	v_and_b32_e32 v2, 4, v2
	s_add_i32 m0, s39, 0x10000
	v_or3_b32 v0, v3, v2, v0
	v_add_lshl_u32 v2, v4, v14, 1
	global_load_lds_dwordx4 v130, s[30:31]
	s_add_i32 m0, s39, 0x12000
	v_lshl_add_u32 v134, v0, 11, v2
	s_add_u32 s8, s30, 0x40000
	global_load_lds_dwordx4 v134, s[30:31]
	s_addc_u32 s9, s31, 0
	s_add_i32 m0, s39, 0x14000
	v_lshl_add_u32 v132, v1, 11, v2
	global_load_lds_dwordx4 v130, s[8:9]
	s_add_i32 m0, s39, 0x16000
	s_add_u32 s28, s76, s4
	s_addc_u32 s29, s77, s5
	s_add_i32 s40, s39, 0x2000
	global_load_lds_dwordx4 v134, s[8:9]
	s_mov_b32 m0, s39
	s_add_u32 s4, s28, 0x40000
	global_load_lds_dwordx4 v128, s[28:29]
	s_mov_b32 m0, s40
	s_addc_u32 s5, s29, 0
	s_add_i32 s41, s39, 0x4000
	global_load_lds_dwordx4 v132, s[28:29]
	s_mov_b32 m0, s41
	s_add_i32 s42, s39, 0x6000
	global_load_lds_dwordx4 v128, s[4:5]
	s_mov_b32 m0, s42
	v_mov_b32_e32 v137, 0
	global_load_lds_dwordx4 v132, s[4:5]
	v_mov_b32_e32 v131, v137
	v_mov_b32_e32 v135, v137
	v_mov_b32_e32 v129, v137
	v_mov_b32_e32 v133, v137
	s_cmp_eq_u32 s3, 1
	s_mov_b32 s7, 0
	v_lshl_add_u64 v[6:7], s[30:31], 0, v[130:131]
	v_lshl_add_u64 v[4:5], s[30:31], 0, v[134:135]
	v_lshl_add_u64 v[0:1], s[28:29], 0, v[128:129]
	s_cselect_b64 s[8:9], -1, 0
	s_cmp_lg_u32 s3, 1
	v_lshl_add_u64 v[2:3], s[28:29], 0, v[132:133]
	s_cbranch_scc1 .LBB0_155
	s_barrier
	s_setprio 1

.LBB0_161:
	ds_read_b128 v[152:155], v143
	ds_read_b128 v[162:165], v143 offset:1024
	ds_read_b128 v[166:169], v143 offset:2048
	ds_read_b128 v[170:173], v143 offset:3072
	ds_read_b128 v[174:177], v158
	ds_read_b128 v[178:181], v158 offset:1024
	ds_read_b128 v[182:185], v158 offset:2048
	ds_read_b128 v[186:189], v158 offset:3072
	s_add_u32 s30, s28, 0xfffc0080
	s_addc_u32 s31, s29, -1
	s_cmp_eq_u32 s55, 12
	s_cselect_b32 s35, s19, s31
	s_cselect_b32 s34, s25, s30
	s_cselect_b32 s31, s17, s54
	s_cselect_b32 s30, s27, s53
	s_waitcnt lgkmcnt(0)
	v_lshl_add_u64 v[156:157], s[28:29], 0, v[144:145]
	s_add_i32 m0, s39, 0xc000
	ds_read_b128 v[190:193], v159
	ds_read_b128 v[194:197], v159 offset:1024
	ds_read_b128 v[198:201], v159 offset:2048
	ds_read_b128 v[202:205], v159 offset:3072
	ds_read_b128 v[206:209], v159 offset:4096
	ds_read_b128 v[210:213], v159 offset:5120
	ds_read_b128 v[214:217], v159 offset:6144
	ds_read_b128 v[218:221], v159 offset:7168
	global_load_lds_dwordx4 v[156:157], off
	v_lshl_add_u64 v[156:157], s[28:29], 0, v[146:147]
	s_add_i32 m0, s39, 0xe000
	s_nop 0
	global_load_lds_dwordx4 v[156:157], off
	s_waitcnt vmcnt(8)
	s_waitcnt lgkmcnt(0)
	s_barrier
	s_waitcnt lgkmcnt(0)
	v_mfma_f32_16x16x32_bf16 v[116:119], v[152:155], v[190:193], v[116:119]
	v_mfma_f32_16x16x32_bf16 v[112:115], v[166:169], v[190:193], v[112:115]
	v_mfma_f32_16x16x32_bf16 v[100:103], v[152:155], v[198:201], v[100:103]
	v_mfma_f32_16x16x32_bf16 v[96:99], v[166:169], v[198:201], v[96:99]
	v_mfma_f32_16x16x32_bf16 v[88:91], v[152:155], v[206:209], v[88:91]
	v_mfma_f32_16x16x32_bf16 v[84:87], v[166:169], v[206:209], v[84:87]
	v_mfma_f32_16x16x32_bf16 v[72:75], v[152:155], v[214:217], v[72:75]
	v_mfma_f32_16x16x32_bf16 v[68:71], v[166:169], v[214:217], v[68:71]
	v_mfma_f32_16x16x32_bf16 v[116:119], v[162:165], v[194:197], v[116:119]
	v_mfma_f32_16x16x32_bf16 v[112:115], v[170:173], v[194:197], v[112:115]
	v_mfma_f32_16x16x32_bf16 v[100:103], v[162:165], v[202:205], v[100:103]
	v_mfma_f32_16x16x32_bf16 v[96:99], v[170:173], v[202:205], v[96:99]
	v_mfma_f32_16x16x32_bf16 v[88:91], v[162:165], v[210:213], v[88:91]
	v_mfma_f32_16x16x32_bf16 v[84:87], v[170:173], v[210:213], v[84:87]
	v_mfma_f32_16x16x32_bf16 v[72:75], v[162:165], v[218:221], v[72:75]
	v_mfma_f32_16x16x32_bf16 v[68:71], v[170:173], v[218:221], v[68:71]
	v_mfma_f32_16x16x32_bf16 v[124:127], v[174:177], v[190:193], v[124:127]
	v_mfma_f32_16x16x32_bf16 v[120:123], v[182:185], v[190:193], v[120:123]
	v_mfma_f32_16x16x32_bf16 v[108:111], v[174:177], v[198:201], v[108:111]
	v_mfma_f32_16x16x32_bf16 v[104:107], v[182:185], v[198:201], v[104:107]
	v_mfma_f32_16x16x32_bf16 v[92:95], v[174:177], v[206:209], v[92:95]
	v_mfma_f32_16x16x32_bf16 v[80:83], v[182:185], v[206:209], v[80:83]
	v_mfma_f32_16x16x32_bf16 v[76:79], v[174:177], v[214:217], v[76:79]
	v_mfma_f32_16x16x32_bf16 v[64:67], v[182:185], v[214:217], v[64:67]
	v_mfma_f32_16x16x32_bf16 v[124:127], v[178:181], v[194:197], v[124:127]
	v_mfma_f32_16x16x32_bf16 v[120:123], v[186:189], v[194:197], v[120:123]
	v_mfma_f32_16x16x32_bf16 v[108:111], v[178:181], v[202:205], v[108:111]
	v_mfma_f32_16x16x32_bf16 v[104:107], v[186:189], v[202:205], v[104:107]
	v_mfma_f32_16x16x32_bf16 v[92:95], v[178:181], v[210:213], v[92:95]
	v_mfma_f32_16x16x32_bf16 v[80:83], v[186:189], v[210:213], v[80:83]
	v_mfma_f32_16x16x32_bf16 v[76:79], v[178:181], v[218:221], v[76:79]
	v_mfma_f32_16x16x32_bf16 v[64:67], v[186:189], v[218:221], v[64:67]
	s_barrier
	s_add_i32 s56, s49, s36
	v_lshl_add_u64 v[156:157], s[30:31], 0, v[130:131]
	s_mov_b32 m0, s56
	ds_read_b128 v[190:193], v159 offset:16384
	ds_read_b128 v[194:197], v159 offset:17408
	ds_read_b128 v[198:201], v159 offset:18432
	ds_read_b128 v[202:205], v159 offset:19456
	ds_read_b128 v[206:209], v159 offset:20480
	ds_read_b128 v[210:213], v159 offset:21504
	ds_read_b128 v[214:217], v159 offset:22528
	ds_read_b128 v[218:221], v159 offset:23552
	global_load_lds_dwordx4 v[156:157], off
	s_add_i32 m0, s56, 0x2000
	s_add_u32 s56, s30, 0x40000
	v_lshl_add_u64 v[222:223], s[30:31], 0, v[134:135]
	s_addc_u32 s57, s31, 0
	s_add_i32 s58, s50, s36
	global_load_lds_dwordx4 v[222:223], off
	v_lshl_add_u64 v[224:225], s[56:57], 0, v[130:131]
	s_mov_b32 m0, s58
	v_lshl_add_u64 v[226:227], s[34:35], 0, v[132:133]
	global_load_lds_dwordx4 v[224:225], off
	v_lshl_add_u64 v[224:225], s[56:57], 0, v[134:135]
	s_add_i32 m0, s58, 0x2000
	s_nop 0
	global_load_lds_dwordx4 v[224:225], off
	v_lshl_add_u64 v[224:225], s[34:35], 0, v[128:129]
	s_mov_b32 m0, s39
	s_nop 0
	global_load_lds_dwordx4 v[224:225], off
	s_mov_b32 m0, s40
	s_nop 0
	global_load_lds_dwordx4 v[226:227], off
	s_waitcnt vmcnt(8)
	s_waitcnt lgkmcnt(0)
	s_barrier
	s_waitcnt lgkmcnt(0)
	v_mfma_f32_16x16x32_bf16 v[56:59], v[152:155], v[190:193], v[56:59]
	v_mfma_f32_16x16x32_bf16 v[52:55], v[166:169], v[190:193], v[52:55]
	v_mfma_f32_16x16x32_bf16 v[40:43], v[152:155], v[198:201], v[40:43]
	v_mfma_f32_16x16x32_bf16 v[36:39], v[166:169], v[198:201], v[36:39]
	v_mfma_f32_16x16x32_bf16 v[24:27], v[152:155], v[206:209], v[24:27]
	v_mfma_f32_16x16x32_bf16 v[20:23], v[166:169], v[206:209], v[20:23]
	v_mfma_f32_16x16x32_bf16 v[8:11], v[152:155], v[214:217], v[8:11]
	v_mfma_f32_16x16x32_bf16 v[4:7], v[166:169], v[214:217], v[4:7]
	v_mfma_f32_16x16x32_bf16 v[56:59], v[162:165], v[194:197], v[56:59]
	v_mfma_f32_16x16x32_bf16 v[52:55], v[170:173], v[194:197], v[52:55]
	v_mfma_f32_16x16x32_bf16 v[40:43], v[162:165], v[202:205], v[40:43]
	v_mfma_f32_16x16x32_bf16 v[36:39], v[170:173], v[202:205], v[36:39]
	v_mfma_f32_16x16x32_bf16 v[24:27], v[162:165], v[210:213], v[24:27]
	v_mfma_f32_16x16x32_bf16 v[20:23], v[170:173], v[210:213], v[20:23]
	v_mfma_f32_16x16x32_bf16 v[8:11], v[162:165], v[218:221], v[8:11]
	v_mfma_f32_16x16x32_bf16 v[4:7], v[170:173], v[218:221], v[4:7]
	v_mfma_f32_16x16x32_bf16 v[60:63], v[174:177], v[190:193], v[60:63]
	v_mfma_f32_16x16x32_bf16 v[48:51], v[182:185], v[190:193], v[48:51]
	v_mfma_f32_16x16x32_bf16 v[44:47], v[174:177], v[198:201], v[44:47]
	v_mfma_f32_16x16x32_bf16 v[32:35], v[182:185], v[198:201], v[32:35]
	v_mfma_f32_16x16x32_bf16 v[28:31], v[174:177], v[206:209], v[28:31]
	v_mfma_f32_16x16x32_bf16 v[16:19], v[182:185], v[206:209], v[16:19]
	v_mfma_f32_16x16x32_bf16 v[12:15], v[174:177], v[214:217], v[12:15]
	v_mfma_f32_16x16x32_bf16 v[0:3], v[182:185], v[214:217], v[0:3]
	v_mfma_f32_16x16x32_bf16 v[60:63], v[178:181], v[194:197], v[60:63]
	v_mfma_f32_16x16x32_bf16 v[48:51], v[186:189], v[194:197], v[48:51]
	v_mfma_f32_16x16x32_bf16 v[44:47], v[178:181], v[202:205], v[44:47]
	v_mfma_f32_16x16x32_bf16 v[32:35], v[186:189], v[202:205], v[32:35]
	v_mfma_f32_16x16x32_bf16 v[28:31], v[178:181], v[210:213], v[28:31]
	v_mfma_f32_16x16x32_bf16 v[16:19], v[186:189], v[210:213], v[16:19]
	v_mfma_f32_16x16x32_bf16 v[12:15], v[178:181], v[218:221], v[12:15]
	v_mfma_f32_16x16x32_bf16 v[0:3], v[186:189], v[218:221], v[0:3]
	s_barrier
	s_add_i32 s56, 0, 0x18000
	s_add_i32 s57, 0, 0x1c000
	v_add_u32_e32 v170, s56, v141
	v_add_u32_e32 v186, s57, v141
	ds_read_b128 v[152:155], v170
	ds_read_b128 v[162:165], v170 offset:1024
	ds_read_b128 v[166:169], v170 offset:2048
	ds_read_b128 v[170:173], v170 offset:3072
	ds_read_b128 v[174:177], v186
	ds_read_b128 v[178:181], v186 offset:1024
	ds_read_b128 v[182:185], v186 offset:2048
	ds_read_b128 v[186:189], v186 offset:3072
	s_add_u32 s34, s34, 0x40000
	s_addc_u32 s35, s35, 0
	s_mov_b32 m0, s41
	v_lshl_add_u64 v[228:229], s[34:35], 0, v[128:129]
	ds_read_b128 v[190:193], v159 offset:32768
	ds_read_b128 v[194:197], v159 offset:33792
	ds_read_b128 v[198:201], v159 offset:34816
	ds_read_b128 v[202:205], v159 offset:35840
	ds_read_b128 v[206:209], v159 offset:36864
	ds_read_b128 v[210:213], v159 offset:37888
	ds_read_b128 v[214:217], v159 offset:38912
	ds_read_b128 v[218:221], v159 offset:39936
	global_load_lds_dwordx4 v[228:229], off
	v_lshl_add_u64 v[228:229], s[34:35], 0, v[132:133]
	s_mov_b32 m0, s42
	s_nop 0
	global_load_lds_dwordx4 v[228:229], off
	s_waitcnt vmcnt(8)
	s_waitcnt lgkmcnt(0)
	s_barrier
	s_waitcnt lgkmcnt(0)
	v_mfma_f32_16x16x32_bf16 v[116:119], v[152:155], v[190:193], v[116:119]
	v_mfma_f32_16x16x32_bf16 v[112:115], v[166:169], v[190:193], v[112:115]
	v_mfma_f32_16x16x32_bf16 v[100:103], v[152:155], v[198:201], v[100:103]
	v_mfma_f32_16x16x32_bf16 v[96:99], v[166:169], v[198:201], v[96:99]
	v_mfma_f32_16x16x32_bf16 v[88:91], v[152:155], v[206:209], v[88:91]
	v_mfma_f32_16x16x32_bf16 v[84:87], v[166:169], v[206:209], v[84:87]
	v_mfma_f32_16x16x32_bf16 v[72:75], v[152:155], v[214:217], v[72:75]
	v_mfma_f32_16x16x32_bf16 v[68:71], v[166:169], v[214:217], v[68:71]
	v_mfma_f32_16x16x32_bf16 v[116:119], v[162:165], v[194:197], v[116:119]
	v_mfma_f32_16x16x32_bf16 v[112:115], v[170:173], v[194:197], v[112:115]
	v_mfma_f32_16x16x32_bf16 v[100:103], v[162:165], v[202:205], v[100:103]
	v_mfma_f32_16x16x32_bf16 v[96:99], v[170:173], v[202:205], v[96:99]
	v_mfma_f32_16x16x32_bf16 v[88:91], v[162:165], v[210:213], v[88:91]
	v_mfma_f32_16x16x32_bf16 v[84:87], v[170:173], v[210:213], v[84:87]
	v_mfma_f32_16x16x32_bf16 v[72:75], v[162:165], v[218:221], v[72:75]
	v_mfma_f32_16x16x32_bf16 v[68:71], v[170:173], v[218:221], v[68:71]
	v_mfma_f32_16x16x32_bf16 v[124:127], v[174:177], v[190:193], v[124:127]
	v_mfma_f32_16x16x32_bf16 v[120:123], v[182:185], v[190:193], v[120:123]
	v_mfma_f32_16x16x32_bf16 v[108:111], v[174:177], v[198:201], v[108:111]
	v_mfma_f32_16x16x32_bf16 v[104:107], v[182:185], v[198:201], v[104:107]
	v_mfma_f32_16x16x32_bf16 v[92:95], v[174:177], v[206:209], v[92:95]
	v_mfma_f32_16x16x32_bf16 v[80:83], v[182:185], v[206:209], v[80:83]
	v_mfma_f32_16x16x32_bf16 v[76:79], v[174:177], v[214:217], v[76:79]
	v_mfma_f32_16x16x32_bf16 v[64:67], v[182:185], v[214:217], v[64:67]
	v_mfma_f32_16x16x32_bf16 v[124:127], v[178:181], v[194:197], v[124:127]
	v_mfma_f32_16x16x32_bf16 v[120:123], v[186:189], v[194:197], v[120:123]
	v_mfma_f32_16x16x32_bf16 v[108:111], v[178:181], v[202:205], v[108:111]
	v_mfma_f32_16x16x32_bf16 v[104:107], v[186:189], v[202:205], v[104:107]
	v_mfma_f32_16x16x32_bf16 v[92:95], v[178:181], v[210:213], v[92:95]
	v_mfma_f32_16x16x32_bf16 v[80:83], v[186:189], v[210:213], v[80:83]
	v_mfma_f32_16x16x32_bf16 v[76:79], v[178:181], v[218:221], v[76:79]
	v_mfma_f32_16x16x32_bf16 v[64:67], v[186:189], v[218:221], v[64:67]
	s_barrier
	s_add_i32 s34, s56, s36
	v_lshl_add_u64 v[156:157], v[156:157], 0, s[10:11]
	s_mov_b32 m0, s34
	ds_read_b128 v[190:193], v159 offset:49152
	ds_read_b128 v[194:197], v159 offset:50176
	ds_read_b128 v[198:201], v159 offset:51200
	ds_read_b128 v[202:205], v159 offset:52224
	ds_read_b128 v[206:209], v159 offset:53248
	ds_read_b128 v[210:213], v159 offset:54272
	ds_read_b128 v[214:217], v159 offset:55296
	ds_read_b128 v[218:221], v159 offset:56320
	global_load_lds_dwordx4 v[156:157], off
	s_add_i32 m0, s34, 0x2000
	s_add_u32 s30, s30, 0x40080
	v_lshl_add_u64 v[156:157], v[222:223], 0, s[10:11]
	s_addc_u32 s31, s31, 0
	s_add_i32 s34, s57, s36
	global_load_lds_dwordx4 v[156:157], off
	v_lshl_add_u64 v[156:157], s[30:31], 0, v[130:131]
	s_mov_b32 m0, s34
	s_nop 0
	global_load_lds_dwordx4 v[156:157], off
	v_lshl_add_u64 v[156:157], s[30:31], 0, v[134:135]
	s_add_i32 m0, s34, 0x2000
	s_nop 0
	global_load_lds_dwordx4 v[156:157], off
	v_lshl_add_u64 v[156:157], v[224:225], 0, s[10:11]
	s_mov_b32 m0, s43
	s_nop 0
	global_load_lds_dwordx4 v[156:157], off
	v_lshl_add_u64 v[156:157], v[226:227], 0, s[10:11]
	s_mov_b32 m0, s44
	s_nop 0
	global_load_lds_dwordx4 v[156:157], off
	s_waitcnt vmcnt(8)
	s_waitcnt lgkmcnt(0)
	s_barrier
	s_waitcnt lgkmcnt(0)
	v_mfma_f32_16x16x32_bf16 v[56:59], v[152:155], v[190:193], v[56:59]
	v_mfma_f32_16x16x32_bf16 v[52:55], v[166:169], v[190:193], v[52:55]
	v_mfma_f32_16x16x32_bf16 v[40:43], v[152:155], v[198:201], v[40:43]
	v_mfma_f32_16x16x32_bf16 v[36:39], v[166:169], v[198:201], v[36:39]
	v_mfma_f32_16x16x32_bf16 v[24:27], v[152:155], v[206:209], v[24:27]
	v_mfma_f32_16x16x32_bf16 v[20:23], v[166:169], v[206:209], v[20:23]
	v_mfma_f32_16x16x32_bf16 v[8:11], v[152:155], v[214:217], v[8:11]
	v_mfma_f32_16x16x32_bf16 v[4:7], v[166:169], v[214:217], v[4:7]
	v_mfma_f32_16x16x32_bf16 v[56:59], v[162:165], v[194:197], v[56:59]
	v_mfma_f32_16x16x32_bf16 v[52:55], v[170:173], v[194:197], v[52:55]
	v_mfma_f32_16x16x32_bf16 v[40:43], v[162:165], v[202:205], v[40:43]
	v_mfma_f32_16x16x32_bf16 v[36:39], v[170:173], v[202:205], v[36:39]
	v_mfma_f32_16x16x32_bf16 v[24:27], v[162:165], v[210:213], v[24:27]
	v_mfma_f32_16x16x32_bf16 v[20:23], v[170:173], v[210:213], v[20:23]
	v_mfma_f32_16x16x32_bf16 v[8:11], v[162:165], v[218:221], v[8:11]
	v_mfma_f32_16x16x32_bf16 v[4:7], v[170:173], v[218:221], v[4:7]
	v_mfma_f32_16x16x32_bf16 v[60:63], v[174:177], v[190:193], v[60:63]
	v_mfma_f32_16x16x32_bf16 v[48:51], v[182:185], v[190:193], v[48:51]
	v_mfma_f32_16x16x32_bf16 v[44:47], v[174:177], v[198:201], v[44:47]
	v_mfma_f32_16x16x32_bf16 v[32:35], v[182:185], v[198:201], v[32:35]
	v_mfma_f32_16x16x32_bf16 v[28:31], v[174:177], v[206:209], v[28:31]
	v_mfma_f32_16x16x32_bf16 v[16:19], v[182:185], v[206:209], v[16:19]
	v_mfma_f32_16x16x32_bf16 v[12:15], v[174:177], v[214:217], v[12:15]
	v_mfma_f32_16x16x32_bf16 v[0:3], v[182:185], v[214:217], v[0:3]
	v_mfma_f32_16x16x32_bf16 v[60:63], v[178:181], v[194:197], v[60:63]
	v_mfma_f32_16x16x32_bf16 v[48:51], v[186:189], v[194:197], v[48:51]
	v_mfma_f32_16x16x32_bf16 v[44:47], v[178:181], v[202:205], v[44:47]
	v_mfma_f32_16x16x32_bf16 v[32:35], v[186:189], v[202:205], v[32:35]
	v_mfma_f32_16x16x32_bf16 v[28:31], v[178:181], v[210:213], v[28:31]
	v_mfma_f32_16x16x32_bf16 v[16:19], v[186:189], v[210:213], v[16:19]
	v_mfma_f32_16x16x32_bf16 v[12:15], v[178:181], v[218:221], v[12:15]
	v_mfma_f32_16x16x32_bf16 v[0:3], v[186:189], v[218:221], v[0:3]
	s_barrier
	s_add_i32 s55, s55, 2
	s_add_u32 s28, s28, 0x100
	s_addc_u32 s29, s29, 0
	s_add_u32 s53, s53, 0x100
	s_addc_u32 s54, s54, 0
	s_cmp_gt_u32 s55, 13
	s_cbranch_scc0 .LBB0_161
	s_and_b64 vcc, exec, s[12:13]
	s_cbranch_vccz .LBB0_166
	s_barrier
	v_lshl_add_u32 v152, s26, 8, v139
	s_cmp_gt_i32 s24, 21
	s_mov_b64 s[26:27], -1
	s_cbranch_scc1 .LBB0_167

.LBB0_193:
	s_waitcnt vmcnt(0)
	s_barrier
	s_setprio 0
	s_load_dwordx2 s[2:3], s[0:1], 0x120

.LBB0_231:
	v_ashrrev_i32_e32 v2, 31, v0
	v_lshrrev_b32_e32 v2, 26, v2
	v_lshlrev_b32_e32 v1, 4, v0
	v_add_u32_e32 v2, v0, v2
	v_bfe_i32 v0, v0, 27, 1
	v_lshrrev_b32_e32 v0, 22, v0
	v_add_u32_e32 v0, v1, v0
	v_and_b32_e32 v0, 0xfffffc00, v0
	v_sub_u32_e32 v0, v1, v0
	v_ashrrev_i32_e32 v9, 6, v2
	v_lshrrev_b32_e32 v2, 4, v0
	v_bitop3_b32 v0, v2, v0, 32 bitop3:0x6c
	v_ashrrev_i32_e32 v3, 31, v0
	v_lshrrev_b32_e32 v3, 26, v3
	v_add_u32_e32 v3, v0, v3
	v_lshlrev_b32_e32 v2, 3, v9
	v_ashrrev_i32_e32 v11, 6, v3
	v_and_b32_e32 v3, 0xc0, v3
	s_ashr_i32 s3, s4, 6
	v_and_b32_e32 v2, 0xfffff0, v2
	v_sub_u32_e32 v0, v0, v3
	v_mov_b32_e32 v3, 1
	s_ashr_i32 s7, s5, 3
	v_add_u32_e32 v2, v11, v2
	v_lshlrev_b32_e32 v4, 5, v9
	v_ashrrev_i16_sdwa v0, v3, sext(v0) dst_sel:DWORD dst_unused:UNUSED_PAD src0_sel:DWORD src1_sel:BYTE_0
	s_movk_i32 s2, 0xb00
	s_ashr_i32 s5, s4, 8
	s_lshl_b32 s37, s3, 10
	v_and_b32_e32 v10, 32, v4
	v_bfe_i32 v12, v0, 0, 16
	v_mul_lo_u32 v0, v2, s2
	s_add_u32 s38, s70, 0x3400000
	v_or_b32_e32 v0, v0, v10
	s_addc_u32 s39, s71, 0
	s_add_i32 s6, s6, s7
	v_add_lshl_u32 v128, v0, v12, 1
	v_add_u32_e32 v0, 0x2000, v1
	s_ashr_i32 s7, s6, 31
	v_ashrrev_i32_e32 v1, 31, v0
	s_lshr_b32 s7, s7, 27
	v_lshrrev_b32_e32 v1, 22, v1
	s_add_i32 s7, s6, s7
	v_add_u32_e32 v1, v0, v1
	s_ashr_i32 s8, s7, 5
	s_andn2_b32 s7, s7, 31
	v_ashrrev_i32_e32 v13, 10, v1
	s_sub_i32 s6, s6, s7
	v_mul_i32_i24_e32 v1, 0x400, v13
	s_bfe_i32 s7, s6, 0x80000
	v_sub_u32_e32 v0, v0, v1
	s_bfe_u32 s7, s7, 0x3000c
	v_lshrrev_b32_e32 v1, 4, v0
	s_add_i32 s7, s6, s7
	v_bitop3_b32 v0, v1, v0, 32 bitop3:0x6c
	s_bfe_i32 s9, s7, 0x80000
	s_and_b32 s7, s7, 0xf8
	v_ashrrev_i32_e32 v2, 31, v0
	s_sub_i32 s6, s6, s7
	v_lshrrev_b32_e32 v2, 26, v2
	s_lshl_b32 s8, s8, 3
	s_sext_i32_i16 s9, s9
	s_sext_i32_i8 s6, s6
	v_add_u32_e32 v2, v0, v2
	s_add_i32 s52, s8, s6
	s_ashr_i32 s6, s9, 3
	v_lshlrev_b32_e32 v1, 3, v13
	v_ashrrev_i32_e32 v14, 6, v2
	v_and_b32_e32 v2, 0xc0, v2
	s_lshr_b32 s16, s9, 3
	s_mul_hi_i32 s7, s6, 0x160000
	s_mul_i32 s6, s6, 0x160000
	v_and_b32_e32 v1, 0xfffff0, v1
	v_sub_u32_e32 v0, v0, v2
	s_add_u32 s28, s38, s6
	v_add_u32_e32 v1, v14, v1
	v_lshlrev_b32_e32 v4, 5, v13
	v_ashrrev_i16_sdwa v0, v3, sext(v0) dst_sel:DWORD dst_unused:UNUSED_PAD src0_sel:DWORD src1_sel:BYTE_0
	s_addc_u32 s29, s39, s7
	s_add_i32 s40, s37, 0
	v_and_b32_e32 v15, 32, v4
	v_bfe_i32 v16, v0, 0, 16
	v_mul_lo_u32 v0, v1, s2
	s_add_i32 m0, s40, 0x10000
	v_or_b32_e32 v0, v0, v15
	global_load_lds_dwordx4 v128, s[28:29]
	s_add_i32 m0, s40, 0x12000
	v_add_lshl_u32 v130, v0, v16, 1
	s_add_u32 s6, s28, 0xb0000
	global_load_lds_dwordx4 v130, s[28:29]
	s_addc_u32 s7, s29, 0
	s_add_i32 m0, s40, 0x14000
	s_mul_i32 s10, s52, 0x160000
	global_load_lds_dwordx4 v128, s[6:7]
	s_add_i32 m0, s40, 0x16000
	s_mul_hi_i32 s8, s52, 0x160000
	s_add_u32 s26, s72, s10
	s_addc_u32 s27, s73, s8
	s_add_i32 s41, s40, 0x2000
	global_load_lds_dwordx4 v130, s[6:7]
	s_mov_b32 m0, s40
	s_add_u32 s6, s26, 0xb0000
	global_load_lds_dwordx4 v128, s[26:27]
	s_mov_b32 m0, s41
	s_addc_u32 s7, s27, 0
	s_add_i32 s42, s40, 0x4000
	global_load_lds_dwordx4 v130, s[26:27]
	s_mov_b32 m0, s42
	s_add_i32 s43, s40, 0x6000
	global_load_lds_dwordx4 v128, s[6:7]
	s_mov_b32 m0, s43
	v_mov_b32_e32 v129, 0
	global_load_lds_dwordx4 v130, s[6:7]
	s_load_dwordx2 s[6:7], s[0:1], 0x0
	s_load_dwordx2 s[8:9], s[0:1], 0x110
	v_mov_b32_e32 v131, v129
	s_cmp_eq_u32 s5, 1
	s_mov_b32 s44, 0
	v_lshl_add_u64 v[6:7], s[28:29], 0, v[128:129]
	v_lshl_add_u64 v[4:5], s[28:29], 0, v[130:131]
	s_mov_b64 s[10:11], 0xb0000
	v_lshl_add_u64 v[0:1], s[26:27], 0, v[128:129]
	s_cselect_b64 s[12:13], -1, 0
	s_cmp_lg_u32 s5, 1
	v_lshl_add_u64 v[2:3], s[26:27], 0, v[130:131]
	s_cbranch_scc1 .LBB0_233
	s_barrier
	s_setprio 1

.LBB0_247:
	ds_read_b128 v[148:151], v145
	ds_read_b128 v[152:155], v145 offset:1024
	ds_read_b128 v[156:159], v145 offset:2048
	ds_read_b128 v[160:163], v145 offset:3072
	ds_read_b128 v[164:167], v146
	ds_read_b128 v[168:171], v146 offset:1024
	ds_read_b128 v[172:175], v146 offset:2048
	ds_read_b128 v[176:179], v146 offset:3072
	s_add_u32 s28, s26, 0x100
	s_addc_u32 s29, s27, 0
	s_cmp_eq_u32 s56, 40
	s_cselect_b32 s35, s5, s29
	s_cselect_b32 s34, s4, s28
	s_cselect_b32 s31, s25, s55
	s_cselect_b32 s30, s24, s54
	v_lshl_add_u64 v[140:141], s[26:27], 0, v[132:133]
	s_add_i32 m0, s40, 0xc000
	ds_read_b128 v[180:183], v147
	ds_read_b128 v[184:187], v147 offset:1024
	ds_read_b128 v[188:191], v147 offset:2048
	ds_read_b128 v[192:195], v147 offset:3072
	ds_read_b128 v[196:199], v147 offset:4096
	ds_read_b128 v[200:203], v147 offset:5120
	ds_read_b128 v[204:207], v147 offset:6144
	ds_read_b128 v[208:211], v147 offset:7168
	global_load_lds_dwordx4 v[140:141], off
	v_lshl_add_u64 v[140:141], s[26:27], 0, v[134:135]
	s_add_i32 m0, s40, 0xe000
	s_nop 0
	global_load_lds_dwordx4 v[140:141], off
	s_waitcnt vmcnt(8)
	s_waitcnt lgkmcnt(0)
	s_barrier
	s_waitcnt lgkmcnt(0)
	v_mfma_f32_16x16x32_bf16 v[124:127], v[148:151], v[180:183], v[124:127]
	v_mfma_f32_16x16x32_bf16 v[120:123], v[156:159], v[180:183], v[120:123]
	v_mfma_f32_16x16x32_bf16 v[112:115], v[148:151], v[188:191], v[112:115]
	v_mfma_f32_16x16x32_bf16 v[108:111], v[156:159], v[188:191], v[108:111]
	v_mfma_f32_16x16x32_bf16 v[96:99], v[148:151], v[196:199], v[96:99]
	v_mfma_f32_16x16x32_bf16 v[92:95], v[156:159], v[196:199], v[92:95]
	v_mfma_f32_16x16x32_bf16 v[80:83], v[148:151], v[204:207], v[80:83]
	v_mfma_f32_16x16x32_bf16 v[76:79], v[156:159], v[204:207], v[76:79]
	v_mfma_f32_16x16x32_bf16 v[124:127], v[152:155], v[184:187], v[124:127]
	v_mfma_f32_16x16x32_bf16 v[120:123], v[160:163], v[184:187], v[120:123]
	v_mfma_f32_16x16x32_bf16 v[112:115], v[152:155], v[192:195], v[112:115]
	v_mfma_f32_16x16x32_bf16 v[108:111], v[160:163], v[192:195], v[108:111]
	v_mfma_f32_16x16x32_bf16 v[96:99], v[152:155], v[200:203], v[96:99]
	v_mfma_f32_16x16x32_bf16 v[92:95], v[160:163], v[200:203], v[92:95]
	v_mfma_f32_16x16x32_bf16 v[80:83], v[152:155], v[208:211], v[80:83]
	v_mfma_f32_16x16x32_bf16 v[76:79], v[160:163], v[208:211], v[76:79]
	v_mfma_f32_16x16x32_bf16 v[116:119], v[164:167], v[180:183], v[116:119]
	v_mfma_f32_16x16x32_bf16 v[104:107], v[172:175], v[180:183], v[104:107]
	v_mfma_f32_16x16x32_bf16 v[100:103], v[164:167], v[188:191], v[100:103]
	v_mfma_f32_16x16x32_bf16 v[88:91], v[172:175], v[188:191], v[88:91]
	v_mfma_f32_16x16x32_bf16 v[84:87], v[164:167], v[196:199], v[84:87]
	v_mfma_f32_16x16x32_bf16 v[72:75], v[172:175], v[196:199], v[72:75]
	v_mfma_f32_16x16x32_bf16 v[68:71], v[164:167], v[204:207], v[68:71]
	v_mfma_f32_16x16x32_bf16 v[64:67], v[172:175], v[204:207], v[64:67]
	v_mfma_f32_16x16x32_bf16 v[116:119], v[168:171], v[184:187], v[116:119]
	v_mfma_f32_16x16x32_bf16 v[104:107], v[176:179], v[184:187], v[104:107]
	v_mfma_f32_16x16x32_bf16 v[100:103], v[168:171], v[192:195], v[100:103]
	v_mfma_f32_16x16x32_bf16 v[88:91], v[176:179], v[192:195], v[88:91]
	v_mfma_f32_16x16x32_bf16 v[84:87], v[168:171], v[200:203], v[84:87]
	v_mfma_f32_16x16x32_bf16 v[72:75], v[176:179], v[200:203], v[72:75]
	v_mfma_f32_16x16x32_bf16 v[68:71], v[168:171], v[208:211], v[68:71]
	v_mfma_f32_16x16x32_bf16 v[64:67], v[176:179], v[208:211], v[64:67]
	s_barrier
	s_add_i32 s26, s48, s37
	v_lshl_add_u64 v[140:141], s[30:31], 0, v[128:129]
	s_mov_b32 m0, s26
	ds_read_b128 v[180:183], v147 offset:16384
	ds_read_b128 v[184:187], v147 offset:17408
	ds_read_b128 v[188:191], v147 offset:18432
	ds_read_b128 v[192:195], v147 offset:19456
	ds_read_b128 v[196:199], v147 offset:20480
	ds_read_b128 v[200:203], v147 offset:21504
	ds_read_b128 v[204:207], v147 offset:22528
	ds_read_b128 v[208:211], v147 offset:23552
	global_load_lds_dwordx4 v[140:141], off
	s_add_i32 m0, s26, 0x2000
	s_add_u32 s26, s30, 0xb0000
	v_lshl_add_u64 v[212:213], s[30:31], 0, v[130:131]
	s_addc_u32 s27, s31, 0
	s_add_i32 s57, s49, s37
	global_load_lds_dwordx4 v[212:213], off
	v_lshl_add_u64 v[214:215], s[26:27], 0, v[128:129]
	s_mov_b32 m0, s57
	v_lshl_add_u64 v[216:217], s[34:35], 0, v[130:131]
	global_load_lds_dwordx4 v[214:215], off
	v_lshl_add_u64 v[214:215], s[26:27], 0, v[130:131]
	s_add_i32 m0, s57, 0x2000
	s_nop 0
	global_load_lds_dwordx4 v[214:215], off
	v_lshl_add_u64 v[214:215], s[34:35], 0, v[128:129]
	s_mov_b32 m0, s40
	s_nop 0
	global_load_lds_dwordx4 v[214:215], off
	s_mov_b32 m0, s41
	s_nop 0
	global_load_lds_dwordx4 v[216:217], off
	s_waitcnt vmcnt(8)
	s_waitcnt lgkmcnt(0)
	s_barrier
	s_waitcnt lgkmcnt(0)
	v_mfma_f32_16x16x32_bf16 v[60:63], v[148:151], v[180:183], v[60:63]
	v_mfma_f32_16x16x32_bf16 v[56:59], v[156:159], v[180:183], v[56:59]
	v_mfma_f32_16x16x32_bf16 v[48:51], v[148:151], v[188:191], v[48:51]
	v_mfma_f32_16x16x32_bf16 v[44:47], v[156:159], v[188:191], v[44:47]
	v_mfma_f32_16x16x32_bf16 v[32:35], v[148:151], v[196:199], v[32:35]
	v_mfma_f32_16x16x32_bf16 v[28:31], v[156:159], v[196:199], v[28:31]
	v_mfma_f32_16x16x32_bf16 v[16:19], v[148:151], v[204:207], v[16:19]
	v_mfma_f32_16x16x32_bf16 v[12:15], v[156:159], v[204:207], v[12:15]
	v_mfma_f32_16x16x32_bf16 v[60:63], v[152:155], v[184:187], v[60:63]
	v_mfma_f32_16x16x32_bf16 v[56:59], v[160:163], v[184:187], v[56:59]
	v_mfma_f32_16x16x32_bf16 v[48:51], v[152:155], v[192:195], v[48:51]
	v_mfma_f32_16x16x32_bf16 v[44:47], v[160:163], v[192:195], v[44:47]
	v_mfma_f32_16x16x32_bf16 v[32:35], v[152:155], v[200:203], v[32:35]
	v_mfma_f32_16x16x32_bf16 v[28:31], v[160:163], v[200:203], v[28:31]
	v_mfma_f32_16x16x32_bf16 v[16:19], v[152:155], v[208:211], v[16:19]
	v_mfma_f32_16x16x32_bf16 v[12:15], v[160:163], v[208:211], v[12:15]
	v_mfma_f32_16x16x32_bf16 v[52:55], v[164:167], v[180:183], v[52:55]
	v_mfma_f32_16x16x32_bf16 v[40:43], v[172:175], v[180:183], v[40:43]
	v_mfma_f32_16x16x32_bf16 v[36:39], v[164:167], v[188:191], v[36:39]
	v_mfma_f32_16x16x32_bf16 v[24:27], v[172:175], v[188:191], v[24:27]
	v_mfma_f32_16x16x32_bf16 v[20:23], v[164:167], v[196:199], v[20:23]
	v_mfma_f32_16x16x32_bf16 v[8:11], v[172:175], v[196:199], v[8:11]
	v_mfma_f32_16x16x32_bf16 v[4:7], v[164:167], v[204:207], v[4:7]
	v_mfma_f32_16x16x32_bf16 v[0:3], v[172:175], v[204:207], v[0:3]
	v_mfma_f32_16x16x32_bf16 v[52:55], v[168:171], v[184:187], v[52:55]
	v_mfma_f32_16x16x32_bf16 v[40:43], v[176:179], v[184:187], v[40:43]
	v_mfma_f32_16x16x32_bf16 v[36:39], v[168:171], v[192:195], v[36:39]
	v_mfma_f32_16x16x32_bf16 v[24:27], v[176:179], v[192:195], v[24:27]
	v_mfma_f32_16x16x32_bf16 v[20:23], v[168:171], v[200:203], v[20:23]
	v_mfma_f32_16x16x32_bf16 v[8:11], v[176:179], v[200:203], v[8:11]
	v_mfma_f32_16x16x32_bf16 v[4:7], v[168:171], v[208:211], v[4:7]
	v_mfma_f32_16x16x32_bf16 v[0:3], v[176:179], v[208:211], v[0:3]
	s_barrier
	s_add_i32 s57, 0, 0x18000
	s_add_i32 s58, 0, 0x1c000
	v_add_u32_e32 v160, s57, v143
	v_add_u32_e32 v176, s58, v143
	ds_read_b128 v[148:151], v160
	ds_read_b128 v[152:155], v160 offset:1024
	ds_read_b128 v[156:159], v160 offset:2048
	ds_read_b128 v[160:163], v160 offset:3072
	ds_read_b128 v[164:167], v176
	ds_read_b128 v[168:171], v176 offset:1024
	ds_read_b128 v[172:175], v176 offset:2048
	ds_read_b128 v[176:179], v176 offset:3072
	s_add_u32 s26, s34, 0xb0000
	s_addc_u32 s27, s35, 0
	s_mov_b32 m0, s42
	v_lshl_add_u64 v[218:219], s[26:27], 0, v[128:129]
	ds_read_b128 v[180:183], v147 offset:32768
	ds_read_b128 v[184:187], v147 offset:33792
	ds_read_b128 v[188:191], v147 offset:34816
	ds_read_b128 v[192:195], v147 offset:35840
	ds_read_b128 v[196:199], v147 offset:36864
	ds_read_b128 v[200:203], v147 offset:37888
	ds_read_b128 v[204:207], v147 offset:38912
	ds_read_b128 v[208:211], v147 offset:39936
	global_load_lds_dwordx4 v[218:219], off
	v_lshl_add_u64 v[218:219], s[26:27], 0, v[130:131]
	s_mov_b32 m0, s43
	s_nop 0
	global_load_lds_dwordx4 v[218:219], off
	s_waitcnt vmcnt(8)
	s_waitcnt lgkmcnt(0)
	s_barrier
	s_waitcnt lgkmcnt(0)
	v_mfma_f32_16x16x32_bf16 v[124:127], v[148:151], v[180:183], v[124:127]
	v_mfma_f32_16x16x32_bf16 v[120:123], v[156:159], v[180:183], v[120:123]
	v_mfma_f32_16x16x32_bf16 v[112:115], v[148:151], v[188:191], v[112:115]
	v_mfma_f32_16x16x32_bf16 v[108:111], v[156:159], v[188:191], v[108:111]
	v_mfma_f32_16x16x32_bf16 v[96:99], v[148:151], v[196:199], v[96:99]
	v_mfma_f32_16x16x32_bf16 v[92:95], v[156:159], v[196:199], v[92:95]
	v_mfma_f32_16x16x32_bf16 v[80:83], v[148:151], v[204:207], v[80:83]
	v_mfma_f32_16x16x32_bf16 v[76:79], v[156:159], v[204:207], v[76:79]
	v_mfma_f32_16x16x32_bf16 v[124:127], v[152:155], v[184:187], v[124:127]
	v_mfma_f32_16x16x32_bf16 v[120:123], v[160:163], v[184:187], v[120:123]
	v_mfma_f32_16x16x32_bf16 v[112:115], v[152:155], v[192:195], v[112:115]
	v_mfma_f32_16x16x32_bf16 v[108:111], v[160:163], v[192:195], v[108:111]
	v_mfma_f32_16x16x32_bf16 v[96:99], v[152:155], v[200:203], v[96:99]
	v_mfma_f32_16x16x32_bf16 v[92:95], v[160:163], v[200:203], v[92:95]
	v_mfma_f32_16x16x32_bf16 v[80:83], v[152:155], v[208:211], v[80:83]
	v_mfma_f32_16x16x32_bf16 v[76:79], v[160:163], v[208:211], v[76:79]
	v_mfma_f32_16x16x32_bf16 v[116:119], v[164:167], v[180:183], v[116:119]
	v_mfma_f32_16x16x32_bf16 v[104:107], v[172:175], v[180:183], v[104:107]
	v_mfma_f32_16x16x32_bf16 v[100:103], v[164:167], v[188:191], v[100:103]
	v_mfma_f32_16x16x32_bf16 v[88:91], v[172:175], v[188:191], v[88:91]
	v_mfma_f32_16x16x32_bf16 v[84:87], v[164:167], v[196:199], v[84:87]
	v_mfma_f32_16x16x32_bf16 v[72:75], v[172:175], v[196:199], v[72:75]
	v_mfma_f32_16x16x32_bf16 v[68:71], v[164:167], v[204:207], v[68:71]
	v_mfma_f32_16x16x32_bf16 v[64:67], v[172:175], v[204:207], v[64:67]
	v_mfma_f32_16x16x32_bf16 v[116:119], v[168:171], v[184:187], v[116:119]
	v_mfma_f32_16x16x32_bf16 v[104:107], v[176:179], v[184:187], v[104:107]
	v_mfma_f32_16x16x32_bf16 v[100:103], v[168:171], v[192:195], v[100:103]
	v_mfma_f32_16x16x32_bf16 v[88:91], v[176:179], v[192:195], v[88:91]
	v_mfma_f32_16x16x32_bf16 v[84:87], v[168:171], v[200:203], v[84:87]
	v_mfma_f32_16x16x32_bf16 v[72:75], v[176:179], v[200:203], v[72:75]
	v_mfma_f32_16x16x32_bf16 v[68:71], v[168:171], v[208:211], v[68:71]
	v_mfma_f32_16x16x32_bf16 v[64:67], v[176:179], v[208:211], v[64:67]
	s_barrier
	s_add_i32 s26, s57, s37
	v_lshl_add_u64 v[140:141], v[140:141], 0, s[14:15]
	s_mov_b32 m0, s26
	ds_read_b128 v[180:183], v147 offset:49152
	ds_read_b128 v[184:187], v147 offset:50176
	ds_read_b128 v[188:191], v147 offset:51200
	ds_read_b128 v[192:195], v147 offset:52224
	ds_read_b128 v[196:199], v147 offset:53248
	ds_read_b128 v[200:203], v147 offset:54272
	ds_read_b128 v[204:207], v147 offset:55296
	ds_read_b128 v[208:211], v147 offset:56320
	global_load_lds_dwordx4 v[140:141], off
	s_add_i32 m0, s26, 0x2000
	s_add_u32 s26, s30, 0xb0080
	v_lshl_add_u64 v[140:141], v[212:213], 0, s[14:15]
	s_addc_u32 s27, s31, 0
	s_add_i32 s30, s58, s37
	global_load_lds_dwordx4 v[140:141], off
	v_lshl_add_u64 v[140:141], s[26:27], 0, v[128:129]
	s_mov_b32 m0, s30
	s_nop 0
	global_load_lds_dwordx4 v[140:141], off
	v_lshl_add_u64 v[140:141], s[26:27], 0, v[130:131]
	s_add_i32 m0, s30, 0x2000
	s_nop 0
	global_load_lds_dwordx4 v[140:141], off
	v_lshl_add_u64 v[140:141], v[214:215], 0, s[14:15]
	s_mov_b32 m0, s45
	s_nop 0
	global_load_lds_dwordx4 v[140:141], off
	v_lshl_add_u64 v[140:141], v[216:217], 0, s[14:15]
	s_mov_b32 m0, s46
	s_nop 0
	global_load_lds_dwordx4 v[140:141], off
	s_waitcnt vmcnt(8)
	s_waitcnt lgkmcnt(0)
	s_barrier
	s_waitcnt lgkmcnt(0)
	v_mfma_f32_16x16x32_bf16 v[60:63], v[148:151], v[180:183], v[60:63]
	v_mfma_f32_16x16x32_bf16 v[56:59], v[156:159], v[180:183], v[56:59]
	v_mfma_f32_16x16x32_bf16 v[48:51], v[148:151], v[188:191], v[48:51]
	v_mfma_f32_16x16x32_bf16 v[44:47], v[156:159], v[188:191], v[44:47]
	v_mfma_f32_16x16x32_bf16 v[32:35], v[148:151], v[196:199], v[32:35]
	v_mfma_f32_16x16x32_bf16 v[28:31], v[156:159], v[196:199], v[28:31]
	v_mfma_f32_16x16x32_bf16 v[16:19], v[148:151], v[204:207], v[16:19]
	v_mfma_f32_16x16x32_bf16 v[12:15], v[156:159], v[204:207], v[12:15]
	v_mfma_f32_16x16x32_bf16 v[60:63], v[152:155], v[184:187], v[60:63]
	v_mfma_f32_16x16x32_bf16 v[56:59], v[160:163], v[184:187], v[56:59]
	v_mfma_f32_16x16x32_bf16 v[48:51], v[152:155], v[192:195], v[48:51]
	v_mfma_f32_16x16x32_bf16 v[44:47], v[160:163], v[192:195], v[44:47]
	v_mfma_f32_16x16x32_bf16 v[32:35], v[152:155], v[200:203], v[32:35]
	v_mfma_f32_16x16x32_bf16 v[28:31], v[160:163], v[200:203], v[28:31]
	v_mfma_f32_16x16x32_bf16 v[16:19], v[152:155], v[208:211], v[16:19]
	v_mfma_f32_16x16x32_bf16 v[12:15], v[160:163], v[208:211], v[12:15]
	v_mfma_f32_16x16x32_bf16 v[52:55], v[164:167], v[180:183], v[52:55]
	v_mfma_f32_16x16x32_bf16 v[40:43], v[172:175], v[180:183], v[40:43]
	v_mfma_f32_16x16x32_bf16 v[36:39], v[164:167], v[188:191], v[36:39]
	v_mfma_f32_16x16x32_bf16 v[24:27], v[172:175], v[188:191], v[24:27]
	v_mfma_f32_16x16x32_bf16 v[20:23], v[164:167], v[196:199], v[20:23]
	v_mfma_f32_16x16x32_bf16 v[8:11], v[172:175], v[196:199], v[8:11]
	v_mfma_f32_16x16x32_bf16 v[4:7], v[164:167], v[204:207], v[4:7]
	v_mfma_f32_16x16x32_bf16 v[0:3], v[172:175], v[204:207], v[0:3]
	v_mfma_f32_16x16x32_bf16 v[52:55], v[168:171], v[184:187], v[52:55]
	v_mfma_f32_16x16x32_bf16 v[40:43], v[176:179], v[184:187], v[40:43]
	v_mfma_f32_16x16x32_bf16 v[36:39], v[168:171], v[192:195], v[36:39]
	v_mfma_f32_16x16x32_bf16 v[24:27], v[176:179], v[192:195], v[24:27]
	v_mfma_f32_16x16x32_bf16 v[20:23], v[168:171], v[200:203], v[20:23]
	v_mfma_f32_16x16x32_bf16 v[8:11], v[176:179], v[200:203], v[8:11]
	v_mfma_f32_16x16x32_bf16 v[4:7], v[168:171], v[208:211], v[4:7]
	v_mfma_f32_16x16x32_bf16 v[0:3], v[176:179], v[208:211], v[0:3]
	s_barrier
	s_add_i32 s56, s56, 2
	s_add_u32 s54, s54, 0x100
	s_addc_u32 s55, s55, 0
	s_cmp_gt_u32 s56, 41
	s_mov_b64 s[26:27], s[28:29]
	s_cbranch_scc0 .LBB0_247
	s_and_b64 vcc, exec, s[16:17]
	s_cbranch_vccz .LBB0_250
	s_barrier

.LBB0_325:
	s_waitcnt lgkmcnt(0)
	s_cmp_lt_i32 s2, 5
	s_cselect_b64 s[4:5], -1, 0
	s_cmp_gt_i32 s3, 4
	s_cselect_b64 s[6:7], -1, 0
	s_and_b64 s[4:5], s[4:5], s[6:7]
	s_andn2_b64 vcc, exec, s[4:5]
	s_cbranch_vccnz .LBB0_367
	v_mbcnt_lo_u32_b32 v9, -1, 0
	v_mbcnt_hi_u32_b32 v9, -1, v9
	s_mov_b32 s2, 0xfffe0
	v_add_u32_e32 v0, s95, v9
	v_ashrrev_i32_e32 v2, 31, v0
	v_lshrrev_b32_e32 v2, 26, v2
	v_readfirstlane_b32 s12, v0
	v_lshlrev_b32_e32 v1, 4, v0
	v_add_u32_e32 v2, v0, v2
	v_bfe_i32 v0, v0, 27, 1
	v_lshrrev_b32_e32 v0, 22, v0
	v_add_u32_e32 v0, v1, v0
	v_and_b32_e32 v0, 0xfffffc00, v0
	v_sub_u32_e32 v0, v1, v0
	v_ashrrev_i32_e32 v8, 6, v2
	v_lshrrev_b32_e32 v2, 4, v0
	v_bitop3_b32 v0, v2, v0, 32 bitop3:0x6c
	v_ashrrev_i32_e32 v3, 31, v0
	v_lshrrev_b32_e32 v3, 26, v3
	v_add_u32_e32 v3, v0, v3
	v_lshlrev_b32_e32 v2, 3, v8
	v_ashrrev_i32_e32 v10, 6, v3
	v_and_b32_e32 v3, 0xc0, v3
	v_and_b32_e32 v2, -16, v2
	v_sub_u32_e32 v0, v0, v3
	v_mov_b32_e32 v3, 1
	v_add_u32_e32 v2, v10, v2
	v_ashrrev_i16_sdwa v0, v3, sext(v0) dst_sel:DWORD dst_unused:UNUSED_PAD src0_sel:DWORD src1_sel:BYTE_0
	v_lshlrev_b32_e32 v4, 5, v8
	v_bfe_i32 v11, v0, 0, 16
	v_lshlrev_b32_e32 v0, 1, v2
	v_lshrrev_b32_e32 v5, 2, v2
	v_and_b32_e32 v6, 3, v10
	v_and_b32_e32 v4, 32, v4
	v_and_b32_e32 v0, 24, v0
	v_and_b32_e32 v5, 4, v5
	v_and_or_b32 v6, v2, s2, v6
	v_or3_b32 v0, v6, v5, v0
	v_add_lshl_u32 v4, v4, v11, 1
	v_lshl_add_u32 v134, v0, 12, v4
	v_add_u32_e32 v0, 0x2000, v1
	v_ashrrev_i32_e32 v1, 31, v0
	v_lshrrev_b32_e32 v1, 22, v1
	v_add_u32_e32 v1, v0, v1
	v_ashrrev_i32_e32 v12, 10, v1
	v_mul_i32_i24_e32 v1, 0x400, v12
	v_sub_u32_e32 v0, v0, v1
	v_lshrrev_b32_e32 v1, 4, v0
	v_bitop3_b32 v0, v1, v0, 32 bitop3:0x6c
	v_lshl_add_u32 v132, v2, 12, v4
	v_ashrrev_i32_e32 v2, 31, v0
	v_lshrrev_b32_e32 v2, 26, v2
	v_add_u32_e32 v2, v0, v2
	v_lshlrev_b32_e32 v1, 3, v12
	v_ashrrev_i32_e32 v13, 6, v2
	v_and_b32_e32 v2, 0xc0, v2
	s_add_u32 s52, s70, 0x1f800000
	v_and_b32_e32 v1, -16, v1
	v_sub_u32_e32 v0, v0, v2
	s_addc_u32 s53, s71, 0
	s_ashr_i32 s10, s12, 6
	v_add_u32_e32 v1, v13, v1
	v_ashrrev_i16_sdwa v0, v3, sext(v0) dst_sel:DWORD dst_unused:UNUSED_PAD src0_sel:DWORD src1_sel:BYTE_0
	v_and_b32_e32 v3, 3, v13
	s_ashr_i32 s13, s12, 8
	v_and_or_b32 v3, v1, s2, v3
	s_cmpk_gt_i32 s33, 0x7f
	s_mul_i32 s2, s33, 3
	s_cselect_b64 s[4:5], -1, 0
	s_add_i32 s54, s2, 0xffffff00
	s_ashr_i32 s3, s54, 2
	s_lshl_b32 s55, s10, 10
	s_and_b32 s6, s2, 3
	s_cmpk_lt_i32 s33, 0x80
	s_cselect_b32 s2, s33, s3
	s_cselect_b32 s80, 4, s6
	s_ashr_i32 s3, s2, 31
	s_lshl_b64 s[6:7], s[2:3], 20
	s_lshl_b32 s3, s80, 20
	s_add_u32 s48, s52, s3
	v_lshlrev_b32_e32 v4, 5, v12
	v_bfe_i32 v14, v0, 0, 16
	v_lshlrev_b32_e32 v0, 1, v1
	v_lshrrev_b32_e32 v2, 2, v1
	s_addc_u32 s49, s53, 0
	s_add_i32 s56, s55, 0
	v_and_b32_e32 v4, 32, v4
	v_and_b32_e32 v0, 24, v0
	v_and_b32_e32 v2, 4, v2
	s_add_i32 m0, s56, 0x10000
	v_or3_b32 v0, v3, v2, v0
	v_add_lshl_u32 v2, v4, v14, 1
	global_load_lds_dwordx4 v134, s[48:49]
	s_add_i32 m0, s56, 0x12000
	v_lshl_add_u32 v138, v0, 12, v2
	s_add_u32 s8, s48, 0x80000
	global_load_lds_dwordx4 v138, s[48:49]
	s_addc_u32 s9, s49, 0
	s_add_i32 m0, s56, 0x14000
	v_lshl_add_u32 v136, v1, 12, v2
	global_load_lds_dwordx4 v134, s[8:9]
	s_add_i32 m0, s56, 0x16000
	s_add_u32 s46, s76, s6
	s_addc_u32 s47, s77, s7
	s_add_i32 s57, s56, 0x2000
	global_load_lds_dwordx4 v138, s[8:9]
	s_mov_b32 m0, s56
	s_add_u32 s6, s46, 0x80000
	global_load_lds_dwordx4 v132, s[46:47]
	s_mov_b32 m0, s57
	s_addc_u32 s7, s47, 0
	s_add_i32 s58, s56, 0x4000
	global_load_lds_dwordx4 v136, s[46:47]
	s_mov_b32 m0, s58
	s_add_i32 s59, s56, 0x6000
	global_load_lds_dwordx4 v132, s[6:7]
	s_mov_b32 m0, s59
	v_mov_b32_e32 v141, 0
	global_load_lds_dwordx4 v136, s[6:7]
	v_mov_b32_e32 v135, v141
	v_mov_b32_e32 v139, v141
	v_mov_b32_e32 v133, v141
	v_mov_b32_e32 v137, v141
	s_cmp_eq_u32 s13, 1
	s_mov_b32 s3, 0
	s_mov_b32 s60, 0x10000
	v_lshl_add_u64 v[4:5], s[48:49], 0, v[134:135]
	v_lshl_add_u64 v[0:1], s[48:49], 0, v[138:139]
	s_mov_b32 s61, 0x14000
	s_mov_b32 s62, 0x16000
	v_lshl_add_u64 v[2:3], s[46:47], 0, v[132:133]
	s_cselect_b64 s[6:7], -1, 0
	s_cmp_lg_u32 s13, 1
	v_lshl_add_u64 v[6:7], s[46:47], 0, v[136:137]
	s_cbranch_scc1 .LBB0_328
	s_barrier
	s_setprio 1

.LBB0_340:
	ds_read_b128 v[128:131], v143
	ds_read_b128 v[150:153], v143 offset:1024
	ds_read_b128 v[154:157], v143 offset:2048
	ds_read_b128 v[164:167], v143 offset:3072
	ds_read_b128 v[168:171], v162
	ds_read_b128 v[172:175], v162 offset:1024
	ds_read_b128 v[176:179], v162 offset:2048
	ds_read_b128 v[180:183], v162 offset:3072
	s_add_i32 s86, s48, 2
	s_add_u32 s49, s46, 0xfff80080
	s_addc_u32 s50, s47, -1
	s_cmp_eq_u32 s83, s48
	s_cselect_b32 s48, s81, s84
	s_cselect_b32 s51, s3, s50
	s_cselect_b32 s50, s35, s49
	s_cselect_b32 s49, s37, s85
	v_lshl_add_u64 v[158:159], s[46:47], 0, v[146:147]
	s_add_i32 m0, s56, 0xc000
	ds_read_b128 v[184:187], v163
	ds_read_b128 v[188:191], v163 offset:1024
	ds_read_b128 v[192:195], v163 offset:2048
	ds_read_b128 v[196:199], v163 offset:3072
	ds_read_b128 v[200:203], v163 offset:4096
	ds_read_b128 v[204:207], v163 offset:5120
	ds_read_b128 v[208:211], v163 offset:6144
	ds_read_b128 v[212:215], v163 offset:7168
	global_load_lds_dwordx4 v[158:159], off
	v_lshl_add_u64 v[158:159], s[46:47], 0, v[148:149]
	s_add_i32 m0, s56, 0xe000
	s_nop 0
	global_load_lds_dwordx4 v[158:159], off
	s_waitcnt vmcnt(8)
	s_waitcnt lgkmcnt(0)
	s_barrier
	s_waitcnt lgkmcnt(0)
	v_mfma_f32_16x16x32_bf16 v[124:127], v[128:131], v[184:187], v[124:127]
	v_mfma_f32_16x16x32_bf16 v[120:123], v[154:157], v[184:187], v[120:123]
	v_mfma_f32_16x16x32_bf16 v[116:119], v[128:131], v[192:195], v[116:119]
	v_mfma_f32_16x16x32_bf16 v[108:111], v[154:157], v[192:195], v[108:111]
	v_mfma_f32_16x16x32_bf16 v[100:103], v[128:131], v[200:203], v[100:103]
	v_mfma_f32_16x16x32_bf16 v[92:95], v[154:157], v[200:203], v[92:95]
	v_mfma_f32_16x16x32_bf16 v[84:87], v[128:131], v[208:211], v[84:87]
	v_mfma_f32_16x16x32_bf16 v[76:79], v[154:157], v[208:211], v[76:79]
	v_mfma_f32_16x16x32_bf16 v[124:127], v[150:153], v[188:191], v[124:127]
	v_mfma_f32_16x16x32_bf16 v[120:123], v[164:167], v[188:191], v[120:123]
	v_mfma_f32_16x16x32_bf16 v[116:119], v[150:153], v[196:199], v[116:119]
	v_mfma_f32_16x16x32_bf16 v[108:111], v[164:167], v[196:199], v[108:111]
	v_mfma_f32_16x16x32_bf16 v[100:103], v[150:153], v[204:207], v[100:103]
	v_mfma_f32_16x16x32_bf16 v[92:95], v[164:167], v[204:207], v[92:95]
	v_mfma_f32_16x16x32_bf16 v[84:87], v[150:153], v[212:215], v[84:87]
	v_mfma_f32_16x16x32_bf16 v[76:79], v[164:167], v[212:215], v[76:79]
	v_mfma_f32_16x16x32_bf16 v[112:115], v[168:171], v[184:187], v[112:115]
	v_mfma_f32_16x16x32_bf16 v[104:107], v[176:179], v[184:187], v[104:107]
	v_mfma_f32_16x16x32_bf16 v[96:99], v[168:171], v[192:195], v[96:99]
	v_mfma_f32_16x16x32_bf16 v[88:91], v[176:179], v[192:195], v[88:91]
	v_mfma_f32_16x16x32_bf16 v[80:83], v[168:171], v[200:203], v[80:83]
	v_mfma_f32_16x16x32_bf16 v[72:75], v[176:179], v[200:203], v[72:75]
	v_mfma_f32_16x16x32_bf16 v[68:71], v[168:171], v[208:211], v[68:71]
	v_mfma_f32_16x16x32_bf16 v[64:67], v[176:179], v[208:211], v[64:67]
	v_mfma_f32_16x16x32_bf16 v[112:115], v[172:175], v[188:191], v[112:115]
	v_mfma_f32_16x16x32_bf16 v[104:107], v[180:183], v[188:191], v[104:107]
	v_mfma_f32_16x16x32_bf16 v[96:99], v[172:175], v[196:199], v[96:99]
	v_mfma_f32_16x16x32_bf16 v[88:91], v[180:183], v[196:199], v[88:91]
	v_mfma_f32_16x16x32_bf16 v[80:83], v[172:175], v[204:207], v[80:83]
	v_mfma_f32_16x16x32_bf16 v[72:75], v[180:183], v[204:207], v[72:75]
	v_mfma_f32_16x16x32_bf16 v[68:71], v[172:175], v[212:215], v[68:71]
	v_mfma_f32_16x16x32_bf16 v[64:67], v[180:183], v[212:215], v[64:67]
	s_barrier
	s_add_i32 s87, s65, s55
	v_lshl_add_u64 v[158:159], s[48:49], 0, v[134:135]
	s_mov_b32 m0, s87
	ds_read_b128 v[184:187], v163 offset:16384
	ds_read_b128 v[188:191], v163 offset:17408
	ds_read_b128 v[192:195], v163 offset:18432
	ds_read_b128 v[196:199], v163 offset:19456
	ds_read_b128 v[200:203], v163 offset:20480
	ds_read_b128 v[204:207], v163 offset:21504
	ds_read_b128 v[208:211], v163 offset:22528
	ds_read_b128 v[212:215], v163 offset:23552
	global_load_lds_dwordx4 v[158:159], off
	s_add_i32 m0, s87, 0x2000
	s_add_u32 s88, s48, 0x80000
	v_lshl_add_u64 v[216:217], s[48:49], 0, v[138:139]
	s_addc_u32 s89, s49, 0
	s_add_i32 s87, s66, s55
	global_load_lds_dwordx4 v[216:217], off
	v_lshl_add_u64 v[218:219], s[88:89], 0, v[134:135]
	s_mov_b32 m0, s87
	v_lshl_add_u64 v[220:221], s[50:51], 0, v[136:137]
	global_load_lds_dwordx4 v[218:219], off
	v_lshl_add_u64 v[218:219], s[88:89], 0, v[138:139]
	s_add_i32 m0, s87, 0x2000
	s_nop 0
	global_load_lds_dwordx4 v[218:219], off
	v_lshl_add_u64 v[218:219], s[50:51], 0, v[132:133]
	s_mov_b32 m0, s56
	s_nop 0
	global_load_lds_dwordx4 v[218:219], off
	s_mov_b32 m0, s57
	s_nop 0
	global_load_lds_dwordx4 v[220:221], off
	s_waitcnt vmcnt(8)
	s_waitcnt lgkmcnt(0)
	s_barrier
	s_waitcnt lgkmcnt(0)
	v_mfma_f32_16x16x32_bf16 v[60:63], v[128:131], v[184:187], v[60:63]
	v_mfma_f32_16x16x32_bf16 v[56:59], v[154:157], v[184:187], v[56:59]
	v_mfma_f32_16x16x32_bf16 v[52:55], v[128:131], v[192:195], v[52:55]
	v_mfma_f32_16x16x32_bf16 v[44:47], v[154:157], v[192:195], v[44:47]
	v_mfma_f32_16x16x32_bf16 v[36:39], v[128:131], v[200:203], v[36:39]
	v_mfma_f32_16x16x32_bf16 v[28:31], v[154:157], v[200:203], v[28:31]
	v_mfma_f32_16x16x32_bf16 v[20:23], v[128:131], v[208:211], v[20:23]
	v_mfma_f32_16x16x32_bf16 v[12:15], v[154:157], v[208:211], v[12:15]
	v_mfma_f32_16x16x32_bf16 v[60:63], v[150:153], v[188:191], v[60:63]
	v_mfma_f32_16x16x32_bf16 v[56:59], v[164:167], v[188:191], v[56:59]
	v_mfma_f32_16x16x32_bf16 v[52:55], v[150:153], v[196:199], v[52:55]
	v_mfma_f32_16x16x32_bf16 v[44:47], v[164:167], v[196:199], v[44:47]
	v_mfma_f32_16x16x32_bf16 v[36:39], v[150:153], v[204:207], v[36:39]
	v_mfma_f32_16x16x32_bf16 v[28:31], v[164:167], v[204:207], v[28:31]
	v_mfma_f32_16x16x32_bf16 v[20:23], v[150:153], v[212:215], v[20:23]
	v_mfma_f32_16x16x32_bf16 v[12:15], v[164:167], v[212:215], v[12:15]
	v_mfma_f32_16x16x32_bf16 v[48:51], v[168:171], v[184:187], v[48:51]
	v_mfma_f32_16x16x32_bf16 v[40:43], v[176:179], v[184:187], v[40:43]
	v_mfma_f32_16x16x32_bf16 v[32:35], v[168:171], v[192:195], v[32:35]
	v_mfma_f32_16x16x32_bf16 v[24:27], v[176:179], v[192:195], v[24:27]
	v_mfma_f32_16x16x32_bf16 v[16:19], v[168:171], v[200:203], v[16:19]
	v_mfma_f32_16x16x32_bf16 v[8:11], v[176:179], v[200:203], v[8:11]
	v_mfma_f32_16x16x32_bf16 v[4:7], v[168:171], v[208:211], v[4:7]
	v_mfma_f32_16x16x32_bf16 v[0:3], v[176:179], v[208:211], v[0:3]
	v_mfma_f32_16x16x32_bf16 v[48:51], v[172:175], v[188:191], v[48:51]
	v_mfma_f32_16x16x32_bf16 v[40:43], v[180:183], v[188:191], v[40:43]
	v_mfma_f32_16x16x32_bf16 v[32:35], v[172:175], v[196:199], v[32:35]
	v_mfma_f32_16x16x32_bf16 v[24:27], v[180:183], v[196:199], v[24:27]
	v_mfma_f32_16x16x32_bf16 v[16:19], v[172:175], v[204:207], v[16:19]
	v_mfma_f32_16x16x32_bf16 v[8:11], v[180:183], v[204:207], v[8:11]
	v_mfma_f32_16x16x32_bf16 v[4:7], v[172:175], v[212:215], v[4:7]
	v_mfma_f32_16x16x32_bf16 v[0:3], v[180:183], v[212:215], v[0:3]
	s_barrier
	s_add_i32 s87, 0, 0x18000
	v_add_u32_e32 v140, s87, v161
	s_add_i32 s88, 0, 0x1c000
	ds_read_b128 v[128:131], v140
	ds_read_b128 v[150:153], v140 offset:1024
	ds_read_b128 v[154:157], v140 offset:2048
	ds_read_b128 v[164:167], v140 offset:3072
	v_add_u32_e32 v140, s88, v161
	ds_read_b128 v[168:171], v140
	ds_read_b128 v[172:175], v140 offset:1024
	ds_read_b128 v[176:179], v140 offset:2048
	ds_read_b128 v[180:183], v140 offset:3072
	s_add_u32 s50, s50, 0x80000
	s_addc_u32 s51, s51, 0
	s_mov_b32 m0, s58
	v_lshl_add_u64 v[222:223], s[50:51], 0, v[132:133]
	ds_read_b128 v[184:187], v163 offset:32768
	ds_read_b128 v[188:191], v163 offset:33792
	ds_read_b128 v[192:195], v163 offset:34816
	ds_read_b128 v[196:199], v163 offset:35840
	ds_read_b128 v[200:203], v163 offset:36864
	ds_read_b128 v[204:207], v163 offset:37888
	ds_read_b128 v[208:211], v163 offset:38912
	ds_read_b128 v[212:215], v163 offset:39936
	global_load_lds_dwordx4 v[222:223], off
	v_lshl_add_u64 v[222:223], s[50:51], 0, v[136:137]
	s_mov_b32 m0, s59
	s_nop 0
	global_load_lds_dwordx4 v[222:223], off
	s_waitcnt vmcnt(8)
	s_waitcnt lgkmcnt(0)
	s_barrier
	s_waitcnt lgkmcnt(0)
	v_mfma_f32_16x16x32_bf16 v[124:127], v[128:131], v[184:187], v[124:127]
	v_mfma_f32_16x16x32_bf16 v[120:123], v[154:157], v[184:187], v[120:123]
	v_mfma_f32_16x16x32_bf16 v[116:119], v[128:131], v[192:195], v[116:119]
	v_mfma_f32_16x16x32_bf16 v[108:111], v[154:157], v[192:195], v[108:111]
	v_mfma_f32_16x16x32_bf16 v[100:103], v[128:131], v[200:203], v[100:103]
	v_mfma_f32_16x16x32_bf16 v[92:95], v[154:157], v[200:203], v[92:95]
	v_mfma_f32_16x16x32_bf16 v[84:87], v[128:131], v[208:211], v[84:87]
	v_mfma_f32_16x16x32_bf16 v[76:79], v[154:157], v[208:211], v[76:79]
	v_mfma_f32_16x16x32_bf16 v[124:127], v[150:153], v[188:191], v[124:127]
	v_mfma_f32_16x16x32_bf16 v[120:123], v[164:167], v[188:191], v[120:123]
	v_mfma_f32_16x16x32_bf16 v[116:119], v[150:153], v[196:199], v[116:119]
	v_mfma_f32_16x16x32_bf16 v[108:111], v[164:167], v[196:199], v[108:111]
	v_mfma_f32_16x16x32_bf16 v[100:103], v[150:153], v[204:207], v[100:103]
	v_mfma_f32_16x16x32_bf16 v[92:95], v[164:167], v[204:207], v[92:95]
	v_mfma_f32_16x16x32_bf16 v[84:87], v[150:153], v[212:215], v[84:87]
	v_mfma_f32_16x16x32_bf16 v[76:79], v[164:167], v[212:215], v[76:79]
	v_mfma_f32_16x16x32_bf16 v[112:115], v[168:171], v[184:187], v[112:115]
	v_mfma_f32_16x16x32_bf16 v[104:107], v[176:179], v[184:187], v[104:107]
	v_mfma_f32_16x16x32_bf16 v[96:99], v[168:171], v[192:195], v[96:99]
	v_mfma_f32_16x16x32_bf16 v[88:91], v[176:179], v[192:195], v[88:91]
	v_mfma_f32_16x16x32_bf16 v[80:83], v[168:171], v[200:203], v[80:83]
	v_mfma_f32_16x16x32_bf16 v[72:75], v[176:179], v[200:203], v[72:75]
	v_mfma_f32_16x16x32_bf16 v[68:71], v[168:171], v[208:211], v[68:71]
	v_mfma_f32_16x16x32_bf16 v[64:67], v[176:179], v[208:211], v[64:67]
	v_mfma_f32_16x16x32_bf16 v[112:115], v[172:175], v[188:191], v[112:115]
	v_mfma_f32_16x16x32_bf16 v[104:107], v[180:183], v[188:191], v[104:107]
	v_mfma_f32_16x16x32_bf16 v[96:99], v[172:175], v[196:199], v[96:99]
	v_mfma_f32_16x16x32_bf16 v[88:91], v[180:183], v[196:199], v[88:91]
	v_mfma_f32_16x16x32_bf16 v[80:83], v[172:175], v[204:207], v[80:83]
	v_mfma_f32_16x16x32_bf16 v[72:75], v[180:183], v[204:207], v[72:75]
	v_mfma_f32_16x16x32_bf16 v[68:71], v[172:175], v[212:215], v[68:71]
	v_mfma_f32_16x16x32_bf16 v[64:67], v[180:183], v[212:215], v[64:67]
	s_barrier
	s_add_i32 s50, s87, s55
	v_lshl_add_u64 v[158:159], v[158:159], 0, s[10:11]
	s_mov_b32 m0, s50
	ds_read_b128 v[184:187], v163 offset:49152
	ds_read_b128 v[188:191], v163 offset:50176
	ds_read_b128 v[192:195], v163 offset:51200
	ds_read_b128 v[196:199], v163 offset:52224
	ds_read_b128 v[200:203], v163 offset:53248
	ds_read_b128 v[204:207], v163 offset:54272
	ds_read_b128 v[208:211], v163 offset:55296
	ds_read_b128 v[212:215], v163 offset:56320
	global_load_lds_dwordx4 v[158:159], off
	s_add_i32 m0, s50, 0x2000
	s_add_u32 s48, s48, 0x80080
	v_lshl_add_u64 v[158:159], v[216:217], 0, s[10:11]
	s_addc_u32 s49, s49, 0
	s_add_i32 s50, s88, s55
	global_load_lds_dwordx4 v[158:159], off
	v_lshl_add_u64 v[158:159], s[48:49], 0, v[134:135]
	s_mov_b32 m0, s50
	s_nop 0
	global_load_lds_dwordx4 v[158:159], off
	v_lshl_add_u64 v[158:159], s[48:49], 0, v[138:139]
	s_add_i32 m0, s50, 0x2000
	s_nop 0
	global_load_lds_dwordx4 v[158:159], off
	v_lshl_add_u64 v[158:159], v[218:219], 0, s[10:11]
	s_mov_b32 m0, s63
	s_nop 0
	global_load_lds_dwordx4 v[158:159], off
	v_lshl_add_u64 v[158:159], v[220:221], 0, s[10:11]
	s_mov_b32 m0, s64
	s_nop 0
	global_load_lds_dwordx4 v[158:159], off
	s_waitcnt vmcnt(8)
	s_waitcnt lgkmcnt(0)
	s_barrier
	s_waitcnt lgkmcnt(0)
	v_mfma_f32_16x16x32_bf16 v[60:63], v[128:131], v[184:187], v[60:63]
	v_mfma_f32_16x16x32_bf16 v[56:59], v[154:157], v[184:187], v[56:59]
	v_mfma_f32_16x16x32_bf16 v[52:55], v[128:131], v[192:195], v[52:55]
	v_mfma_f32_16x16x32_bf16 v[44:47], v[154:157], v[192:195], v[44:47]
	v_mfma_f32_16x16x32_bf16 v[36:39], v[128:131], v[200:203], v[36:39]
	v_mfma_f32_16x16x32_bf16 v[28:31], v[154:157], v[200:203], v[28:31]
	v_mfma_f32_16x16x32_bf16 v[20:23], v[128:131], v[208:211], v[20:23]
	v_mfma_f32_16x16x32_bf16 v[12:15], v[154:157], v[208:211], v[12:15]
	v_mfma_f32_16x16x32_bf16 v[60:63], v[150:153], v[188:191], v[60:63]
	v_mfma_f32_16x16x32_bf16 v[56:59], v[164:167], v[188:191], v[56:59]
	v_mfma_f32_16x16x32_bf16 v[52:55], v[150:153], v[196:199], v[52:55]
	v_mfma_f32_16x16x32_bf16 v[44:47], v[164:167], v[196:199], v[44:47]
	v_mfma_f32_16x16x32_bf16 v[36:39], v[150:153], v[204:207], v[36:39]
	v_mfma_f32_16x16x32_bf16 v[28:31], v[164:167], v[204:207], v[28:31]
	v_mfma_f32_16x16x32_bf16 v[20:23], v[150:153], v[212:215], v[20:23]
	v_mfma_f32_16x16x32_bf16 v[12:15], v[164:167], v[212:215], v[12:15]
	v_mfma_f32_16x16x32_bf16 v[48:51], v[168:171], v[184:187], v[48:51]
	v_mfma_f32_16x16x32_bf16 v[40:43], v[176:179], v[184:187], v[40:43]
	v_mfma_f32_16x16x32_bf16 v[32:35], v[168:171], v[192:195], v[32:35]
	v_mfma_f32_16x16x32_bf16 v[24:27], v[176:179], v[192:195], v[24:27]
	v_mfma_f32_16x16x32_bf16 v[16:19], v[168:171], v[200:203], v[16:19]
	v_mfma_f32_16x16x32_bf16 v[8:11], v[176:179], v[200:203], v[8:11]
	v_mfma_f32_16x16x32_bf16 v[4:7], v[168:171], v[208:211], v[4:7]
	v_mfma_f32_16x16x32_bf16 v[0:3], v[176:179], v[208:211], v[0:3]
	v_mfma_f32_16x16x32_bf16 v[48:51], v[172:175], v[188:191], v[48:51]
	v_mfma_f32_16x16x32_bf16 v[40:43], v[180:183], v[188:191], v[40:43]
	v_mfma_f32_16x16x32_bf16 v[32:35], v[172:175], v[196:199], v[32:35]
	v_mfma_f32_16x16x32_bf16 v[24:27], v[180:183], v[196:199], v[24:27]
	v_mfma_f32_16x16x32_bf16 v[16:19], v[172:175], v[204:207], v[16:19]
	v_mfma_f32_16x16x32_bf16 v[8:11], v[180:183], v[204:207], v[8:11]
	v_mfma_f32_16x16x32_bf16 v[4:7], v[172:175], v[212:215], v[4:7]
	v_mfma_f32_16x16x32_bf16 v[0:3], v[180:183], v[212:215], v[0:3]
	s_barrier
	s_add_u32 s46, s46, 0x100
	s_addc_u32 s47, s47, 0
	s_add_u32 s84, s84, 0x100
	s_addc_u32 s85, s85, 0
	s_cmp_ge_u32 s86, s82
	s_mov_b32 s48, s86
	s_cbranch_scc0 .LBB0_340
	s_and_b64 vcc, exec, s[12:13]
	s_cbranch_vccz .LBB0_343
	s_barrier

.LBB0_404:
	v_ashrrev_i32_e32 v2, 31, v0
	v_lshrrev_b32_e32 v2, 26, v2
	v_lshlrev_b32_e32 v1, 4, v0
	v_add_u32_e32 v2, v0, v2
	v_bfe_i32 v0, v0, 27, 1
	v_lshrrev_b32_e32 v0, 22, v0
	v_add_u32_e32 v0, v1, v0
	v_and_b32_e32 v0, 0xfffffc00, v0
	v_sub_u32_e32 v0, v1, v0
	v_ashrrev_i32_e32 v9, 6, v2
	v_lshrrev_b32_e32 v2, 4, v0
	v_bitop3_b32 v0, v2, v0, 32 bitop3:0x6c
	v_ashrrev_i32_e32 v3, 31, v0
	v_lshrrev_b32_e32 v3, 26, v3
	v_add_u32_e32 v3, v0, v3
	v_lshlrev_b32_e32 v2, 3, v9
	v_ashrrev_i32_e32 v10, 6, v3
	v_and_b32_e32 v3, 0xc0, v3
	v_and_b32_e32 v2, -16, v2
	v_sub_u32_e32 v0, v0, v3
	v_mov_b32_e32 v3, 1
	v_add_u32_e32 v2, v10, v2
	v_ashrrev_i16_sdwa v0, v3, sext(v0) dst_sel:DWORD dst_unused:UNUSED_PAD src0_sel:DWORD src1_sel:BYTE_0
	s_ashr_i32 s2, s7, 3
	v_lshlrev_b32_e32 v4, 5, v9
	v_bfe_i32 v11, v0, 0, 16
	v_lshlrev_b32_e32 v0, 1, v2
	v_lshrrev_b32_e32 v5, 2, v2
	v_and_b32_e32 v6, 3, v10
	s_mov_b32 s7, 0x1fffe0
	v_and_b32_e32 v4, 32, v4
	v_and_b32_e32 v0, 24, v0
	v_and_b32_e32 v5, 4, v5
	v_and_or_b32 v6, v2, s7, v6
	v_or3_b32 v0, v6, v5, v0
	v_add_lshl_u32 v4, v4, v11, 1
	v_lshl_add_u32 v130, v0, 11, v4
	v_add_u32_e32 v0, 0x2000, v1
	v_ashrrev_i32_e32 v1, 31, v0
	v_lshrrev_b32_e32 v1, 22, v1
	v_add_u32_e32 v1, v0, v1
	v_ashrrev_i32_e32 v12, 10, v1
	v_mul_i32_i24_e32 v1, 0x400, v12
	v_sub_u32_e32 v0, v0, v1
	v_lshrrev_b32_e32 v1, 4, v0
	s_add_u32 s39, s70, 0xdc00000
	v_bitop3_b32 v0, v1, v0, 32 bitop3:0x6c
	s_addc_u32 s40, s71, 0
	v_lshl_add_u32 v128, v2, 11, v4
	v_ashrrev_i32_e32 v2, 31, v0
	s_add_u32 s41, s70, 0x4c00000
	v_lshrrev_b32_e32 v2, 26, v2
	s_addc_u32 s42, s71, 0
	v_add_u32_e32 v2, v0, v2
	s_add_i32 s2, s6, s2
	v_lshlrev_b32_e32 v1, 3, v12
	v_ashrrev_i32_e32 v13, 6, v2
	v_and_b32_e32 v2, 0xc0, v2
	s_ashr_i32 s6, s2, 31
	v_and_b32_e32 v1, -16, v1
	v_sub_u32_e32 v0, v0, v2
	s_lshr_b32 s6, s6, 27
	v_add_u32_e32 v1, v13, v1
	v_ashrrev_i16_sdwa v0, v3, sext(v0) dst_sel:DWORD dst_unused:UNUSED_PAD src0_sel:DWORD src1_sel:BYTE_0
	v_and_b32_e32 v3, 3, v13
	s_add_i32 s6, s2, s6
	v_and_or_b32 v3, v1, s7, v3
	s_ashr_i32 s7, s6, 5
	s_andn2_b32 s6, s6, 31
	s_sub_i32 s6, s2, s6
	s_bfe_i32 s2, s6, 0x80000
	s_bfe_u32 s2, s2, 0x3000c
	s_add_i32 s8, s6, s2
	s_bfe_i32 s2, s8, 0x80000
	s_and_b32 s8, s8, 0xf8
	s_sub_i32 s6, s6, s8
	s_lshl_b32 s7, s7, 3
	s_sext_i32_i16 s2, s2
	s_sext_i32_i8 s6, s6
	s_ashr_i32 s3, s12, 8
	s_lshr_b32 s2, s2, 3
	s_add_i32 s28, s7, s6
	s_ashr_i32 s10, s12, 6
	s_ashr_i32 s29, s28, 31
	s_bfe_i64 s[8:9], s[2:3], 0x100000
	s_lshl_b32 s43, s10, 10
	s_lshl_b64 s[6:7], s[28:29], 19
	s_lshl_b64 s[8:9], s[8:9], 19
	s_add_u32 s34, s41, s8
	v_lshlrev_b32_e32 v4, 5, v12
	v_bfe_i32 v14, v0, 0, 16
	v_lshlrev_b32_e32 v0, 1, v1
	v_lshrrev_b32_e32 v2, 2, v1
	s_addc_u32 s35, s42, s9
	s_add_i32 s29, s43, 0
	v_and_b32_e32 v4, 32, v4
	v_and_b32_e32 v0, 24, v0
	v_and_b32_e32 v2, 4, v2
	s_add_i32 m0, s29, 0x10000
	v_or3_b32 v0, v3, v2, v0
	v_add_lshl_u32 v2, v4, v14, 1
	global_load_lds_dwordx4 v130, s[34:35]
	s_add_i32 m0, s29, 0x12000
	v_lshl_add_u32 v134, v0, 11, v2
	s_add_u32 s8, s34, 0x40000
	global_load_lds_dwordx4 v134, s[34:35]
	s_addc_u32 s9, s35, 0
	s_add_i32 m0, s29, 0x14000
	v_lshl_add_u32 v132, v1, 11, v2
	global_load_lds_dwordx4 v130, s[8:9]
	s_add_i32 m0, s29, 0x16000
	s_add_u32 s30, s39, s6
	s_addc_u32 s31, s40, s7
	s_add_i32 s44, s29, 0x2000
	global_load_lds_dwordx4 v134, s[8:9]
	s_mov_b32 m0, s29
	s_add_u32 s6, s30, 0x40000
	global_load_lds_dwordx4 v128, s[30:31]
	s_mov_b32 m0, s44
	s_addc_u32 s7, s31, 0
	s_add_i32 s45, s29, 0x4000
	global_load_lds_dwordx4 v132, s[30:31]
	s_mov_b32 m0, s45
	s_add_i32 s46, s29, 0x6000
	global_load_lds_dwordx4 v128, s[6:7]
	s_mov_b32 m0, s46
	v_mov_b32_e32 v131, 0
	global_load_lds_dwordx4 v132, s[6:7]
	v_mov_b32_e32 v135, v131
	v_mov_b32_e32 v129, v131
	v_mov_b32_e32 v133, v131
	s_cmp_eq_u32 s3, 1
	s_mov_b32 s47, 0
	v_lshl_add_u64 v[6:7], s[34:35], 0, v[130:131]
	v_lshl_add_u64 v[2:3], s[34:35], 0, v[134:135]
	s_mov_b64 s[6:7], 0x40000
	v_lshl_add_u64 v[0:1], s[30:31], 0, v[128:129]
	s_cselect_b64 s[8:9], -1, 0
	s_cmp_lg_u32 s3, 1
	v_lshl_add_u64 v[4:5], s[30:31], 0, v[132:133]
	s_cbranch_scc1 .LBB0_406
	s_barrier
	s_setprio 1

.LBB0_416:
	ds_read_b128 v[152:155], v149
	ds_read_b128 v[156:159], v149 offset:1024
	ds_read_b128 v[160:163], v149 offset:2048
	ds_read_b128 v[164:167], v149 offset:3072
	ds_read_b128 v[168:171], v150
	ds_read_b128 v[172:175], v150 offset:1024
	ds_read_b128 v[176:179], v150 offset:2048
	ds_read_b128 v[180:183], v150 offset:3072
	s_add_u32 s34, s30, 0xfffc0080
	s_addc_u32 s35, s31, -1
	s_cmp_eq_u32 s62, 12
	s_cselect_b32 s37, s23, s35
	s_cselect_b32 s36, s58, s34
	s_cselect_b32 s35, s21, s61
	s_cselect_b32 s34, s59, s60
	v_lshl_add_u64 v[144:145], s[30:31], 0, v[136:137]
	s_add_i32 m0, s29, 0xc000
	ds_read_b128 v[184:187], v151
	ds_read_b128 v[188:191], v151 offset:1024
	ds_read_b128 v[192:195], v151 offset:2048
	ds_read_b128 v[196:199], v151 offset:3072
	ds_read_b128 v[200:203], v151 offset:4096
	ds_read_b128 v[204:207], v151 offset:5120
	ds_read_b128 v[208:211], v151 offset:6144
	ds_read_b128 v[212:215], v151 offset:7168
	global_load_lds_dwordx4 v[144:145], off
	v_lshl_add_u64 v[144:145], s[30:31], 0, v[138:139]
	s_add_i32 m0, s29, 0xe000
	s_nop 0
	global_load_lds_dwordx4 v[144:145], off
	s_waitcnt vmcnt(8)
	s_waitcnt lgkmcnt(0)
	s_barrier
	s_waitcnt lgkmcnt(0)
	v_mfma_f32_16x16x32_bf16 v[124:127], v[152:155], v[184:187], v[124:127]
	v_mfma_f32_16x16x32_bf16 v[120:123], v[160:163], v[184:187], v[120:123]
	v_mfma_f32_16x16x32_bf16 v[116:119], v[152:155], v[192:195], v[116:119]
	v_mfma_f32_16x16x32_bf16 v[108:111], v[160:163], v[192:195], v[108:111]
	v_mfma_f32_16x16x32_bf16 v[100:103], v[152:155], v[200:203], v[100:103]
	v_mfma_f32_16x16x32_bf16 v[92:95], v[160:163], v[200:203], v[92:95]
	v_mfma_f32_16x16x32_bf16 v[84:87], v[152:155], v[208:211], v[84:87]
	v_mfma_f32_16x16x32_bf16 v[76:79], v[160:163], v[208:211], v[76:79]
	v_mfma_f32_16x16x32_bf16 v[124:127], v[156:159], v[188:191], v[124:127]
	v_mfma_f32_16x16x32_bf16 v[120:123], v[164:167], v[188:191], v[120:123]
	v_mfma_f32_16x16x32_bf16 v[116:119], v[156:159], v[196:199], v[116:119]
	v_mfma_f32_16x16x32_bf16 v[108:111], v[164:167], v[196:199], v[108:111]
	v_mfma_f32_16x16x32_bf16 v[100:103], v[156:159], v[204:207], v[100:103]
	v_mfma_f32_16x16x32_bf16 v[92:95], v[164:167], v[204:207], v[92:95]
	v_mfma_f32_16x16x32_bf16 v[84:87], v[156:159], v[212:215], v[84:87]
	v_mfma_f32_16x16x32_bf16 v[76:79], v[164:167], v[212:215], v[76:79]
	v_mfma_f32_16x16x32_bf16 v[112:115], v[168:171], v[184:187], v[112:115]
	v_mfma_f32_16x16x32_bf16 v[104:107], v[176:179], v[184:187], v[104:107]
	v_mfma_f32_16x16x32_bf16 v[96:99], v[168:171], v[192:195], v[96:99]
	v_mfma_f32_16x16x32_bf16 v[88:91], v[176:179], v[192:195], v[88:91]
	v_mfma_f32_16x16x32_bf16 v[80:83], v[168:171], v[200:203], v[80:83]
	v_mfma_f32_16x16x32_bf16 v[72:75], v[176:179], v[200:203], v[72:75]
	v_mfma_f32_16x16x32_bf16 v[68:71], v[168:171], v[208:211], v[68:71]
	v_mfma_f32_16x16x32_bf16 v[64:67], v[176:179], v[208:211], v[64:67]
	v_mfma_f32_16x16x32_bf16 v[112:115], v[172:175], v[188:191], v[112:115]
	v_mfma_f32_16x16x32_bf16 v[104:107], v[180:183], v[188:191], v[104:107]
	v_mfma_f32_16x16x32_bf16 v[96:99], v[172:175], v[196:199], v[96:99]
	v_mfma_f32_16x16x32_bf16 v[88:91], v[180:183], v[196:199], v[88:91]
	v_mfma_f32_16x16x32_bf16 v[80:83], v[172:175], v[204:207], v[80:83]
	v_mfma_f32_16x16x32_bf16 v[72:75], v[180:183], v[204:207], v[72:75]
	v_mfma_f32_16x16x32_bf16 v[68:71], v[172:175], v[212:215], v[68:71]
	v_mfma_f32_16x16x32_bf16 v[64:67], v[180:183], v[212:215], v[64:67]
	s_barrier
	s_add_i32 s63, s51, s43
	v_lshl_add_u64 v[144:145], s[34:35], 0, v[130:131]
	s_mov_b32 m0, s63
	ds_read_b128 v[184:187], v151 offset:16384
	ds_read_b128 v[188:191], v151 offset:17408
	ds_read_b128 v[192:195], v151 offset:18432
	ds_read_b128 v[196:199], v151 offset:19456
	ds_read_b128 v[200:203], v151 offset:20480
	ds_read_b128 v[204:207], v151 offset:21504
	ds_read_b128 v[208:211], v151 offset:22528
	ds_read_b128 v[212:215], v151 offset:23552
	global_load_lds_dwordx4 v[144:145], off
	s_add_i32 m0, s63, 0x2000
	s_add_u32 s64, s34, 0x40000
	v_lshl_add_u64 v[216:217], s[34:35], 0, v[134:135]
	s_addc_u32 s65, s35, 0
	s_add_i32 s63, s52, s43
	global_load_lds_dwordx4 v[216:217], off
	v_lshl_add_u64 v[218:219], s[64:65], 0, v[130:131]
	s_mov_b32 m0, s63
	v_lshl_add_u64 v[220:221], s[36:37], 0, v[132:133]
	global_load_lds_dwordx4 v[218:219], off
	v_lshl_add_u64 v[218:219], s[64:65], 0, v[134:135]
	s_add_i32 m0, s63, 0x2000
	s_nop 0
	global_load_lds_dwordx4 v[218:219], off
	v_lshl_add_u64 v[218:219], s[36:37], 0, v[128:129]
	s_mov_b32 m0, s29
	s_nop 0
	global_load_lds_dwordx4 v[218:219], off
	s_mov_b32 m0, s44
	s_nop 0
	global_load_lds_dwordx4 v[220:221], off
	s_waitcnt vmcnt(8)
	s_waitcnt lgkmcnt(0)
	s_barrier
	s_waitcnt lgkmcnt(0)
	v_mfma_f32_16x16x32_bf16 v[60:63], v[152:155], v[184:187], v[60:63]
	v_mfma_f32_16x16x32_bf16 v[56:59], v[160:163], v[184:187], v[56:59]
	v_mfma_f32_16x16x32_bf16 v[52:55], v[152:155], v[192:195], v[52:55]
	v_mfma_f32_16x16x32_bf16 v[44:47], v[160:163], v[192:195], v[44:47]
	v_mfma_f32_16x16x32_bf16 v[36:39], v[152:155], v[200:203], v[36:39]
	v_mfma_f32_16x16x32_bf16 v[28:31], v[160:163], v[200:203], v[28:31]
	v_mfma_f32_16x16x32_bf16 v[20:23], v[152:155], v[208:211], v[20:23]
	v_mfma_f32_16x16x32_bf16 v[12:15], v[160:163], v[208:211], v[12:15]
	v_mfma_f32_16x16x32_bf16 v[60:63], v[156:159], v[188:191], v[60:63]
	v_mfma_f32_16x16x32_bf16 v[56:59], v[164:167], v[188:191], v[56:59]
	v_mfma_f32_16x16x32_bf16 v[52:55], v[156:159], v[196:199], v[52:55]
	v_mfma_f32_16x16x32_bf16 v[44:47], v[164:167], v[196:199], v[44:47]
	v_mfma_f32_16x16x32_bf16 v[36:39], v[156:159], v[204:207], v[36:39]
	v_mfma_f32_16x16x32_bf16 v[28:31], v[164:167], v[204:207], v[28:31]
	v_mfma_f32_16x16x32_bf16 v[20:23], v[156:159], v[212:215], v[20:23]
	v_mfma_f32_16x16x32_bf16 v[12:15], v[164:167], v[212:215], v[12:15]
	v_mfma_f32_16x16x32_bf16 v[48:51], v[168:171], v[184:187], v[48:51]
	v_mfma_f32_16x16x32_bf16 v[40:43], v[176:179], v[184:187], v[40:43]
	v_mfma_f32_16x16x32_bf16 v[32:35], v[168:171], v[192:195], v[32:35]
	v_mfma_f32_16x16x32_bf16 v[24:27], v[176:179], v[192:195], v[24:27]
	v_mfma_f32_16x16x32_bf16 v[16:19], v[168:171], v[200:203], v[16:19]
	v_mfma_f32_16x16x32_bf16 v[8:11], v[176:179], v[200:203], v[8:11]
	v_mfma_f32_16x16x32_bf16 v[4:7], v[168:171], v[208:211], v[4:7]
	v_mfma_f32_16x16x32_bf16 v[0:3], v[176:179], v[208:211], v[0:3]
	v_mfma_f32_16x16x32_bf16 v[48:51], v[172:175], v[188:191], v[48:51]
	v_mfma_f32_16x16x32_bf16 v[40:43], v[180:183], v[188:191], v[40:43]
	v_mfma_f32_16x16x32_bf16 v[32:35], v[172:175], v[196:199], v[32:35]
	v_mfma_f32_16x16x32_bf16 v[24:27], v[180:183], v[196:199], v[24:27]
	v_mfma_f32_16x16x32_bf16 v[16:19], v[172:175], v[204:207], v[16:19]
	v_mfma_f32_16x16x32_bf16 v[8:11], v[180:183], v[204:207], v[8:11]
	v_mfma_f32_16x16x32_bf16 v[4:7], v[172:175], v[212:215], v[4:7]
	v_mfma_f32_16x16x32_bf16 v[0:3], v[180:183], v[212:215], v[0:3]
	s_barrier
	s_add_i32 s63, 0, 0x18000
	s_add_i32 s64, 0, 0x1c000
	v_add_u32_e32 v164, s63, v147
	v_add_u32_e32 v180, s64, v147
	ds_read_b128 v[152:155], v164
	ds_read_b128 v[156:159], v164 offset:1024
	ds_read_b128 v[160:163], v164 offset:2048
	ds_read_b128 v[164:167], v164 offset:3072
	ds_read_b128 v[168:171], v180
	ds_read_b128 v[172:175], v180 offset:1024
	ds_read_b128 v[176:179], v180 offset:2048
	ds_read_b128 v[180:183], v180 offset:3072
	s_add_u32 s36, s36, 0x40000
	s_addc_u32 s37, s37, 0
	s_mov_b32 m0, s45
	v_lshl_add_u64 v[222:223], s[36:37], 0, v[128:129]
	ds_read_b128 v[184:187], v151 offset:32768
	ds_read_b128 v[188:191], v151 offset:33792
	ds_read_b128 v[192:195], v151 offset:34816
	ds_read_b128 v[196:199], v151 offset:35840
	ds_read_b128 v[200:203], v151 offset:36864
	ds_read_b128 v[204:207], v151 offset:37888
	ds_read_b128 v[208:211], v151 offset:38912
	ds_read_b128 v[212:215], v151 offset:39936
	global_load_lds_dwordx4 v[222:223], off
	v_lshl_add_u64 v[222:223], s[36:37], 0, v[132:133]
	s_mov_b32 m0, s46
	s_nop 0
	global_load_lds_dwordx4 v[222:223], off
	s_waitcnt vmcnt(8)
	s_waitcnt lgkmcnt(0)
	s_barrier
	s_waitcnt lgkmcnt(0)
	v_mfma_f32_16x16x32_bf16 v[124:127], v[152:155], v[184:187], v[124:127]
	v_mfma_f32_16x16x32_bf16 v[120:123], v[160:163], v[184:187], v[120:123]
	v_mfma_f32_16x16x32_bf16 v[116:119], v[152:155], v[192:195], v[116:119]
	v_mfma_f32_16x16x32_bf16 v[108:111], v[160:163], v[192:195], v[108:111]
	v_mfma_f32_16x16x32_bf16 v[100:103], v[152:155], v[200:203], v[100:103]
	v_mfma_f32_16x16x32_bf16 v[92:95], v[160:163], v[200:203], v[92:95]
	v_mfma_f32_16x16x32_bf16 v[84:87], v[152:155], v[208:211], v[84:87]
	v_mfma_f32_16x16x32_bf16 v[76:79], v[160:163], v[208:211], v[76:79]
	v_mfma_f32_16x16x32_bf16 v[124:127], v[156:159], v[188:191], v[124:127]
	v_mfma_f32_16x16x32_bf16 v[120:123], v[164:167], v[188:191], v[120:123]
	v_mfma_f32_16x16x32_bf16 v[116:119], v[156:159], v[196:199], v[116:119]
	v_mfma_f32_16x16x32_bf16 v[108:111], v[164:167], v[196:199], v[108:111]
	v_mfma_f32_16x16x32_bf16 v[100:103], v[156:159], v[204:207], v[100:103]
	v_mfma_f32_16x16x32_bf16 v[92:95], v[164:167], v[204:207], v[92:95]
	v_mfma_f32_16x16x32_bf16 v[84:87], v[156:159], v[212:215], v[84:87]
	v_mfma_f32_16x16x32_bf16 v[76:79], v[164:167], v[212:215], v[76:79]
	v_mfma_f32_16x16x32_bf16 v[112:115], v[168:171], v[184:187], v[112:115]
	v_mfma_f32_16x16x32_bf16 v[104:107], v[176:179], v[184:187], v[104:107]
	v_mfma_f32_16x16x32_bf16 v[96:99], v[168:171], v[192:195], v[96:99]
	v_mfma_f32_16x16x32_bf16 v[88:91], v[176:179], v[192:195], v[88:91]
	v_mfma_f32_16x16x32_bf16 v[80:83], v[168:171], v[200:203], v[80:83]
	v_mfma_f32_16x16x32_bf16 v[72:75], v[176:179], v[200:203], v[72:75]
	v_mfma_f32_16x16x32_bf16 v[68:71], v[168:171], v[208:211], v[68:71]
	v_mfma_f32_16x16x32_bf16 v[64:67], v[176:179], v[208:211], v[64:67]
	v_mfma_f32_16x16x32_bf16 v[112:115], v[172:175], v[188:191], v[112:115]
	v_mfma_f32_16x16x32_bf16 v[104:107], v[180:183], v[188:191], v[104:107]
	v_mfma_f32_16x16x32_bf16 v[96:99], v[172:175], v[196:199], v[96:99]
	v_mfma_f32_16x16x32_bf16 v[88:91], v[180:183], v[196:199], v[88:91]
	v_mfma_f32_16x16x32_bf16 v[80:83], v[172:175], v[204:207], v[80:83]
	v_mfma_f32_16x16x32_bf16 v[72:75], v[180:183], v[204:207], v[72:75]
	v_mfma_f32_16x16x32_bf16 v[68:71], v[172:175], v[212:215], v[68:71]
	v_mfma_f32_16x16x32_bf16 v[64:67], v[180:183], v[212:215], v[64:67]
	s_barrier
	s_add_i32 s36, s63, s43
	v_lshl_add_u64 v[144:145], v[144:145], 0, s[10:11]
	s_mov_b32 m0, s36
	ds_read_b128 v[184:187], v151 offset:49152
	ds_read_b128 v[188:191], v151 offset:50176
	ds_read_b128 v[192:195], v151 offset:51200
	ds_read_b128 v[196:199], v151 offset:52224
	ds_read_b128 v[200:203], v151 offset:53248
	ds_read_b128 v[204:207], v151 offset:54272
	ds_read_b128 v[208:211], v151 offset:55296
	ds_read_b128 v[212:215], v151 offset:56320
	global_load_lds_dwordx4 v[144:145], off
	s_add_i32 m0, s36, 0x2000
	s_add_u32 s34, s34, 0x40080
	v_lshl_add_u64 v[144:145], v[216:217], 0, s[10:11]
	s_addc_u32 s35, s35, 0
	s_add_i32 s36, s64, s43
	global_load_lds_dwordx4 v[144:145], off
	v_lshl_add_u64 v[144:145], s[34:35], 0, v[130:131]
	s_mov_b32 m0, s36
	s_nop 0
	global_load_lds_dwordx4 v[144:145], off
	v_lshl_add_u64 v[144:145], s[34:35], 0, v[134:135]
	s_add_i32 m0, s36, 0x2000
	s_nop 0
	global_load_lds_dwordx4 v[144:145], off
	v_lshl_add_u64 v[144:145], v[218:219], 0, s[10:11]
	s_mov_b32 m0, s48
	s_nop 0
	global_load_lds_dwordx4 v[144:145], off
	v_lshl_add_u64 v[144:145], v[220:221], 0, s[10:11]
	s_mov_b32 m0, s49
	s_nop 0
	global_load_lds_dwordx4 v[144:145], off
	s_waitcnt vmcnt(8)
	s_waitcnt lgkmcnt(0)
	s_barrier
	s_waitcnt lgkmcnt(0)
	v_mfma_f32_16x16x32_bf16 v[60:63], v[152:155], v[184:187], v[60:63]
	v_mfma_f32_16x16x32_bf16 v[56:59], v[160:163], v[184:187], v[56:59]
	v_mfma_f32_16x16x32_bf16 v[52:55], v[152:155], v[192:195], v[52:55]
	v_mfma_f32_16x16x32_bf16 v[44:47], v[160:163], v[192:195], v[44:47]
	v_mfma_f32_16x16x32_bf16 v[36:39], v[152:155], v[200:203], v[36:39]
	v_mfma_f32_16x16x32_bf16 v[28:31], v[160:163], v[200:203], v[28:31]
	v_mfma_f32_16x16x32_bf16 v[20:23], v[152:155], v[208:211], v[20:23]
	v_mfma_f32_16x16x32_bf16 v[12:15], v[160:163], v[208:211], v[12:15]
	v_mfma_f32_16x16x32_bf16 v[60:63], v[156:159], v[188:191], v[60:63]
	v_mfma_f32_16x16x32_bf16 v[56:59], v[164:167], v[188:191], v[56:59]
	v_mfma_f32_16x16x32_bf16 v[52:55], v[156:159], v[196:199], v[52:55]
	v_mfma_f32_16x16x32_bf16 v[44:47], v[164:167], v[196:199], v[44:47]
	v_mfma_f32_16x16x32_bf16 v[36:39], v[156:159], v[204:207], v[36:39]
	v_mfma_f32_16x16x32_bf16 v[28:31], v[164:167], v[204:207], v[28:31]
	v_mfma_f32_16x16x32_bf16 v[20:23], v[156:159], v[212:215], v[20:23]
	v_mfma_f32_16x16x32_bf16 v[12:15], v[164:167], v[212:215], v[12:15]
	v_mfma_f32_16x16x32_bf16 v[48:51], v[168:171], v[184:187], v[48:51]
	v_mfma_f32_16x16x32_bf16 v[40:43], v[176:179], v[184:187], v[40:43]
	v_mfma_f32_16x16x32_bf16 v[32:35], v[168:171], v[192:195], v[32:35]
	v_mfma_f32_16x16x32_bf16 v[24:27], v[176:179], v[192:195], v[24:27]
	v_mfma_f32_16x16x32_bf16 v[16:19], v[168:171], v[200:203], v[16:19]
	v_mfma_f32_16x16x32_bf16 v[8:11], v[176:179], v[200:203], v[8:11]
	v_mfma_f32_16x16x32_bf16 v[4:7], v[168:171], v[208:211], v[4:7]
	v_mfma_f32_16x16x32_bf16 v[0:3], v[176:179], v[208:211], v[0:3]
	v_mfma_f32_16x16x32_bf16 v[48:51], v[172:175], v[188:191], v[48:51]
	v_mfma_f32_16x16x32_bf16 v[40:43], v[180:183], v[188:191], v[40:43]
	v_mfma_f32_16x16x32_bf16 v[32:35], v[172:175], v[196:199], v[32:35]
	v_mfma_f32_16x16x32_bf16 v[24:27], v[180:183], v[196:199], v[24:27]
	v_mfma_f32_16x16x32_bf16 v[16:19], v[172:175], v[204:207], v[16:19]
	v_mfma_f32_16x16x32_bf16 v[8:11], v[180:183], v[204:207], v[8:11]
	v_mfma_f32_16x16x32_bf16 v[4:7], v[172:175], v[212:215], v[4:7]
	v_mfma_f32_16x16x32_bf16 v[0:3], v[180:183], v[212:215], v[0:3]
	s_barrier
	s_add_i32 s62, s62, 2
	s_add_u32 s30, s30, 0x100
	s_addc_u32 s31, s31, 0
	s_add_u32 s60, s60, 0x100
	s_addc_u32 s61, s61, 0
	s_cmp_gt_u32 s62, 13
	s_cbranch_scc0 .LBB0_416
	s_and_b64 vcc, exec, s[12:13]
	s_cbranch_vccz .LBB0_419
	s_barrier

.LBB0_428:
	v_ashrrev_i32_e32 v2, 31, v0
	v_lshrrev_b32_e32 v2, 26, v2
	v_lshlrev_b32_e32 v1, 4, v0
	v_add_u32_e32 v2, v0, v2
	v_bfe_i32 v0, v0, 27, 1
	v_lshrrev_b32_e32 v0, 22, v0
	v_add_u32_e32 v0, v1, v0
	v_and_b32_e32 v0, 0xfffffc00, v0
	v_sub_u32_e32 v0, v1, v0
	v_ashrrev_i32_e32 v9, 6, v2
	v_lshrrev_b32_e32 v2, 4, v0
	v_bitop3_b32 v0, v2, v0, 32 bitop3:0x6c
	v_ashrrev_i32_e32 v3, 31, v0
	v_lshrrev_b32_e32 v3, 26, v3
	v_add_u32_e32 v3, v0, v3
	v_lshlrev_b32_e32 v2, 3, v9
	v_ashrrev_i32_e32 v10, 6, v3
	v_and_b32_e32 v3, 0xc0, v3
	v_and_b32_e32 v2, -16, v2
	v_sub_u32_e32 v0, v0, v3
	v_mov_b32_e32 v3, 1
	v_add_u32_e32 v2, v10, v2
	v_ashrrev_i16_sdwa v0, v3, sext(v0) dst_sel:DWORD dst_unused:UNUSED_PAD src0_sel:DWORD src1_sel:BYTE_0
	s_ashr_i32 s2, s5, 3
	v_lshlrev_b32_e32 v4, 5, v9
	v_bfe_i32 v11, v0, 0, 16
	v_lshlrev_b32_e32 v0, 1, v2
	v_lshrrev_b32_e32 v5, 2, v2
	v_and_b32_e32 v6, 3, v10
	s_mov_b32 s5, 0x1fffe0
	v_and_b32_e32 v4, 32, v4
	v_and_b32_e32 v0, 24, v0
	v_and_b32_e32 v5, 4, v5
	v_and_or_b32 v6, v2, s5, v6
	v_or3_b32 v0, v6, v5, v0
	v_add_lshl_u32 v4, v4, v11, 1
	v_lshl_add_u32 v130, v0, 11, v4
	v_add_u32_e32 v0, 0x2000, v1
	v_ashrrev_i32_e32 v1, 31, v0
	v_lshrrev_b32_e32 v1, 22, v1
	v_add_u32_e32 v1, v0, v1
	v_ashrrev_i32_e32 v12, 10, v1
	v_mul_i32_i24_e32 v1, 0x400, v12
	v_sub_u32_e32 v0, v0, v1
	v_lshrrev_b32_e32 v1, 4, v0
	s_add_u32 s37, s70, 0x11c00000
	v_bitop3_b32 v0, v1, v0, 32 bitop3:0x6c
	s_addc_u32 s38, s71, 0
	v_lshl_add_u32 v128, v2, 11, v4
	v_ashrrev_i32_e32 v2, 31, v0
	s_add_u32 s39, s70, 0x4e00000
	v_lshrrev_b32_e32 v2, 26, v2
	s_addc_u32 s40, s71, 0
	v_add_u32_e32 v2, v0, v2
	s_add_i32 s2, s4, s2
	v_lshlrev_b32_e32 v1, 3, v12
	v_ashrrev_i32_e32 v13, 6, v2
	v_and_b32_e32 v2, 0xc0, v2
	s_ashr_i32 s4, s2, 31
	v_and_b32_e32 v1, -16, v1
	v_sub_u32_e32 v0, v0, v2
	s_lshr_b32 s4, s4, 27
	v_add_u32_e32 v1, v13, v1
	v_ashrrev_i16_sdwa v0, v3, sext(v0) dst_sel:DWORD dst_unused:UNUSED_PAD src0_sel:DWORD src1_sel:BYTE_0
	v_and_b32_e32 v3, 3, v13
	s_add_i32 s4, s2, s4
	v_and_or_b32 v3, v1, s5, v3
	s_ashr_i32 s5, s4, 5
	s_andn2_b32 s4, s4, 31
	s_sub_i32 s4, s2, s4
	s_bfe_i32 s2, s4, 0x80000
	s_bfe_u32 s2, s2, 0x3000c
	s_add_i32 s6, s4, s2
	s_bfe_i32 s2, s6, 0x80000
	s_and_b32 s6, s6, 0xf8
	s_sub_i32 s4, s4, s6
	s_lshl_b32 s5, s5, 3
	s_sext_i32_i16 s2, s2
	s_sext_i32_i8 s4, s4
	s_ashr_i32 s3, s10, 8
	s_lshr_b32 s2, s2, 3
	s_add_i32 s26, s5, s4
	s_ashr_i32 s8, s10, 6
	s_ashr_i32 s27, s26, 31
	s_bfe_i64 s[6:7], s[2:3], 0x100000
	s_lshl_b32 s41, s8, 10
	s_lshl_b64 s[4:5], s[26:27], 19
	s_lshl_b64 s[6:7], s[6:7], 19
	s_add_u32 s30, s39, s6
	v_lshlrev_b32_e32 v4, 5, v12
	v_bfe_i32 v14, v0, 0, 16
	v_lshlrev_b32_e32 v0, 1, v1
	v_lshrrev_b32_e32 v2, 2, v1
	s_addc_u32 s31, s40, s7
	s_add_i32 s27, s41, 0
	v_and_b32_e32 v4, 32, v4
	v_and_b32_e32 v0, 24, v0
	v_and_b32_e32 v2, 4, v2
	s_add_i32 m0, s27, 0x10000
	v_or3_b32 v0, v3, v2, v0
	v_add_lshl_u32 v2, v4, v14, 1
	global_load_lds_dwordx4 v130, s[30:31]
	s_add_i32 m0, s27, 0x12000
	v_lshl_add_u32 v134, v0, 11, v2
	s_add_u32 s6, s30, 0x40000
	global_load_lds_dwordx4 v134, s[30:31]
	s_addc_u32 s7, s31, 0
	s_add_i32 m0, s27, 0x14000
	v_lshl_add_u32 v132, v1, 11, v2
	global_load_lds_dwordx4 v130, s[6:7]
	s_add_i32 m0, s27, 0x16000
	s_add_u32 s28, s37, s4
	s_addc_u32 s29, s38, s5
	s_add_i32 s42, s27, 0x2000
	global_load_lds_dwordx4 v134, s[6:7]
	s_mov_b32 m0, s27
	s_add_u32 s4, s28, 0x40000
	global_load_lds_dwordx4 v128, s[28:29]
	s_mov_b32 m0, s42
	s_addc_u32 s5, s29, 0
	s_add_i32 s43, s27, 0x4000
	global_load_lds_dwordx4 v132, s[28:29]
	s_mov_b32 m0, s43
	s_add_i32 s44, s27, 0x6000
	global_load_lds_dwordx4 v128, s[4:5]
	s_mov_b32 m0, s44
	v_mov_b32_e32 v131, 0
	global_load_lds_dwordx4 v132, s[4:5]
	v_mov_b32_e32 v135, v131
	v_mov_b32_e32 v129, v131
	v_mov_b32_e32 v133, v131
	s_cmp_eq_u32 s3, 1
	s_mov_b32 s45, 0
	v_lshl_add_u64 v[6:7], s[30:31], 0, v[130:131]
	v_lshl_add_u64 v[2:3], s[30:31], 0, v[134:135]
	s_mov_b64 s[4:5], 0x40000
	v_lshl_add_u64 v[0:1], s[28:29], 0, v[128:129]
	s_cselect_b64 s[6:7], -1, 0
	s_cmp_lg_u32 s3, 1
	v_lshl_add_u64 v[4:5], s[28:29], 0, v[132:133]
	s_cbranch_scc1 .LBB0_430
	s_barrier
	s_setprio 1

.LBB0_440:
	ds_read_b128 v[152:155], v149
	ds_read_b128 v[156:159], v149 offset:1024
	ds_read_b128 v[160:163], v149 offset:2048
	ds_read_b128 v[164:167], v149 offset:3072
	ds_read_b128 v[168:171], v150
	ds_read_b128 v[172:175], v150 offset:1024
	ds_read_b128 v[176:179], v150 offset:2048
	ds_read_b128 v[180:183], v150 offset:3072
	s_add_u32 s30, s28, 0xfffc0080
	s_addc_u32 s31, s29, -1
	s_cmp_eq_u32 s60, 12
	s_cselect_b32 s35, s21, s31
	s_cselect_b32 s34, s56, s30
	s_cselect_b32 s31, s19, s59
	s_cselect_b32 s30, s57, s58
	v_lshl_add_u64 v[144:145], s[28:29], 0, v[136:137]
	s_add_i32 m0, s27, 0xc000
	ds_read_b128 v[184:187], v151
	ds_read_b128 v[188:191], v151 offset:1024
	ds_read_b128 v[192:195], v151 offset:2048
	ds_read_b128 v[196:199], v151 offset:3072
	ds_read_b128 v[200:203], v151 offset:4096
	ds_read_b128 v[204:207], v151 offset:5120
	ds_read_b128 v[208:211], v151 offset:6144
	ds_read_b128 v[212:215], v151 offset:7168
	global_load_lds_dwordx4 v[144:145], off
	v_lshl_add_u64 v[144:145], s[28:29], 0, v[138:139]
	s_add_i32 m0, s27, 0xe000
	s_nop 0
	global_load_lds_dwordx4 v[144:145], off
	s_waitcnt vmcnt(8)
	s_waitcnt lgkmcnt(0)
	s_barrier
	s_waitcnt lgkmcnt(0)
	v_mfma_f32_16x16x32_bf16 v[124:127], v[152:155], v[184:187], v[124:127]
	v_mfma_f32_16x16x32_bf16 v[120:123], v[160:163], v[184:187], v[120:123]
	v_mfma_f32_16x16x32_bf16 v[116:119], v[152:155], v[192:195], v[116:119]
	v_mfma_f32_16x16x32_bf16 v[108:111], v[160:163], v[192:195], v[108:111]
	v_mfma_f32_16x16x32_bf16 v[100:103], v[152:155], v[200:203], v[100:103]
	v_mfma_f32_16x16x32_bf16 v[92:95], v[160:163], v[200:203], v[92:95]
	v_mfma_f32_16x16x32_bf16 v[84:87], v[152:155], v[208:211], v[84:87]
	v_mfma_f32_16x16x32_bf16 v[76:79], v[160:163], v[208:211], v[76:79]
	v_mfma_f32_16x16x32_bf16 v[124:127], v[156:159], v[188:191], v[124:127]
	v_mfma_f32_16x16x32_bf16 v[120:123], v[164:167], v[188:191], v[120:123]
	v_mfma_f32_16x16x32_bf16 v[116:119], v[156:159], v[196:199], v[116:119]
	v_mfma_f32_16x16x32_bf16 v[108:111], v[164:167], v[196:199], v[108:111]
	v_mfma_f32_16x16x32_bf16 v[100:103], v[156:159], v[204:207], v[100:103]
	v_mfma_f32_16x16x32_bf16 v[92:95], v[164:167], v[204:207], v[92:95]
	v_mfma_f32_16x16x32_bf16 v[84:87], v[156:159], v[212:215], v[84:87]
	v_mfma_f32_16x16x32_bf16 v[76:79], v[164:167], v[212:215], v[76:79]
	v_mfma_f32_16x16x32_bf16 v[112:115], v[168:171], v[184:187], v[112:115]
	v_mfma_f32_16x16x32_bf16 v[104:107], v[176:179], v[184:187], v[104:107]
	v_mfma_f32_16x16x32_bf16 v[96:99], v[168:171], v[192:195], v[96:99]
	v_mfma_f32_16x16x32_bf16 v[88:91], v[176:179], v[192:195], v[88:91]
	v_mfma_f32_16x16x32_bf16 v[80:83], v[168:171], v[200:203], v[80:83]
	v_mfma_f32_16x16x32_bf16 v[72:75], v[176:179], v[200:203], v[72:75]
	v_mfma_f32_16x16x32_bf16 v[68:71], v[168:171], v[208:211], v[68:71]
	v_mfma_f32_16x16x32_bf16 v[64:67], v[176:179], v[208:211], v[64:67]
	v_mfma_f32_16x16x32_bf16 v[112:115], v[172:175], v[188:191], v[112:115]
	v_mfma_f32_16x16x32_bf16 v[104:107], v[180:183], v[188:191], v[104:107]
	v_mfma_f32_16x16x32_bf16 v[96:99], v[172:175], v[196:199], v[96:99]
	v_mfma_f32_16x16x32_bf16 v[88:91], v[180:183], v[196:199], v[88:91]
	v_mfma_f32_16x16x32_bf16 v[80:83], v[172:175], v[204:207], v[80:83]
	v_mfma_f32_16x16x32_bf16 v[72:75], v[180:183], v[204:207], v[72:75]
	v_mfma_f32_16x16x32_bf16 v[68:71], v[172:175], v[212:215], v[68:71]
	v_mfma_f32_16x16x32_bf16 v[64:67], v[180:183], v[212:215], v[64:67]
	s_barrier
	s_add_i32 s61, s49, s41
	v_lshl_add_u64 v[144:145], s[30:31], 0, v[130:131]
	s_mov_b32 m0, s61
	ds_read_b128 v[184:187], v151 offset:16384
	ds_read_b128 v[188:191], v151 offset:17408
	ds_read_b128 v[192:195], v151 offset:18432
	ds_read_b128 v[196:199], v151 offset:19456
	ds_read_b128 v[200:203], v151 offset:20480
	ds_read_b128 v[204:207], v151 offset:21504
	ds_read_b128 v[208:211], v151 offset:22528
	ds_read_b128 v[212:215], v151 offset:23552
	global_load_lds_dwordx4 v[144:145], off
	s_add_i32 m0, s61, 0x2000
	s_add_u32 s62, s30, 0x40000
	v_lshl_add_u64 v[216:217], s[30:31], 0, v[134:135]
	s_addc_u32 s63, s31, 0
	s_add_i32 s61, s50, s41
	global_load_lds_dwordx4 v[216:217], off
	v_lshl_add_u64 v[218:219], s[62:63], 0, v[130:131]
	s_mov_b32 m0, s61
	v_lshl_add_u64 v[220:221], s[34:35], 0, v[132:133]
	global_load_lds_dwordx4 v[218:219], off
	v_lshl_add_u64 v[218:219], s[62:63], 0, v[134:135]
	s_add_i32 m0, s61, 0x2000
	s_nop 0
	global_load_lds_dwordx4 v[218:219], off
	v_lshl_add_u64 v[218:219], s[34:35], 0, v[128:129]
	s_mov_b32 m0, s27
	s_nop 0
	global_load_lds_dwordx4 v[218:219], off
	s_mov_b32 m0, s42
	s_nop 0
	global_load_lds_dwordx4 v[220:221], off
	s_waitcnt vmcnt(8)
	s_waitcnt lgkmcnt(0)
	s_barrier
	s_waitcnt lgkmcnt(0)
	v_mfma_f32_16x16x32_bf16 v[60:63], v[152:155], v[184:187], v[60:63]
	v_mfma_f32_16x16x32_bf16 v[56:59], v[160:163], v[184:187], v[56:59]
	v_mfma_f32_16x16x32_bf16 v[52:55], v[152:155], v[192:195], v[52:55]
	v_mfma_f32_16x16x32_bf16 v[44:47], v[160:163], v[192:195], v[44:47]
	v_mfma_f32_16x16x32_bf16 v[36:39], v[152:155], v[200:203], v[36:39]
	v_mfma_f32_16x16x32_bf16 v[28:31], v[160:163], v[200:203], v[28:31]
	v_mfma_f32_16x16x32_bf16 v[20:23], v[152:155], v[208:211], v[20:23]
	v_mfma_f32_16x16x32_bf16 v[12:15], v[160:163], v[208:211], v[12:15]
	v_mfma_f32_16x16x32_bf16 v[60:63], v[156:159], v[188:191], v[60:63]
	v_mfma_f32_16x16x32_bf16 v[56:59], v[164:167], v[188:191], v[56:59]
	v_mfma_f32_16x16x32_bf16 v[52:55], v[156:159], v[196:199], v[52:55]
	v_mfma_f32_16x16x32_bf16 v[44:47], v[164:167], v[196:199], v[44:47]
	v_mfma_f32_16x16x32_bf16 v[36:39], v[156:159], v[204:207], v[36:39]
	v_mfma_f32_16x16x32_bf16 v[28:31], v[164:167], v[204:207], v[28:31]
	v_mfma_f32_16x16x32_bf16 v[20:23], v[156:159], v[212:215], v[20:23]
	v_mfma_f32_16x16x32_bf16 v[12:15], v[164:167], v[212:215], v[12:15]
	v_mfma_f32_16x16x32_bf16 v[48:51], v[168:171], v[184:187], v[48:51]
	v_mfma_f32_16x16x32_bf16 v[40:43], v[176:179], v[184:187], v[40:43]
	v_mfma_f32_16x16x32_bf16 v[32:35], v[168:171], v[192:195], v[32:35]
	v_mfma_f32_16x16x32_bf16 v[24:27], v[176:179], v[192:195], v[24:27]
	v_mfma_f32_16x16x32_bf16 v[16:19], v[168:171], v[200:203], v[16:19]
	v_mfma_f32_16x16x32_bf16 v[8:11], v[176:179], v[200:203], v[8:11]
	v_mfma_f32_16x16x32_bf16 v[4:7], v[168:171], v[208:211], v[4:7]
	v_mfma_f32_16x16x32_bf16 v[0:3], v[176:179], v[208:211], v[0:3]
	v_mfma_f32_16x16x32_bf16 v[48:51], v[172:175], v[188:191], v[48:51]
	v_mfma_f32_16x16x32_bf16 v[40:43], v[180:183], v[188:191], v[40:43]
	v_mfma_f32_16x16x32_bf16 v[32:35], v[172:175], v[196:199], v[32:35]
	v_mfma_f32_16x16x32_bf16 v[24:27], v[180:183], v[196:199], v[24:27]
	v_mfma_f32_16x16x32_bf16 v[16:19], v[172:175], v[204:207], v[16:19]
	v_mfma_f32_16x16x32_bf16 v[8:11], v[180:183], v[204:207], v[8:11]
	v_mfma_f32_16x16x32_bf16 v[4:7], v[172:175], v[212:215], v[4:7]
	v_mfma_f32_16x16x32_bf16 v[0:3], v[180:183], v[212:215], v[0:3]
	s_barrier
	s_add_i32 s61, 0, 0x18000
	s_add_i32 s62, 0, 0x1c000
	v_add_u32_e32 v164, s61, v147
	v_add_u32_e32 v180, s62, v147
	ds_read_b128 v[152:155], v164
	ds_read_b128 v[156:159], v164 offset:1024
	ds_read_b128 v[160:163], v164 offset:2048
	ds_read_b128 v[164:167], v164 offset:3072
	ds_read_b128 v[168:171], v180
	ds_read_b128 v[172:175], v180 offset:1024
	ds_read_b128 v[176:179], v180 offset:2048
	ds_read_b128 v[180:183], v180 offset:3072
	s_add_u32 s34, s34, 0x40000
	s_addc_u32 s35, s35, 0
	s_mov_b32 m0, s43
	v_lshl_add_u64 v[222:223], s[34:35], 0, v[128:129]
	ds_read_b128 v[184:187], v151 offset:32768
	ds_read_b128 v[188:191], v151 offset:33792
	ds_read_b128 v[192:195], v151 offset:34816
	ds_read_b128 v[196:199], v151 offset:35840
	ds_read_b128 v[200:203], v151 offset:36864
	ds_read_b128 v[204:207], v151 offset:37888
	ds_read_b128 v[208:211], v151 offset:38912
	ds_read_b128 v[212:215], v151 offset:39936
	global_load_lds_dwordx4 v[222:223], off
	v_lshl_add_u64 v[222:223], s[34:35], 0, v[132:133]
	s_mov_b32 m0, s44
	s_nop 0
	global_load_lds_dwordx4 v[222:223], off
	s_waitcnt vmcnt(8)
	s_waitcnt lgkmcnt(0)
	s_barrier
	s_waitcnt lgkmcnt(0)
	v_mfma_f32_16x16x32_bf16 v[124:127], v[152:155], v[184:187], v[124:127]
	v_mfma_f32_16x16x32_bf16 v[120:123], v[160:163], v[184:187], v[120:123]
	v_mfma_f32_16x16x32_bf16 v[116:119], v[152:155], v[192:195], v[116:119]
	v_mfma_f32_16x16x32_bf16 v[108:111], v[160:163], v[192:195], v[108:111]
	v_mfma_f32_16x16x32_bf16 v[100:103], v[152:155], v[200:203], v[100:103]
	v_mfma_f32_16x16x32_bf16 v[92:95], v[160:163], v[200:203], v[92:95]
	v_mfma_f32_16x16x32_bf16 v[84:87], v[152:155], v[208:211], v[84:87]
	v_mfma_f32_16x16x32_bf16 v[76:79], v[160:163], v[208:211], v[76:79]
	v_mfma_f32_16x16x32_bf16 v[124:127], v[156:159], v[188:191], v[124:127]
	v_mfma_f32_16x16x32_bf16 v[120:123], v[164:167], v[188:191], v[120:123]
	v_mfma_f32_16x16x32_bf16 v[116:119], v[156:159], v[196:199], v[116:119]
	v_mfma_f32_16x16x32_bf16 v[108:111], v[164:167], v[196:199], v[108:111]
	v_mfma_f32_16x16x32_bf16 v[100:103], v[156:159], v[204:207], v[100:103]
	v_mfma_f32_16x16x32_bf16 v[92:95], v[164:167], v[204:207], v[92:95]
	v_mfma_f32_16x16x32_bf16 v[84:87], v[156:159], v[212:215], v[84:87]
	v_mfma_f32_16x16x32_bf16 v[76:79], v[164:167], v[212:215], v[76:79]
	v_mfma_f32_16x16x32_bf16 v[112:115], v[168:171], v[184:187], v[112:115]
	v_mfma_f32_16x16x32_bf16 v[104:107], v[176:179], v[184:187], v[104:107]
	v_mfma_f32_16x16x32_bf16 v[96:99], v[168:171], v[192:195], v[96:99]
	v_mfma_f32_16x16x32_bf16 v[88:91], v[176:179], v[192:195], v[88:91]
	v_mfma_f32_16x16x32_bf16 v[80:83], v[168:171], v[200:203], v[80:83]
	v_mfma_f32_16x16x32_bf16 v[72:75], v[176:179], v[200:203], v[72:75]
	v_mfma_f32_16x16x32_bf16 v[68:71], v[168:171], v[208:211], v[68:71]
	v_mfma_f32_16x16x32_bf16 v[64:67], v[176:179], v[208:211], v[64:67]
	v_mfma_f32_16x16x32_bf16 v[112:115], v[172:175], v[188:191], v[112:115]
	v_mfma_f32_16x16x32_bf16 v[104:107], v[180:183], v[188:191], v[104:107]
	v_mfma_f32_16x16x32_bf16 v[96:99], v[172:175], v[196:199], v[96:99]
	v_mfma_f32_16x16x32_bf16 v[88:91], v[180:183], v[196:199], v[88:91]
	v_mfma_f32_16x16x32_bf16 v[80:83], v[172:175], v[204:207], v[80:83]
	v_mfma_f32_16x16x32_bf16 v[72:75], v[180:183], v[204:207], v[72:75]
	v_mfma_f32_16x16x32_bf16 v[68:71], v[172:175], v[212:215], v[68:71]
	v_mfma_f32_16x16x32_bf16 v[64:67], v[180:183], v[212:215], v[64:67]
	s_barrier
	s_add_i32 s34, s61, s41
	v_lshl_add_u64 v[144:145], v[144:145], 0, s[8:9]
	s_mov_b32 m0, s34
	ds_read_b128 v[184:187], v151 offset:49152
	ds_read_b128 v[188:191], v151 offset:50176
	ds_read_b128 v[192:195], v151 offset:51200
	ds_read_b128 v[196:199], v151 offset:52224
	ds_read_b128 v[200:203], v151 offset:53248
	ds_read_b128 v[204:207], v151 offset:54272
	ds_read_b128 v[208:211], v151 offset:55296
	ds_read_b128 v[212:215], v151 offset:56320
	global_load_lds_dwordx4 v[144:145], off
	s_add_i32 m0, s34, 0x2000
	s_add_u32 s30, s30, 0x40080
	v_lshl_add_u64 v[144:145], v[216:217], 0, s[8:9]
	s_addc_u32 s31, s31, 0
	s_add_i32 s34, s62, s41
	global_load_lds_dwordx4 v[144:145], off
	v_lshl_add_u64 v[144:145], s[30:31], 0, v[130:131]
	s_mov_b32 m0, s34
	s_nop 0
	global_load_lds_dwordx4 v[144:145], off
	v_lshl_add_u64 v[144:145], s[30:31], 0, v[134:135]
	s_add_i32 m0, s34, 0x2000
	s_nop 0
	global_load_lds_dwordx4 v[144:145], off
	v_lshl_add_u64 v[144:145], v[218:219], 0, s[8:9]
	s_mov_b32 m0, s46
	s_nop 0
	global_load_lds_dwordx4 v[144:145], off
	v_lshl_add_u64 v[144:145], v[220:221], 0, s[8:9]
	s_mov_b32 m0, s47
	s_nop 0
	global_load_lds_dwordx4 v[144:145], off
	s_waitcnt vmcnt(8)
	s_waitcnt lgkmcnt(0)
	s_barrier
	s_waitcnt lgkmcnt(0)
	v_mfma_f32_16x16x32_bf16 v[60:63], v[152:155], v[184:187], v[60:63]
	v_mfma_f32_16x16x32_bf16 v[56:59], v[160:163], v[184:187], v[56:59]
	v_mfma_f32_16x16x32_bf16 v[52:55], v[152:155], v[192:195], v[52:55]
	v_mfma_f32_16x16x32_bf16 v[44:47], v[160:163], v[192:195], v[44:47]
	v_mfma_f32_16x16x32_bf16 v[36:39], v[152:155], v[200:203], v[36:39]
	v_mfma_f32_16x16x32_bf16 v[28:31], v[160:163], v[200:203], v[28:31]
	v_mfma_f32_16x16x32_bf16 v[20:23], v[152:155], v[208:211], v[20:23]
	v_mfma_f32_16x16x32_bf16 v[12:15], v[160:163], v[208:211], v[12:15]
	v_mfma_f32_16x16x32_bf16 v[60:63], v[156:159], v[188:191], v[60:63]
	v_mfma_f32_16x16x32_bf16 v[56:59], v[164:167], v[188:191], v[56:59]
	v_mfma_f32_16x16x32_bf16 v[52:55], v[156:159], v[196:199], v[52:55]
	v_mfma_f32_16x16x32_bf16 v[44:47], v[164:167], v[196:199], v[44:47]
	v_mfma_f32_16x16x32_bf16 v[36:39], v[156:159], v[204:207], v[36:39]
	v_mfma_f32_16x16x32_bf16 v[28:31], v[164:167], v[204:207], v[28:31]
	v_mfma_f32_16x16x32_bf16 v[20:23], v[156:159], v[212:215], v[20:23]
	v_mfma_f32_16x16x32_bf16 v[12:15], v[164:167], v[212:215], v[12:15]
	v_mfma_f32_16x16x32_bf16 v[48:51], v[168:171], v[184:187], v[48:51]
	v_mfma_f32_16x16x32_bf16 v[40:43], v[176:179], v[184:187], v[40:43]
	v_mfma_f32_16x16x32_bf16 v[32:35], v[168:171], v[192:195], v[32:35]
	v_mfma_f32_16x16x32_bf16 v[24:27], v[176:179], v[192:195], v[24:27]
	v_mfma_f32_16x16x32_bf16 v[16:19], v[168:171], v[200:203], v[16:19]
	v_mfma_f32_16x16x32_bf16 v[8:11], v[176:179], v[200:203], v[8:11]
	v_mfma_f32_16x16x32_bf16 v[4:7], v[168:171], v[208:211], v[4:7]
	v_mfma_f32_16x16x32_bf16 v[0:3], v[176:179], v[208:211], v[0:3]
	v_mfma_f32_16x16x32_bf16 v[48:51], v[172:175], v[188:191], v[48:51]
	v_mfma_f32_16x16x32_bf16 v[40:43], v[180:183], v[188:191], v[40:43]
	v_mfma_f32_16x16x32_bf16 v[32:35], v[172:175], v[196:199], v[32:35]
	v_mfma_f32_16x16x32_bf16 v[24:27], v[180:183], v[196:199], v[24:27]
	v_mfma_f32_16x16x32_bf16 v[16:19], v[172:175], v[204:207], v[16:19]
	v_mfma_f32_16x16x32_bf16 v[8:11], v[180:183], v[204:207], v[8:11]
	v_mfma_f32_16x16x32_bf16 v[4:7], v[172:175], v[212:215], v[4:7]
	v_mfma_f32_16x16x32_bf16 v[0:3], v[180:183], v[212:215], v[0:3]
	s_barrier
	s_add_i32 s60, s60, 2
	s_add_u32 s28, s28, 0x100
	s_addc_u32 s29, s29, 0
	s_add_u32 s58, s58, 0x100
	s_addc_u32 s59, s59, 0
	s_cmp_gt_u32 s60, 13
	s_cbranch_scc0 .LBB0_440
	s_and_b64 vcc, exec, s[10:11]
	s_cbranch_vccz .LBB0_443
	s_barrier

.LBB0_453:
	s_andn2_b64 vcc, exec, s[2:3]
	s_cbranch_vccnz .LBB0_503
	v_ashrrev_i32_e32 v2, 31, v0
	v_lshrrev_b32_e32 v2, 26, v2
	v_lshlrev_b32_e32 v1, 4, v0
	v_add_u32_e32 v2, v0, v2
	v_bfe_i32 v0, v0, 27, 1
	v_lshrrev_b32_e32 v0, 22, v0
	v_add_u32_e32 v0, v1, v0
	v_and_b32_e32 v0, 0xfffffc00, v0
	v_sub_u32_e32 v0, v1, v0
	v_lshrrev_b32_e32 v3, 4, v0
	v_bitop3_b32 v0, v3, v0, 32 bitop3:0x6c
	v_ashrrev_i32_e32 v4, 31, v0
	v_ashrrev_i32_e32 v2, 6, v2
	v_lshrrev_b32_e32 v4, 26, v4
	v_lshlrev_b32_e32 v3, 3, v2
	v_add_u32_e32 v4, v0, v4
	v_and_b32_e32 v3, -16, v3
	v_ashrrev_i32_e32 v5, 6, v4
	v_and_b32_e32 v4, 0xc0, v4
	v_add_u32_e32 v3, v5, v3
	v_sub_u32_e32 v0, v0, v4
	v_mov_b32_e32 v4, 1
	v_lshlrev_b32_e32 v2, 5, v2
	v_ashrrev_i16_sdwa v0, v4, sext(v0) dst_sel:DWORD dst_unused:UNUSED_PAD src0_sel:DWORD src1_sel:BYTE_0
	v_lshlrev_b32_e32 v6, 1, v3
	v_lshrrev_b32_e32 v7, 2, v3
	v_and_b32_e32 v5, 3, v5
	s_mov_b32 s3, 0x7fffe0
	v_and_b32_e32 v2, 32, v2
	v_bfe_i32 v0, v0, 0, 16
	v_and_b32_e32 v6, 24, v6
	v_and_b32_e32 v7, 4, v7
	v_and_or_b32 v5, v3, s3, v5
	v_or3_b32 v5, v5, v7, v6
	v_add_lshl_u32 v0, v2, v0, 1
	v_lshl_add_u32 v128, v3, 9, v0
	v_lshl_add_u32 v130, v5, 9, v0
	v_add_u32_e32 v0, 0x2000, v1
	v_ashrrev_i32_e32 v1, 31, v0
	v_lshrrev_b32_e32 v1, 22, v1
	v_add_u32_e32 v1, v0, v1
	v_ashrrev_i32_e32 v1, 10, v1
	v_mul_i32_i24_e32 v2, 0x400, v1
	v_sub_u32_e32 v0, v0, v2
	v_lshrrev_b32_e32 v2, 4, v0
	v_bitop3_b32 v0, v2, v0, 32 bitop3:0x6c
	v_ashrrev_i32_e32 v3, 31, v0
	v_lshrrev_b32_e32 v3, 26, v3
	s_add_u32 s50, s70, 0x19c00000
	v_lshlrev_b32_e32 v2, 3, v1
	v_add_u32_e32 v3, v0, v3
	s_addc_u32 s51, s71, 0
	v_and_b32_e32 v2, -16, v2
	v_ashrrev_i32_e32 v5, 6, v3
	s_add_u32 s52, s70, 0x5300000
	v_add_u32_e32 v2, v5, v2
	v_and_b32_e32 v5, 3, v5
	s_addc_u32 s53, s71, 0
	v_and_or_b32 v5, v2, s3, v5
	s_ashr_i32 s3, s14, 6
	s_ashr_i32 s5, s4, 31
	s_ashr_i32 s41, s40, 31
	s_ashr_i32 s2, s14, 8
	v_and_b32_e32 v3, 0xc0, v3
	s_lshl_b32 s54, s3, 10
	s_lshl_b64 s[10:11], s[4:5], 17
	s_lshl_b64 s[12:13], s[40:41], 17
	v_sub_u32_e32 v0, v0, v3
	s_add_u32 s44, s52, s12
	v_lshlrev_b32_e32 v1, 5, v1
	v_ashrrev_i16_sdwa v0, v4, sext(v0) dst_sel:DWORD dst_unused:UNUSED_PAD src0_sel:DWORD src1_sel:BYTE_0
	v_lshlrev_b32_e32 v3, 1, v2
	v_lshrrev_b32_e32 v4, 2, v2
	s_addc_u32 s45, s53, s13
	s_add_i32 s55, s54, 0
	v_and_b32_e32 v1, 32, v1
	v_bfe_i32 v0, v0, 0, 16
	v_and_b32_e32 v3, 24, v3
	v_and_b32_e32 v4, 4, v4
	s_add_i32 m0, s55, 0x10000
	v_or3_b32 v3, v5, v4, v3
	v_add_lshl_u32 v0, v1, v0, 1
	global_load_lds_dwordx4 v130, s[44:45]
	s_add_i32 m0, s55, 0x12000
	v_lshl_add_u32 v134, v3, 9, v0
	s_add_u32 s12, s44, 0x10000
	global_load_lds_dwordx4 v134, s[44:45]
	s_addc_u32 s13, s45, 0
	s_add_i32 m0, s55, 0x14000
	v_lshl_add_u32 v132, v2, 9, v0
	global_load_lds_dwordx4 v130, s[12:13]
	s_add_i32 m0, s55, 0x16000
	s_add_u32 s42, s50, s10
	s_addc_u32 s43, s51, s11
	s_add_i32 s56, s55, 0x2000
	global_load_lds_dwordx4 v134, s[12:13]
	s_mov_b32 m0, s55
	s_add_u32 s10, s42, 0x10000
	global_load_lds_dwordx4 v128, s[42:43]
	s_mov_b32 m0, s56
	s_addc_u32 s11, s43, 0
	s_add_i32 s57, s55, 0x4000
	global_load_lds_dwordx4 v132, s[42:43]
	s_mov_b32 m0, s57
	s_add_i32 s58, s55, 0x6000
	global_load_lds_dwordx4 v128, s[10:11]
	s_mov_b32 m0, s58
	v_mov_b32_e32 v137, 0
	global_load_lds_dwordx4 v132, s[10:11]
	v_mov_b32_e32 v131, v137
	v_mov_b32_e32 v135, v137
	v_mov_b32_e32 v129, v137
	v_mov_b32_e32 v133, v137
	s_cmp_eq_u32 s2, 1
	v_lshl_add_u64 v[6:7], s[44:45], 0, v[130:131]
	v_lshl_add_u64 v[4:5], s[44:45], 0, v[134:135]
	v_lshl_add_u64 v[0:1], s[42:43], 0, v[128:129]
	s_cselect_b64 s[10:11], -1, 0
	s_cmp_lg_u32 s2, 1
	v_lshl_add_u64 v[2:3], s[42:43], 0, v[132:133]
	s_cbranch_scc1 .LBB0_456
	s_barrier
	s_setprio 1

.LBB0_465:
	s_ashr_i32 s35, s34, 31
	s_lshl_b64 s[36:37], s[34:35], 17
	s_add_u32 s36, s50, s36
	s_addc_u32 s37, s51, s37
	s_and_b64 s[38:39], s[2:3], exec
	s_cselect_b32 s49, s37, s43
	s_cselect_b32 s48, s36, s42
	s_ashr_i32 s31, s30, 31
	s_lshl_b64 s[38:39], s[30:31], 17
	s_add_u32 s38, s52, s38
	s_addc_u32 s39, s53, s39
	s_and_b64 s[46:47], s[2:3], exec
	s_cselect_b32 s47, s39, s45
	s_cselect_b32 s46, s38, s44
	s_add_u32 s68, s42, 0x10080
	s_addc_u32 s69, s43, 0
	v_lshl_add_u64 v[64:65], s[68:69], 0, v[128:129]
	v_lshl_add_u64 v[64:65], s[68:69], 0, v[132:133]
	s_add_i32 s41, s62, s54
	v_lshl_add_u64 v[214:215], s[44:45], 0, v[130:131]
	s_add_i32 s5, s41, 0x2000
	v_lshl_add_u64 v[144:145], v[214:215], 0, s[18:19]
	v_lshl_add_u64 v[216:217], s[44:45], 0, v[134:135]
	s_add_u32 s68, s44, 0x10100
	v_lshl_add_u64 v[144:145], v[216:217], 0, s[18:19]
	s_addc_u32 s69, s45, 0
	s_add_i32 s31, s63, s54
	v_lshl_add_u64 v[144:145], s[68:69], 0, v[130:131]
	s_add_i32 s35, s31, 0x2000
	v_lshl_add_u64 v[144:145], s[68:69], 0, v[134:135]
	v_lshl_add_u64 v[218:219], s[42:43], 0, v[128:129]
	v_lshl_add_u64 v[144:145], v[218:219], 0, s[18:19]
	v_lshl_add_u64 v[220:221], s[42:43], 0, v[132:133]
	v_lshl_add_u64 v[144:145], v[220:221], 0, s[18:19]
	s_add_i32 s67, 0, 0x18000
	s_add_i32 s80, 0, 0x1c000
	v_add_u32_e32 v136, s67, v152
	v_add_u32_e32 v142, s80, v152
	s_add_u32 s68, s42, 0x10100
	s_addc_u32 s69, s43, 0
	v_lshl_add_u64 v[222:223], s[68:69], 0, v[128:129]
	v_lshl_add_u64 v[222:223], s[68:69], 0, v[132:133]
	s_add_i32 s68, s67, s54
	s_add_i32 s67, s68, 0x2000
	v_lshl_add_u64 v[214:215], v[214:215], 0, s[20:21]
	s_add_u32 s78, s44, 0x10180
	v_lshl_add_u64 v[214:215], v[216:217], 0, s[20:21]
	s_addc_u32 s79, s45, 0
	s_add_i32 s44, s80, s54
	v_lshl_add_u64 v[214:215], s[78:79], 0, v[130:131]
	s_add_i32 s45, s44, 0x2000
	v_lshl_add_u64 v[214:215], s[78:79], 0, v[134:135]
	v_lshl_add_u64 v[214:215], v[218:219], 0, s[20:21]
	v_lshl_add_u64 v[214:215], v[220:221], 0, s[20:21]
	ds_read_b128 v[104:107], v154
	ds_read_b128 v[108:111], v154 offset:1024
	ds_read_b128 v[112:115], v154 offset:2048
	ds_read_b128 v[116:119], v154 offset:3072
	ds_read_b128 v[120:123], v155
	ds_read_b128 v[124:127], v155 offset:1024
	ds_read_b128 v[174:177], v155 offset:2048
	ds_read_b128 v[178:181], v155 offset:3072
	s_add_u32 s42, s42, 0x10080
	s_addc_u32 s43, s43, 0
	s_mov_b32 m0, s64
	v_lshl_add_u64 v[214:215], s[42:43], 0, v[128:129]
	ds_read_b128 v[182:185], v156
	ds_read_b128 v[186:189], v156 offset:1024
	ds_read_b128 v[190:193], v156 offset:2048
	ds_read_b128 v[194:197], v156 offset:3072
	ds_read_b128 v[198:201], v156 offset:4096
	ds_read_b128 v[202:205], v156 offset:5120
	ds_read_b128 v[206:209], v156 offset:6144
	ds_read_b128 v[210:213], v156 offset:7168
	global_load_lds_dwordx4 v[214:215], off
	v_lshl_add_u64 v[214:215], s[42:43], 0, v[132:133]
	s_mov_b32 m0, s65
	s_nop 0
	global_load_lds_dwordx4 v[214:215], off
	s_waitcnt vmcnt(8)
	s_waitcnt lgkmcnt(0)
	s_barrier
	s_waitcnt lgkmcnt(0)
	v_mfma_f32_16x16x32_bf16 v[64:67], v[104:107], v[182:185], 0
	v_mfma_f32_16x16x32_bf16 v[68:71], v[112:115], v[182:185], 0
	v_mfma_f32_16x16x32_bf16 v[72:75], v[104:107], v[190:193], 0
	v_mfma_f32_16x16x32_bf16 v[76:79], v[112:115], v[190:193], 0
	v_mfma_f32_16x16x32_bf16 v[80:83], v[104:107], v[198:201], 0
	v_mfma_f32_16x16x32_bf16 v[84:87], v[112:115], v[198:201], 0
	v_mfma_f32_16x16x32_bf16 v[88:91], v[104:107], v[206:209], 0
	v_mfma_f32_16x16x32_bf16 v[64:67], v[108:111], v[186:189], v[64:67]
	v_mfma_f32_16x16x32_bf16 v[68:71], v[116:119], v[186:189], v[68:71]
	v_mfma_f32_16x16x32_bf16 v[72:75], v[108:111], v[194:197], v[72:75]
	v_mfma_f32_16x16x32_bf16 v[76:79], v[116:119], v[194:197], v[76:79]
	v_mfma_f32_16x16x32_bf16 v[80:83], v[108:111], v[202:205], v[80:83]
	v_mfma_f32_16x16x32_bf16 v[84:87], v[116:119], v[202:205], v[84:87]
	v_mfma_f32_16x16x32_bf16 v[214:217], v[108:111], v[210:213], v[88:91]
	v_mfma_f32_16x16x32_bf16 v[88:91], v[112:115], v[206:209], 0
	v_mfma_f32_16x16x32_bf16 v[218:221], v[116:119], v[210:213], v[88:91]
	v_mfma_f32_16x16x32_bf16 v[88:91], v[120:123], v[182:185], 0
	v_mfma_f32_16x16x32_bf16 v[32:35], v[174:177], v[182:185], 0
	v_mfma_f32_16x16x32_bf16 v[36:39], v[120:123], v[190:193], 0
	v_mfma_f32_16x16x32_bf16 v[40:43], v[174:177], v[190:193], 0
	v_mfma_f32_16x16x32_bf16 v[44:47], v[120:123], v[198:201], 0
	v_mfma_f32_16x16x32_bf16 v[48:51], v[174:177], v[198:201], 0
	v_mfma_f32_16x16x32_bf16 v[52:55], v[120:123], v[206:209], 0
	v_mfma_f32_16x16x32_bf16 v[56:59], v[174:177], v[206:209], 0
	v_mfma_f32_16x16x32_bf16 v[96:99], v[124:127], v[186:189], v[88:91]
	v_mfma_f32_16x16x32_bf16 v[32:35], v[178:181], v[186:189], v[32:35]
	v_mfma_f32_16x16x32_bf16 v[36:39], v[124:127], v[194:197], v[36:39]
	v_mfma_f32_16x16x32_bf16 v[40:43], v[178:181], v[194:197], v[40:43]
	v_mfma_f32_16x16x32_bf16 v[44:47], v[124:127], v[202:205], v[44:47]
	v_mfma_f32_16x16x32_bf16 v[48:51], v[178:181], v[202:205], v[48:51]
	v_mfma_f32_16x16x32_bf16 v[52:55], v[124:127], v[210:213], v[52:55]
	v_mfma_f32_16x16x32_bf16 v[56:59], v[178:181], v[210:213], v[56:59]
	s_barrier
	s_mov_b32 m0, s41
	v_lshl_add_u64 v[250:251], s[46:47], 0, v[130:131]
	s_add_u32 s42, s46, 0x10000
	ds_read_b128 v[88:91], v156 offset:16384
	ds_read_b128 v[92:95], v156 offset:17408
	ds_read_b128 v[182:185], v156 offset:18432
	ds_read_b128 v[186:189], v156 offset:19456
	ds_read_b128 v[190:193], v156 offset:20480
	ds_read_b128 v[194:197], v156 offset:21504
	ds_read_b128 v[198:201], v156 offset:22528
	ds_read_b128 v[202:205], v156 offset:23552
	global_load_lds_dwordx4 v[250:251], off
	v_lshl_add_u64 v[252:253], s[46:47], 0, v[134:135]
	s_mov_b32 m0, s5
	s_addc_u32 s43, s47, 0
	global_load_lds_dwordx4 v[252:253], off
	v_lshl_add_u64 v[206:207], s[42:43], 0, v[130:131]
	s_mov_b32 m0, s31
	v_lshl_add_u64 v[138:139], s[48:49], 0, v[128:129]
	global_load_lds_dwordx4 v[206:207], off
	v_lshl_add_u64 v[206:207], s[42:43], 0, v[134:135]
	s_mov_b32 m0, s35
	v_lshl_add_u64 v[140:141], s[48:49], 0, v[132:133]
	global_load_lds_dwordx4 v[206:207], off
	s_mov_b32 m0, s55
	s_nop 0
	global_load_lds_dwordx4 v[138:139], off
	s_mov_b32 m0, s56
	s_nop 0
	global_load_lds_dwordx4 v[140:141], off
	s_waitcnt vmcnt(8)
	s_waitcnt lgkmcnt(0)
	s_barrier
	s_waitcnt lgkmcnt(0)
	v_mfma_f32_16x16x32_bf16 v[0:3], v[104:107], v[198:201], 0
	v_mfma_f32_16x16x32_bf16 v[4:7], v[112:115], v[198:201], 0
	v_mfma_f32_16x16x32_bf16 v[144:147], v[104:107], v[88:91], 0
	v_mfma_f32_16x16x32_bf16 v[148:151], v[112:115], v[88:91], 0
	v_mfma_f32_16x16x32_bf16 v[158:161], v[104:107], v[182:185], 0
	v_mfma_f32_16x16x32_bf16 v[162:165], v[112:115], v[182:185], 0
	v_mfma_f32_16x16x32_bf16 v[166:169], v[104:107], v[190:193], 0
	v_mfma_f32_16x16x32_bf16 v[170:173], v[112:115], v[190:193], 0
	v_mfma_f32_16x16x32_bf16 v[0:3], v[108:111], v[202:205], v[0:3]
	v_mfma_f32_16x16x32_bf16 v[4:7], v[116:119], v[202:205], v[4:7]
	v_mfma_f32_16x16x32_bf16 v[144:147], v[108:111], v[92:95], v[144:147]
	v_mfma_f32_16x16x32_bf16 v[148:151], v[116:119], v[92:95], v[148:151]
	v_mfma_f32_16x16x32_bf16 v[158:161], v[108:111], v[186:189], v[158:161]
	v_mfma_f32_16x16x32_bf16 v[162:165], v[116:119], v[186:189], v[162:165]
	v_mfma_f32_16x16x32_bf16 v[166:169], v[108:111], v[194:197], v[166:169]
	v_mfma_f32_16x16x32_bf16 v[170:173], v[116:119], v[194:197], v[170:173]
	v_mfma_f32_16x16x32_bf16 v[8:11], v[120:123], v[88:91], 0
	v_mfma_f32_16x16x32_bf16 v[206:209], v[124:127], v[92:95], v[8:11]
	v_mfma_f32_16x16x32_bf16 v[8:11], v[174:177], v[88:91], 0
	v_mfma_f32_16x16x32_bf16 v[210:213], v[178:181], v[92:95], v[8:11]
	v_mfma_f32_16x16x32_bf16 v[8:11], v[120:123], v[182:185], 0
	v_mfma_f32_16x16x32_bf16 v[222:225], v[124:127], v[186:189], v[8:11]
	v_mfma_f32_16x16x32_bf16 v[8:11], v[174:177], v[182:185], 0
	v_mfma_f32_16x16x32_bf16 v[182:185], v[178:181], v[186:189], v[8:11]
	v_mfma_f32_16x16x32_bf16 v[8:11], v[120:123], v[190:193], 0
	v_mfma_f32_16x16x32_bf16 v[186:189], v[124:127], v[194:197], v[8:11]
	v_mfma_f32_16x16x32_bf16 v[8:11], v[174:177], v[190:193], 0
	v_mfma_f32_16x16x32_bf16 v[190:193], v[178:181], v[194:197], v[8:11]
	v_mfma_f32_16x16x32_bf16 v[8:11], v[120:123], v[198:201], 0
	v_mfma_f32_16x16x32_bf16 v[194:197], v[124:127], v[202:205], v[8:11]
	v_mfma_f32_16x16x32_bf16 v[8:11], v[174:177], v[198:201], 0
	v_mfma_f32_16x16x32_bf16 v[174:177], v[178:181], v[202:205], v[8:11]
	s_barrier
	s_nop 4
	ds_read_b128 v[8:11], v136
	ds_read_b128 v[12:15], v136 offset:1024
	ds_read_b128 v[16:19], v136 offset:2048
	ds_read_b128 v[20:23], v136 offset:3072
	ds_read_b128 v[178:181], v142
	ds_read_b128 v[198:201], v142 offset:1024
	ds_read_b128 v[202:205], v142 offset:2048
	ds_read_b128 v[226:229], v142 offset:3072
	s_add_u32 s42, s48, 0x10000
	s_addc_u32 s43, s49, 0
	s_mov_b32 m0, s57
	v_lshl_add_u64 v[88:89], s[42:43], 0, v[128:129]
	ds_read_b128 v[24:27], v156 offset:32768
	ds_read_b128 v[28:31], v156 offset:33792
	ds_read_b128 v[60:63], v156 offset:34816
	ds_read_b128 v[230:233], v156 offset:35840
	ds_read_b128 v[234:237], v156 offset:36864
	ds_read_b128 v[238:241], v156 offset:37888
	ds_read_b128 v[242:245], v156 offset:38912
	ds_read_b128 v[246:249], v156 offset:39936
	global_load_lds_dwordx4 v[88:89], off
	v_lshl_add_u64 v[88:89], s[42:43], 0, v[132:133]
	s_mov_b32 m0, s58
	s_nop 0
	global_load_lds_dwordx4 v[88:89], off
	s_waitcnt vmcnt(8)
	s_waitcnt lgkmcnt(0)
	s_barrier
	s_waitcnt lgkmcnt(0)
	v_mfma_f32_16x16x32_bf16 v[64:67], v[8:11], v[24:27], v[64:67]
	v_mfma_f32_16x16x32_bf16 v[124:127], v[12:15], v[28:31], v[64:67]
	v_mfma_f32_16x16x32_bf16 v[64:67], v[16:19], v[24:27], v[68:71]
	v_mfma_f32_16x16x32_bf16 v[120:123], v[20:23], v[28:31], v[64:67]
	v_mfma_f32_16x16x32_bf16 v[64:67], v[8:11], v[60:63], v[72:75]
	v_mfma_f32_16x16x32_bf16 v[108:111], v[12:15], v[230:233], v[64:67]
	v_mfma_f32_16x16x32_bf16 v[64:67], v[16:19], v[60:63], v[76:79]
	v_mfma_f32_16x16x32_bf16 v[104:107], v[20:23], v[230:233], v[64:67]
	v_mfma_f32_16x16x32_bf16 v[64:67], v[8:11], v[234:237], v[80:83]
	v_mfma_f32_16x16x32_bf16 v[92:95], v[12:15], v[238:241], v[64:67]
	v_mfma_f32_16x16x32_bf16 v[64:67], v[16:19], v[234:237], v[84:87]
	v_mfma_f32_16x16x32_bf16 v[88:91], v[20:23], v[238:241], v[64:67]
	v_mfma_f32_16x16x32_bf16 v[64:67], v[8:11], v[242:245], v[214:217]
	v_mfma_f32_16x16x32_bf16 v[76:79], v[12:15], v[246:249], v[64:67]
	v_mfma_f32_16x16x32_bf16 v[64:67], v[16:19], v[242:245], v[218:221]
	v_mfma_f32_16x16x32_bf16 v[72:75], v[20:23], v[246:249], v[64:67]
	v_mfma_f32_16x16x32_bf16 v[64:67], v[178:181], v[24:27], v[96:99]
	v_mfma_f32_16x16x32_bf16 v[24:27], v[202:205], v[24:27], v[32:35]
	v_mfma_f32_16x16x32_bf16 v[112:115], v[226:229], v[28:31], v[24:27]
	v_mfma_f32_16x16x32_bf16 v[24:27], v[178:181], v[60:63], v[36:39]
	v_mfma_f32_16x16x32_bf16 v[100:103], v[198:201], v[230:233], v[24:27]
	v_mfma_f32_16x16x32_bf16 v[24:27], v[202:205], v[60:63], v[40:43]
	v_mfma_f32_16x16x32_bf16 v[96:99], v[226:229], v[230:233], v[24:27]
	v_mfma_f32_16x16x32_bf16 v[24:27], v[178:181], v[234:237], v[44:47]
	v_mfma_f32_16x16x32_bf16 v[84:87], v[198:201], v[238:241], v[24:27]
	v_mfma_f32_16x16x32_bf16 v[24:27], v[202:205], v[234:237], v[48:51]
	v_mfma_f32_16x16x32_bf16 v[80:83], v[226:229], v[238:241], v[24:27]
	v_mfma_f32_16x16x32_bf16 v[24:27], v[178:181], v[242:245], v[52:55]
	v_mfma_f32_16x16x32_bf16 v[68:71], v[198:201], v[246:249], v[24:27]
	v_mfma_f32_16x16x32_bf16 v[24:27], v[202:205], v[242:245], v[56:59]
	v_mfma_f32_16x16x32_bf16 v[116:119], v[198:201], v[28:31], v[64:67]
	v_mfma_f32_16x16x32_bf16 v[64:67], v[226:229], v[246:249], v[24:27]
	s_barrier
	s_mov_b32 m0, s68
	s_nop 2
	v_lshl_add_u64 v[24:25], v[250:251], 0, s[12:13]
	s_add_u32 s42, s46, 0x10080
	ds_read_b128 v[32:35], v156 offset:49152
	ds_read_b128 v[36:39], v156 offset:50176
	ds_read_b128 v[214:217], v156 offset:51200
	ds_read_b128 v[218:221], v156 offset:52224
	ds_read_b128 v[230:233], v156 offset:53248
	ds_read_b128 v[234:237], v156 offset:54272
	ds_read_b128 v[238:241], v156 offset:55296
	ds_read_b128 v[242:245], v156 offset:56320
	global_load_lds_dwordx4 v[24:25], off
	v_lshl_add_u64 v[24:25], v[252:253], 0, s[12:13]
	s_mov_b32 m0, s67
	s_addc_u32 s43, s47, 0
	global_load_lds_dwordx4 v[24:25], off
	v_lshl_add_u64 v[24:25], s[42:43], 0, v[130:131]
	s_mov_b32 m0, s44
	s_nop 0
	global_load_lds_dwordx4 v[24:25], off
	v_lshl_add_u64 v[24:25], s[42:43], 0, v[134:135]
	s_mov_b32 m0, s45
	s_nop 0
	global_load_lds_dwordx4 v[24:25], off
	v_lshl_add_u64 v[24:25], v[138:139], 0, s[12:13]
	s_mov_b32 m0, s59
	s_nop 0
	global_load_lds_dwordx4 v[24:25], off
	v_lshl_add_u64 v[24:25], v[140:141], 0, s[12:13]
	s_mov_b32 m0, s60
	s_nop 0
	global_load_lds_dwordx4 v[24:25], off
	s_waitcnt vmcnt(8)
	s_waitcnt lgkmcnt(0)
	s_barrier
	s_waitcnt lgkmcnt(0)
	v_mfma_f32_16x16x32_bf16 v[24:27], v[8:11], v[32:35], v[144:147]
	v_mfma_f32_16x16x32_bf16 v[60:63], v[12:15], v[36:39], v[24:27]
	v_mfma_f32_16x16x32_bf16 v[24:27], v[16:19], v[32:35], v[148:151]
	v_mfma_f32_16x16x32_bf16 v[56:59], v[20:23], v[36:39], v[24:27]
	v_mfma_f32_16x16x32_bf16 v[24:27], v[8:11], v[214:217], v[158:161]
	v_mfma_f32_16x16x32_bf16 v[44:47], v[12:15], v[218:221], v[24:27]
	v_mfma_f32_16x16x32_bf16 v[24:27], v[16:19], v[214:217], v[162:165]
	v_mfma_f32_16x16x32_bf16 v[40:43], v[20:23], v[218:221], v[24:27]
	v_mfma_f32_16x16x32_bf16 v[24:27], v[8:11], v[230:233], v[166:169]
	v_mfma_f32_16x16x32_bf16 v[0:3], v[8:11], v[238:241], v[0:3]
	v_mfma_f32_16x16x32_bf16 v[28:31], v[12:15], v[234:237], v[24:27]
	v_mfma_f32_16x16x32_bf16 v[24:27], v[16:19], v[230:233], v[170:173]
	v_mfma_f32_16x16x32_bf16 v[12:15], v[12:15], v[242:245], v[0:3]
	v_mfma_f32_16x16x32_bf16 v[0:3], v[16:19], v[238:241], v[4:7]
	v_mfma_f32_16x16x32_bf16 v[24:27], v[20:23], v[234:237], v[24:27]
	v_mfma_f32_16x16x32_bf16 v[8:11], v[20:23], v[242:245], v[0:3]
	v_mfma_f32_16x16x32_bf16 v[0:3], v[178:181], v[32:35], v[206:209]
	v_mfma_f32_16x16x32_bf16 v[52:55], v[198:201], v[36:39], v[0:3]
	v_mfma_f32_16x16x32_bf16 v[0:3], v[202:205], v[32:35], v[210:213]
	v_mfma_f32_16x16x32_bf16 v[48:51], v[226:229], v[36:39], v[0:3]
	v_mfma_f32_16x16x32_bf16 v[0:3], v[178:181], v[214:217], v[222:225]
	v_mfma_f32_16x16x32_bf16 v[36:39], v[198:201], v[218:221], v[0:3]
	v_mfma_f32_16x16x32_bf16 v[0:3], v[202:205], v[214:217], v[182:185]
	v_mfma_f32_16x16x32_bf16 v[32:35], v[226:229], v[218:221], v[0:3]
	v_mfma_f32_16x16x32_bf16 v[0:3], v[178:181], v[230:233], v[186:189]
	v_mfma_f32_16x16x32_bf16 v[20:23], v[198:201], v[234:237], v[0:3]
	v_mfma_f32_16x16x32_bf16 v[0:3], v[202:205], v[230:233], v[190:193]
	v_mfma_f32_16x16x32_bf16 v[16:19], v[226:229], v[234:237], v[0:3]
	v_mfma_f32_16x16x32_bf16 v[0:3], v[178:181], v[238:241], v[194:197]
	v_mfma_f32_16x16x32_bf16 v[4:7], v[198:201], v[242:245], v[0:3]
	v_mfma_f32_16x16x32_bf16 v[0:3], v[202:205], v[238:241], v[174:177]
	v_mfma_f32_16x16x32_bf16 v[0:3], v[226:229], v[242:245], v[0:3]
	s_barrier
	s_andn2_b64 vcc, exec, s[14:15]
	s_cbranch_vccnz .LBB0_467
	s_barrier

.LBB0_503:
	s_setprio 0
	s_load_dwordx2 s[2:3], s[0:1], 0x120
	s_waitcnt lgkmcnt(0)
	s_cmp_lt_i32 s2, 6
	s_cselect_b64 s[4:5], -1, 0
	s_cmp_gt_i32 s3, 6
	s_cselect_b64 s[6:7], -1, 0
	s_and_b64 s[4:5], s[4:5], s[6:7]
	s_andn2_b64 vcc, exec, s[4:5]
	s_cbranch_vccnz .LBB0_534
	v_readlane_b32 s2, v254, 0
	s_waitcnt vmcnt(0) lgkmcnt(0)
	s_lshl_b32 s2, s2, 6
	s_sub_i32 s2, 0, s2
	s_waitcnt vmcnt(0)
	s_barrier
	v_mbcnt_lo_u32_b32 v0, -1, 0
	v_mbcnt_hi_u32_b32 v0, -1, v0
	s_nop 0
	v_cmp_eq_u32_e32 vcc, s2, v0
	s_and_saveexec_b64 s[78:79], vcc
	s_cbranch_execz .LBB0_533
	s_add_i32 s2, 0, 0x20040
	v_mov_b32_e32 v0, s2
	ds_read_b32 v1, v0
	s_add_i32 s2, 0, 0x20044
	v_mov_b32_e32 v0, s2
	ds_read_b32 v0, v0
	s_waitcnt lgkmcnt(1)
	v_cmp_ne_u32_e32 vcc, 0, v1
	s_cbranch_vccnz .LBB0_511
	s_cmp_eq_u32 s97, 0
	s_cselect_b64 s[2:3], -1, 0
	s_cmp_eq_u32 s97, 1
	s_cselect_b64 s[4:5], -1, 0
	s_cmp_eq_u32 s97, 2
	s_cselect_b64 s[6:7], -1, 0
	s_cmp_eq_u32 s97, 3
	s_cselect_b64 s[8:9], -1, 0
	s_cmp_eq_u32 s97, 4
	s_cselect_b64 s[10:11], -1, 0
	s_cmp_eq_u32 s97, 5
	s_cselect_b64 s[12:13], -1, 0
	s_cmp_eq_u32 s97, 6
	s_cselect_b64 s[14:15], -1, 0
	s_cmp_eq_u32 s97, 7
	s_cselect_b64 s[16:17], -1, 0
	s_cmp_eq_u32 s97, 8
	s_cselect_b64 s[18:19], -1, 0
	s_cmp_eq_u32 s97, 9
	s_cselect_b64 s[20:21], -1, 0
	s_cmp_eq_u32 s97, 10
	s_cselect_b64 s[22:23], -1, 0
	s_cmp_eq_u32 s97, 11
	s_cselect_b64 s[24:25], -1, 0
	s_add_u32 s80, s70, 0x1000
	s_addc_u32 s81, s71, 0
	s_cmp_eq_u32 s97, 12
	s_cselect_b64 s[26:27], -1, 0
	s_add_u32 s82, s70, 0x1100
	s_addc_u32 s83, s71, 0
	s_cmp_eq_u32 s97, 13
	s_cselect_b64 s[28:29], -1, 0
	s_add_u32 s84, s70, 0x1200
	s_addc_u32 s85, s71, 0
	s_cmp_eq_u32 s97, 14
	s_cselect_b64 s[30:31], -1, 0
	s_add_u32 s86, s70, 0x1300
	s_addc_u32 s87, s71, 0
	s_cmp_eq_u32 s97, 15
	s_cselect_b64 s[34:35], -1, 0
	v_mov_b32_e32 v2, 0
	v_mov_b32_e32 v1, 0
	s_branch .LBB0_508

.LBB0_773:
	s_andn2_b64 vcc, exec, s[10:11]
	s_cbranch_vccnz .LBB0_823
	v_ashrrev_i32_e32 v2, 31, v0
	v_lshrrev_b32_e32 v2, 26, v2
	v_lshlrev_b32_e32 v1, 4, v0
	v_add_u32_e32 v2, v0, v2
	v_bfe_i32 v0, v0, 27, 1
	v_lshrrev_b32_e32 v0, 22, v0
	v_add_u32_e32 v0, v1, v0
	v_and_b32_e32 v0, 0xfffffc00, v0
	v_sub_u32_e32 v0, v1, v0
	v_lshrrev_b32_e32 v3, 4, v0
	v_bitop3_b32 v0, v3, v0, 32 bitop3:0x6c
	v_ashrrev_i32_e32 v4, 31, v0
	v_ashrrev_i32_e32 v2, 6, v2
	v_lshrrev_b32_e32 v4, 26, v4
	v_lshlrev_b32_e32 v3, 3, v2
	v_add_u32_e32 v4, v0, v4
	v_and_b32_e32 v3, -16, v3
	v_ashrrev_i32_e32 v5, 6, v4
	v_and_b32_e32 v4, 0xc0, v4
	v_add_u32_e32 v3, v5, v3
	v_sub_u32_e32 v0, v0, v4
	v_mov_b32_e32 v4, 1
	v_lshlrev_b32_e32 v2, 5, v2
	v_ashrrev_i16_sdwa v0, v4, sext(v0) dst_sel:DWORD dst_unused:UNUSED_PAD src0_sel:DWORD src1_sel:BYTE_0
	v_lshlrev_b32_e32 v6, 1, v3
	v_lshrrev_b32_e32 v7, 2, v3
	v_and_b32_e32 v5, 3, v5
	s_mov_b32 s3, 0x7fffe0
	v_and_b32_e32 v2, 32, v2
	v_bfe_i32 v0, v0, 0, 16
	v_and_b32_e32 v6, 24, v6
	v_and_b32_e32 v7, 4, v7
	v_and_or_b32 v5, v3, s3, v5
	v_or3_b32 v5, v5, v7, v6
	v_add_lshl_u32 v0, v2, v0, 1
	v_lshl_add_u32 v128, v3, 9, v0
	v_lshl_add_u32 v130, v5, 9, v0
	v_add_u32_e32 v0, 0x2000, v1
	v_ashrrev_i32_e32 v1, 31, v0
	v_lshrrev_b32_e32 v1, 22, v1
	v_add_u32_e32 v1, v0, v1
	v_ashrrev_i32_e32 v1, 10, v1
	v_mul_i32_i24_e32 v2, 0x400, v1
	v_sub_u32_e32 v0, v0, v2
	v_lshrrev_b32_e32 v2, 4, v0
	v_bitop3_b32 v0, v2, v0, 32 bitop3:0x6c
	v_ashrrev_i32_e32 v3, 31, v0
	v_lshrrev_b32_e32 v3, 26, v3
	s_add_u32 s50, s70, 0x19c00100
	v_lshlrev_b32_e32 v2, 3, v1
	v_add_u32_e32 v3, v0, v3
	s_addc_u32 s51, s71, 0
	v_and_b32_e32 v2, -16, v2
	v_ashrrev_i32_e32 v5, 6, v3
	s_add_u32 s52, s70, 0x5400100
	v_add_u32_e32 v2, v5, v2
	v_and_b32_e32 v5, 3, v5
	s_addc_u32 s53, s71, 0
	v_and_or_b32 v5, v2, s3, v5
	s_ashr_i32 s3, s14, 6
	s_ashr_i32 s5, s4, 31
	s_ashr_i32 s41, s40, 31
	s_ashr_i32 s2, s14, 8
	v_and_b32_e32 v3, 0xc0, v3
	s_lshl_b32 s54, s3, 10
	s_lshl_b64 s[10:11], s[4:5], 17
	s_lshl_b64 s[12:13], s[40:41], 17
	v_sub_u32_e32 v0, v0, v3
	s_add_u32 s44, s52, s12
	v_lshlrev_b32_e32 v1, 5, v1
	v_ashrrev_i16_sdwa v0, v4, sext(v0) dst_sel:DWORD dst_unused:UNUSED_PAD src0_sel:DWORD src1_sel:BYTE_0
	v_lshlrev_b32_e32 v3, 1, v2
	v_lshrrev_b32_e32 v4, 2, v2
	s_addc_u32 s45, s53, s13
	s_add_i32 s55, s54, 0
	v_and_b32_e32 v1, 32, v1
	v_bfe_i32 v0, v0, 0, 16
	v_and_b32_e32 v3, 24, v3
	v_and_b32_e32 v4, 4, v4
	s_add_i32 m0, s55, 0x10000
	v_or3_b32 v3, v5, v4, v3
	v_add_lshl_u32 v0, v1, v0, 1
	global_load_lds_dwordx4 v130, s[44:45]
	s_add_i32 m0, s55, 0x12000
	v_lshl_add_u32 v134, v3, 9, v0
	s_add_u32 s12, s44, 0x10000
	global_load_lds_dwordx4 v134, s[44:45]
	s_addc_u32 s13, s45, 0
	s_add_i32 m0, s55, 0x14000
	v_lshl_add_u32 v132, v2, 9, v0
	global_load_lds_dwordx4 v130, s[12:13]
	s_add_i32 m0, s55, 0x16000
	s_add_u32 s42, s50, s10
	s_addc_u32 s43, s51, s11
	s_add_i32 s56, s55, 0x2000
	global_load_lds_dwordx4 v134, s[12:13]
	s_mov_b32 m0, s55
	s_add_u32 s10, s42, 0x10000
	global_load_lds_dwordx4 v128, s[42:43]
	s_mov_b32 m0, s56
	s_addc_u32 s11, s43, 0
	s_add_i32 s57, s55, 0x4000
	global_load_lds_dwordx4 v132, s[42:43]
	s_mov_b32 m0, s57
	s_add_i32 s58, s55, 0x6000
	global_load_lds_dwordx4 v128, s[10:11]
	s_mov_b32 m0, s58
	v_mov_b32_e32 v137, 0
	global_load_lds_dwordx4 v132, s[10:11]
	v_mov_b32_e32 v131, v137
	v_mov_b32_e32 v135, v137
	v_mov_b32_e32 v129, v137
	v_mov_b32_e32 v133, v137
	s_cmp_eq_u32 s2, 1
	v_lshl_add_u64 v[6:7], s[44:45], 0, v[130:131]
	v_lshl_add_u64 v[4:5], s[44:45], 0, v[134:135]
	v_lshl_add_u64 v[0:1], s[42:43], 0, v[128:129]
	s_cselect_b64 s[10:11], -1, 0
	s_cmp_lg_u32 s2, 1
	v_lshl_add_u64 v[2:3], s[42:43], 0, v[132:133]
	s_cbranch_scc1 .LBB0_776
	s_barrier
	s_setprio 1

.LBB0_898:
	s_andn2_b64 vcc, exec, s[2:3]
	s_cbranch_vccnz .LBB0_934
	v_ashrrev_i32_e32 v1, 31, v2
	v_lshrrev_b32_e32 v1, 26, v1
	v_add_u32_e32 v1, v2, v1
	v_ashrrev_i32_e32 v9, 6, v1
	v_bfe_i32 v1, v2, 27, 1
	v_lshlrev_b32_e32 v0, 4, v2
	v_lshrrev_b32_e32 v1, 22, v1
	v_add_u32_e32 v1, v0, v1
	v_and_b32_e32 v1, 0xfffffc00, v1
	v_sub_u32_e32 v1, v0, v1
	v_lshrrev_b32_e32 v2, 4, v1
	v_bitop3_b32 v1, v2, v1, 32 bitop3:0x6c
	v_ashrrev_i32_e32 v3, 31, v1
	v_lshrrev_b32_e32 v3, 26, v3
	v_add_u32_e32 v3, v1, v3
	v_ashrrev_i32_e32 v10, 6, v3
	v_and_b32_e32 v3, 0xc0, v3
	v_sub_u32_e32 v1, v1, v3
	v_mov_b32_e32 v3, 1
	v_lshlrev_b32_e32 v2, 3, v9
	v_lshlrev_b32_e32 v4, 5, v9
	v_ashrrev_i16_sdwa v1, v3, sext(v1) dst_sel:DWORD dst_unused:UNUSED_PAD src0_sel:DWORD src1_sel:BYTE_0
	v_and_b32_e32 v2, 0x1ffff0, v2
	v_and_b32_e32 v4, 32, v4
	v_bfe_i32 v11, v1, 0, 16
	v_add_u32_e32 v1, v4, v11
	v_add_lshl_u32 v2, v10, v2, 11
	v_add_u32_e32 v0, 0x2000, v0
	v_lshl_add_u32 v128, v1, 1, v2
	v_ashrrev_i32_e32 v1, 31, v0
	v_lshrrev_b32_e32 v1, 22, v1
	v_add_u32_e32 v1, v0, v1
	v_ashrrev_i32_e32 v12, 10, v1
	v_mul_i32_i24_e32 v1, 0x400, v12
	v_sub_u32_e32 v0, v0, v1
	v_lshrrev_b32_e32 v1, 4, v0
	s_add_u32 s36, s70, 0x1ac00000
	v_bitop3_b32 v0, v1, v0, 32 bitop3:0x6c
	s_addc_u32 s37, s71, 0
	v_ashrrev_i32_e32 v2, 31, v0
	s_add_u32 s38, s70, 0x5000000
	v_lshrrev_b32_e32 v2, 26, v2
	s_addc_u32 s39, s71, 0
	s_ashr_i32 s2, s16, 6
	v_add_u32_e32 v2, v0, v2
	s_ashr_i32 s27, s26, 31
	s_ashr_i32 s11, s10, 31
	v_ashrrev_i32_e32 v13, 6, v2
	v_and_b32_e32 v2, 0xc0, v2
	s_ashr_i32 s3, s16, 8
	s_lshl_b32 s40, s2, 10
	s_lshl_b64 s[4:5], s[26:27], 19
	s_lshl_b64 s[12:13], s[10:11], 19
	v_sub_u32_e32 v0, v0, v2
	s_add_u32 s30, s38, s12
	v_lshlrev_b32_e32 v1, 3, v12
	v_lshlrev_b32_e32 v4, 5, v12
	v_ashrrev_i16_sdwa v0, v3, sext(v0) dst_sel:DWORD dst_unused:UNUSED_PAD src0_sel:DWORD src1_sel:BYTE_0
	s_addc_u32 s31, s39, s13
	s_add_i32 s41, s40, 0
	v_and_b32_e32 v1, 0x1ffff0, v1
	v_and_b32_e32 v4, 32, v4
	v_bfe_i32 v14, v0, 0, 16
	s_add_i32 m0, s41, 0x10000
	v_add_u32_e32 v0, v4, v14
	v_add_lshl_u32 v1, v13, v1, 11
	global_load_lds_dwordx4 v128, s[30:31]
	s_add_i32 m0, s41, 0x12000
	v_lshl_add_u32 v130, v0, 1, v1
	s_add_u32 s12, s30, 0x40000
	global_load_lds_dwordx4 v130, s[30:31]
	s_addc_u32 s13, s31, 0
	s_add_i32 m0, s41, 0x14000
	v_mov_b32_e32 v129, 0
	global_load_lds_dwordx4 v128, s[12:13]
	s_add_i32 m0, s41, 0x16000
	s_add_u32 s28, s36, s4
	s_addc_u32 s29, s37, s5
	s_add_i32 s42, s41, 0x2000
	global_load_lds_dwordx4 v130, s[12:13]
	s_mov_b32 m0, s41
	s_add_u32 s4, s28, 0x40000
	global_load_lds_dwordx4 v128, s[28:29]
	s_mov_b32 m0, s42
	s_addc_u32 s5, s29, 0
	s_add_i32 s43, s41, 0x4000
	global_load_lds_dwordx4 v130, s[28:29]
	s_mov_b32 m0, s43
	s_add_i32 s44, s41, 0x6000
	global_load_lds_dwordx4 v128, s[4:5]
	s_mov_b32 m0, s44
	v_mov_b32_e32 v131, v129
	global_load_lds_dwordx4 v130, s[4:5]
	s_cmp_eq_u32 s3, 1
	s_mov_b32 s11, 0
	v_lshl_add_u64 v[6:7], s[30:31], 0, v[128:129]
	v_lshl_add_u64 v[4:5], s[30:31], 0, v[130:131]
	v_lshl_add_u64 v[0:1], s[28:29], 0, v[128:129]
	s_cselect_b64 s[12:13], -1, 0
	s_cmp_lg_u32 s3, 1
	v_lshl_add_u64 v[2:3], s[28:29], 0, v[130:131]
	s_cbranch_scc1 .LBB0_901
	s_barrier
	s_setprio 1

.LBB0_911:
	ds_read_b128 v[140:143], v147
	ds_read_b128 v[152:155], v147 offset:1024
	ds_read_b128 v[156:159], v147 offset:2048
	ds_read_b128 v[160:163], v147 offset:3072
	ds_read_b128 v[164:167], v148
	ds_read_b128 v[168:171], v148 offset:1024
	ds_read_b128 v[172:175], v148 offset:2048
	ds_read_b128 v[176:179], v148 offset:3072
	s_add_u32 s30, s28, 0xfffc0080
	s_addc_u32 s31, s29, -1
	s_cmp_eq_u32 s56, 12
	s_cselect_b32 s35, s21, s31
	s_cselect_b32 s34, s27, s30
	s_cselect_b32 s31, s19, s55
	s_cselect_b32 s30, s53, s54
	v_lshl_add_u64 v[212:213], s[28:29], 0, v[132:133]
	s_add_i32 m0, s41, 0xc000
	ds_read_b128 v[180:183], v149
	ds_read_b128 v[184:187], v149 offset:1024
	ds_read_b128 v[188:191], v149 offset:2048
	ds_read_b128 v[192:195], v149 offset:3072
	ds_read_b128 v[196:199], v149 offset:4096
	ds_read_b128 v[200:203], v149 offset:5120
	ds_read_b128 v[204:207], v149 offset:6144
	ds_read_b128 v[208:211], v149 offset:7168
	global_load_lds_dwordx4 v[212:213], off
	v_lshl_add_u64 v[212:213], s[28:29], 0, v[134:135]
	s_add_i32 m0, s41, 0xe000
	s_nop 0
	global_load_lds_dwordx4 v[212:213], off
	s_waitcnt vmcnt(8)
	s_waitcnt lgkmcnt(0)
	s_barrier
	s_waitcnt lgkmcnt(0)
	v_mfma_f32_16x16x32_bf16 v[124:127], v[140:143], v[180:183], v[124:127]
	v_mfma_f32_16x16x32_bf16 v[120:123], v[156:159], v[180:183], v[120:123]
	v_mfma_f32_16x16x32_bf16 v[108:111], v[140:143], v[188:191], v[108:111]
	v_mfma_f32_16x16x32_bf16 v[104:107], v[156:159], v[188:191], v[104:107]
	v_mfma_f32_16x16x32_bf16 v[92:95], v[140:143], v[196:199], v[92:95]
	v_mfma_f32_16x16x32_bf16 v[88:91], v[156:159], v[196:199], v[88:91]
	v_mfma_f32_16x16x32_bf16 v[76:79], v[140:143], v[204:207], v[76:79]
	v_mfma_f32_16x16x32_bf16 v[72:75], v[156:159], v[204:207], v[72:75]
	v_mfma_f32_16x16x32_bf16 v[124:127], v[152:155], v[184:187], v[124:127]
	v_mfma_f32_16x16x32_bf16 v[120:123], v[160:163], v[184:187], v[120:123]
	v_mfma_f32_16x16x32_bf16 v[108:111], v[152:155], v[192:195], v[108:111]
	v_mfma_f32_16x16x32_bf16 v[104:107], v[160:163], v[192:195], v[104:107]
	v_mfma_f32_16x16x32_bf16 v[92:95], v[152:155], v[200:203], v[92:95]
	v_mfma_f32_16x16x32_bf16 v[88:91], v[160:163], v[200:203], v[88:91]
	v_mfma_f32_16x16x32_bf16 v[76:79], v[152:155], v[208:211], v[76:79]
	v_mfma_f32_16x16x32_bf16 v[72:75], v[160:163], v[208:211], v[72:75]
	v_mfma_f32_16x16x32_bf16 v[116:119], v[164:167], v[180:183], v[116:119]
	v_mfma_f32_16x16x32_bf16 v[112:115], v[172:175], v[180:183], v[112:115]
	v_mfma_f32_16x16x32_bf16 v[100:103], v[164:167], v[188:191], v[100:103]
	v_mfma_f32_16x16x32_bf16 v[96:99], v[172:175], v[188:191], v[96:99]
	v_mfma_f32_16x16x32_bf16 v[84:87], v[164:167], v[196:199], v[84:87]
	v_mfma_f32_16x16x32_bf16 v[80:83], v[172:175], v[196:199], v[80:83]
	v_mfma_f32_16x16x32_bf16 v[68:71], v[164:167], v[204:207], v[68:71]
	v_mfma_f32_16x16x32_bf16 v[64:67], v[172:175], v[204:207], v[64:67]
	v_mfma_f32_16x16x32_bf16 v[116:119], v[168:171], v[184:187], v[116:119]
	v_mfma_f32_16x16x32_bf16 v[112:115], v[176:179], v[184:187], v[112:115]
	v_mfma_f32_16x16x32_bf16 v[100:103], v[168:171], v[192:195], v[100:103]
	v_mfma_f32_16x16x32_bf16 v[96:99], v[176:179], v[192:195], v[96:99]
	v_mfma_f32_16x16x32_bf16 v[84:87], v[168:171], v[200:203], v[84:87]
	v_mfma_f32_16x16x32_bf16 v[80:83], v[176:179], v[200:203], v[80:83]
	v_mfma_f32_16x16x32_bf16 v[68:71], v[168:171], v[208:211], v[68:71]
	v_mfma_f32_16x16x32_bf16 v[64:67], v[176:179], v[208:211], v[64:67]
	s_barrier
	s_add_i32 s57, s50, s40
	v_lshl_add_u64 v[212:213], s[30:31], 0, v[128:129]
	s_mov_b32 m0, s57
	ds_read_b128 v[180:183], v149 offset:16384
	ds_read_b128 v[184:187], v149 offset:17408
	ds_read_b128 v[188:191], v149 offset:18432
	ds_read_b128 v[192:195], v149 offset:19456
	ds_read_b128 v[196:199], v149 offset:20480
	ds_read_b128 v[200:203], v149 offset:21504
	ds_read_b128 v[204:207], v149 offset:22528
	ds_read_b128 v[208:211], v149 offset:23552
	global_load_lds_dwordx4 v[212:213], off
	s_add_i32 m0, s57, 0x2000
	s_add_u32 s58, s30, 0x40000
	v_lshl_add_u64 v[214:215], s[30:31], 0, v[130:131]
	s_addc_u32 s59, s31, 0
	s_add_i32 s57, s51, s40
	global_load_lds_dwordx4 v[214:215], off
	v_lshl_add_u64 v[216:217], s[58:59], 0, v[128:129]
	s_mov_b32 m0, s57
	v_lshl_add_u64 v[218:219], s[34:35], 0, v[130:131]
	global_load_lds_dwordx4 v[216:217], off
	v_lshl_add_u64 v[216:217], s[58:59], 0, v[130:131]
	s_add_i32 m0, s57, 0x2000
	s_nop 0
	global_load_lds_dwordx4 v[216:217], off
	v_lshl_add_u64 v[216:217], s[34:35], 0, v[128:129]
	s_mov_b32 m0, s41
	s_nop 0
	global_load_lds_dwordx4 v[216:217], off
	s_mov_b32 m0, s42
	s_nop 0
	global_load_lds_dwordx4 v[218:219], off
	s_waitcnt vmcnt(8)
	s_waitcnt lgkmcnt(0)
	s_barrier
	s_waitcnt lgkmcnt(0)
	v_mfma_f32_16x16x32_bf16 v[60:63], v[140:143], v[180:183], v[60:63]
	v_mfma_f32_16x16x32_bf16 v[56:59], v[156:159], v[180:183], v[56:59]
	v_mfma_f32_16x16x32_bf16 v[44:47], v[140:143], v[188:191], v[44:47]
	v_mfma_f32_16x16x32_bf16 v[40:43], v[156:159], v[188:191], v[40:43]
	v_mfma_f32_16x16x32_bf16 v[28:31], v[140:143], v[196:199], v[28:31]
	v_mfma_f32_16x16x32_bf16 v[24:27], v[156:159], v[196:199], v[24:27]
	v_mfma_f32_16x16x32_bf16 v[12:15], v[140:143], v[204:207], v[12:15]
	v_mfma_f32_16x16x32_bf16 v[8:11], v[156:159], v[204:207], v[8:11]
	v_mfma_f32_16x16x32_bf16 v[60:63], v[152:155], v[184:187], v[60:63]
	v_mfma_f32_16x16x32_bf16 v[56:59], v[160:163], v[184:187], v[56:59]
	v_mfma_f32_16x16x32_bf16 v[44:47], v[152:155], v[192:195], v[44:47]
	v_mfma_f32_16x16x32_bf16 v[40:43], v[160:163], v[192:195], v[40:43]
	v_mfma_f32_16x16x32_bf16 v[28:31], v[152:155], v[200:203], v[28:31]
	v_mfma_f32_16x16x32_bf16 v[24:27], v[160:163], v[200:203], v[24:27]
	v_mfma_f32_16x16x32_bf16 v[12:15], v[152:155], v[208:211], v[12:15]
	v_mfma_f32_16x16x32_bf16 v[8:11], v[160:163], v[208:211], v[8:11]
	v_mfma_f32_16x16x32_bf16 v[52:55], v[164:167], v[180:183], v[52:55]
	v_mfma_f32_16x16x32_bf16 v[48:51], v[172:175], v[180:183], v[48:51]
	v_mfma_f32_16x16x32_bf16 v[36:39], v[164:167], v[188:191], v[36:39]
	v_mfma_f32_16x16x32_bf16 v[32:35], v[172:175], v[188:191], v[32:35]
	v_mfma_f32_16x16x32_bf16 v[20:23], v[164:167], v[196:199], v[20:23]
	v_mfma_f32_16x16x32_bf16 v[16:19], v[172:175], v[196:199], v[16:19]
	v_mfma_f32_16x16x32_bf16 v[4:7], v[164:167], v[204:207], v[4:7]
	v_mfma_f32_16x16x32_bf16 v[0:3], v[172:175], v[204:207], v[0:3]
	v_mfma_f32_16x16x32_bf16 v[52:55], v[168:171], v[184:187], v[52:55]
	v_mfma_f32_16x16x32_bf16 v[48:51], v[176:179], v[184:187], v[48:51]
	v_mfma_f32_16x16x32_bf16 v[36:39], v[168:171], v[192:195], v[36:39]
	v_mfma_f32_16x16x32_bf16 v[32:35], v[176:179], v[192:195], v[32:35]
	v_mfma_f32_16x16x32_bf16 v[20:23], v[168:171], v[200:203], v[20:23]
	v_mfma_f32_16x16x32_bf16 v[16:19], v[176:179], v[200:203], v[16:19]
	v_mfma_f32_16x16x32_bf16 v[4:7], v[168:171], v[208:211], v[4:7]
	v_mfma_f32_16x16x32_bf16 v[0:3], v[176:179], v[208:211], v[0:3]
	s_barrier
	s_add_i32 s57, 0, 0x18000
	v_add_u32_e32 v151, s57, v145
	s_add_i32 s58, 0, 0x1c000
	ds_read_b128 v[140:143], v151
	ds_read_b128 v[152:155], v151 offset:1024
	ds_read_b128 v[156:159], v151 offset:2048
	ds_read_b128 v[160:163], v151 offset:3072
	v_add_u32_e32 v151, s58, v145
	ds_read_b128 v[164:167], v151
	ds_read_b128 v[168:171], v151 offset:1024
	ds_read_b128 v[172:175], v151 offset:2048
	ds_read_b128 v[176:179], v151 offset:3072
	s_add_u32 s34, s34, 0x40000
	s_addc_u32 s35, s35, 0
	s_mov_b32 m0, s43
	v_lshl_add_u64 v[220:221], s[34:35], 0, v[128:129]
	ds_read_b128 v[180:183], v149 offset:32768
	ds_read_b128 v[184:187], v149 offset:33792
	ds_read_b128 v[188:191], v149 offset:34816
	ds_read_b128 v[192:195], v149 offset:35840
	ds_read_b128 v[196:199], v149 offset:36864
	ds_read_b128 v[200:203], v149 offset:37888
	ds_read_b128 v[204:207], v149 offset:38912
	ds_read_b128 v[208:211], v149 offset:39936
	global_load_lds_dwordx4 v[220:221], off
	v_lshl_add_u64 v[220:221], s[34:35], 0, v[130:131]
	s_mov_b32 m0, s44
	s_nop 0
	global_load_lds_dwordx4 v[220:221], off
	s_waitcnt vmcnt(8)
	s_waitcnt lgkmcnt(0)
	s_barrier
	s_waitcnt lgkmcnt(0)
	v_mfma_f32_16x16x32_bf16 v[124:127], v[140:143], v[180:183], v[124:127]
	v_mfma_f32_16x16x32_bf16 v[120:123], v[156:159], v[180:183], v[120:123]
	v_mfma_f32_16x16x32_bf16 v[108:111], v[140:143], v[188:191], v[108:111]
	v_mfma_f32_16x16x32_bf16 v[104:107], v[156:159], v[188:191], v[104:107]
	v_mfma_f32_16x16x32_bf16 v[92:95], v[140:143], v[196:199], v[92:95]
	v_mfma_f32_16x16x32_bf16 v[88:91], v[156:159], v[196:199], v[88:91]
	v_mfma_f32_16x16x32_bf16 v[76:79], v[140:143], v[204:207], v[76:79]
	v_mfma_f32_16x16x32_bf16 v[72:75], v[156:159], v[204:207], v[72:75]
	v_mfma_f32_16x16x32_bf16 v[124:127], v[152:155], v[184:187], v[124:127]
	v_mfma_f32_16x16x32_bf16 v[120:123], v[160:163], v[184:187], v[120:123]
	v_mfma_f32_16x16x32_bf16 v[108:111], v[152:155], v[192:195], v[108:111]
	v_mfma_f32_16x16x32_bf16 v[104:107], v[160:163], v[192:195], v[104:107]
	v_mfma_f32_16x16x32_bf16 v[92:95], v[152:155], v[200:203], v[92:95]
	v_mfma_f32_16x16x32_bf16 v[88:91], v[160:163], v[200:203], v[88:91]
	v_mfma_f32_16x16x32_bf16 v[76:79], v[152:155], v[208:211], v[76:79]
	v_mfma_f32_16x16x32_bf16 v[72:75], v[160:163], v[208:211], v[72:75]
	v_mfma_f32_16x16x32_bf16 v[116:119], v[164:167], v[180:183], v[116:119]
	v_mfma_f32_16x16x32_bf16 v[112:115], v[172:175], v[180:183], v[112:115]
	v_mfma_f32_16x16x32_bf16 v[100:103], v[164:167], v[188:191], v[100:103]
	v_mfma_f32_16x16x32_bf16 v[96:99], v[172:175], v[188:191], v[96:99]
	v_mfma_f32_16x16x32_bf16 v[84:87], v[164:167], v[196:199], v[84:87]
	v_mfma_f32_16x16x32_bf16 v[80:83], v[172:175], v[196:199], v[80:83]
	v_mfma_f32_16x16x32_bf16 v[68:71], v[164:167], v[204:207], v[68:71]
	v_mfma_f32_16x16x32_bf16 v[64:67], v[172:175], v[204:207], v[64:67]
	v_mfma_f32_16x16x32_bf16 v[116:119], v[168:171], v[184:187], v[116:119]
	v_mfma_f32_16x16x32_bf16 v[112:115], v[176:179], v[184:187], v[112:115]
	v_mfma_f32_16x16x32_bf16 v[100:103], v[168:171], v[192:195], v[100:103]
	v_mfma_f32_16x16x32_bf16 v[96:99], v[176:179], v[192:195], v[96:99]
	v_mfma_f32_16x16x32_bf16 v[84:87], v[168:171], v[200:203], v[84:87]
	v_mfma_f32_16x16x32_bf16 v[80:83], v[176:179], v[200:203], v[80:83]
	v_mfma_f32_16x16x32_bf16 v[68:71], v[168:171], v[208:211], v[68:71]
	v_mfma_f32_16x16x32_bf16 v[64:67], v[176:179], v[208:211], v[64:67]
	s_barrier
	s_add_i32 s34, s57, s40
	v_lshl_add_u64 v[212:213], v[212:213], 0, s[14:15]
	s_mov_b32 m0, s34
	ds_read_b128 v[180:183], v149 offset:49152
	ds_read_b128 v[184:187], v149 offset:50176
	ds_read_b128 v[188:191], v149 offset:51200
	ds_read_b128 v[192:195], v149 offset:52224
	ds_read_b128 v[196:199], v149 offset:53248
	ds_read_b128 v[200:203], v149 offset:54272
	ds_read_b128 v[204:207], v149 offset:55296
	ds_read_b128 v[208:211], v149 offset:56320
	global_load_lds_dwordx4 v[212:213], off
	s_add_i32 m0, s34, 0x2000
	s_add_u32 s30, s30, 0x40080
	v_lshl_add_u64 v[212:213], v[214:215], 0, s[14:15]
	s_addc_u32 s31, s31, 0
	s_add_i32 s34, s58, s40
	global_load_lds_dwordx4 v[212:213], off
	v_lshl_add_u64 v[212:213], s[30:31], 0, v[128:129]
	s_mov_b32 m0, s34
	s_nop 0
	global_load_lds_dwordx4 v[212:213], off
	v_lshl_add_u64 v[212:213], s[30:31], 0, v[130:131]
	s_add_i32 m0, s34, 0x2000
	s_nop 0
	global_load_lds_dwordx4 v[212:213], off
	v_lshl_add_u64 v[212:213], v[216:217], 0, s[14:15]
	s_mov_b32 m0, s46
	s_nop 0
	global_load_lds_dwordx4 v[212:213], off
	v_lshl_add_u64 v[212:213], v[218:219], 0, s[14:15]
	s_mov_b32 m0, s47
	s_nop 0
	global_load_lds_dwordx4 v[212:213], off
	s_waitcnt vmcnt(8)
	s_waitcnt lgkmcnt(0)
	s_barrier
	s_waitcnt lgkmcnt(0)
	v_mfma_f32_16x16x32_bf16 v[60:63], v[140:143], v[180:183], v[60:63]
	v_mfma_f32_16x16x32_bf16 v[56:59], v[156:159], v[180:183], v[56:59]
	v_mfma_f32_16x16x32_bf16 v[44:47], v[140:143], v[188:191], v[44:47]
	v_mfma_f32_16x16x32_bf16 v[40:43], v[156:159], v[188:191], v[40:43]
	v_mfma_f32_16x16x32_bf16 v[28:31], v[140:143], v[196:199], v[28:31]
	v_mfma_f32_16x16x32_bf16 v[24:27], v[156:159], v[196:199], v[24:27]
	v_mfma_f32_16x16x32_bf16 v[12:15], v[140:143], v[204:207], v[12:15]
	v_mfma_f32_16x16x32_bf16 v[8:11], v[156:159], v[204:207], v[8:11]
	v_mfma_f32_16x16x32_bf16 v[60:63], v[152:155], v[184:187], v[60:63]
	v_mfma_f32_16x16x32_bf16 v[56:59], v[160:163], v[184:187], v[56:59]
	v_mfma_f32_16x16x32_bf16 v[44:47], v[152:155], v[192:195], v[44:47]
	v_mfma_f32_16x16x32_bf16 v[40:43], v[160:163], v[192:195], v[40:43]
	v_mfma_f32_16x16x32_bf16 v[28:31], v[152:155], v[200:203], v[28:31]
	v_mfma_f32_16x16x32_bf16 v[24:27], v[160:163], v[200:203], v[24:27]
	v_mfma_f32_16x16x32_bf16 v[12:15], v[152:155], v[208:211], v[12:15]
	v_mfma_f32_16x16x32_bf16 v[8:11], v[160:163], v[208:211], v[8:11]
	v_mfma_f32_16x16x32_bf16 v[52:55], v[164:167], v[180:183], v[52:55]
	v_mfma_f32_16x16x32_bf16 v[48:51], v[172:175], v[180:183], v[48:51]
	v_mfma_f32_16x16x32_bf16 v[36:39], v[164:167], v[188:191], v[36:39]
	v_mfma_f32_16x16x32_bf16 v[32:35], v[172:175], v[188:191], v[32:35]
	v_mfma_f32_16x16x32_bf16 v[20:23], v[164:167], v[196:199], v[20:23]
	v_mfma_f32_16x16x32_bf16 v[16:19], v[172:175], v[196:199], v[16:19]
	v_mfma_f32_16x16x32_bf16 v[4:7], v[164:167], v[204:207], v[4:7]
	v_mfma_f32_16x16x32_bf16 v[0:3], v[172:175], v[204:207], v[0:3]
	v_mfma_f32_16x16x32_bf16 v[52:55], v[168:171], v[184:187], v[52:55]
	v_mfma_f32_16x16x32_bf16 v[48:51], v[176:179], v[184:187], v[48:51]
	v_mfma_f32_16x16x32_bf16 v[36:39], v[168:171], v[192:195], v[36:39]
	v_mfma_f32_16x16x32_bf16 v[32:35], v[176:179], v[192:195], v[32:35]
	v_mfma_f32_16x16x32_bf16 v[20:23], v[168:171], v[200:203], v[20:23]
	v_mfma_f32_16x16x32_bf16 v[16:19], v[176:179], v[200:203], v[16:19]
	v_mfma_f32_16x16x32_bf16 v[4:7], v[168:171], v[208:211], v[4:7]
	v_mfma_f32_16x16x32_bf16 v[0:3], v[176:179], v[208:211], v[0:3]
	s_barrier
	s_add_i32 s56, s56, 2
	s_add_u32 s28, s28, 0x100
	s_addc_u32 s29, s29, 0
	s_add_u32 s54, s54, 0x100
	s_addc_u32 s55, s55, 0
	s_cmp_gt_u32 s56, 13
	s_cbranch_scc0 .LBB0_911
	s_and_b64 vcc, exec, s[16:17]
	s_cbranch_vccz .LBB0_914
	s_barrier

.LBB0_933:
	s_waitcnt vmcnt(0)
	s_barrier
	s_setprio 0
	s_load_dwordx2 s[2:3], s[0:1], 0x120
	s_waitcnt lgkmcnt(0)
	v_mov_b32_e32 v0, s2
	v_mov_b32_e32 v1, s3

.LBB0_968:
	s_andn2_b64 vcc, exec, s[2:3]
	s_cbranch_vccnz .LBB0_1010
	v_ashrrev_i32_e32 v1, 31, v2
	v_lshrrev_b32_e32 v1, 26, v1
	v_add_u32_e32 v1, v2, v1
	v_ashrrev_i32_e32 v9, 6, v1
	v_bfe_i32 v1, v2, 27, 1
	v_lshlrev_b32_e32 v0, 4, v2
	v_lshrrev_b32_e32 v1, 22, v1
	v_add_u32_e32 v1, v0, v1
	v_and_b32_e32 v1, 0xfffffc00, v1
	v_sub_u32_e32 v1, v0, v1
	v_lshrrev_b32_e32 v2, 4, v1
	v_bitop3_b32 v1, v2, v1, 32 bitop3:0x6c
	v_ashrrev_i32_e32 v3, 31, v1
	v_lshrrev_b32_e32 v3, 26, v3
	v_add_u32_e32 v3, v1, v3
	v_lshlrev_b32_e32 v2, 3, v9
	v_ashrrev_i32_e32 v10, 6, v3
	v_and_b32_e32 v3, 0xc0, v3
	v_and_b32_e32 v2, -16, v2
	v_sub_u32_e32 v1, v1, v3
	v_mov_b32_e32 v3, 1
	v_add_u32_e32 v2, v10, v2
	v_ashrrev_i16_sdwa v1, v3, sext(v1) dst_sel:DWORD dst_unused:UNUSED_PAD src0_sel:DWORD src1_sel:BYTE_0
	v_lshlrev_b32_e32 v4, 5, v9
	v_bfe_i32 v11, v1, 0, 16
	v_lshlrev_b32_e32 v1, 1, v2
	v_lshrrev_b32_e32 v5, 2, v2
	v_and_b32_e32 v6, 3, v10
	s_mov_b32 s3, 0x1fffe0
	v_and_b32_e32 v4, 32, v4
	v_and_b32_e32 v1, 24, v1
	v_and_b32_e32 v5, 4, v5
	v_and_or_b32 v6, v2, s3, v6
	v_or3_b32 v1, v6, v5, v1
	v_add_lshl_u32 v4, v4, v11, 1
	v_add_u32_e32 v0, 0x2000, v0
	v_lshl_add_u32 v130, v1, 11, v4
	v_ashrrev_i32_e32 v1, 31, v0
	v_lshrrev_b32_e32 v1, 22, v1
	v_add_u32_e32 v1, v0, v1
	v_ashrrev_i32_e32 v12, 10, v1
	v_mul_i32_i24_e32 v1, 0x400, v12
	v_sub_u32_e32 v0, v0, v1
	v_lshrrev_b32_e32 v1, 4, v0
	v_bitop3_b32 v0, v1, v0, 32 bitop3:0x6c
	v_lshl_add_u32 v128, v2, 11, v4
	v_ashrrev_i32_e32 v2, 31, v0
	v_lshrrev_b32_e32 v2, 26, v2
	v_add_u32_e32 v2, v0, v2
	v_lshlrev_b32_e32 v1, 3, v12
	v_ashrrev_i32_e32 v13, 6, v2
	v_and_b32_e32 v2, 0xc0, v2
	s_add_u32 s38, s70, 0x1000000
	v_and_b32_e32 v1, -16, v1
	v_sub_u32_e32 v0, v0, v2
	s_addc_u32 s39, s71, 0
	s_ashr_i32 s2, s4, 6
	v_add_u32_e32 v1, v13, v1
	v_ashrrev_i16_sdwa v0, v3, sext(v0) dst_sel:DWORD dst_unused:UNUSED_PAD src0_sel:DWORD src1_sel:BYTE_0
	v_and_b32_e32 v3, 3, v13
	s_ashr_i32 s29, s28, 31
	s_ashr_i32 s27, s26, 31
	v_and_or_b32 v3, v1, s3, v3
	s_ashr_i32 s3, s4, 8
	s_lshl_b32 s40, s2, 10
	s_waitcnt lgkmcnt(0)
	s_lshl_b64 s[8:9], s[28:29], 19
	s_lshl_b64 s[10:11], s[26:27], 19
	s_add_u32 s34, s38, s10
	v_lshlrev_b32_e32 v4, 5, v12
	v_bfe_i32 v14, v0, 0, 16
	v_lshlrev_b32_e32 v0, 1, v1
	v_lshrrev_b32_e32 v2, 2, v1
	s_addc_u32 s35, s39, s11
	s_add_i32 s41, s40, 0
	v_and_b32_e32 v4, 32, v4
	v_and_b32_e32 v0, 24, v0
	v_and_b32_e32 v2, 4, v2
	s_add_i32 m0, s41, 0x10000
	v_or3_b32 v0, v3, v2, v0
	v_add_lshl_u32 v2, v4, v14, 1
	global_load_lds_dwordx4 v130, s[34:35]
	s_add_i32 m0, s41, 0x12000
	v_lshl_add_u32 v134, v0, 11, v2
	s_add_u32 s10, s34, 0x40000
	global_load_lds_dwordx4 v134, s[34:35]
	s_addc_u32 s11, s35, 0
	s_add_i32 m0, s41, 0x14000
	v_lshl_add_u32 v132, v1, 11, v2
	global_load_lds_dwordx4 v130, s[10:11]
	s_add_i32 m0, s41, 0x16000
	s_add_u32 s30, s76, s8
	s_addc_u32 s31, s77, s9
	s_add_i32 s42, s41, 0x2000
	global_load_lds_dwordx4 v134, s[10:11]
	s_mov_b32 m0, s41
	s_add_u32 s8, s30, 0x40000
	global_load_lds_dwordx4 v128, s[30:31]
	s_mov_b32 m0, s42
	s_addc_u32 s9, s31, 0
	s_add_i32 s43, s41, 0x4000
	global_load_lds_dwordx4 v132, s[30:31]
	s_mov_b32 m0, s43
	s_add_i32 s44, s41, 0x6000
	global_load_lds_dwordx4 v128, s[8:9]
	s_mov_b32 m0, s44
	v_mov_b32_e32 v137, 0
	global_load_lds_dwordx4 v132, s[8:9]
	v_mov_b32_e32 v131, v137
	v_mov_b32_e32 v135, v137
	v_mov_b32_e32 v129, v137
	v_mov_b32_e32 v133, v137
	s_cmp_eq_u32 s3, 1
	s_mov_b32 s9, 0
	v_lshl_add_u64 v[6:7], s[34:35], 0, v[130:131]
	v_lshl_add_u64 v[4:5], s[34:35], 0, v[134:135]
	v_lshl_add_u64 v[0:1], s[30:31], 0, v[128:129]
	s_cselect_b64 s[10:11], -1, 0
	s_cmp_lg_u32 s3, 1
	v_lshl_add_u64 v[2:3], s[30:31], 0, v[132:133]
	s_cbranch_scc1 .LBB0_971
	s_barrier
	s_setprio 1

.LBB0_977:
	ds_read_b128 v[152:155], v143
	ds_read_b128 v[162:165], v143 offset:1024
	ds_read_b128 v[166:169], v143 offset:2048
	ds_read_b128 v[170:173], v143 offset:3072
	ds_read_b128 v[174:177], v158
	ds_read_b128 v[178:181], v158 offset:1024
	ds_read_b128 v[182:185], v158 offset:2048
	ds_read_b128 v[186:189], v158 offset:3072
	s_add_u32 s34, s30, 0xfffc0080
	s_addc_u32 s35, s31, -1
	s_cmp_eq_u32 s57, 12
	s_cselect_b32 s37, s21, s35
	s_cselect_b32 s36, s27, s34
	s_cselect_b32 s35, s19, s56
	s_cselect_b32 s34, s29, s55
	s_waitcnt lgkmcnt(0)
	v_lshl_add_u64 v[156:157], s[30:31], 0, v[144:145]
	s_add_i32 m0, s41, 0xc000
	ds_read_b128 v[190:193], v159
	ds_read_b128 v[194:197], v159 offset:1024
	ds_read_b128 v[198:201], v159 offset:2048
	ds_read_b128 v[202:205], v159 offset:3072
	ds_read_b128 v[206:209], v159 offset:4096
	ds_read_b128 v[210:213], v159 offset:5120
	ds_read_b128 v[214:217], v159 offset:6144
	ds_read_b128 v[218:221], v159 offset:7168
	global_load_lds_dwordx4 v[156:157], off
	v_lshl_add_u64 v[156:157], s[30:31], 0, v[146:147]
	s_add_i32 m0, s41, 0xe000
	s_nop 0
	global_load_lds_dwordx4 v[156:157], off
	s_waitcnt vmcnt(8)
	s_waitcnt lgkmcnt(0)
	s_barrier
	s_waitcnt lgkmcnt(0)
	v_mfma_f32_16x16x32_bf16 v[116:119], v[152:155], v[190:193], v[116:119]
	v_mfma_f32_16x16x32_bf16 v[112:115], v[166:169], v[190:193], v[112:115]
	v_mfma_f32_16x16x32_bf16 v[100:103], v[152:155], v[198:201], v[100:103]
	v_mfma_f32_16x16x32_bf16 v[96:99], v[166:169], v[198:201], v[96:99]
	v_mfma_f32_16x16x32_bf16 v[88:91], v[152:155], v[206:209], v[88:91]
	v_mfma_f32_16x16x32_bf16 v[84:87], v[166:169], v[206:209], v[84:87]
	v_mfma_f32_16x16x32_bf16 v[72:75], v[152:155], v[214:217], v[72:75]
	v_mfma_f32_16x16x32_bf16 v[68:71], v[166:169], v[214:217], v[68:71]
	v_mfma_f32_16x16x32_bf16 v[116:119], v[162:165], v[194:197], v[116:119]
	v_mfma_f32_16x16x32_bf16 v[112:115], v[170:173], v[194:197], v[112:115]
	v_mfma_f32_16x16x32_bf16 v[100:103], v[162:165], v[202:205], v[100:103]
	v_mfma_f32_16x16x32_bf16 v[96:99], v[170:173], v[202:205], v[96:99]
	v_mfma_f32_16x16x32_bf16 v[88:91], v[162:165], v[210:213], v[88:91]
	v_mfma_f32_16x16x32_bf16 v[84:87], v[170:173], v[210:213], v[84:87]
	v_mfma_f32_16x16x32_bf16 v[72:75], v[162:165], v[218:221], v[72:75]
	v_mfma_f32_16x16x32_bf16 v[68:71], v[170:173], v[218:221], v[68:71]
	v_mfma_f32_16x16x32_bf16 v[124:127], v[174:177], v[190:193], v[124:127]
	v_mfma_f32_16x16x32_bf16 v[120:123], v[182:185], v[190:193], v[120:123]
	v_mfma_f32_16x16x32_bf16 v[108:111], v[174:177], v[198:201], v[108:111]
	v_mfma_f32_16x16x32_bf16 v[104:107], v[182:185], v[198:201], v[104:107]
	v_mfma_f32_16x16x32_bf16 v[92:95], v[174:177], v[206:209], v[92:95]
	v_mfma_f32_16x16x32_bf16 v[80:83], v[182:185], v[206:209], v[80:83]
	v_mfma_f32_16x16x32_bf16 v[76:79], v[174:177], v[214:217], v[76:79]
	v_mfma_f32_16x16x32_bf16 v[64:67], v[182:185], v[214:217], v[64:67]
	v_mfma_f32_16x16x32_bf16 v[124:127], v[178:181], v[194:197], v[124:127]
	v_mfma_f32_16x16x32_bf16 v[120:123], v[186:189], v[194:197], v[120:123]
	v_mfma_f32_16x16x32_bf16 v[108:111], v[178:181], v[202:205], v[108:111]
	v_mfma_f32_16x16x32_bf16 v[104:107], v[186:189], v[202:205], v[104:107]
	v_mfma_f32_16x16x32_bf16 v[92:95], v[178:181], v[210:213], v[92:95]
	v_mfma_f32_16x16x32_bf16 v[80:83], v[186:189], v[210:213], v[80:83]
	v_mfma_f32_16x16x32_bf16 v[76:79], v[178:181], v[218:221], v[76:79]
	v_mfma_f32_16x16x32_bf16 v[64:67], v[186:189], v[218:221], v[64:67]
	s_barrier
	s_add_i32 s58, s51, s40
	v_lshl_add_u64 v[156:157], s[34:35], 0, v[130:131]
	s_mov_b32 m0, s58
	ds_read_b128 v[190:193], v159 offset:16384
	ds_read_b128 v[194:197], v159 offset:17408
	ds_read_b128 v[198:201], v159 offset:18432
	ds_read_b128 v[202:205], v159 offset:19456
	ds_read_b128 v[206:209], v159 offset:20480
	ds_read_b128 v[210:213], v159 offset:21504
	ds_read_b128 v[214:217], v159 offset:22528
	ds_read_b128 v[218:221], v159 offset:23552
	global_load_lds_dwordx4 v[156:157], off
	s_add_i32 m0, s58, 0x2000
	s_add_u32 s58, s34, 0x40000
	v_lshl_add_u64 v[222:223], s[34:35], 0, v[134:135]
	s_addc_u32 s59, s35, 0
	s_add_i32 s60, s52, s40
	global_load_lds_dwordx4 v[222:223], off
	v_lshl_add_u64 v[224:225], s[58:59], 0, v[130:131]
	s_mov_b32 m0, s60
	v_lshl_add_u64 v[226:227], s[36:37], 0, v[132:133]
	global_load_lds_dwordx4 v[224:225], off
	v_lshl_add_u64 v[224:225], s[58:59], 0, v[134:135]
	s_add_i32 m0, s60, 0x2000
	s_nop 0
	global_load_lds_dwordx4 v[224:225], off
	v_lshl_add_u64 v[224:225], s[36:37], 0, v[128:129]
	s_mov_b32 m0, s41
	s_nop 0
	global_load_lds_dwordx4 v[224:225], off
	s_mov_b32 m0, s42
	s_nop 0
	global_load_lds_dwordx4 v[226:227], off
	s_waitcnt vmcnt(8)
	s_waitcnt lgkmcnt(0)
	s_barrier
	s_waitcnt lgkmcnt(0)
	v_mfma_f32_16x16x32_bf16 v[56:59], v[152:155], v[190:193], v[56:59]
	v_mfma_f32_16x16x32_bf16 v[52:55], v[166:169], v[190:193], v[52:55]
	v_mfma_f32_16x16x32_bf16 v[40:43], v[152:155], v[198:201], v[40:43]
	v_mfma_f32_16x16x32_bf16 v[36:39], v[166:169], v[198:201], v[36:39]
	v_mfma_f32_16x16x32_bf16 v[24:27], v[152:155], v[206:209], v[24:27]
	v_mfma_f32_16x16x32_bf16 v[20:23], v[166:169], v[206:209], v[20:23]
	v_mfma_f32_16x16x32_bf16 v[8:11], v[152:155], v[214:217], v[8:11]
	v_mfma_f32_16x16x32_bf16 v[4:7], v[166:169], v[214:217], v[4:7]
	v_mfma_f32_16x16x32_bf16 v[56:59], v[162:165], v[194:197], v[56:59]
	v_mfma_f32_16x16x32_bf16 v[52:55], v[170:173], v[194:197], v[52:55]
	v_mfma_f32_16x16x32_bf16 v[40:43], v[162:165], v[202:205], v[40:43]
	v_mfma_f32_16x16x32_bf16 v[36:39], v[170:173], v[202:205], v[36:39]
	v_mfma_f32_16x16x32_bf16 v[24:27], v[162:165], v[210:213], v[24:27]
	v_mfma_f32_16x16x32_bf16 v[20:23], v[170:173], v[210:213], v[20:23]
	v_mfma_f32_16x16x32_bf16 v[8:11], v[162:165], v[218:221], v[8:11]
	v_mfma_f32_16x16x32_bf16 v[4:7], v[170:173], v[218:221], v[4:7]
	v_mfma_f32_16x16x32_bf16 v[60:63], v[174:177], v[190:193], v[60:63]
	v_mfma_f32_16x16x32_bf16 v[48:51], v[182:185], v[190:193], v[48:51]
	v_mfma_f32_16x16x32_bf16 v[44:47], v[174:177], v[198:201], v[44:47]
	v_mfma_f32_16x16x32_bf16 v[32:35], v[182:185], v[198:201], v[32:35]
	v_mfma_f32_16x16x32_bf16 v[28:31], v[174:177], v[206:209], v[28:31]
	v_mfma_f32_16x16x32_bf16 v[16:19], v[182:185], v[206:209], v[16:19]
	v_mfma_f32_16x16x32_bf16 v[12:15], v[174:177], v[214:217], v[12:15]
	v_mfma_f32_16x16x32_bf16 v[0:3], v[182:185], v[214:217], v[0:3]
	v_mfma_f32_16x16x32_bf16 v[60:63], v[178:181], v[194:197], v[60:63]
	v_mfma_f32_16x16x32_bf16 v[48:51], v[186:189], v[194:197], v[48:51]
	v_mfma_f32_16x16x32_bf16 v[44:47], v[178:181], v[202:205], v[44:47]
	v_mfma_f32_16x16x32_bf16 v[32:35], v[186:189], v[202:205], v[32:35]
	v_mfma_f32_16x16x32_bf16 v[28:31], v[178:181], v[210:213], v[28:31]
	v_mfma_f32_16x16x32_bf16 v[16:19], v[186:189], v[210:213], v[16:19]
	v_mfma_f32_16x16x32_bf16 v[12:15], v[178:181], v[218:221], v[12:15]
	v_mfma_f32_16x16x32_bf16 v[0:3], v[186:189], v[218:221], v[0:3]
	s_barrier
	s_add_i32 s58, 0, 0x18000
	s_add_i32 s59, 0, 0x1c000
	v_add_u32_e32 v170, s58, v141
	v_add_u32_e32 v186, s59, v141
	ds_read_b128 v[152:155], v170
	ds_read_b128 v[162:165], v170 offset:1024
	ds_read_b128 v[166:169], v170 offset:2048
	ds_read_b128 v[170:173], v170 offset:3072
	ds_read_b128 v[174:177], v186
	ds_read_b128 v[178:181], v186 offset:1024
	ds_read_b128 v[182:185], v186 offset:2048
	ds_read_b128 v[186:189], v186 offset:3072
	s_add_u32 s36, s36, 0x40000
	s_addc_u32 s37, s37, 0
	s_mov_b32 m0, s43
	v_lshl_add_u64 v[228:229], s[36:37], 0, v[128:129]
	ds_read_b128 v[190:193], v159 offset:32768
	ds_read_b128 v[194:197], v159 offset:33792
	ds_read_b128 v[198:201], v159 offset:34816
	ds_read_b128 v[202:205], v159 offset:35840
	ds_read_b128 v[206:209], v159 offset:36864
	ds_read_b128 v[210:213], v159 offset:37888
	ds_read_b128 v[214:217], v159 offset:38912
	ds_read_b128 v[218:221], v159 offset:39936
	global_load_lds_dwordx4 v[228:229], off
	v_lshl_add_u64 v[228:229], s[36:37], 0, v[132:133]
	s_mov_b32 m0, s44
	s_nop 0
	global_load_lds_dwordx4 v[228:229], off
	s_waitcnt vmcnt(8)
	s_waitcnt lgkmcnt(0)
	s_barrier
	s_waitcnt lgkmcnt(0)
	v_mfma_f32_16x16x32_bf16 v[116:119], v[152:155], v[190:193], v[116:119]
	v_mfma_f32_16x16x32_bf16 v[112:115], v[166:169], v[190:193], v[112:115]
	v_mfma_f32_16x16x32_bf16 v[100:103], v[152:155], v[198:201], v[100:103]
	v_mfma_f32_16x16x32_bf16 v[96:99], v[166:169], v[198:201], v[96:99]
	v_mfma_f32_16x16x32_bf16 v[88:91], v[152:155], v[206:209], v[88:91]
	v_mfma_f32_16x16x32_bf16 v[84:87], v[166:169], v[206:209], v[84:87]
	v_mfma_f32_16x16x32_bf16 v[72:75], v[152:155], v[214:217], v[72:75]
	v_mfma_f32_16x16x32_bf16 v[68:71], v[166:169], v[214:217], v[68:71]
	v_mfma_f32_16x16x32_bf16 v[116:119], v[162:165], v[194:197], v[116:119]
	v_mfma_f32_16x16x32_bf16 v[112:115], v[170:173], v[194:197], v[112:115]
	v_mfma_f32_16x16x32_bf16 v[100:103], v[162:165], v[202:205], v[100:103]
	v_mfma_f32_16x16x32_bf16 v[96:99], v[170:173], v[202:205], v[96:99]
	v_mfma_f32_16x16x32_bf16 v[88:91], v[162:165], v[210:213], v[88:91]
	v_mfma_f32_16x16x32_bf16 v[84:87], v[170:173], v[210:213], v[84:87]
	v_mfma_f32_16x16x32_bf16 v[72:75], v[162:165], v[218:221], v[72:75]
	v_mfma_f32_16x16x32_bf16 v[68:71], v[170:173], v[218:221], v[68:71]
	v_mfma_f32_16x16x32_bf16 v[124:127], v[174:177], v[190:193], v[124:127]
	v_mfma_f32_16x16x32_bf16 v[120:123], v[182:185], v[190:193], v[120:123]
	v_mfma_f32_16x16x32_bf16 v[108:111], v[174:177], v[198:201], v[108:111]
	v_mfma_f32_16x16x32_bf16 v[104:107], v[182:185], v[198:201], v[104:107]
	v_mfma_f32_16x16x32_bf16 v[92:95], v[174:177], v[206:209], v[92:95]
	v_mfma_f32_16x16x32_bf16 v[80:83], v[182:185], v[206:209], v[80:83]
	v_mfma_f32_16x16x32_bf16 v[76:79], v[174:177], v[214:217], v[76:79]
	v_mfma_f32_16x16x32_bf16 v[64:67], v[182:185], v[214:217], v[64:67]
	v_mfma_f32_16x16x32_bf16 v[124:127], v[178:181], v[194:197], v[124:127]
	v_mfma_f32_16x16x32_bf16 v[120:123], v[186:189], v[194:197], v[120:123]
	v_mfma_f32_16x16x32_bf16 v[108:111], v[178:181], v[202:205], v[108:111]
	v_mfma_f32_16x16x32_bf16 v[104:107], v[186:189], v[202:205], v[104:107]
	v_mfma_f32_16x16x32_bf16 v[92:95], v[178:181], v[210:213], v[92:95]
	v_mfma_f32_16x16x32_bf16 v[80:83], v[186:189], v[210:213], v[80:83]
	v_mfma_f32_16x16x32_bf16 v[76:79], v[178:181], v[218:221], v[76:79]
	v_mfma_f32_16x16x32_bf16 v[64:67], v[186:189], v[218:221], v[64:67]
	s_barrier
	s_add_i32 s36, s58, s40
	v_lshl_add_u64 v[156:157], v[156:157], 0, s[12:13]
	s_mov_b32 m0, s36
	ds_read_b128 v[190:193], v159 offset:49152
	ds_read_b128 v[194:197], v159 offset:50176
	ds_read_b128 v[198:201], v159 offset:51200
	ds_read_b128 v[202:205], v159 offset:52224
	ds_read_b128 v[206:209], v159 offset:53248
	ds_read_b128 v[210:213], v159 offset:54272
	ds_read_b128 v[214:217], v159 offset:55296
	ds_read_b128 v[218:221], v159 offset:56320
	global_load_lds_dwordx4 v[156:157], off
	s_add_i32 m0, s36, 0x2000
	s_add_u32 s34, s34, 0x40080
	v_lshl_add_u64 v[156:157], v[222:223], 0, s[12:13]
	s_addc_u32 s35, s35, 0
	s_add_i32 s36, s59, s40
	global_load_lds_dwordx4 v[156:157], off
	v_lshl_add_u64 v[156:157], s[34:35], 0, v[130:131]
	s_mov_b32 m0, s36
	s_nop 0
	global_load_lds_dwordx4 v[156:157], off
	v_lshl_add_u64 v[156:157], s[34:35], 0, v[134:135]
	s_add_i32 m0, s36, 0x2000
	s_nop 0
	global_load_lds_dwordx4 v[156:157], off
	v_lshl_add_u64 v[156:157], v[224:225], 0, s[12:13]
	s_mov_b32 m0, s45
	s_nop 0
	global_load_lds_dwordx4 v[156:157], off
	v_lshl_add_u64 v[156:157], v[226:227], 0, s[12:13]
	s_mov_b32 m0, s46
	s_nop 0
	global_load_lds_dwordx4 v[156:157], off
	s_waitcnt vmcnt(8)
	s_waitcnt lgkmcnt(0)
	s_barrier
	s_waitcnt lgkmcnt(0)
	v_mfma_f32_16x16x32_bf16 v[56:59], v[152:155], v[190:193], v[56:59]
	v_mfma_f32_16x16x32_bf16 v[52:55], v[166:169], v[190:193], v[52:55]
	v_mfma_f32_16x16x32_bf16 v[40:43], v[152:155], v[198:201], v[40:43]
	v_mfma_f32_16x16x32_bf16 v[36:39], v[166:169], v[198:201], v[36:39]
	v_mfma_f32_16x16x32_bf16 v[24:27], v[152:155], v[206:209], v[24:27]
	v_mfma_f32_16x16x32_bf16 v[20:23], v[166:169], v[206:209], v[20:23]
	v_mfma_f32_16x16x32_bf16 v[8:11], v[152:155], v[214:217], v[8:11]
	v_mfma_f32_16x16x32_bf16 v[4:7], v[166:169], v[214:217], v[4:7]
	v_mfma_f32_16x16x32_bf16 v[56:59], v[162:165], v[194:197], v[56:59]
	v_mfma_f32_16x16x32_bf16 v[52:55], v[170:173], v[194:197], v[52:55]
	v_mfma_f32_16x16x32_bf16 v[40:43], v[162:165], v[202:205], v[40:43]
	v_mfma_f32_16x16x32_bf16 v[36:39], v[170:173], v[202:205], v[36:39]
	v_mfma_f32_16x16x32_bf16 v[24:27], v[162:165], v[210:213], v[24:27]
	v_mfma_f32_16x16x32_bf16 v[20:23], v[170:173], v[210:213], v[20:23]
	v_mfma_f32_16x16x32_bf16 v[8:11], v[162:165], v[218:221], v[8:11]
	v_mfma_f32_16x16x32_bf16 v[4:7], v[170:173], v[218:221], v[4:7]
	v_mfma_f32_16x16x32_bf16 v[60:63], v[174:177], v[190:193], v[60:63]
	v_mfma_f32_16x16x32_bf16 v[48:51], v[182:185], v[190:193], v[48:51]
	v_mfma_f32_16x16x32_bf16 v[44:47], v[174:177], v[198:201], v[44:47]
	v_mfma_f32_16x16x32_bf16 v[32:35], v[182:185], v[198:201], v[32:35]
	v_mfma_f32_16x16x32_bf16 v[28:31], v[174:177], v[206:209], v[28:31]
	v_mfma_f32_16x16x32_bf16 v[16:19], v[182:185], v[206:209], v[16:19]
	v_mfma_f32_16x16x32_bf16 v[12:15], v[174:177], v[214:217], v[12:15]
	v_mfma_f32_16x16x32_bf16 v[0:3], v[182:185], v[214:217], v[0:3]
	v_mfma_f32_16x16x32_bf16 v[60:63], v[178:181], v[194:197], v[60:63]
	v_mfma_f32_16x16x32_bf16 v[48:51], v[186:189], v[194:197], v[48:51]
	v_mfma_f32_16x16x32_bf16 v[44:47], v[178:181], v[202:205], v[44:47]
	v_mfma_f32_16x16x32_bf16 v[32:35], v[186:189], v[202:205], v[32:35]
	v_mfma_f32_16x16x32_bf16 v[28:31], v[178:181], v[210:213], v[28:31]
	v_mfma_f32_16x16x32_bf16 v[16:19], v[186:189], v[210:213], v[16:19]
	v_mfma_f32_16x16x32_bf16 v[12:15], v[178:181], v[218:221], v[12:15]
	v_mfma_f32_16x16x32_bf16 v[0:3], v[186:189], v[218:221], v[0:3]
	s_barrier
	s_add_i32 s57, s57, 2
	s_add_u32 s30, s30, 0x100
	s_addc_u32 s31, s31, 0
	s_add_u32 s55, s55, 0x100
	s_addc_u32 s56, s56, 0
	s_cmp_gt_u32 s57, 13
	s_cbranch_scc0 .LBB0_977
	s_and_b64 vcc, exec, s[14:15]
	s_cbranch_vccz .LBB0_982
	s_barrier
	v_lshl_add_u32 v152, s28, 8, v139
	s_cmp_gt_i32 s26, 21
	s_mov_b64 s[28:29], -1
	s_cbranch_scc1 .LBB0_983

.LBB0_1048:
	s_andn2_b64 vcc, exec, s[2:3]
	s_cbranch_vccnz .LBB0_1088
	v_ashrrev_i32_e32 v1, 31, v2
	v_lshrrev_b32_e32 v1, 26, v1
	v_add_u32_e32 v1, v2, v1
	v_ashrrev_i32_e32 v9, 6, v1
	v_bfe_i32 v1, v2, 27, 1
	v_lshlrev_b32_e32 v0, 4, v2
	v_lshrrev_b32_e32 v1, 22, v1
	v_add_u32_e32 v1, v0, v1
	v_and_b32_e32 v1, 0xfffffc00, v1
	v_sub_u32_e32 v1, v0, v1
	v_lshrrev_b32_e32 v2, 4, v1
	v_bitop3_b32 v1, v2, v1, 32 bitop3:0x6c
	v_ashrrev_i32_e32 v3, 31, v1
	v_lshrrev_b32_e32 v3, 26, v3
	v_add_u32_e32 v3, v1, v3
	v_lshlrev_b32_e32 v2, 3, v9
	v_ashrrev_i32_e32 v11, 6, v3
	v_and_b32_e32 v3, 0xc0, v3
	v_and_b32_e32 v2, 0xfffff0, v2
	v_sub_u32_e32 v1, v1, v3
	v_mov_b32_e32 v3, 1
	v_add_u32_e32 v2, v11, v2
	v_lshlrev_b32_e32 v4, 5, v9
	v_ashrrev_i16_sdwa v1, v3, sext(v1) dst_sel:DWORD dst_unused:UNUSED_PAD src0_sel:DWORD src1_sel:BYTE_0
	s_movk_i32 s4, 0xb00
	v_and_b32_e32 v10, 32, v4
	v_bfe_i32 v12, v1, 0, 16
	v_mul_lo_u32 v1, v2, s4
	v_or_b32_e32 v1, v1, v10
	v_add_u32_e32 v0, 0x2000, v0
	v_add_lshl_u32 v128, v1, v12, 1
	v_ashrrev_i32_e32 v1, 31, v0
	v_lshrrev_b32_e32 v1, 22, v1
	v_add_u32_e32 v1, v0, v1
	v_ashrrev_i32_e32 v13, 10, v1
	v_mul_i32_i24_e32 v1, 0x400, v13
	v_sub_u32_e32 v0, v0, v1
	v_lshrrev_b32_e32 v1, 4, v0
	v_bitop3_b32 v0, v1, v0, 32 bitop3:0x6c
	v_ashrrev_i32_e32 v2, 31, v0
	s_add_u32 s30, s70, 0x3980000
	v_lshrrev_b32_e32 v2, 26, v2
	s_addc_u32 s31, s71, 0
	s_ashr_i32 s2, s6, 6
	v_add_u32_e32 v2, v0, v2
	v_lshlrev_b32_e32 v1, 3, v13
	v_ashrrev_i32_e32 v14, 6, v2
	v_and_b32_e32 v2, 0xc0, v2
	s_ashr_i32 s3, s6, 8
	s_lshl_b32 s34, s2, 10
	s_mul_i32 s14, s12, 0x160000
	v_and_b32_e32 v1, 0xfffff0, v1
	v_sub_u32_e32 v0, v0, v2
	s_mul_hi_i32 s13, s12, 0x160000
	s_add_u32 s24, s30, s14
	v_add_u32_e32 v1, v14, v1
	v_lshlrev_b32_e32 v4, 5, v13
	v_ashrrev_i16_sdwa v0, v3, sext(v0) dst_sel:DWORD dst_unused:UNUSED_PAD src0_sel:DWORD src1_sel:BYTE_0
	s_addc_u32 s25, s31, s13
	s_add_i32 s35, s34, 0
	v_and_b32_e32 v15, 32, v4
	v_bfe_i32 v16, v0, 0, 16
	v_mul_lo_u32 v0, v1, s4
	s_add_i32 m0, s35, 0x10000
	v_or_b32_e32 v0, v0, v15
	global_load_lds_dwordx4 v128, s[24:25]
	s_add_i32 m0, s35, 0x12000
	v_add_lshl_u32 v130, v0, v16, 1
	s_add_u32 s14, s24, 0xb0000
	global_load_lds_dwordx4 v130, s[24:25]
	s_addc_u32 s15, s25, 0
	s_add_i32 m0, s35, 0x14000
	s_mul_i32 s7, s49, 0x160000
	global_load_lds_dwordx4 v128, s[14:15]
	s_add_i32 m0, s35, 0x16000
	s_mul_hi_i32 s5, s49, 0x160000
	s_add_u32 s22, s72, s7
	s_addc_u32 s23, s73, s5
	s_add_i32 s36, s35, 0x2000
	global_load_lds_dwordx4 v130, s[14:15]
	s_mov_b32 m0, s35
	s_add_u32 s14, s22, 0xb0000
	global_load_lds_dwordx4 v128, s[22:23]
	s_mov_b32 m0, s36
	s_addc_u32 s15, s23, 0
	s_add_i32 s37, s35, 0x4000
	global_load_lds_dwordx4 v130, s[22:23]
	s_mov_b32 m0, s37
	s_add_i32 s38, s35, 0x6000
	global_load_lds_dwordx4 v128, s[14:15]
	s_mov_b32 m0, s38
	v_mov_b32_e32 v129, 0
	global_load_lds_dwordx4 v130, s[14:15]
	v_mov_b32_e32 v131, v129
	s_cmp_eq_u32 s3, 1
	s_mov_b32 s13, 0
	v_lshl_add_u64 v[6:7], s[24:25], 0, v[128:129]
	v_lshl_add_u64 v[4:5], s[24:25], 0, v[130:131]
	v_lshl_add_u64 v[0:1], s[22:23], 0, v[128:129]
	s_cselect_b64 s[14:15], -1, 0
	s_cmp_lg_u32 s3, 1
	v_lshl_add_u64 v[2:3], s[22:23], 0, v[130:131]
	s_cbranch_scc1 .LBB0_1051
	s_barrier
	s_setprio 1

.LBB0_1065:
	ds_read_b128 v[140:143], v147
	ds_read_b128 v[152:155], v147 offset:1024
	ds_read_b128 v[156:159], v147 offset:2048
	ds_read_b128 v[160:163], v147 offset:3072
	ds_read_b128 v[164:167], v148
	ds_read_b128 v[168:171], v148 offset:1024
	ds_read_b128 v[172:175], v148 offset:2048
	ds_read_b128 v[176:179], v148 offset:3072
	s_add_u32 s24, s22, 0x100
	s_addc_u32 s25, s23, 0
	s_cmp_eq_u32 s52, 40
	s_cselect_b32 s29, s7, s25
	s_cselect_b32 s28, s6, s24
	s_cselect_b32 s27, s21, s51
	s_cselect_b32 s26, s20, s50
	v_lshl_add_u64 v[212:213], s[22:23], 0, v[132:133]
	s_add_i32 m0, s35, 0xc000
	ds_read_b128 v[180:183], v149
	ds_read_b128 v[184:187], v149 offset:1024
	ds_read_b128 v[188:191], v149 offset:2048
	ds_read_b128 v[192:195], v149 offset:3072
	ds_read_b128 v[196:199], v149 offset:4096
	ds_read_b128 v[200:203], v149 offset:5120
	ds_read_b128 v[204:207], v149 offset:6144
	ds_read_b128 v[208:211], v149 offset:7168
	global_load_lds_dwordx4 v[212:213], off
	v_lshl_add_u64 v[212:213], s[22:23], 0, v[134:135]
	s_add_i32 m0, s35, 0xe000
	s_nop 0
	global_load_lds_dwordx4 v[212:213], off
	s_waitcnt vmcnt(8)
	s_waitcnt lgkmcnt(0)
	s_barrier
	s_waitcnt lgkmcnt(0)
	v_mfma_f32_16x16x32_bf16 v[124:127], v[140:143], v[180:183], v[124:127]
	v_mfma_f32_16x16x32_bf16 v[120:123], v[156:159], v[180:183], v[120:123]
	v_mfma_f32_16x16x32_bf16 v[108:111], v[140:143], v[188:191], v[108:111]
	v_mfma_f32_16x16x32_bf16 v[104:107], v[156:159], v[188:191], v[104:107]
	v_mfma_f32_16x16x32_bf16 v[92:95], v[140:143], v[196:199], v[92:95]
	v_mfma_f32_16x16x32_bf16 v[88:91], v[156:159], v[196:199], v[88:91]
	v_mfma_f32_16x16x32_bf16 v[76:79], v[140:143], v[204:207], v[76:79]
	v_mfma_f32_16x16x32_bf16 v[72:75], v[156:159], v[204:207], v[72:75]
	v_mfma_f32_16x16x32_bf16 v[124:127], v[152:155], v[184:187], v[124:127]
	v_mfma_f32_16x16x32_bf16 v[120:123], v[160:163], v[184:187], v[120:123]
	v_mfma_f32_16x16x32_bf16 v[108:111], v[152:155], v[192:195], v[108:111]
	v_mfma_f32_16x16x32_bf16 v[104:107], v[160:163], v[192:195], v[104:107]
	v_mfma_f32_16x16x32_bf16 v[92:95], v[152:155], v[200:203], v[92:95]
	v_mfma_f32_16x16x32_bf16 v[88:91], v[160:163], v[200:203], v[88:91]
	v_mfma_f32_16x16x32_bf16 v[76:79], v[152:155], v[208:211], v[76:79]
	v_mfma_f32_16x16x32_bf16 v[72:75], v[160:163], v[208:211], v[72:75]
	v_mfma_f32_16x16x32_bf16 v[116:119], v[164:167], v[180:183], v[116:119]
	v_mfma_f32_16x16x32_bf16 v[112:115], v[172:175], v[180:183], v[112:115]
	v_mfma_f32_16x16x32_bf16 v[100:103], v[164:167], v[188:191], v[100:103]
	v_mfma_f32_16x16x32_bf16 v[96:99], v[172:175], v[188:191], v[96:99]
	v_mfma_f32_16x16x32_bf16 v[84:87], v[164:167], v[196:199], v[84:87]
	v_mfma_f32_16x16x32_bf16 v[80:83], v[172:175], v[196:199], v[80:83]
	v_mfma_f32_16x16x32_bf16 v[68:71], v[164:167], v[204:207], v[68:71]
	v_mfma_f32_16x16x32_bf16 v[64:67], v[172:175], v[204:207], v[64:67]
	v_mfma_f32_16x16x32_bf16 v[116:119], v[168:171], v[184:187], v[116:119]
	v_mfma_f32_16x16x32_bf16 v[112:115], v[176:179], v[184:187], v[112:115]
	v_mfma_f32_16x16x32_bf16 v[100:103], v[168:171], v[192:195], v[100:103]
	v_mfma_f32_16x16x32_bf16 v[96:99], v[176:179], v[192:195], v[96:99]
	v_mfma_f32_16x16x32_bf16 v[84:87], v[168:171], v[200:203], v[84:87]
	v_mfma_f32_16x16x32_bf16 v[80:83], v[176:179], v[200:203], v[80:83]
	v_mfma_f32_16x16x32_bf16 v[68:71], v[168:171], v[208:211], v[68:71]
	v_mfma_f32_16x16x32_bf16 v[64:67], v[176:179], v[208:211], v[64:67]
	s_barrier
	s_add_i32 s22, s44, s34
	v_lshl_add_u64 v[212:213], s[26:27], 0, v[128:129]
	s_mov_b32 m0, s22
	ds_read_b128 v[180:183], v149 offset:16384
	ds_read_b128 v[184:187], v149 offset:17408
	ds_read_b128 v[188:191], v149 offset:18432
	ds_read_b128 v[192:195], v149 offset:19456
	ds_read_b128 v[196:199], v149 offset:20480
	ds_read_b128 v[200:203], v149 offset:21504
	ds_read_b128 v[204:207], v149 offset:22528
	ds_read_b128 v[208:211], v149 offset:23552
	global_load_lds_dwordx4 v[212:213], off
	s_add_i32 m0, s22, 0x2000
	s_add_u32 s22, s26, 0xb0000
	v_lshl_add_u64 v[214:215], s[26:27], 0, v[130:131]
	s_addc_u32 s23, s27, 0
	s_add_i32 s53, s45, s34
	global_load_lds_dwordx4 v[214:215], off
	v_lshl_add_u64 v[216:217], s[22:23], 0, v[128:129]
	s_mov_b32 m0, s53
	v_lshl_add_u64 v[218:219], s[28:29], 0, v[130:131]
	global_load_lds_dwordx4 v[216:217], off
	v_lshl_add_u64 v[216:217], s[22:23], 0, v[130:131]
	s_add_i32 m0, s53, 0x2000
	s_nop 0
	global_load_lds_dwordx4 v[216:217], off
	v_lshl_add_u64 v[216:217], s[28:29], 0, v[128:129]
	s_mov_b32 m0, s35
	s_nop 0
	global_load_lds_dwordx4 v[216:217], off
	s_mov_b32 m0, s36
	s_nop 0
	global_load_lds_dwordx4 v[218:219], off
	s_waitcnt vmcnt(8)
	s_waitcnt lgkmcnt(0)
	s_barrier
	s_waitcnt lgkmcnt(0)
	v_mfma_f32_16x16x32_bf16 v[60:63], v[140:143], v[180:183], v[60:63]
	v_mfma_f32_16x16x32_bf16 v[56:59], v[156:159], v[180:183], v[56:59]
	v_mfma_f32_16x16x32_bf16 v[44:47], v[140:143], v[188:191], v[44:47]
	v_mfma_f32_16x16x32_bf16 v[40:43], v[156:159], v[188:191], v[40:43]
	v_mfma_f32_16x16x32_bf16 v[28:31], v[140:143], v[196:199], v[28:31]
	v_mfma_f32_16x16x32_bf16 v[24:27], v[156:159], v[196:199], v[24:27]
	v_mfma_f32_16x16x32_bf16 v[12:15], v[140:143], v[204:207], v[12:15]
	v_mfma_f32_16x16x32_bf16 v[8:11], v[156:159], v[204:207], v[8:11]
	v_mfma_f32_16x16x32_bf16 v[60:63], v[152:155], v[184:187], v[60:63]
	v_mfma_f32_16x16x32_bf16 v[56:59], v[160:163], v[184:187], v[56:59]
	v_mfma_f32_16x16x32_bf16 v[44:47], v[152:155], v[192:195], v[44:47]
	v_mfma_f32_16x16x32_bf16 v[40:43], v[160:163], v[192:195], v[40:43]
	v_mfma_f32_16x16x32_bf16 v[28:31], v[152:155], v[200:203], v[28:31]
	v_mfma_f32_16x16x32_bf16 v[24:27], v[160:163], v[200:203], v[24:27]
	v_mfma_f32_16x16x32_bf16 v[12:15], v[152:155], v[208:211], v[12:15]
	v_mfma_f32_16x16x32_bf16 v[8:11], v[160:163], v[208:211], v[8:11]
	v_mfma_f32_16x16x32_bf16 v[52:55], v[164:167], v[180:183], v[52:55]
	v_mfma_f32_16x16x32_bf16 v[48:51], v[172:175], v[180:183], v[48:51]
	v_mfma_f32_16x16x32_bf16 v[36:39], v[164:167], v[188:191], v[36:39]
	v_mfma_f32_16x16x32_bf16 v[32:35], v[172:175], v[188:191], v[32:35]
	v_mfma_f32_16x16x32_bf16 v[20:23], v[164:167], v[196:199], v[20:23]
	v_mfma_f32_16x16x32_bf16 v[16:19], v[172:175], v[196:199], v[16:19]
	v_mfma_f32_16x16x32_bf16 v[4:7], v[164:167], v[204:207], v[4:7]
	v_mfma_f32_16x16x32_bf16 v[0:3], v[172:175], v[204:207], v[0:3]
	v_mfma_f32_16x16x32_bf16 v[52:55], v[168:171], v[184:187], v[52:55]
	v_mfma_f32_16x16x32_bf16 v[48:51], v[176:179], v[184:187], v[48:51]
	v_mfma_f32_16x16x32_bf16 v[36:39], v[168:171], v[192:195], v[36:39]
	v_mfma_f32_16x16x32_bf16 v[32:35], v[176:179], v[192:195], v[32:35]
	v_mfma_f32_16x16x32_bf16 v[20:23], v[168:171], v[200:203], v[20:23]
	v_mfma_f32_16x16x32_bf16 v[16:19], v[176:179], v[200:203], v[16:19]
	v_mfma_f32_16x16x32_bf16 v[4:7], v[168:171], v[208:211], v[4:7]
	v_mfma_f32_16x16x32_bf16 v[0:3], v[176:179], v[208:211], v[0:3]
	s_barrier
	s_add_i32 s53, 0, 0x18000
	v_add_u32_e32 v151, s53, v145
	s_add_i32 s54, 0, 0x1c000
	ds_read_b128 v[140:143], v151
	ds_read_b128 v[152:155], v151 offset:1024
	ds_read_b128 v[156:159], v151 offset:2048
	ds_read_b128 v[160:163], v151 offset:3072
	v_add_u32_e32 v151, s54, v145
	ds_read_b128 v[164:167], v151
	ds_read_b128 v[168:171], v151 offset:1024
	ds_read_b128 v[172:175], v151 offset:2048
	ds_read_b128 v[176:179], v151 offset:3072
	s_add_u32 s22, s28, 0xb0000
	s_addc_u32 s23, s29, 0
	s_mov_b32 m0, s37
	v_lshl_add_u64 v[220:221], s[22:23], 0, v[128:129]
	ds_read_b128 v[180:183], v149 offset:32768
	ds_read_b128 v[184:187], v149 offset:33792
	ds_read_b128 v[188:191], v149 offset:34816
	ds_read_b128 v[192:195], v149 offset:35840
	ds_read_b128 v[196:199], v149 offset:36864
	ds_read_b128 v[200:203], v149 offset:37888
	ds_read_b128 v[204:207], v149 offset:38912
	ds_read_b128 v[208:211], v149 offset:39936
	global_load_lds_dwordx4 v[220:221], off
	v_lshl_add_u64 v[220:221], s[22:23], 0, v[130:131]
	s_mov_b32 m0, s38
	s_nop 0
	global_load_lds_dwordx4 v[220:221], off
	s_waitcnt vmcnt(8)
	s_waitcnt lgkmcnt(0)
	s_barrier
	s_waitcnt lgkmcnt(0)
	v_mfma_f32_16x16x32_bf16 v[124:127], v[140:143], v[180:183], v[124:127]
	v_mfma_f32_16x16x32_bf16 v[120:123], v[156:159], v[180:183], v[120:123]
	v_mfma_f32_16x16x32_bf16 v[108:111], v[140:143], v[188:191], v[108:111]
	v_mfma_f32_16x16x32_bf16 v[104:107], v[156:159], v[188:191], v[104:107]
	v_mfma_f32_16x16x32_bf16 v[92:95], v[140:143], v[196:199], v[92:95]
	v_mfma_f32_16x16x32_bf16 v[88:91], v[156:159], v[196:199], v[88:91]
	v_mfma_f32_16x16x32_bf16 v[76:79], v[140:143], v[204:207], v[76:79]
	v_mfma_f32_16x16x32_bf16 v[72:75], v[156:159], v[204:207], v[72:75]
	v_mfma_f32_16x16x32_bf16 v[124:127], v[152:155], v[184:187], v[124:127]
	v_mfma_f32_16x16x32_bf16 v[120:123], v[160:163], v[184:187], v[120:123]
	v_mfma_f32_16x16x32_bf16 v[108:111], v[152:155], v[192:195], v[108:111]
	v_mfma_f32_16x16x32_bf16 v[104:107], v[160:163], v[192:195], v[104:107]
	v_mfma_f32_16x16x32_bf16 v[92:95], v[152:155], v[200:203], v[92:95]
	v_mfma_f32_16x16x32_bf16 v[88:91], v[160:163], v[200:203], v[88:91]
	v_mfma_f32_16x16x32_bf16 v[76:79], v[152:155], v[208:211], v[76:79]
	v_mfma_f32_16x16x32_bf16 v[72:75], v[160:163], v[208:211], v[72:75]
	v_mfma_f32_16x16x32_bf16 v[116:119], v[164:167], v[180:183], v[116:119]
	v_mfma_f32_16x16x32_bf16 v[112:115], v[172:175], v[180:183], v[112:115]
	v_mfma_f32_16x16x32_bf16 v[100:103], v[164:167], v[188:191], v[100:103]
	v_mfma_f32_16x16x32_bf16 v[96:99], v[172:175], v[188:191], v[96:99]
	v_mfma_f32_16x16x32_bf16 v[84:87], v[164:167], v[196:199], v[84:87]
	v_mfma_f32_16x16x32_bf16 v[80:83], v[172:175], v[196:199], v[80:83]
	v_mfma_f32_16x16x32_bf16 v[68:71], v[164:167], v[204:207], v[68:71]
	v_mfma_f32_16x16x32_bf16 v[64:67], v[172:175], v[204:207], v[64:67]
	v_mfma_f32_16x16x32_bf16 v[116:119], v[168:171], v[184:187], v[116:119]
	v_mfma_f32_16x16x32_bf16 v[112:115], v[176:179], v[184:187], v[112:115]
	v_mfma_f32_16x16x32_bf16 v[100:103], v[168:171], v[192:195], v[100:103]
	v_mfma_f32_16x16x32_bf16 v[96:99], v[176:179], v[192:195], v[96:99]
	v_mfma_f32_16x16x32_bf16 v[84:87], v[168:171], v[200:203], v[84:87]
	v_mfma_f32_16x16x32_bf16 v[80:83], v[176:179], v[200:203], v[80:83]
	v_mfma_f32_16x16x32_bf16 v[68:71], v[168:171], v[208:211], v[68:71]
	v_mfma_f32_16x16x32_bf16 v[64:67], v[176:179], v[208:211], v[64:67]
	s_barrier
	s_add_i32 s22, s53, s34
	v_lshl_add_u64 v[212:213], v[212:213], 0, s[16:17]
	s_mov_b32 m0, s22
	ds_read_b128 v[180:183], v149 offset:49152
	ds_read_b128 v[184:187], v149 offset:50176
	ds_read_b128 v[188:191], v149 offset:51200
	ds_read_b128 v[192:195], v149 offset:52224
	ds_read_b128 v[196:199], v149 offset:53248
	ds_read_b128 v[200:203], v149 offset:54272
	ds_read_b128 v[204:207], v149 offset:55296
	ds_read_b128 v[208:211], v149 offset:56320
	global_load_lds_dwordx4 v[212:213], off
	s_add_i32 m0, s22, 0x2000
	s_add_u32 s22, s26, 0xb0080
	v_lshl_add_u64 v[212:213], v[214:215], 0, s[16:17]
	s_addc_u32 s23, s27, 0
	s_add_i32 s26, s54, s34
	global_load_lds_dwordx4 v[212:213], off
	v_lshl_add_u64 v[212:213], s[22:23], 0, v[128:129]
	s_mov_b32 m0, s26
	s_nop 0
	global_load_lds_dwordx4 v[212:213], off
	v_lshl_add_u64 v[212:213], s[22:23], 0, v[130:131]
	s_add_i32 m0, s26, 0x2000
	s_nop 0
	global_load_lds_dwordx4 v[212:213], off
	v_lshl_add_u64 v[212:213], v[216:217], 0, s[16:17]
	s_mov_b32 m0, s40
	s_nop 0
	global_load_lds_dwordx4 v[212:213], off
	v_lshl_add_u64 v[212:213], v[218:219], 0, s[16:17]
	s_mov_b32 m0, s41
	s_nop 0
	global_load_lds_dwordx4 v[212:213], off
	s_waitcnt vmcnt(8)
	s_waitcnt lgkmcnt(0)
	s_barrier
	s_waitcnt lgkmcnt(0)
	v_mfma_f32_16x16x32_bf16 v[60:63], v[140:143], v[180:183], v[60:63]
	v_mfma_f32_16x16x32_bf16 v[56:59], v[156:159], v[180:183], v[56:59]
	v_mfma_f32_16x16x32_bf16 v[44:47], v[140:143], v[188:191], v[44:47]
	v_mfma_f32_16x16x32_bf16 v[40:43], v[156:159], v[188:191], v[40:43]
	v_mfma_f32_16x16x32_bf16 v[28:31], v[140:143], v[196:199], v[28:31]
	v_mfma_f32_16x16x32_bf16 v[24:27], v[156:159], v[196:199], v[24:27]
	v_mfma_f32_16x16x32_bf16 v[12:15], v[140:143], v[204:207], v[12:15]
	v_mfma_f32_16x16x32_bf16 v[8:11], v[156:159], v[204:207], v[8:11]
	v_mfma_f32_16x16x32_bf16 v[60:63], v[152:155], v[184:187], v[60:63]
	v_mfma_f32_16x16x32_bf16 v[56:59], v[160:163], v[184:187], v[56:59]
	v_mfma_f32_16x16x32_bf16 v[44:47], v[152:155], v[192:195], v[44:47]
	v_mfma_f32_16x16x32_bf16 v[40:43], v[160:163], v[192:195], v[40:43]
	v_mfma_f32_16x16x32_bf16 v[28:31], v[152:155], v[200:203], v[28:31]
	v_mfma_f32_16x16x32_bf16 v[24:27], v[160:163], v[200:203], v[24:27]
	v_mfma_f32_16x16x32_bf16 v[12:15], v[152:155], v[208:211], v[12:15]
	v_mfma_f32_16x16x32_bf16 v[8:11], v[160:163], v[208:211], v[8:11]
	v_mfma_f32_16x16x32_bf16 v[52:55], v[164:167], v[180:183], v[52:55]
	v_mfma_f32_16x16x32_bf16 v[48:51], v[172:175], v[180:183], v[48:51]
	v_mfma_f32_16x16x32_bf16 v[36:39], v[164:167], v[188:191], v[36:39]
	v_mfma_f32_16x16x32_bf16 v[32:35], v[172:175], v[188:191], v[32:35]
	v_mfma_f32_16x16x32_bf16 v[20:23], v[164:167], v[196:199], v[20:23]
	v_mfma_f32_16x16x32_bf16 v[16:19], v[172:175], v[196:199], v[16:19]
	v_mfma_f32_16x16x32_bf16 v[4:7], v[164:167], v[204:207], v[4:7]
	v_mfma_f32_16x16x32_bf16 v[0:3], v[172:175], v[204:207], v[0:3]
	v_mfma_f32_16x16x32_bf16 v[52:55], v[168:171], v[184:187], v[52:55]
	v_mfma_f32_16x16x32_bf16 v[48:51], v[176:179], v[184:187], v[48:51]
	v_mfma_f32_16x16x32_bf16 v[36:39], v[168:171], v[192:195], v[36:39]
	v_mfma_f32_16x16x32_bf16 v[32:35], v[176:179], v[192:195], v[32:35]
	v_mfma_f32_16x16x32_bf16 v[20:23], v[168:171], v[200:203], v[20:23]
	v_mfma_f32_16x16x32_bf16 v[16:19], v[176:179], v[200:203], v[16:19]
	v_mfma_f32_16x16x32_bf16 v[4:7], v[168:171], v[208:211], v[4:7]
	v_mfma_f32_16x16x32_bf16 v[0:3], v[176:179], v[208:211], v[0:3]
	s_barrier
	s_add_i32 s52, s52, 2
	s_add_u32 s50, s50, 0x100
	s_addc_u32 s51, s51, 0
	s_cmp_gt_u32 s52, 41
	s_mov_b64 s[22:23], s[24:25]
	s_cbranch_scc0 .LBB0_1065
	s_and_b64 vcc, exec, s[18:19]
	s_cbranch_vccz .LBB0_1068
	s_barrier

.LBB0_1122:
	s_andn2_b64 vcc, exec, s[2:3]
	s_cbranch_vccnz .LBB0_1164
	v_ashrrev_i32_e32 v1, 31, v2
	v_lshrrev_b32_e32 v1, 26, v1
	v_add_u32_e32 v1, v2, v1
	v_ashrrev_i32_e32 v9, 6, v1
	v_bfe_i32 v1, v2, 27, 1
	v_lshlrev_b32_e32 v0, 4, v2
	v_lshrrev_b32_e32 v1, 22, v1
	v_add_u32_e32 v1, v0, v1
	v_and_b32_e32 v1, 0xfffffc00, v1
	v_sub_u32_e32 v1, v0, v1
	v_lshrrev_b32_e32 v2, 4, v1
	v_bitop3_b32 v1, v2, v1, 32 bitop3:0x6c
	v_ashrrev_i32_e32 v3, 31, v1
	v_lshrrev_b32_e32 v3, 26, v3
	v_add_u32_e32 v3, v1, v3
	v_lshlrev_b32_e32 v2, 3, v9
	v_ashrrev_i32_e32 v10, 6, v3
	v_and_b32_e32 v3, 0xc0, v3
	v_and_b32_e32 v2, -16, v2
	v_sub_u32_e32 v1, v1, v3
	v_mov_b32_e32 v3, 1
	v_add_u32_e32 v2, v10, v2
	v_ashrrev_i16_sdwa v1, v3, sext(v1) dst_sel:DWORD dst_unused:UNUSED_PAD src0_sel:DWORD src1_sel:BYTE_0
	v_lshlrev_b32_e32 v4, 5, v9
	v_bfe_i32 v11, v1, 0, 16
	v_lshlrev_b32_e32 v1, 1, v2
	v_lshrrev_b32_e32 v5, 2, v2
	v_and_b32_e32 v6, 3, v10
	s_mov_b32 s3, 0x1fffe0
	v_and_b32_e32 v4, 32, v4
	v_and_b32_e32 v1, 24, v1
	v_and_b32_e32 v5, 4, v5
	v_and_or_b32 v6, v2, s3, v6
	v_or3_b32 v1, v6, v5, v1
	v_add_lshl_u32 v4, v4, v11, 1
	v_add_u32_e32 v0, 0x2000, v0
	v_lshl_add_u32 v130, v1, 11, v4
	v_ashrrev_i32_e32 v1, 31, v0
	v_lshrrev_b32_e32 v1, 22, v1
	v_add_u32_e32 v1, v0, v1
	v_ashrrev_i32_e32 v12, 10, v1
	v_mul_i32_i24_e32 v1, 0x400, v12
	v_sub_u32_e32 v0, v0, v1
	v_lshrrev_b32_e32 v1, 4, v0
	v_bitop3_b32 v0, v1, v0, 32 bitop3:0x6c
	v_lshl_add_u32 v128, v2, 11, v4
	v_ashrrev_i32_e32 v2, 31, v0
	v_lshrrev_b32_e32 v2, 26, v2
	v_add_u32_e32 v2, v0, v2
	v_lshlrev_b32_e32 v1, 3, v12
	v_ashrrev_i32_e32 v13, 6, v2
	v_and_b32_e32 v2, 0xc0, v2
	s_add_u32 s40, s70, 0x1c00000
	v_and_b32_e32 v1, -16, v1
	v_sub_u32_e32 v0, v0, v2
	s_addc_u32 s41, s71, 0
	s_ashr_i32 s2, s4, 6
	v_add_u32_e32 v1, v13, v1
	v_ashrrev_i16_sdwa v0, v3, sext(v0) dst_sel:DWORD dst_unused:UNUSED_PAD src0_sel:DWORD src1_sel:BYTE_0
	v_and_b32_e32 v3, 3, v13
	s_ashr_i32 s31, s30, 31
	s_ashr_i32 s29, s28, 31
	v_and_or_b32 v3, v1, s3, v3
	s_ashr_i32 s3, s4, 8
	s_lshl_b32 s42, s2, 10
	s_lshl_b64 s[8:9], s[30:31], 19
	s_waitcnt lgkmcnt(0)
	s_lshl_b64 s[10:11], s[28:29], 19
	s_add_u32 s36, s40, s10
	v_lshlrev_b32_e32 v4, 5, v12
	v_bfe_i32 v14, v0, 0, 16
	v_lshlrev_b32_e32 v0, 1, v1
	v_lshrrev_b32_e32 v2, 2, v1
	s_addc_u32 s37, s41, s11
	s_add_i32 s43, s42, 0
	v_and_b32_e32 v4, 32, v4
	v_and_b32_e32 v0, 24, v0
	v_and_b32_e32 v2, 4, v2
	s_add_i32 m0, s43, 0x10000
	v_or3_b32 v0, v3, v2, v0
	v_add_lshl_u32 v2, v4, v14, 1
	global_load_lds_dwordx4 v130, s[36:37]
	s_add_i32 m0, s43, 0x12000
	v_lshl_add_u32 v134, v0, 11, v2
	s_add_u32 s10, s36, 0x40000
	global_load_lds_dwordx4 v134, s[36:37]
	s_addc_u32 s11, s37, 0
	s_add_i32 m0, s43, 0x14000
	v_lshl_add_u32 v132, v1, 11, v2
	global_load_lds_dwordx4 v130, s[10:11]
	s_add_i32 m0, s43, 0x16000
	s_add_u32 s34, s76, s8
	s_addc_u32 s35, s77, s9
	s_add_i32 s44, s43, 0x2000
	global_load_lds_dwordx4 v134, s[10:11]
	s_mov_b32 m0, s43
	s_add_u32 s8, s34, 0x40000
	global_load_lds_dwordx4 v128, s[34:35]
	s_mov_b32 m0, s44
	s_addc_u32 s9, s35, 0
	s_add_i32 s45, s43, 0x4000
	global_load_lds_dwordx4 v132, s[34:35]
	s_mov_b32 m0, s45
	s_add_i32 s46, s43, 0x6000
	global_load_lds_dwordx4 v128, s[8:9]
	s_mov_b32 m0, s46
	v_mov_b32_e32 v137, 0
	global_load_lds_dwordx4 v132, s[8:9]
	v_mov_b32_e32 v131, v137
	v_mov_b32_e32 v135, v137
	v_mov_b32_e32 v129, v137
	v_mov_b32_e32 v133, v137
	s_cmp_eq_u32 s3, 1
	s_mov_b32 s9, 0
	v_lshl_add_u64 v[6:7], s[36:37], 0, v[130:131]
	v_lshl_add_u64 v[4:5], s[36:37], 0, v[134:135]
	v_lshl_add_u64 v[0:1], s[34:35], 0, v[128:129]
	s_cselect_b64 s[10:11], -1, 0
	s_cmp_lg_u32 s3, 1
	v_lshl_add_u64 v[2:3], s[34:35], 0, v[132:133]
	s_cbranch_scc1 .LBB0_1125
	s_barrier
	s_setprio 1

.LBB0_1131:
	ds_read_b128 v[154:157], v160
	ds_read_b128 v[166:169], v160 offset:1024
	ds_read_b128 v[170:173], v160 offset:2048
	ds_read_b128 v[174:177], v160 offset:3072
	ds_read_b128 v[178:181], v161
	ds_read_b128 v[182:185], v161 offset:1024
	ds_read_b128 v[186:189], v161 offset:2048
	ds_read_b128 v[190:193], v161 offset:3072
	s_add_u32 s36, s34, 0xfffc0080
	s_addc_u32 s37, s35, -1
	s_cmp_eq_u32 s58, 12
	s_cselect_b32 s39, s23, s37
	s_cselect_b32 s38, s29, s36
	s_cselect_b32 s37, s21, s57
	s_cselect_b32 s36, s31, s56
	v_lshl_add_u64 v[226:227], s[34:35], 0, v[146:147]
	s_add_i32 m0, s43, 0xc000
	ds_read_b128 v[194:197], v162
	ds_read_b128 v[198:201], v162 offset:1024
	ds_read_b128 v[202:205], v162 offset:2048
	ds_read_b128 v[206:209], v162 offset:3072
	ds_read_b128 v[210:213], v162 offset:4096
	ds_read_b128 v[214:217], v162 offset:5120
	ds_read_b128 v[218:221], v162 offset:6144
	ds_read_b128 v[222:225], v162 offset:7168
	global_load_lds_dwordx4 v[226:227], off
	v_lshl_add_u64 v[226:227], s[34:35], 0, v[148:149]
	s_add_i32 m0, s43, 0xe000
	s_nop 0
	global_load_lds_dwordx4 v[226:227], off
	s_waitcnt vmcnt(8)
	s_waitcnt lgkmcnt(0)
	s_barrier
	s_waitcnt lgkmcnt(0)
	v_mfma_f32_16x16x32_bf16 v[116:119], v[154:157], v[194:197], v[116:119]
	v_mfma_f32_16x16x32_bf16 v[112:115], v[170:173], v[194:197], v[112:115]
	v_mfma_f32_16x16x32_bf16 v[100:103], v[154:157], v[202:205], v[100:103]
	v_mfma_f32_16x16x32_bf16 v[96:99], v[170:173], v[202:205], v[96:99]
	v_mfma_f32_16x16x32_bf16 v[88:91], v[154:157], v[210:213], v[88:91]
	v_mfma_f32_16x16x32_bf16 v[84:87], v[170:173], v[210:213], v[84:87]
	v_mfma_f32_16x16x32_bf16 v[72:75], v[154:157], v[218:221], v[72:75]
	v_mfma_f32_16x16x32_bf16 v[68:71], v[170:173], v[218:221], v[68:71]
	v_mfma_f32_16x16x32_bf16 v[116:119], v[166:169], v[198:201], v[116:119]
	v_mfma_f32_16x16x32_bf16 v[112:115], v[174:177], v[198:201], v[112:115]
	v_mfma_f32_16x16x32_bf16 v[100:103], v[166:169], v[206:209], v[100:103]
	v_mfma_f32_16x16x32_bf16 v[96:99], v[174:177], v[206:209], v[96:99]
	v_mfma_f32_16x16x32_bf16 v[88:91], v[166:169], v[214:217], v[88:91]
	v_mfma_f32_16x16x32_bf16 v[84:87], v[174:177], v[214:217], v[84:87]
	v_mfma_f32_16x16x32_bf16 v[72:75], v[166:169], v[222:225], v[72:75]
	v_mfma_f32_16x16x32_bf16 v[68:71], v[174:177], v[222:225], v[68:71]
	v_mfma_f32_16x16x32_bf16 v[124:127], v[178:181], v[194:197], v[124:127]
	v_mfma_f32_16x16x32_bf16 v[120:123], v[186:189], v[194:197], v[120:123]
	v_mfma_f32_16x16x32_bf16 v[108:111], v[178:181], v[202:205], v[108:111]
	v_mfma_f32_16x16x32_bf16 v[104:107], v[186:189], v[202:205], v[104:107]
	v_mfma_f32_16x16x32_bf16 v[92:95], v[178:181], v[210:213], v[92:95]
	v_mfma_f32_16x16x32_bf16 v[80:83], v[186:189], v[210:213], v[80:83]
	v_mfma_f32_16x16x32_bf16 v[76:79], v[178:181], v[218:221], v[76:79]
	v_mfma_f32_16x16x32_bf16 v[64:67], v[186:189], v[218:221], v[64:67]
	v_mfma_f32_16x16x32_bf16 v[124:127], v[182:185], v[198:201], v[124:127]
	v_mfma_f32_16x16x32_bf16 v[120:123], v[190:193], v[198:201], v[120:123]
	v_mfma_f32_16x16x32_bf16 v[108:111], v[182:185], v[206:209], v[108:111]
	v_mfma_f32_16x16x32_bf16 v[104:107], v[190:193], v[206:209], v[104:107]
	v_mfma_f32_16x16x32_bf16 v[92:95], v[182:185], v[214:217], v[92:95]
	v_mfma_f32_16x16x32_bf16 v[80:83], v[190:193], v[214:217], v[80:83]
	v_mfma_f32_16x16x32_bf16 v[76:79], v[182:185], v[222:225], v[76:79]
	v_mfma_f32_16x16x32_bf16 v[64:67], v[190:193], v[222:225], v[64:67]
	s_barrier
	s_add_i32 s59, s52, s42
	v_lshl_add_u64 v[226:227], s[36:37], 0, v[130:131]
	s_mov_b32 m0, s59
	ds_read_b128 v[194:197], v162 offset:16384
	ds_read_b128 v[198:201], v162 offset:17408
	ds_read_b128 v[202:205], v162 offset:18432
	ds_read_b128 v[206:209], v162 offset:19456
	ds_read_b128 v[210:213], v162 offset:20480
	ds_read_b128 v[214:217], v162 offset:21504
	ds_read_b128 v[218:221], v162 offset:22528
	ds_read_b128 v[222:225], v162 offset:23552
	global_load_lds_dwordx4 v[226:227], off
	s_add_i32 m0, s59, 0x2000
	s_add_u32 s60, s36, 0x40000
	v_lshl_add_u64 v[228:229], s[36:37], 0, v[134:135]
	s_addc_u32 s61, s37, 0
	s_add_i32 s59, s53, s42
	global_load_lds_dwordx4 v[228:229], off
	v_lshl_add_u64 v[230:231], s[60:61], 0, v[130:131]
	s_mov_b32 m0, s59
	v_lshl_add_u64 v[232:233], s[38:39], 0, v[132:133]
	global_load_lds_dwordx4 v[230:231], off
	v_lshl_add_u64 v[230:231], s[60:61], 0, v[134:135]
	s_add_i32 m0, s59, 0x2000
	s_nop 0
	global_load_lds_dwordx4 v[230:231], off
	v_lshl_add_u64 v[230:231], s[38:39], 0, v[128:129]
	s_mov_b32 m0, s43
	s_nop 0
	global_load_lds_dwordx4 v[230:231], off
	s_mov_b32 m0, s44
	s_nop 0
	global_load_lds_dwordx4 v[232:233], off
	s_waitcnt vmcnt(8)
	s_waitcnt lgkmcnt(0)
	s_barrier
	s_waitcnt lgkmcnt(0)
	v_mfma_f32_16x16x32_bf16 v[56:59], v[154:157], v[194:197], v[56:59]
	v_mfma_f32_16x16x32_bf16 v[52:55], v[170:173], v[194:197], v[52:55]
	v_mfma_f32_16x16x32_bf16 v[40:43], v[154:157], v[202:205], v[40:43]
	v_mfma_f32_16x16x32_bf16 v[36:39], v[170:173], v[202:205], v[36:39]
	v_mfma_f32_16x16x32_bf16 v[24:27], v[154:157], v[210:213], v[24:27]
	v_mfma_f32_16x16x32_bf16 v[20:23], v[170:173], v[210:213], v[20:23]
	v_mfma_f32_16x16x32_bf16 v[8:11], v[154:157], v[218:221], v[8:11]
	v_mfma_f32_16x16x32_bf16 v[4:7], v[170:173], v[218:221], v[4:7]
	v_mfma_f32_16x16x32_bf16 v[56:59], v[166:169], v[198:201], v[56:59]
	v_mfma_f32_16x16x32_bf16 v[52:55], v[174:177], v[198:201], v[52:55]
	v_mfma_f32_16x16x32_bf16 v[40:43], v[166:169], v[206:209], v[40:43]
	v_mfma_f32_16x16x32_bf16 v[36:39], v[174:177], v[206:209], v[36:39]
	v_mfma_f32_16x16x32_bf16 v[24:27], v[166:169], v[214:217], v[24:27]
	v_mfma_f32_16x16x32_bf16 v[20:23], v[174:177], v[214:217], v[20:23]
	v_mfma_f32_16x16x32_bf16 v[8:11], v[166:169], v[222:225], v[8:11]
	v_mfma_f32_16x16x32_bf16 v[4:7], v[174:177], v[222:225], v[4:7]
	v_mfma_f32_16x16x32_bf16 v[60:63], v[178:181], v[194:197], v[60:63]
	v_mfma_f32_16x16x32_bf16 v[48:51], v[186:189], v[194:197], v[48:51]
	v_mfma_f32_16x16x32_bf16 v[44:47], v[178:181], v[202:205], v[44:47]
	v_mfma_f32_16x16x32_bf16 v[32:35], v[186:189], v[202:205], v[32:35]
	v_mfma_f32_16x16x32_bf16 v[28:31], v[178:181], v[210:213], v[28:31]
	v_mfma_f32_16x16x32_bf16 v[16:19], v[186:189], v[210:213], v[16:19]
	v_mfma_f32_16x16x32_bf16 v[12:15], v[178:181], v[218:221], v[12:15]
	v_mfma_f32_16x16x32_bf16 v[0:3], v[186:189], v[218:221], v[0:3]
	v_mfma_f32_16x16x32_bf16 v[60:63], v[182:185], v[198:201], v[60:63]
	v_mfma_f32_16x16x32_bf16 v[48:51], v[190:193], v[198:201], v[48:51]
	v_mfma_f32_16x16x32_bf16 v[44:47], v[182:185], v[206:209], v[44:47]
	v_mfma_f32_16x16x32_bf16 v[32:35], v[190:193], v[206:209], v[32:35]
	v_mfma_f32_16x16x32_bf16 v[28:31], v[182:185], v[214:217], v[28:31]
	v_mfma_f32_16x16x32_bf16 v[16:19], v[190:193], v[214:217], v[16:19]
	v_mfma_f32_16x16x32_bf16 v[12:15], v[182:185], v[222:225], v[12:15]
	v_mfma_f32_16x16x32_bf16 v[0:3], v[190:193], v[222:225], v[0:3]
	s_barrier
	s_add_i32 s59, 0, 0x18000
	v_add_u32_e32 v165, s59, v159
	s_add_i32 s60, 0, 0x1c000
	ds_read_b128 v[154:157], v165
	ds_read_b128 v[166:169], v165 offset:1024
	ds_read_b128 v[170:173], v165 offset:2048
	ds_read_b128 v[174:177], v165 offset:3072
	v_add_u32_e32 v165, s60, v159
	ds_read_b128 v[178:181], v165
	ds_read_b128 v[182:185], v165 offset:1024
	ds_read_b128 v[186:189], v165 offset:2048
	ds_read_b128 v[190:193], v165 offset:3072
	s_add_u32 s38, s38, 0x40000
	s_addc_u32 s39, s39, 0
	s_mov_b32 m0, s45
	v_lshl_add_u64 v[234:235], s[38:39], 0, v[128:129]
	ds_read_b128 v[194:197], v162 offset:32768
	ds_read_b128 v[198:201], v162 offset:33792
	ds_read_b128 v[202:205], v162 offset:34816
	ds_read_b128 v[206:209], v162 offset:35840
	ds_read_b128 v[210:213], v162 offset:36864
	ds_read_b128 v[214:217], v162 offset:37888
	ds_read_b128 v[218:221], v162 offset:38912
	ds_read_b128 v[222:225], v162 offset:39936
	global_load_lds_dwordx4 v[234:235], off
	v_lshl_add_u64 v[234:235], s[38:39], 0, v[132:133]
	s_mov_b32 m0, s46
	s_nop 0
	global_load_lds_dwordx4 v[234:235], off
	s_waitcnt vmcnt(8)
	s_waitcnt lgkmcnt(0)
	s_barrier
	s_waitcnt lgkmcnt(0)
	v_mfma_f32_16x16x32_bf16 v[116:119], v[154:157], v[194:197], v[116:119]
	v_mfma_f32_16x16x32_bf16 v[112:115], v[170:173], v[194:197], v[112:115]
	v_mfma_f32_16x16x32_bf16 v[100:103], v[154:157], v[202:205], v[100:103]
	v_mfma_f32_16x16x32_bf16 v[96:99], v[170:173], v[202:205], v[96:99]
	v_mfma_f32_16x16x32_bf16 v[88:91], v[154:157], v[210:213], v[88:91]
	v_mfma_f32_16x16x32_bf16 v[84:87], v[170:173], v[210:213], v[84:87]
	v_mfma_f32_16x16x32_bf16 v[72:75], v[154:157], v[218:221], v[72:75]
	v_mfma_f32_16x16x32_bf16 v[68:71], v[170:173], v[218:221], v[68:71]
	v_mfma_f32_16x16x32_bf16 v[116:119], v[166:169], v[198:201], v[116:119]
	v_mfma_f32_16x16x32_bf16 v[112:115], v[174:177], v[198:201], v[112:115]
	v_mfma_f32_16x16x32_bf16 v[100:103], v[166:169], v[206:209], v[100:103]
	v_mfma_f32_16x16x32_bf16 v[96:99], v[174:177], v[206:209], v[96:99]
	v_mfma_f32_16x16x32_bf16 v[88:91], v[166:169], v[214:217], v[88:91]
	v_mfma_f32_16x16x32_bf16 v[84:87], v[174:177], v[214:217], v[84:87]
	v_mfma_f32_16x16x32_bf16 v[72:75], v[166:169], v[222:225], v[72:75]
	v_mfma_f32_16x16x32_bf16 v[68:71], v[174:177], v[222:225], v[68:71]
	v_mfma_f32_16x16x32_bf16 v[124:127], v[178:181], v[194:197], v[124:127]
	v_mfma_f32_16x16x32_bf16 v[120:123], v[186:189], v[194:197], v[120:123]
	v_mfma_f32_16x16x32_bf16 v[108:111], v[178:181], v[202:205], v[108:111]
	v_mfma_f32_16x16x32_bf16 v[104:107], v[186:189], v[202:205], v[104:107]
	v_mfma_f32_16x16x32_bf16 v[92:95], v[178:181], v[210:213], v[92:95]
	v_mfma_f32_16x16x32_bf16 v[80:83], v[186:189], v[210:213], v[80:83]
	v_mfma_f32_16x16x32_bf16 v[76:79], v[178:181], v[218:221], v[76:79]
	v_mfma_f32_16x16x32_bf16 v[64:67], v[186:189], v[218:221], v[64:67]
	v_mfma_f32_16x16x32_bf16 v[124:127], v[182:185], v[198:201], v[124:127]
	v_mfma_f32_16x16x32_bf16 v[120:123], v[190:193], v[198:201], v[120:123]
	v_mfma_f32_16x16x32_bf16 v[108:111], v[182:185], v[206:209], v[108:111]
	v_mfma_f32_16x16x32_bf16 v[104:107], v[190:193], v[206:209], v[104:107]
	v_mfma_f32_16x16x32_bf16 v[92:95], v[182:185], v[214:217], v[92:95]
	v_mfma_f32_16x16x32_bf16 v[80:83], v[190:193], v[214:217], v[80:83]
	v_mfma_f32_16x16x32_bf16 v[76:79], v[182:185], v[222:225], v[76:79]
	v_mfma_f32_16x16x32_bf16 v[64:67], v[190:193], v[222:225], v[64:67]
	s_barrier
	s_add_i32 s38, s59, s42
	v_lshl_add_u64 v[226:227], v[226:227], 0, s[12:13]
	s_mov_b32 m0, s38
	ds_read_b128 v[194:197], v162 offset:49152
	ds_read_b128 v[198:201], v162 offset:50176
	ds_read_b128 v[202:205], v162 offset:51200
	ds_read_b128 v[206:209], v162 offset:52224
	ds_read_b128 v[210:213], v162 offset:53248
	ds_read_b128 v[214:217], v162 offset:54272
	ds_read_b128 v[218:221], v162 offset:55296
	ds_read_b128 v[222:225], v162 offset:56320
	global_load_lds_dwordx4 v[226:227], off
	s_add_i32 m0, s38, 0x2000
	s_add_u32 s36, s36, 0x40080
	v_lshl_add_u64 v[226:227], v[228:229], 0, s[12:13]
	s_addc_u32 s37, s37, 0
	s_add_i32 s38, s60, s42
	global_load_lds_dwordx4 v[226:227], off
	v_lshl_add_u64 v[226:227], s[36:37], 0, v[130:131]
	s_mov_b32 m0, s38
	s_nop 0
	global_load_lds_dwordx4 v[226:227], off
	v_lshl_add_u64 v[226:227], s[36:37], 0, v[134:135]
	s_add_i32 m0, s38, 0x2000
	s_nop 0
	global_load_lds_dwordx4 v[226:227], off
	v_lshl_add_u64 v[226:227], v[230:231], 0, s[12:13]
	s_mov_b32 m0, s47
	s_nop 0
	global_load_lds_dwordx4 v[226:227], off
	v_lshl_add_u64 v[226:227], v[232:233], 0, s[12:13]
	s_mov_b32 m0, s48
	s_nop 0
	global_load_lds_dwordx4 v[226:227], off
	s_waitcnt vmcnt(8)
	s_waitcnt lgkmcnt(0)
	s_barrier
	s_waitcnt lgkmcnt(0)
	v_mfma_f32_16x16x32_bf16 v[56:59], v[154:157], v[194:197], v[56:59]
	v_mfma_f32_16x16x32_bf16 v[52:55], v[170:173], v[194:197], v[52:55]
	v_mfma_f32_16x16x32_bf16 v[40:43], v[154:157], v[202:205], v[40:43]
	v_mfma_f32_16x16x32_bf16 v[36:39], v[170:173], v[202:205], v[36:39]
	v_mfma_f32_16x16x32_bf16 v[24:27], v[154:157], v[210:213], v[24:27]
	v_mfma_f32_16x16x32_bf16 v[20:23], v[170:173], v[210:213], v[20:23]
	v_mfma_f32_16x16x32_bf16 v[8:11], v[154:157], v[218:221], v[8:11]
	v_mfma_f32_16x16x32_bf16 v[4:7], v[170:173], v[218:221], v[4:7]
	v_mfma_f32_16x16x32_bf16 v[56:59], v[166:169], v[198:201], v[56:59]
	v_mfma_f32_16x16x32_bf16 v[52:55], v[174:177], v[198:201], v[52:55]
	v_mfma_f32_16x16x32_bf16 v[40:43], v[166:169], v[206:209], v[40:43]
	v_mfma_f32_16x16x32_bf16 v[36:39], v[174:177], v[206:209], v[36:39]
	v_mfma_f32_16x16x32_bf16 v[24:27], v[166:169], v[214:217], v[24:27]
	v_mfma_f32_16x16x32_bf16 v[20:23], v[174:177], v[214:217], v[20:23]
	v_mfma_f32_16x16x32_bf16 v[8:11], v[166:169], v[222:225], v[8:11]
	v_mfma_f32_16x16x32_bf16 v[4:7], v[174:177], v[222:225], v[4:7]
	v_mfma_f32_16x16x32_bf16 v[60:63], v[178:181], v[194:197], v[60:63]
	v_mfma_f32_16x16x32_bf16 v[48:51], v[186:189], v[194:197], v[48:51]
	v_mfma_f32_16x16x32_bf16 v[44:47], v[178:181], v[202:205], v[44:47]
	v_mfma_f32_16x16x32_bf16 v[32:35], v[186:189], v[202:205], v[32:35]
	v_mfma_f32_16x16x32_bf16 v[28:31], v[178:181], v[210:213], v[28:31]
	v_mfma_f32_16x16x32_bf16 v[16:19], v[186:189], v[210:213], v[16:19]
	v_mfma_f32_16x16x32_bf16 v[12:15], v[178:181], v[218:221], v[12:15]
	v_mfma_f32_16x16x32_bf16 v[0:3], v[186:189], v[218:221], v[0:3]
	v_mfma_f32_16x16x32_bf16 v[60:63], v[182:185], v[198:201], v[60:63]
	v_mfma_f32_16x16x32_bf16 v[48:51], v[190:193], v[198:201], v[48:51]
	v_mfma_f32_16x16x32_bf16 v[44:47], v[182:185], v[206:209], v[44:47]
	v_mfma_f32_16x16x32_bf16 v[32:35], v[190:193], v[206:209], v[32:35]
	v_mfma_f32_16x16x32_bf16 v[28:31], v[182:185], v[214:217], v[28:31]
	v_mfma_f32_16x16x32_bf16 v[16:19], v[190:193], v[214:217], v[16:19]
	v_mfma_f32_16x16x32_bf16 v[12:15], v[182:185], v[222:225], v[12:15]
	v_mfma_f32_16x16x32_bf16 v[0:3], v[190:193], v[222:225], v[0:3]
	s_barrier
	s_add_i32 s58, s58, 2
	s_add_u32 s34, s34, 0x100
	s_addc_u32 s35, s35, 0
	s_add_u32 s56, s56, 0x100
	s_addc_u32 s57, s57, 0
	s_cmp_gt_u32 s58, 13
	s_cbranch_scc0 .LBB0_1131
	s_and_b64 vcc, exec, s[14:15]
	s_cbranch_vccz .LBB0_1136
	s_barrier
	v_lshl_add_u32 v154, s30, 8, v158
	s_cmp_gt_i32 s28, 21
	s_mov_b64 s[30:31], -1
	s_cbranch_scc1 .LBB0_1137

.LBB0_1202:
	v_cndmask_b32_e64 v1, 0, 1, s[4:5]
	v_cmp_ne_u32_e64 s[2:3], 1, v1
	s_andn2_b64 vcc, exec, s[4:5]
	s_cbranch_vccnz .LBB0_1242
	v_ashrrev_i32_e32 v2, 31, v0
	v_lshrrev_b32_e32 v2, 26, v2
	v_lshlrev_b32_e32 v1, 4, v0
	v_add_u32_e32 v2, v0, v2
	v_bfe_i32 v0, v0, 27, 1
	v_lshrrev_b32_e32 v0, 22, v0
	v_add_u32_e32 v0, v1, v0
	v_and_b32_e32 v0, 0xfffffc00, v0
	v_sub_u32_e32 v0, v1, v0
	v_ashrrev_i32_e32 v9, 6, v2
	v_lshrrev_b32_e32 v2, 4, v0
	v_bitop3_b32 v0, v2, v0, 32 bitop3:0x6c
	v_ashrrev_i32_e32 v3, 31, v0
	v_lshrrev_b32_e32 v3, 26, v3
	v_add_u32_e32 v3, v0, v3
	v_lshlrev_b32_e32 v2, 3, v9
	v_ashrrev_i32_e32 v11, 6, v3
	v_and_b32_e32 v3, 0xc0, v3
	v_and_b32_e32 v2, 0xfffff0, v2
	v_sub_u32_e32 v0, v0, v3
	v_mov_b32_e32 v3, 1
	v_add_u32_e32 v2, v11, v2
	v_lshlrev_b32_e32 v4, 5, v9
	v_ashrrev_i16_sdwa v0, v3, sext(v0) dst_sel:DWORD dst_unused:UNUSED_PAD src0_sel:DWORD src1_sel:BYTE_0
	s_movk_i32 s7, 0xb00
	v_and_b32_e32 v10, 32, v4
	v_bfe_i32 v12, v0, 0, 16
	v_mul_lo_u32 v0, v2, s7
	v_or_b32_e32 v0, v0, v10
	v_add_lshl_u32 v128, v0, v12, 1
	v_add_u32_e32 v0, 0x2000, v1
	v_ashrrev_i32_e32 v1, 31, v0
	v_lshrrev_b32_e32 v1, 22, v1
	v_add_u32_e32 v1, v0, v1
	v_ashrrev_i32_e32 v13, 10, v1
	v_mul_i32_i24_e32 v1, 0x400, v13
	v_sub_u32_e32 v0, v0, v1
	v_lshrrev_b32_e32 v1, 4, v0
	v_bitop3_b32 v0, v1, v0, 32 bitop3:0x6c
	v_ashrrev_i32_e32 v2, 31, v0
	s_add_u32 s34, s70, 0x3f00000
	v_lshrrev_b32_e32 v2, 26, v2
	s_addc_u32 s35, s71, 0
	s_ashr_i32 s4, s6, 6
	v_add_u32_e32 v2, v0, v2
	v_lshlrev_b32_e32 v1, 3, v13
	v_ashrrev_i32_e32 v14, 6, v2
	v_and_b32_e32 v2, 0xc0, v2
	s_ashr_i32 s5, s6, 8
	s_lshl_b32 s36, s4, 10
	s_mul_i32 s9, s14, 0x160000
	v_and_b32_e32 v1, 0xfffff0, v1
	v_sub_u32_e32 v0, v0, v2
	s_mul_hi_i32 s8, s14, 0x160000
	s_add_u32 s26, s34, s9
	v_add_u32_e32 v1, v14, v1
	v_lshlrev_b32_e32 v4, 5, v13
	v_ashrrev_i16_sdwa v0, v3, sext(v0) dst_sel:DWORD dst_unused:UNUSED_PAD src0_sel:DWORD src1_sel:BYTE_0
	s_addc_u32 s27, s35, s8
	s_add_i32 s37, s36, 0
	v_and_b32_e32 v15, 32, v4
	v_bfe_i32 v16, v0, 0, 16
	v_mul_lo_u32 v0, v1, s7
	s_add_i32 m0, s37, 0x10000
	v_or_b32_e32 v0, v0, v15
	global_load_lds_dwordx4 v128, s[26:27]
	s_add_i32 m0, s37, 0x12000
	v_add_lshl_u32 v130, v0, v16, 1
	s_add_u32 s8, s26, 0xb0000
	global_load_lds_dwordx4 v130, s[26:27]
	s_addc_u32 s9, s27, 0
	s_add_i32 m0, s37, 0x14000
	s_mul_i32 s16, s51, 0x160000
	global_load_lds_dwordx4 v128, s[8:9]
	s_add_i32 m0, s37, 0x16000
	s_mul_hi_i32 s15, s51, 0x160000
	s_add_u32 s24, s72, s16
	s_addc_u32 s25, s73, s15
	s_add_i32 s38, s37, 0x2000
	global_load_lds_dwordx4 v130, s[8:9]
	s_mov_b32 m0, s37
	s_add_u32 s8, s24, 0xb0000
	global_load_lds_dwordx4 v128, s[24:25]
	s_mov_b32 m0, s38
	s_addc_u32 s9, s25, 0
	s_add_i32 s39, s37, 0x4000
	global_load_lds_dwordx4 v130, s[24:25]
	s_mov_b32 m0, s39
	s_add_i32 s40, s37, 0x6000
	global_load_lds_dwordx4 v128, s[8:9]
	s_mov_b32 m0, s40
	v_mov_b32_e32 v129, 0
	global_load_lds_dwordx4 v130, s[8:9]
	v_mov_b32_e32 v131, v129
	s_cmp_eq_u32 s5, 1
	s_mov_b32 s15, 0
	v_lshl_add_u64 v[6:7], s[26:27], 0, v[128:129]
	v_lshl_add_u64 v[4:5], s[26:27], 0, v[130:131]
	v_lshl_add_u64 v[0:1], s[24:25], 0, v[128:129]
	s_cselect_b64 s[16:17], -1, 0
	s_cmp_lg_u32 s5, 1
	v_lshl_add_u64 v[2:3], s[24:25], 0, v[130:131]
	s_cbranch_scc1 .LBB0_1205
	s_barrier
	s_setprio 1

.LBB0_1219:
	ds_read_b128 v[140:143], v147
	ds_read_b128 v[152:155], v147 offset:1024
	ds_read_b128 v[156:159], v147 offset:2048
	ds_read_b128 v[160:163], v147 offset:3072
	ds_read_b128 v[164:167], v148
	ds_read_b128 v[168:171], v148 offset:1024
	ds_read_b128 v[172:175], v148 offset:2048
	ds_read_b128 v[176:179], v148 offset:3072
	s_add_u32 s26, s24, 0x100
	s_addc_u32 s27, s25, 0
	s_cmp_eq_u32 s54, 40
	s_cselect_b32 s31, s9, s27
	s_cselect_b32 s30, s8, s26
	s_cselect_b32 s29, s23, s53
	s_cselect_b32 s28, s22, s52
	v_lshl_add_u64 v[212:213], s[24:25], 0, v[132:133]
	s_add_i32 m0, s37, 0xc000
	ds_read_b128 v[180:183], v149
	ds_read_b128 v[184:187], v149 offset:1024
	ds_read_b128 v[188:191], v149 offset:2048
	ds_read_b128 v[192:195], v149 offset:3072
	ds_read_b128 v[196:199], v149 offset:4096
	ds_read_b128 v[200:203], v149 offset:5120
	ds_read_b128 v[204:207], v149 offset:6144
	ds_read_b128 v[208:211], v149 offset:7168
	global_load_lds_dwordx4 v[212:213], off
	v_lshl_add_u64 v[212:213], s[24:25], 0, v[134:135]
	s_add_i32 m0, s37, 0xe000
	s_nop 0
	global_load_lds_dwordx4 v[212:213], off
	s_waitcnt vmcnt(8)
	s_waitcnt lgkmcnt(0)
	s_barrier
	s_waitcnt lgkmcnt(0)
	v_mfma_f32_16x16x32_bf16 v[124:127], v[140:143], v[180:183], v[124:127]
	v_mfma_f32_16x16x32_bf16 v[120:123], v[156:159], v[180:183], v[120:123]
	v_mfma_f32_16x16x32_bf16 v[108:111], v[140:143], v[188:191], v[108:111]
	v_mfma_f32_16x16x32_bf16 v[104:107], v[156:159], v[188:191], v[104:107]
	v_mfma_f32_16x16x32_bf16 v[92:95], v[140:143], v[196:199], v[92:95]
	v_mfma_f32_16x16x32_bf16 v[88:91], v[156:159], v[196:199], v[88:91]
	v_mfma_f32_16x16x32_bf16 v[76:79], v[140:143], v[204:207], v[76:79]
	v_mfma_f32_16x16x32_bf16 v[72:75], v[156:159], v[204:207], v[72:75]
	v_mfma_f32_16x16x32_bf16 v[124:127], v[152:155], v[184:187], v[124:127]
	v_mfma_f32_16x16x32_bf16 v[120:123], v[160:163], v[184:187], v[120:123]
	v_mfma_f32_16x16x32_bf16 v[108:111], v[152:155], v[192:195], v[108:111]
	v_mfma_f32_16x16x32_bf16 v[104:107], v[160:163], v[192:195], v[104:107]
	v_mfma_f32_16x16x32_bf16 v[92:95], v[152:155], v[200:203], v[92:95]
	v_mfma_f32_16x16x32_bf16 v[88:91], v[160:163], v[200:203], v[88:91]
	v_mfma_f32_16x16x32_bf16 v[76:79], v[152:155], v[208:211], v[76:79]
	v_mfma_f32_16x16x32_bf16 v[72:75], v[160:163], v[208:211], v[72:75]
	v_mfma_f32_16x16x32_bf16 v[116:119], v[164:167], v[180:183], v[116:119]
	v_mfma_f32_16x16x32_bf16 v[112:115], v[172:175], v[180:183], v[112:115]
	v_mfma_f32_16x16x32_bf16 v[100:103], v[164:167], v[188:191], v[100:103]
	v_mfma_f32_16x16x32_bf16 v[96:99], v[172:175], v[188:191], v[96:99]
	v_mfma_f32_16x16x32_bf16 v[84:87], v[164:167], v[196:199], v[84:87]
	v_mfma_f32_16x16x32_bf16 v[80:83], v[172:175], v[196:199], v[80:83]
	v_mfma_f32_16x16x32_bf16 v[68:71], v[164:167], v[204:207], v[68:71]
	v_mfma_f32_16x16x32_bf16 v[64:67], v[172:175], v[204:207], v[64:67]
	v_mfma_f32_16x16x32_bf16 v[116:119], v[168:171], v[184:187], v[116:119]
	v_mfma_f32_16x16x32_bf16 v[112:115], v[176:179], v[184:187], v[112:115]
	v_mfma_f32_16x16x32_bf16 v[100:103], v[168:171], v[192:195], v[100:103]
	v_mfma_f32_16x16x32_bf16 v[96:99], v[176:179], v[192:195], v[96:99]
	v_mfma_f32_16x16x32_bf16 v[84:87], v[168:171], v[200:203], v[84:87]
	v_mfma_f32_16x16x32_bf16 v[80:83], v[176:179], v[200:203], v[80:83]
	v_mfma_f32_16x16x32_bf16 v[68:71], v[168:171], v[208:211], v[68:71]
	v_mfma_f32_16x16x32_bf16 v[64:67], v[176:179], v[208:211], v[64:67]
	s_barrier
	s_add_i32 s24, s46, s36
	v_lshl_add_u64 v[212:213], s[28:29], 0, v[128:129]
	s_mov_b32 m0, s24
	ds_read_b128 v[180:183], v149 offset:16384
	ds_read_b128 v[184:187], v149 offset:17408
	ds_read_b128 v[188:191], v149 offset:18432
	ds_read_b128 v[192:195], v149 offset:19456
	ds_read_b128 v[196:199], v149 offset:20480
	ds_read_b128 v[200:203], v149 offset:21504
	ds_read_b128 v[204:207], v149 offset:22528
	ds_read_b128 v[208:211], v149 offset:23552
	global_load_lds_dwordx4 v[212:213], off
	s_add_i32 m0, s24, 0x2000
	s_add_u32 s24, s28, 0xb0000
	v_lshl_add_u64 v[214:215], s[28:29], 0, v[130:131]
	s_addc_u32 s25, s29, 0
	s_add_i32 s55, s47, s36
	global_load_lds_dwordx4 v[214:215], off
	v_lshl_add_u64 v[216:217], s[24:25], 0, v[128:129]
	s_mov_b32 m0, s55
	v_lshl_add_u64 v[218:219], s[30:31], 0, v[130:131]
	global_load_lds_dwordx4 v[216:217], off
	v_lshl_add_u64 v[216:217], s[24:25], 0, v[130:131]
	s_add_i32 m0, s55, 0x2000
	s_nop 0
	global_load_lds_dwordx4 v[216:217], off
	v_lshl_add_u64 v[216:217], s[30:31], 0, v[128:129]
	s_mov_b32 m0, s37
	s_nop 0
	global_load_lds_dwordx4 v[216:217], off
	s_mov_b32 m0, s38
	s_nop 0
	global_load_lds_dwordx4 v[218:219], off
	s_waitcnt vmcnt(8)
	s_waitcnt lgkmcnt(0)
	s_barrier
	s_waitcnt lgkmcnt(0)
	v_mfma_f32_16x16x32_bf16 v[60:63], v[140:143], v[180:183], v[60:63]
	v_mfma_f32_16x16x32_bf16 v[56:59], v[156:159], v[180:183], v[56:59]
	v_mfma_f32_16x16x32_bf16 v[44:47], v[140:143], v[188:191], v[44:47]
	v_mfma_f32_16x16x32_bf16 v[40:43], v[156:159], v[188:191], v[40:43]
	v_mfma_f32_16x16x32_bf16 v[28:31], v[140:143], v[196:199], v[28:31]
	v_mfma_f32_16x16x32_bf16 v[24:27], v[156:159], v[196:199], v[24:27]
	v_mfma_f32_16x16x32_bf16 v[12:15], v[140:143], v[204:207], v[12:15]
	v_mfma_f32_16x16x32_bf16 v[8:11], v[156:159], v[204:207], v[8:11]
	v_mfma_f32_16x16x32_bf16 v[60:63], v[152:155], v[184:187], v[60:63]
	v_mfma_f32_16x16x32_bf16 v[56:59], v[160:163], v[184:187], v[56:59]
	v_mfma_f32_16x16x32_bf16 v[44:47], v[152:155], v[192:195], v[44:47]
	v_mfma_f32_16x16x32_bf16 v[40:43], v[160:163], v[192:195], v[40:43]
	v_mfma_f32_16x16x32_bf16 v[28:31], v[152:155], v[200:203], v[28:31]
	v_mfma_f32_16x16x32_bf16 v[24:27], v[160:163], v[200:203], v[24:27]
	v_mfma_f32_16x16x32_bf16 v[12:15], v[152:155], v[208:211], v[12:15]
	v_mfma_f32_16x16x32_bf16 v[8:11], v[160:163], v[208:211], v[8:11]
	v_mfma_f32_16x16x32_bf16 v[52:55], v[164:167], v[180:183], v[52:55]
	v_mfma_f32_16x16x32_bf16 v[48:51], v[172:175], v[180:183], v[48:51]
	v_mfma_f32_16x16x32_bf16 v[36:39], v[164:167], v[188:191], v[36:39]
	v_mfma_f32_16x16x32_bf16 v[32:35], v[172:175], v[188:191], v[32:35]
	v_mfma_f32_16x16x32_bf16 v[20:23], v[164:167], v[196:199], v[20:23]
	v_mfma_f32_16x16x32_bf16 v[16:19], v[172:175], v[196:199], v[16:19]
	v_mfma_f32_16x16x32_bf16 v[4:7], v[164:167], v[204:207], v[4:7]
	v_mfma_f32_16x16x32_bf16 v[0:3], v[172:175], v[204:207], v[0:3]
	v_mfma_f32_16x16x32_bf16 v[52:55], v[168:171], v[184:187], v[52:55]
	v_mfma_f32_16x16x32_bf16 v[48:51], v[176:179], v[184:187], v[48:51]
	v_mfma_f32_16x16x32_bf16 v[36:39], v[168:171], v[192:195], v[36:39]
	v_mfma_f32_16x16x32_bf16 v[32:35], v[176:179], v[192:195], v[32:35]
	v_mfma_f32_16x16x32_bf16 v[20:23], v[168:171], v[200:203], v[20:23]
	v_mfma_f32_16x16x32_bf16 v[16:19], v[176:179], v[200:203], v[16:19]
	v_mfma_f32_16x16x32_bf16 v[4:7], v[168:171], v[208:211], v[4:7]
	v_mfma_f32_16x16x32_bf16 v[0:3], v[176:179], v[208:211], v[0:3]
	s_barrier
	s_add_i32 s55, 0, 0x18000
	v_add_u32_e32 v151, s55, v145
	s_add_i32 s56, 0, 0x1c000
	ds_read_b128 v[140:143], v151
	ds_read_b128 v[152:155], v151 offset:1024
	ds_read_b128 v[156:159], v151 offset:2048
	ds_read_b128 v[160:163], v151 offset:3072
	v_add_u32_e32 v151, s56, v145
	ds_read_b128 v[164:167], v151
	ds_read_b128 v[168:171], v151 offset:1024
	ds_read_b128 v[172:175], v151 offset:2048
	ds_read_b128 v[176:179], v151 offset:3072
	s_add_u32 s24, s30, 0xb0000
	s_addc_u32 s25, s31, 0
	s_mov_b32 m0, s39
	v_lshl_add_u64 v[220:221], s[24:25], 0, v[128:129]
	ds_read_b128 v[180:183], v149 offset:32768
	ds_read_b128 v[184:187], v149 offset:33792
	ds_read_b128 v[188:191], v149 offset:34816
	ds_read_b128 v[192:195], v149 offset:35840
	ds_read_b128 v[196:199], v149 offset:36864
	ds_read_b128 v[200:203], v149 offset:37888
	ds_read_b128 v[204:207], v149 offset:38912
	ds_read_b128 v[208:211], v149 offset:39936
	global_load_lds_dwordx4 v[220:221], off
	v_lshl_add_u64 v[220:221], s[24:25], 0, v[130:131]
	s_mov_b32 m0, s40
	s_nop 0
	global_load_lds_dwordx4 v[220:221], off
	s_waitcnt vmcnt(8)
	s_waitcnt lgkmcnt(0)
	s_barrier
	s_waitcnt lgkmcnt(0)
	v_mfma_f32_16x16x32_bf16 v[124:127], v[140:143], v[180:183], v[124:127]
	v_mfma_f32_16x16x32_bf16 v[120:123], v[156:159], v[180:183], v[120:123]
	v_mfma_f32_16x16x32_bf16 v[108:111], v[140:143], v[188:191], v[108:111]
	v_mfma_f32_16x16x32_bf16 v[104:107], v[156:159], v[188:191], v[104:107]
	v_mfma_f32_16x16x32_bf16 v[92:95], v[140:143], v[196:199], v[92:95]
	v_mfma_f32_16x16x32_bf16 v[88:91], v[156:159], v[196:199], v[88:91]
	v_mfma_f32_16x16x32_bf16 v[76:79], v[140:143], v[204:207], v[76:79]
	v_mfma_f32_16x16x32_bf16 v[72:75], v[156:159], v[204:207], v[72:75]
	v_mfma_f32_16x16x32_bf16 v[124:127], v[152:155], v[184:187], v[124:127]
	v_mfma_f32_16x16x32_bf16 v[120:123], v[160:163], v[184:187], v[120:123]
	v_mfma_f32_16x16x32_bf16 v[108:111], v[152:155], v[192:195], v[108:111]
	v_mfma_f32_16x16x32_bf16 v[104:107], v[160:163], v[192:195], v[104:107]
	v_mfma_f32_16x16x32_bf16 v[92:95], v[152:155], v[200:203], v[92:95]
	v_mfma_f32_16x16x32_bf16 v[88:91], v[160:163], v[200:203], v[88:91]
	v_mfma_f32_16x16x32_bf16 v[76:79], v[152:155], v[208:211], v[76:79]
	v_mfma_f32_16x16x32_bf16 v[72:75], v[160:163], v[208:211], v[72:75]
	v_mfma_f32_16x16x32_bf16 v[116:119], v[164:167], v[180:183], v[116:119]
	v_mfma_f32_16x16x32_bf16 v[112:115], v[172:175], v[180:183], v[112:115]
	v_mfma_f32_16x16x32_bf16 v[100:103], v[164:167], v[188:191], v[100:103]
	v_mfma_f32_16x16x32_bf16 v[96:99], v[172:175], v[188:191], v[96:99]
	v_mfma_f32_16x16x32_bf16 v[84:87], v[164:167], v[196:199], v[84:87]
	v_mfma_f32_16x16x32_bf16 v[80:83], v[172:175], v[196:199], v[80:83]
	v_mfma_f32_16x16x32_bf16 v[68:71], v[164:167], v[204:207], v[68:71]
	v_mfma_f32_16x16x32_bf16 v[64:67], v[172:175], v[204:207], v[64:67]
	v_mfma_f32_16x16x32_bf16 v[116:119], v[168:171], v[184:187], v[116:119]
	v_mfma_f32_16x16x32_bf16 v[112:115], v[176:179], v[184:187], v[112:115]
	v_mfma_f32_16x16x32_bf16 v[100:103], v[168:171], v[192:195], v[100:103]
	v_mfma_f32_16x16x32_bf16 v[96:99], v[176:179], v[192:195], v[96:99]
	v_mfma_f32_16x16x32_bf16 v[84:87], v[168:171], v[200:203], v[84:87]
	v_mfma_f32_16x16x32_bf16 v[80:83], v[176:179], v[200:203], v[80:83]
	v_mfma_f32_16x16x32_bf16 v[68:71], v[168:171], v[208:211], v[68:71]
	v_mfma_f32_16x16x32_bf16 v[64:67], v[176:179], v[208:211], v[64:67]
	s_barrier
	s_add_i32 s24, s55, s36
	v_lshl_add_u64 v[212:213], v[212:213], 0, s[18:19]
	s_mov_b32 m0, s24
	ds_read_b128 v[180:183], v149 offset:49152
	ds_read_b128 v[184:187], v149 offset:50176
	ds_read_b128 v[188:191], v149 offset:51200
	ds_read_b128 v[192:195], v149 offset:52224
	ds_read_b128 v[196:199], v149 offset:53248
	ds_read_b128 v[200:203], v149 offset:54272
	ds_read_b128 v[204:207], v149 offset:55296
	ds_read_b128 v[208:211], v149 offset:56320
	global_load_lds_dwordx4 v[212:213], off
	s_add_i32 m0, s24, 0x2000
	s_add_u32 s24, s28, 0xb0080
	v_lshl_add_u64 v[212:213], v[214:215], 0, s[18:19]
	s_addc_u32 s25, s29, 0
	s_add_i32 s28, s56, s36
	global_load_lds_dwordx4 v[212:213], off
	v_lshl_add_u64 v[212:213], s[24:25], 0, v[128:129]
	s_mov_b32 m0, s28
	s_nop 0
	global_load_lds_dwordx4 v[212:213], off
	v_lshl_add_u64 v[212:213], s[24:25], 0, v[130:131]
	s_add_i32 m0, s28, 0x2000
	s_nop 0
	global_load_lds_dwordx4 v[212:213], off
	v_lshl_add_u64 v[212:213], v[216:217], 0, s[18:19]
	s_mov_b32 m0, s42
	s_nop 0
	global_load_lds_dwordx4 v[212:213], off
	v_lshl_add_u64 v[212:213], v[218:219], 0, s[18:19]
	s_mov_b32 m0, s43
	s_nop 0
	global_load_lds_dwordx4 v[212:213], off
	s_waitcnt vmcnt(8)
	s_waitcnt lgkmcnt(0)
	s_barrier
	s_waitcnt lgkmcnt(0)
	v_mfma_f32_16x16x32_bf16 v[60:63], v[140:143], v[180:183], v[60:63]
	v_mfma_f32_16x16x32_bf16 v[56:59], v[156:159], v[180:183], v[56:59]
	v_mfma_f32_16x16x32_bf16 v[44:47], v[140:143], v[188:191], v[44:47]
	v_mfma_f32_16x16x32_bf16 v[40:43], v[156:159], v[188:191], v[40:43]
	v_mfma_f32_16x16x32_bf16 v[28:31], v[140:143], v[196:199], v[28:31]
	v_mfma_f32_16x16x32_bf16 v[24:27], v[156:159], v[196:199], v[24:27]
	v_mfma_f32_16x16x32_bf16 v[12:15], v[140:143], v[204:207], v[12:15]
	v_mfma_f32_16x16x32_bf16 v[8:11], v[156:159], v[204:207], v[8:11]
	v_mfma_f32_16x16x32_bf16 v[60:63], v[152:155], v[184:187], v[60:63]
	v_mfma_f32_16x16x32_bf16 v[56:59], v[160:163], v[184:187], v[56:59]
	v_mfma_f32_16x16x32_bf16 v[44:47], v[152:155], v[192:195], v[44:47]
	v_mfma_f32_16x16x32_bf16 v[40:43], v[160:163], v[192:195], v[40:43]
	v_mfma_f32_16x16x32_bf16 v[28:31], v[152:155], v[200:203], v[28:31]
	v_mfma_f32_16x16x32_bf16 v[24:27], v[160:163], v[200:203], v[24:27]
	v_mfma_f32_16x16x32_bf16 v[12:15], v[152:155], v[208:211], v[12:15]
	v_mfma_f32_16x16x32_bf16 v[8:11], v[160:163], v[208:211], v[8:11]
	v_mfma_f32_16x16x32_bf16 v[52:55], v[164:167], v[180:183], v[52:55]
	v_mfma_f32_16x16x32_bf16 v[48:51], v[172:175], v[180:183], v[48:51]
	v_mfma_f32_16x16x32_bf16 v[36:39], v[164:167], v[188:191], v[36:39]
	v_mfma_f32_16x16x32_bf16 v[32:35], v[172:175], v[188:191], v[32:35]
	v_mfma_f32_16x16x32_bf16 v[20:23], v[164:167], v[196:199], v[20:23]
	v_mfma_f32_16x16x32_bf16 v[16:19], v[172:175], v[196:199], v[16:19]
	v_mfma_f32_16x16x32_bf16 v[4:7], v[164:167], v[204:207], v[4:7]
	v_mfma_f32_16x16x32_bf16 v[0:3], v[172:175], v[204:207], v[0:3]
	v_mfma_f32_16x16x32_bf16 v[52:55], v[168:171], v[184:187], v[52:55]
	v_mfma_f32_16x16x32_bf16 v[48:51], v[176:179], v[184:187], v[48:51]
	v_mfma_f32_16x16x32_bf16 v[36:39], v[168:171], v[192:195], v[36:39]
	v_mfma_f32_16x16x32_bf16 v[32:35], v[176:179], v[192:195], v[32:35]
	v_mfma_f32_16x16x32_bf16 v[20:23], v[168:171], v[200:203], v[20:23]
	v_mfma_f32_16x16x32_bf16 v[16:19], v[176:179], v[200:203], v[16:19]
	v_mfma_f32_16x16x32_bf16 v[4:7], v[168:171], v[208:211], v[4:7]
	v_mfma_f32_16x16x32_bf16 v[0:3], v[176:179], v[208:211], v[0:3]
	s_barrier
	s_add_i32 s54, s54, 2
	s_add_u32 s52, s52, 0x100
	s_addc_u32 s53, s53, 0
	s_cmp_gt_u32 s54, 41
	s_mov_b64 s[24:25], s[26:27]
	s_cbranch_scc0 .LBB0_1219
	s_and_b64 vcc, exec, s[20:21]
	s_cbranch_vccz .LBB0_1222
	s_barrier

.LBB0_1247:
	v_ashrrev_i32_e32 v2, 31, v0
	v_lshrrev_b32_e32 v2, 26, v2
	s_waitcnt lgkmcnt(0)
	v_lshlrev_b32_e32 v1, 4, v0
	v_add_u32_e32 v2, v0, v2
	v_bfe_i32 v0, v0, 27, 1
	v_lshrrev_b32_e32 v0, 22, v0
	v_add_u32_e32 v0, v1, v0
	v_and_b32_e32 v0, 0xfffffc00, v0
	v_sub_u32_e32 v0, v1, v0
	v_lshrrev_b32_e32 v3, 4, v0
	v_bitop3_b32 v0, v3, v0, 32 bitop3:0x6c
	v_ashrrev_i32_e32 v4, 31, v0
	v_ashrrev_i32_e32 v2, 6, v2
	v_lshrrev_b32_e32 v4, 26, v4
	v_lshlrev_b32_e32 v3, 3, v2
	v_add_u32_e32 v4, v0, v4
	v_and_b32_e32 v3, -16, v3
	v_ashrrev_i32_e32 v5, 6, v4
	v_and_b32_e32 v4, 0xc0, v4
	v_add_u32_e32 v3, v5, v3
	v_sub_u32_e32 v0, v0, v4
	v_mov_b32_e32 v4, 1
	s_ashr_i32 s4, s7, 3
	v_lshlrev_b32_e32 v2, 5, v2
	v_ashrrev_i16_sdwa v0, v4, sext(v0) dst_sel:DWORD dst_unused:UNUSED_PAD src0_sel:DWORD src1_sel:BYTE_0
	v_lshlrev_b32_e32 v6, 1, v3
	v_lshrrev_b32_e32 v7, 2, v3
	v_and_b32_e32 v5, 3, v5
	s_mov_b32 s7, 0x7fffe0
	v_and_b32_e32 v2, 32, v2
	v_bfe_i32 v0, v0, 0, 16
	v_and_b32_e32 v6, 24, v6
	v_and_b32_e32 v7, 4, v7
	v_and_or_b32 v5, v3, s7, v5
	v_or3_b32 v5, v5, v7, v6
	v_add_lshl_u32 v0, v2, v0, 1
	v_lshl_add_u32 v128, v3, 9, v0
	v_lshl_add_u32 v130, v5, 9, v0
	v_add_u32_e32 v0, 0x2000, v1
	v_ashrrev_i32_e32 v1, 31, v0
	v_lshrrev_b32_e32 v1, 22, v1
	v_add_u32_e32 v1, v0, v1
	v_ashrrev_i32_e32 v1, 10, v1
	v_mul_i32_i24_e32 v2, 0x400, v1
	v_sub_u32_e32 v0, v0, v2
	v_lshrrev_b32_e32 v2, 4, v0
	v_bitop3_b32 v0, v2, v0, 32 bitop3:0x6c
	s_add_u32 s42, s70, 0x5500000
	v_ashrrev_i32_e32 v3, 31, v0
	s_addc_u32 s43, s71, 0
	v_lshrrev_b32_e32 v3, 26, v3
	s_add_i32 s4, s6, s4
	v_lshlrev_b32_e32 v2, 3, v1
	v_add_u32_e32 v3, v0, v3
	s_ashr_i32 s6, s4, 31
	v_and_b32_e32 v2, -16, v2
	v_ashrrev_i32_e32 v5, 6, v3
	s_lshr_b32 s6, s6, 27
	v_add_u32_e32 v2, v5, v2
	v_and_b32_e32 v5, 3, v5
	s_add_i32 s6, s4, s6
	v_and_or_b32 v5, v2, s7, v5
	s_ashr_i32 s7, s6, 5
	s_andn2_b32 s6, s6, 31
	s_sub_i32 s6, s4, s6
	s_bfe_i32 s4, s6, 0x80000
	s_bfe_u32 s4, s4, 0x3000c
	s_add_i32 s8, s6, s4
	s_bfe_i32 s4, s8, 0x80000
	s_and_b32 s8, s8, 0xf8
	s_sub_i32 s6, s6, s8
	s_lshl_b32 s7, s7, 3
	s_sext_i32_i16 s4, s4
	s_sext_i32_i8 s6, s6
	s_ashr_i32 s5, s14, 8
	s_lshr_b32 s4, s4, 3
	s_add_i32 s30, s7, s6
	s_ashr_i32 s12, s14, 6
	s_ashr_i32 s31, s30, 31
	s_bfe_i64 s[8:9], s[4:5], 0x100000
	v_and_b32_e32 v3, 0xc0, v3
	s_lshl_b32 s44, s12, 10
	s_lshl_b64 s[6:7], s[30:31], 17
	s_lshl_b64 s[8:9], s[8:9], 17
	v_sub_u32_e32 v0, v0, v3
	s_add_u32 s36, s42, s8
	v_lshlrev_b32_e32 v1, 5, v1
	v_ashrrev_i16_sdwa v0, v4, sext(v0) dst_sel:DWORD dst_unused:UNUSED_PAD src0_sel:DWORD src1_sel:BYTE_0
	v_lshlrev_b32_e32 v3, 1, v2
	v_lshrrev_b32_e32 v4, 2, v2
	s_addc_u32 s37, s43, s9
	s_add_i32 s31, s44, 0
	v_and_b32_e32 v1, 32, v1
	v_bfe_i32 v0, v0, 0, 16
	v_and_b32_e32 v3, 24, v3
	v_and_b32_e32 v4, 4, v4
	s_add_i32 m0, s31, 0x10000
	v_or3_b32 v3, v5, v4, v3
	v_add_lshl_u32 v0, v1, v0, 1
	global_load_lds_dwordx4 v130, s[36:37]
	s_add_i32 m0, s31, 0x12000
	v_lshl_add_u32 v134, v3, 9, v0
	s_add_u32 s8, s36, 0x10000
	global_load_lds_dwordx4 v134, s[36:37]
	s_addc_u32 s9, s37, 0
	s_add_i32 m0, s31, 0x14000
	v_lshl_add_u32 v132, v2, 9, v0
	global_load_lds_dwordx4 v130, s[8:9]
	s_add_i32 m0, s31, 0x16000
	s_add_u32 s34, s48, s6
	s_addc_u32 s35, s49, s7
	s_add_i32 s45, s31, 0x2000
	global_load_lds_dwordx4 v134, s[8:9]
	s_mov_b32 m0, s31
	s_add_u32 s6, s34, 0x10000
	global_load_lds_dwordx4 v128, s[34:35]
	s_mov_b32 m0, s45
	s_addc_u32 s7, s35, 0
	s_add_i32 s46, s31, 0x4000
	global_load_lds_dwordx4 v132, s[34:35]
	s_mov_b32 m0, s46
	s_add_i32 s47, s31, 0x6000
	global_load_lds_dwordx4 v128, s[6:7]
	s_mov_b32 m0, s47
	v_mov_b32_e32 v131, 0
	global_load_lds_dwordx4 v132, s[6:7]
	v_mov_b32_e32 v135, v131
	v_mov_b32_e32 v129, v131
	v_mov_b32_e32 v133, v131
	s_cmp_eq_u32 s5, 1
	v_lshl_add_u64 v[6:7], s[36:37], 0, v[130:131]
	v_lshl_add_u64 v[4:5], s[36:37], 0, v[134:135]
	v_lshl_add_u64 v[0:1], s[34:35], 0, v[128:129]
	s_cselect_b64 s[6:7], -1, 0
	s_cmp_lg_u32 s5, 1
	v_lshl_add_u64 v[2:3], s[34:35], 0, v[132:133]
	s_cbranch_scc1 .LBB0_1249
	s_barrier
	s_setprio 1

.LBB0_1258:
	ds_read_b128 v[0:3], v147
	ds_read_b128 v[4:7], v147 offset:1024
	ds_read_b128 v[8:11], v147 offset:2048
	ds_read_b128 v[12:15], v147 offset:3072
	ds_read_b128 v[16:19], v148
	ds_read_b128 v[20:23], v148 offset:1024
	ds_read_b128 v[24:27], v148 offset:2048
	ds_read_b128 v[28:31], v148 offset:3072
	s_ashr_i32 s25, s24, 31
	s_lshl_b64 s[26:27], s[24:25], 17
	s_add_u32 s26, s48, s26
	s_addc_u32 s27, s49, s27
	s_and_b64 s[28:29], s[4:5], exec
	s_cselect_b32 s41, s27, s35
	s_cselect_b32 s40, s26, s34
	s_ashr_i32 s23, s22, 31
	s_lshl_b64 s[28:29], s[22:23], 17
	s_add_u32 s28, s42, s28
	s_addc_u32 s29, s43, s29
	s_and_b64 s[38:39], s[4:5], exec
	s_cselect_b32 s39, s29, s37
	s_cselect_b32 s38, s28, s36
	s_add_u32 s58, s34, 0x10080
	s_addc_u32 s59, s35, 0
	s_mov_b32 m0, s55
	v_lshl_add_u64 v[64:65], s[58:59], 0, v[128:129]
	ds_read_b128 v[32:35], v149
	ds_read_b128 v[36:39], v149 offset:1024
	ds_read_b128 v[40:43], v149 offset:2048
	ds_read_b128 v[44:47], v149 offset:3072
	ds_read_b128 v[48:51], v149 offset:4096
	ds_read_b128 v[52:55], v149 offset:5120
	ds_read_b128 v[56:59], v149 offset:6144
	ds_read_b128 v[60:63], v149 offset:7168
	global_load_lds_dwordx4 v[64:65], off
	v_lshl_add_u64 v[64:65], s[58:59], 0, v[132:133]
	s_mov_b32 m0, s56
	s_nop 0
	global_load_lds_dwordx4 v[64:65], off
	s_waitcnt vmcnt(8)
	s_waitcnt lgkmcnt(0)
	s_barrier
	s_waitcnt lgkmcnt(0)
	v_mfma_f32_16x16x32_bf16 v[64:67], v[0:3], v[32:35], 0
	v_mfma_f32_16x16x32_bf16 v[68:71], v[8:11], v[32:35], 0
	v_mfma_f32_16x16x32_bf16 v[72:75], v[0:3], v[40:43], 0
	v_mfma_f32_16x16x32_bf16 v[76:79], v[8:11], v[40:43], 0
	v_mfma_f32_16x16x32_bf16 v[80:83], v[0:3], v[48:51], 0
	v_mfma_f32_16x16x32_bf16 v[84:87], v[8:11], v[48:51], 0
	v_mfma_f32_16x16x32_bf16 v[88:91], v[0:3], v[56:59], 0
	v_mfma_f32_16x16x32_bf16 v[92:95], v[8:11], v[56:59], 0
	v_mfma_f32_16x16x32_bf16 v[64:67], v[4:7], v[36:39], v[64:67]
	v_mfma_f32_16x16x32_bf16 v[68:71], v[12:15], v[36:39], v[68:71]
	v_mfma_f32_16x16x32_bf16 v[72:75], v[4:7], v[44:47], v[72:75]
	v_mfma_f32_16x16x32_bf16 v[76:79], v[12:15], v[44:47], v[76:79]
	v_mfma_f32_16x16x32_bf16 v[80:83], v[4:7], v[52:55], v[80:83]
	v_mfma_f32_16x16x32_bf16 v[84:87], v[12:15], v[52:55], v[84:87]
	v_mfma_f32_16x16x32_bf16 v[88:91], v[4:7], v[60:63], v[88:91]
	v_mfma_f32_16x16x32_bf16 v[92:95], v[12:15], v[60:63], v[92:95]
	v_mfma_f32_16x16x32_bf16 v[96:99], v[16:19], v[32:35], 0
	v_mfma_f32_16x16x32_bf16 v[32:35], v[24:27], v[32:35], 0
	v_mfma_f32_16x16x32_bf16 v[96:99], v[20:23], v[36:39], v[96:99]
	v_mfma_f32_16x16x32_bf16 v[32:35], v[28:31], v[36:39], v[32:35]
	v_mfma_f32_16x16x32_bf16 v[36:39], v[16:19], v[40:43], 0
	v_mfma_f32_16x16x32_bf16 v[40:43], v[24:27], v[40:43], 0
	v_mfma_f32_16x16x32_bf16 v[36:39], v[20:23], v[44:47], v[36:39]
	v_mfma_f32_16x16x32_bf16 v[40:43], v[28:31], v[44:47], v[40:43]
	v_mfma_f32_16x16x32_bf16 v[44:47], v[16:19], v[48:51], 0
	v_mfma_f32_16x16x32_bf16 v[48:51], v[24:27], v[48:51], 0
	v_mfma_f32_16x16x32_bf16 v[44:47], v[20:23], v[52:55], v[44:47]
	v_mfma_f32_16x16x32_bf16 v[48:51], v[28:31], v[52:55], v[48:51]
	v_mfma_f32_16x16x32_bf16 v[52:55], v[16:19], v[56:59], 0
	v_mfma_f32_16x16x32_bf16 v[56:59], v[24:27], v[56:59], 0
	v_mfma_f32_16x16x32_bf16 v[52:55], v[20:23], v[60:63], v[52:55]
	v_mfma_f32_16x16x32_bf16 v[56:59], v[28:31], v[60:63], v[56:59]
	s_barrier
	s_add_i32 s59, s53, s44
	v_lshl_add_u64 v[212:213], s[36:37], 0, v[130:131]
	s_add_i32 s23, s59, 0x2000
	v_lshl_add_u64 v[140:141], v[212:213], 0, s[18:19]
	s_mov_b32 m0, s59
	v_lshl_add_u64 v[214:215], s[36:37], 0, v[134:135]
	s_add_u32 s60, s36, 0x10100
	ds_read_b128 v[60:63], v149 offset:16384
	ds_read_b128 v[100:103], v149 offset:17408
	ds_read_b128 v[104:107], v149 offset:18432
	ds_read_b128 v[108:111], v149 offset:19456
	ds_read_b128 v[112:115], v149 offset:20480
	ds_read_b128 v[116:119], v149 offset:21504
	ds_read_b128 v[120:123], v149 offset:22528
	ds_read_b128 v[124:127], v149 offset:23552
	global_load_lds_dwordx4 v[140:141], off
	v_lshl_add_u64 v[140:141], v[214:215], 0, s[18:19]
	s_mov_b32 m0, s23
	s_addc_u32 s61, s37, 0
	s_add_i32 s25, s54, s44
	global_load_lds_dwordx4 v[140:141], off
	v_lshl_add_u64 v[140:141], s[60:61], 0, v[130:131]
	s_mov_b32 m0, s25
	s_add_i32 s58, s25, 0x2000
	global_load_lds_dwordx4 v[140:141], off
	v_lshl_add_u64 v[140:141], s[60:61], 0, v[134:135]
	s_mov_b32 m0, s58
	v_lshl_add_u64 v[216:217], s[34:35], 0, v[128:129]
	global_load_lds_dwordx4 v[140:141], off
	v_lshl_add_u64 v[140:141], v[216:217], 0, s[18:19]
	s_mov_b32 m0, s31
	v_lshl_add_u64 v[218:219], s[34:35], 0, v[132:133]
	global_load_lds_dwordx4 v[140:141], off
	v_lshl_add_u64 v[140:141], v[218:219], 0, s[18:19]
	s_mov_b32 m0, s45
	s_nop 0
	global_load_lds_dwordx4 v[140:141], off
	s_waitcnt vmcnt(8)
	s_waitcnt lgkmcnt(0)
	s_barrier
	s_waitcnt lgkmcnt(0)
	v_mfma_f32_16x16x32_bf16 v[140:143], v[0:3], v[60:63], 0
	v_mfma_f32_16x16x32_bf16 v[156:159], v[0:3], v[104:107], 0
	v_mfma_f32_16x16x32_bf16 v[164:167], v[0:3], v[112:115], 0
	v_mfma_f32_16x16x32_bf16 v[0:3], v[0:3], v[120:123], 0
	v_mfma_f32_16x16x32_bf16 v[140:143], v[4:7], v[100:103], v[140:143]
	v_mfma_f32_16x16x32_bf16 v[156:159], v[4:7], v[108:111], v[156:159]
	v_mfma_f32_16x16x32_bf16 v[164:167], v[4:7], v[116:119], v[164:167]
	v_mfma_f32_16x16x32_bf16 v[0:3], v[4:7], v[124:127], v[0:3]
	v_mfma_f32_16x16x32_bf16 v[4:7], v[8:11], v[120:123], 0
	v_mfma_f32_16x16x32_bf16 v[152:155], v[8:11], v[60:63], 0
	v_mfma_f32_16x16x32_bf16 v[160:163], v[8:11], v[104:107], 0
	v_mfma_f32_16x16x32_bf16 v[168:171], v[8:11], v[112:115], 0
	v_mfma_f32_16x16x32_bf16 v[4:7], v[12:15], v[124:127], v[4:7]
	v_mfma_f32_16x16x32_bf16 v[152:155], v[12:15], v[100:103], v[152:155]
	v_mfma_f32_16x16x32_bf16 v[160:163], v[12:15], v[108:111], v[160:163]
	v_mfma_f32_16x16x32_bf16 v[168:171], v[12:15], v[116:119], v[168:171]
	v_mfma_f32_16x16x32_bf16 v[8:11], v[16:19], v[60:63], 0
	v_mfma_f32_16x16x32_bf16 v[12:15], v[24:27], v[60:63], 0
	v_mfma_f32_16x16x32_bf16 v[8:11], v[20:23], v[100:103], v[8:11]
	v_mfma_f32_16x16x32_bf16 v[12:15], v[28:31], v[100:103], v[12:15]
	v_mfma_f32_16x16x32_bf16 v[60:63], v[16:19], v[104:107], 0
	v_mfma_f32_16x16x32_bf16 v[100:103], v[24:27], v[104:107], 0
	v_mfma_f32_16x16x32_bf16 v[104:107], v[16:19], v[112:115], 0
	v_mfma_f32_16x16x32_bf16 v[16:19], v[16:19], v[120:123], 0
	v_mfma_f32_16x16x32_bf16 v[60:63], v[20:23], v[108:111], v[60:63]
	v_mfma_f32_16x16x32_bf16 v[100:103], v[28:31], v[108:111], v[100:103]
	v_mfma_f32_16x16x32_bf16 v[104:107], v[20:23], v[116:119], v[104:107]
	v_mfma_f32_16x16x32_bf16 v[108:111], v[24:27], v[112:115], 0
	v_mfma_f32_16x16x32_bf16 v[16:19], v[20:23], v[124:127], v[16:19]
	v_mfma_f32_16x16x32_bf16 v[20:23], v[24:27], v[120:123], 0
	v_mfma_f32_16x16x32_bf16 v[108:111], v[28:31], v[116:119], v[108:111]
	v_mfma_f32_16x16x32_bf16 v[20:23], v[28:31], v[124:127], v[20:23]
	s_barrier
	s_add_i32 s62, 0, 0x18000
	s_add_i32 s64, 0, 0x1c000
	v_add_u32_e32 v151, s62, v145
	v_add_u32_e32 v222, s64, v145
	ds_read_b128 v[24:27], v151
	ds_read_b128 v[28:31], v151 offset:1024
	ds_read_b128 v[112:115], v151 offset:2048
	ds_read_b128 v[116:119], v151 offset:3072
	ds_read_b128 v[120:123], v222
	ds_read_b128 v[124:127], v222 offset:1024
	ds_read_b128 v[172:175], v222 offset:2048
	ds_read_b128 v[176:179], v222 offset:3072
	s_add_u32 s60, s34, 0x10100
	s_addc_u32 s61, s35, 0
	s_mov_b32 m0, s46
	v_lshl_add_u64 v[220:221], s[60:61], 0, v[128:129]
	ds_read_b128 v[180:183], v149 offset:32768
	ds_read_b128 v[184:187], v149 offset:33792
	ds_read_b128 v[188:191], v149 offset:34816
	ds_read_b128 v[192:195], v149 offset:35840
	ds_read_b128 v[196:199], v149 offset:36864
	ds_read_b128 v[200:203], v149 offset:37888
	ds_read_b128 v[204:207], v149 offset:38912
	ds_read_b128 v[208:211], v149 offset:39936
	global_load_lds_dwordx4 v[220:221], off
	v_lshl_add_u64 v[220:221], s[60:61], 0, v[132:133]
	s_mov_b32 m0, s47
	s_nop 0
	global_load_lds_dwordx4 v[220:221], off
	s_waitcnt vmcnt(8)
	s_waitcnt lgkmcnt(0)
	s_barrier
	s_waitcnt lgkmcnt(0)
	v_mfma_f32_16x16x32_bf16 v[64:67], v[24:27], v[180:183], v[64:67]
	v_mfma_f32_16x16x32_bf16 v[68:71], v[112:115], v[180:183], v[68:71]
	v_mfma_f32_16x16x32_bf16 v[72:75], v[24:27], v[188:191], v[72:75]
	v_mfma_f32_16x16x32_bf16 v[76:79], v[112:115], v[188:191], v[76:79]
	v_mfma_f32_16x16x32_bf16 v[80:83], v[24:27], v[196:199], v[80:83]
	v_mfma_f32_16x16x32_bf16 v[84:87], v[112:115], v[196:199], v[84:87]
	v_mfma_f32_16x16x32_bf16 v[88:91], v[24:27], v[204:207], v[88:91]
	v_mfma_f32_16x16x32_bf16 v[92:95], v[112:115], v[204:207], v[92:95]
	v_mfma_f32_16x16x32_bf16 v[64:67], v[28:31], v[184:187], v[64:67]
	v_mfma_f32_16x16x32_bf16 v[68:71], v[116:119], v[184:187], v[68:71]
	v_mfma_f32_16x16x32_bf16 v[72:75], v[28:31], v[192:195], v[72:75]
	v_mfma_f32_16x16x32_bf16 v[76:79], v[116:119], v[192:195], v[76:79]
	v_mfma_f32_16x16x32_bf16 v[80:83], v[28:31], v[200:203], v[80:83]
	v_mfma_f32_16x16x32_bf16 v[84:87], v[116:119], v[200:203], v[84:87]
	v_mfma_f32_16x16x32_bf16 v[88:91], v[28:31], v[208:211], v[88:91]
	v_mfma_f32_16x16x32_bf16 v[92:95], v[116:119], v[208:211], v[92:95]
	v_mfma_f32_16x16x32_bf16 v[96:99], v[120:123], v[180:183], v[96:99]
	v_mfma_f32_16x16x32_bf16 v[32:35], v[172:175], v[180:183], v[32:35]
	v_mfma_f32_16x16x32_bf16 v[36:39], v[120:123], v[188:191], v[36:39]
	v_mfma_f32_16x16x32_bf16 v[40:43], v[172:175], v[188:191], v[40:43]
	v_mfma_f32_16x16x32_bf16 v[44:47], v[120:123], v[196:199], v[44:47]
	v_mfma_f32_16x16x32_bf16 v[48:51], v[172:175], v[196:199], v[48:51]
	v_mfma_f32_16x16x32_bf16 v[52:55], v[120:123], v[204:207], v[52:55]
	v_mfma_f32_16x16x32_bf16 v[56:59], v[172:175], v[204:207], v[56:59]
	v_mfma_f32_16x16x32_bf16 v[96:99], v[124:127], v[184:187], v[96:99]
	v_mfma_f32_16x16x32_bf16 v[32:35], v[176:179], v[184:187], v[32:35]
	v_mfma_f32_16x16x32_bf16 v[36:39], v[124:127], v[192:195], v[36:39]
	v_mfma_f32_16x16x32_bf16 v[40:43], v[176:179], v[192:195], v[40:43]
	v_mfma_f32_16x16x32_bf16 v[44:47], v[124:127], v[200:203], v[44:47]
	v_mfma_f32_16x16x32_bf16 v[48:51], v[176:179], v[200:203], v[48:51]
	v_mfma_f32_16x16x32_bf16 v[52:55], v[124:127], v[208:211], v[52:55]
	v_mfma_f32_16x16x32_bf16 v[56:59], v[176:179], v[208:211], v[56:59]
	s_barrier
	s_add_i32 s61, s62, s44
	s_add_i32 s60, s61, 0x2000
	v_lshl_add_u64 v[212:213], v[212:213], 0, s[20:21]
	s_mov_b32 m0, s61
	s_add_u32 s62, s36, 0x10180
	ds_read_b128 v[180:183], v149 offset:49152
	ds_read_b128 v[184:187], v149 offset:50176
	ds_read_b128 v[188:191], v149 offset:51200
	ds_read_b128 v[192:195], v149 offset:52224
	ds_read_b128 v[196:199], v149 offset:53248
	ds_read_b128 v[200:203], v149 offset:54272
	ds_read_b128 v[204:207], v149 offset:55296
	ds_read_b128 v[208:211], v149 offset:56320
	global_load_lds_dwordx4 v[212:213], off
	v_lshl_add_u64 v[212:213], v[214:215], 0, s[20:21]
	s_mov_b32 m0, s60
	s_addc_u32 s63, s37, 0
	s_add_i32 s36, s64, s44
	global_load_lds_dwordx4 v[212:213], off
	v_lshl_add_u64 v[212:213], s[62:63], 0, v[130:131]
	s_mov_b32 m0, s36
	s_add_i32 s37, s36, 0x2000
	global_load_lds_dwordx4 v[212:213], off
	v_lshl_add_u64 v[212:213], s[62:63], 0, v[134:135]
	s_mov_b32 m0, s37
	s_nop 0
	global_load_lds_dwordx4 v[212:213], off
	v_lshl_add_u64 v[212:213], v[216:217], 0, s[20:21]
	s_mov_b32 m0, s50
	s_nop 0
	global_load_lds_dwordx4 v[212:213], off
	v_lshl_add_u64 v[212:213], v[218:219], 0, s[20:21]
	s_mov_b32 m0, s51
	s_nop 0
	global_load_lds_dwordx4 v[212:213], off
	s_waitcnt vmcnt(8)
	s_waitcnt lgkmcnt(0)
	s_barrier
	s_waitcnt lgkmcnt(0)
	v_mfma_f32_16x16x32_bf16 v[0:3], v[24:27], v[204:207], v[0:3]
	v_mfma_f32_16x16x32_bf16 v[4:7], v[112:115], v[204:207], v[4:7]
	v_mfma_f32_16x16x32_bf16 v[140:143], v[24:27], v[180:183], v[140:143]
	v_mfma_f32_16x16x32_bf16 v[152:155], v[112:115], v[180:183], v[152:155]
	v_mfma_f32_16x16x32_bf16 v[156:159], v[24:27], v[188:191], v[156:159]
	v_mfma_f32_16x16x32_bf16 v[160:163], v[112:115], v[188:191], v[160:163]
	v_mfma_f32_16x16x32_bf16 v[164:167], v[24:27], v[196:199], v[164:167]
	v_mfma_f32_16x16x32_bf16 v[168:171], v[112:115], v[196:199], v[168:171]
	v_mfma_f32_16x16x32_bf16 v[0:3], v[28:31], v[208:211], v[0:3]
	v_mfma_f32_16x16x32_bf16 v[4:7], v[116:119], v[208:211], v[4:7]
	v_mfma_f32_16x16x32_bf16 v[140:143], v[28:31], v[184:187], v[140:143]
	v_mfma_f32_16x16x32_bf16 v[152:155], v[116:119], v[184:187], v[152:155]
	v_mfma_f32_16x16x32_bf16 v[156:159], v[28:31], v[192:195], v[156:159]
	v_mfma_f32_16x16x32_bf16 v[160:163], v[116:119], v[192:195], v[160:163]
	v_mfma_f32_16x16x32_bf16 v[164:167], v[28:31], v[200:203], v[164:167]
	v_mfma_f32_16x16x32_bf16 v[168:171], v[116:119], v[200:203], v[168:171]
	v_mfma_f32_16x16x32_bf16 v[8:11], v[120:123], v[180:183], v[8:11]
	v_mfma_f32_16x16x32_bf16 v[12:15], v[172:175], v[180:183], v[12:15]
	v_mfma_f32_16x16x32_bf16 v[24:27], v[120:123], v[188:191], v[60:63]
	v_mfma_f32_16x16x32_bf16 v[28:31], v[172:175], v[188:191], v[100:103]
	v_mfma_f32_16x16x32_bf16 v[60:63], v[120:123], v[196:199], v[104:107]
	v_mfma_f32_16x16x32_bf16 v[100:103], v[172:175], v[196:199], v[108:111]
	v_mfma_f32_16x16x32_bf16 v[16:19], v[120:123], v[204:207], v[16:19]
	v_mfma_f32_16x16x32_bf16 v[20:23], v[172:175], v[204:207], v[20:23]
	v_mfma_f32_16x16x32_bf16 v[8:11], v[124:127], v[184:187], v[8:11]
	v_mfma_f32_16x16x32_bf16 v[12:15], v[176:179], v[184:187], v[12:15]
	v_mfma_f32_16x16x32_bf16 v[24:27], v[124:127], v[192:195], v[24:27]
	v_mfma_f32_16x16x32_bf16 v[28:31], v[176:179], v[192:195], v[28:31]
	v_mfma_f32_16x16x32_bf16 v[60:63], v[124:127], v[200:203], v[60:63]
	v_mfma_f32_16x16x32_bf16 v[100:103], v[176:179], v[200:203], v[100:103]
	v_mfma_f32_16x16x32_bf16 v[16:19], v[124:127], v[208:211], v[16:19]
	v_mfma_f32_16x16x32_bf16 v[20:23], v[176:179], v[208:211], v[20:23]
	s_barrier
	ds_read_b128 v[104:107], v147
	ds_read_b128 v[108:111], v147 offset:1024
	ds_read_b128 v[112:115], v147 offset:2048
	ds_read_b128 v[116:119], v147 offset:3072
	ds_read_b128 v[120:123], v148
	ds_read_b128 v[124:127], v148 offset:1024
	ds_read_b128 v[172:175], v148 offset:2048
	ds_read_b128 v[176:179], v148 offset:3072
	s_add_u32 s34, s34, 0x10180
	s_addc_u32 s35, s35, 0
	s_mov_b32 m0, s55
	v_lshl_add_u64 v[212:213], s[34:35], 0, v[128:129]
	ds_read_b128 v[180:183], v149
	ds_read_b128 v[184:187], v149 offset:1024
	ds_read_b128 v[188:191], v149 offset:2048
	ds_read_b128 v[192:195], v149 offset:3072
	ds_read_b128 v[196:199], v149 offset:4096
	ds_read_b128 v[200:203], v149 offset:5120
	ds_read_b128 v[204:207], v149 offset:6144
	ds_read_b128 v[208:211], v149 offset:7168
	global_load_lds_dwordx4 v[212:213], off
	v_lshl_add_u64 v[212:213], s[34:35], 0, v[132:133]
	s_mov_b32 m0, s56
	s_nop 0
	global_load_lds_dwordx4 v[212:213], off
	s_waitcnt vmcnt(8)
	s_waitcnt lgkmcnt(0)
	s_barrier
	s_waitcnt lgkmcnt(0)
	v_mfma_f32_16x16x32_bf16 v[64:67], v[104:107], v[180:183], v[64:67]
	v_mfma_f32_16x16x32_bf16 v[68:71], v[112:115], v[180:183], v[68:71]
	v_mfma_f32_16x16x32_bf16 v[72:75], v[104:107], v[188:191], v[72:75]
	v_mfma_f32_16x16x32_bf16 v[76:79], v[112:115], v[188:191], v[76:79]
	v_mfma_f32_16x16x32_bf16 v[80:83], v[104:107], v[196:199], v[80:83]
	v_mfma_f32_16x16x32_bf16 v[84:87], v[112:115], v[196:199], v[84:87]
	v_mfma_f32_16x16x32_bf16 v[88:91], v[104:107], v[204:207], v[88:91]
	v_mfma_f32_16x16x32_bf16 v[92:95], v[112:115], v[204:207], v[92:95]
	v_mfma_f32_16x16x32_bf16 v[64:67], v[108:111], v[184:187], v[64:67]
	v_mfma_f32_16x16x32_bf16 v[68:71], v[116:119], v[184:187], v[68:71]
	v_mfma_f32_16x16x32_bf16 v[72:75], v[108:111], v[192:195], v[72:75]
	v_mfma_f32_16x16x32_bf16 v[76:79], v[116:119], v[192:195], v[76:79]
	v_mfma_f32_16x16x32_bf16 v[80:83], v[108:111], v[200:203], v[80:83]
	v_mfma_f32_16x16x32_bf16 v[84:87], v[116:119], v[200:203], v[84:87]
	v_mfma_f32_16x16x32_bf16 v[88:91], v[108:111], v[208:211], v[88:91]
	v_mfma_f32_16x16x32_bf16 v[92:95], v[116:119], v[208:211], v[92:95]
	v_mfma_f32_16x16x32_bf16 v[32:35], v[172:175], v[180:183], v[32:35]
	v_mfma_f32_16x16x32_bf16 v[36:39], v[120:123], v[188:191], v[36:39]
	v_mfma_f32_16x16x32_bf16 v[40:43], v[172:175], v[188:191], v[40:43]
	v_mfma_f32_16x16x32_bf16 v[44:47], v[120:123], v[196:199], v[44:47]
	v_mfma_f32_16x16x32_bf16 v[48:51], v[172:175], v[196:199], v[48:51]
	v_mfma_f32_16x16x32_bf16 v[52:55], v[120:123], v[204:207], v[52:55]
	v_mfma_f32_16x16x32_bf16 v[56:59], v[172:175], v[204:207], v[56:59]
	v_mfma_f32_16x16x32_bf16 v[96:99], v[120:123], v[180:183], v[96:99]
	v_mfma_f32_16x16x32_bf16 v[32:35], v[176:179], v[184:187], v[32:35]
	v_mfma_f32_16x16x32_bf16 v[36:39], v[124:127], v[192:195], v[36:39]
	v_mfma_f32_16x16x32_bf16 v[40:43], v[176:179], v[192:195], v[40:43]
	v_mfma_f32_16x16x32_bf16 v[44:47], v[124:127], v[200:203], v[44:47]
	v_mfma_f32_16x16x32_bf16 v[48:51], v[176:179], v[200:203], v[48:51]
	v_mfma_f32_16x16x32_bf16 v[52:55], v[124:127], v[208:211], v[52:55]
	v_mfma_f32_16x16x32_bf16 v[56:59], v[176:179], v[208:211], v[56:59]
	v_mfma_f32_16x16x32_bf16 v[212:215], v[124:127], v[184:187], v[96:99]
	s_barrier
	s_mov_b32 m0, s59
	v_lshl_add_u64 v[240:241], s[38:39], 0, v[130:131]
	s_add_u32 s34, s38, 0x10000
	ds_read_b128 v[96:99], v149 offset:16384
	ds_read_b128 v[180:183], v149 offset:17408
	ds_read_b128 v[184:187], v149 offset:18432
	ds_read_b128 v[188:191], v149 offset:19456
	ds_read_b128 v[192:195], v149 offset:20480
	ds_read_b128 v[196:199], v149 offset:21504
	ds_read_b128 v[200:203], v149 offset:22528
	ds_read_b128 v[204:207], v149 offset:23552
	global_load_lds_dwordx4 v[240:241], off
	v_lshl_add_u64 v[242:243], s[38:39], 0, v[134:135]
	s_mov_b32 m0, s23
	s_addc_u32 s35, s39, 0
	global_load_lds_dwordx4 v[242:243], off
	v_lshl_add_u64 v[208:209], s[34:35], 0, v[130:131]
	s_mov_b32 m0, s25
	v_lshl_add_u64 v[244:245], s[40:41], 0, v[128:129]
	global_load_lds_dwordx4 v[208:209], off
	v_lshl_add_u64 v[208:209], s[34:35], 0, v[134:135]
	s_mov_b32 m0, s58
	v_lshl_add_u64 v[246:247], s[40:41], 0, v[132:133]
	global_load_lds_dwordx4 v[208:209], off
	s_mov_b32 m0, s31
	s_nop 0
	global_load_lds_dwordx4 v[244:245], off
	s_mov_b32 m0, s45
	s_nop 0
	global_load_lds_dwordx4 v[246:247], off
	s_waitcnt vmcnt(8)
	s_waitcnt lgkmcnt(0)
	s_barrier
	s_waitcnt lgkmcnt(0)
	v_mfma_f32_16x16x32_bf16 v[0:3], v[104:107], v[200:203], v[0:3]
	v_mfma_f32_16x16x32_bf16 v[4:7], v[112:115], v[200:203], v[4:7]
	v_mfma_f32_16x16x32_bf16 v[140:143], v[104:107], v[96:99], v[140:143]
	v_mfma_f32_16x16x32_bf16 v[152:155], v[112:115], v[96:99], v[152:155]
	v_mfma_f32_16x16x32_bf16 v[156:159], v[104:107], v[184:187], v[156:159]
	v_mfma_f32_16x16x32_bf16 v[160:163], v[112:115], v[184:187], v[160:163]
	v_mfma_f32_16x16x32_bf16 v[164:167], v[104:107], v[192:195], v[164:167]
	v_mfma_f32_16x16x32_bf16 v[168:171], v[112:115], v[192:195], v[168:171]
	v_mfma_f32_16x16x32_bf16 v[0:3], v[108:111], v[204:207], v[0:3]
	v_mfma_f32_16x16x32_bf16 v[4:7], v[116:119], v[204:207], v[4:7]
	v_mfma_f32_16x16x32_bf16 v[140:143], v[108:111], v[180:183], v[140:143]
	v_mfma_f32_16x16x32_bf16 v[152:155], v[116:119], v[180:183], v[152:155]
	v_mfma_f32_16x16x32_bf16 v[156:159], v[108:111], v[188:191], v[156:159]
	v_mfma_f32_16x16x32_bf16 v[160:163], v[116:119], v[188:191], v[160:163]
	v_mfma_f32_16x16x32_bf16 v[164:167], v[108:111], v[196:199], v[164:167]
	v_mfma_f32_16x16x32_bf16 v[168:171], v[116:119], v[196:199], v[168:171]
	v_mfma_f32_16x16x32_bf16 v[8:11], v[120:123], v[96:99], v[8:11]
	v_mfma_f32_16x16x32_bf16 v[12:15], v[172:175], v[96:99], v[12:15]
	v_mfma_f32_16x16x32_bf16 v[24:27], v[120:123], v[184:187], v[24:27]
	v_mfma_f32_16x16x32_bf16 v[28:31], v[172:175], v[184:187], v[28:31]
	v_mfma_f32_16x16x32_bf16 v[60:63], v[120:123], v[192:195], v[60:63]
	v_mfma_f32_16x16x32_bf16 v[16:19], v[120:123], v[200:203], v[16:19]
	v_mfma_f32_16x16x32_bf16 v[8:11], v[124:127], v[180:183], v[8:11]
	v_mfma_f32_16x16x32_bf16 v[12:15], v[176:179], v[180:183], v[12:15]
	v_mfma_f32_16x16x32_bf16 v[24:27], v[124:127], v[188:191], v[24:27]
	v_mfma_f32_16x16x32_bf16 v[28:31], v[176:179], v[188:191], v[28:31]
	v_mfma_f32_16x16x32_bf16 v[180:183], v[124:127], v[196:199], v[60:63]
	v_mfma_f32_16x16x32_bf16 v[60:63], v[172:175], v[192:195], v[100:103]
	v_mfma_f32_16x16x32_bf16 v[188:191], v[124:127], v[204:207], v[16:19]
	v_mfma_f32_16x16x32_bf16 v[16:19], v[172:175], v[200:203], v[20:23]
	v_mfma_f32_16x16x32_bf16 v[184:187], v[176:179], v[196:199], v[60:63]
	v_mfma_f32_16x16x32_bf16 v[172:175], v[176:179], v[204:207], v[16:19]
	s_barrier
	s_nop 1
	ds_read_b128 v[60:63], v151
	ds_read_b128 v[176:179], v151 offset:1024
	ds_read_b128 v[192:195], v151 offset:2048
	ds_read_b128 v[196:199], v151 offset:3072
	ds_read_b128 v[200:203], v222
	ds_read_b128 v[204:207], v222 offset:1024
	ds_read_b128 v[208:211], v222 offset:2048
	ds_read_b128 v[216:219], v222 offset:3072
	s_add_u32 s34, s40, 0x10000
	s_addc_u32 s35, s41, 0
	s_mov_b32 m0, s46
	v_lshl_add_u64 v[96:97], s[34:35], 0, v[128:129]
	ds_read_b128 v[16:19], v149 offset:32768
	ds_read_b128 v[20:23], v149 offset:33792
	ds_read_b128 v[108:111], v149 offset:34816
	ds_read_b128 v[220:223], v149 offset:35840
	ds_read_b128 v[224:227], v149 offset:36864
	ds_read_b128 v[228:231], v149 offset:37888
	ds_read_b128 v[232:235], v149 offset:38912
	ds_read_b128 v[236:239], v149 offset:39936
	global_load_lds_dwordx4 v[96:97], off
	v_lshl_add_u64 v[96:97], s[34:35], 0, v[132:133]
	s_mov_b32 m0, s47
	s_nop 0
	global_load_lds_dwordx4 v[96:97], off
	s_waitcnt vmcnt(8)
	s_waitcnt lgkmcnt(0)
	s_barrier
	s_waitcnt lgkmcnt(0)
	v_mfma_f32_16x16x32_bf16 v[64:67], v[60:63], v[16:19], v[64:67]
	v_mfma_f32_16x16x32_bf16 v[112:115], v[176:179], v[20:23], v[64:67]
	v_mfma_f32_16x16x32_bf16 v[64:67], v[192:195], v[16:19], v[68:71]
	v_mfma_f32_16x16x32_bf16 v[116:119], v[196:199], v[20:23], v[64:67]
	v_mfma_f32_16x16x32_bf16 v[64:67], v[60:63], v[108:111], v[72:75]
	v_mfma_f32_16x16x32_bf16 v[96:99], v[176:179], v[220:223], v[64:67]
	v_mfma_f32_16x16x32_bf16 v[64:67], v[192:195], v[108:111], v[76:79]
	v_mfma_f32_16x16x32_bf16 v[100:103], v[196:199], v[220:223], v[64:67]
	v_mfma_f32_16x16x32_bf16 v[64:67], v[60:63], v[224:227], v[80:83]
	v_mfma_f32_16x16x32_bf16 v[80:83], v[176:179], v[228:231], v[64:67]
	v_mfma_f32_16x16x32_bf16 v[64:67], v[192:195], v[224:227], v[84:87]
	v_mfma_f32_16x16x32_bf16 v[84:87], v[196:199], v[228:231], v[64:67]
	v_mfma_f32_16x16x32_bf16 v[64:67], v[60:63], v[232:235], v[88:91]
	v_mfma_f32_16x16x32_bf16 v[68:71], v[192:195], v[232:235], v[92:95]
	v_mfma_f32_16x16x32_bf16 v[64:67], v[176:179], v[236:239], v[64:67]
	v_mfma_f32_16x16x32_bf16 v[68:71], v[196:199], v[236:239], v[68:71]
	v_mfma_f32_16x16x32_bf16 v[72:75], v[200:203], v[16:19], v[212:215]
	v_mfma_f32_16x16x32_bf16 v[16:19], v[208:211], v[16:19], v[32:35]
	v_mfma_f32_16x16x32_bf16 v[124:127], v[216:219], v[20:23], v[16:19]
	v_mfma_f32_16x16x32_bf16 v[16:19], v[200:203], v[108:111], v[36:39]
	v_mfma_f32_16x16x32_bf16 v[104:107], v[204:207], v[220:223], v[16:19]
	v_mfma_f32_16x16x32_bf16 v[16:19], v[208:211], v[108:111], v[40:43]
	v_mfma_f32_16x16x32_bf16 v[108:111], v[216:219], v[220:223], v[16:19]
	v_mfma_f32_16x16x32_bf16 v[16:19], v[200:203], v[224:227], v[44:47]
	v_mfma_f32_16x16x32_bf16 v[88:91], v[204:207], v[228:231], v[16:19]
	v_mfma_f32_16x16x32_bf16 v[16:19], v[208:211], v[224:227], v[48:51]
	v_mfma_f32_16x16x32_bf16 v[92:95], v[216:219], v[228:231], v[16:19]
	v_mfma_f32_16x16x32_bf16 v[16:19], v[200:203], v[232:235], v[52:55]
	v_mfma_f32_16x16x32_bf16 v[120:123], v[204:207], v[20:23], v[72:75]
	v_mfma_f32_16x16x32_bf16 v[72:75], v[204:207], v[236:239], v[16:19]
	v_mfma_f32_16x16x32_bf16 v[16:19], v[208:211], v[232:235], v[56:59]
	v_mfma_f32_16x16x32_bf16 v[76:79], v[216:219], v[236:239], v[16:19]
	s_barrier
	s_mov_b32 m0, s61
	s_nop 3
	v_lshl_add_u64 v[16:17], v[240:241], 0, s[12:13]
	s_add_u32 s34, s38, 0x10080
	ds_read_b128 v[40:43], v149 offset:49152
	ds_read_b128 v[44:47], v149 offset:50176
	ds_read_b128 v[212:215], v149 offset:51200
	ds_read_b128 v[220:223], v149 offset:52224
	ds_read_b128 v[224:227], v149 offset:53248
	ds_read_b128 v[228:231], v149 offset:54272
	ds_read_b128 v[232:235], v149 offset:55296
	ds_read_b128 v[236:239], v149 offset:56320
	global_load_lds_dwordx4 v[16:17], off
	v_lshl_add_u64 v[16:17], v[242:243], 0, s[12:13]
	s_mov_b32 m0, s60
	s_addc_u32 s35, s39, 0
	global_load_lds_dwordx4 v[16:17], off
	v_lshl_add_u64 v[16:17], s[34:35], 0, v[130:131]
	s_mov_b32 m0, s36
	s_nop 0
	global_load_lds_dwordx4 v[16:17], off
	v_lshl_add_u64 v[16:17], s[34:35], 0, v[134:135]
	s_mov_b32 m0, s37
	s_nop 0
	global_load_lds_dwordx4 v[16:17], off
	v_lshl_add_u64 v[16:17], v[244:245], 0, s[12:13]
	s_mov_b32 m0, s50
	s_nop 0
	global_load_lds_dwordx4 v[16:17], off
	v_lshl_add_u64 v[16:17], v[246:247], 0, s[12:13]
	s_mov_b32 m0, s51
	s_nop 0
	global_load_lds_dwordx4 v[16:17], off
	s_waitcnt vmcnt(8)
	s_waitcnt lgkmcnt(0)
	s_barrier
	s_waitcnt lgkmcnt(0)
	v_mfma_f32_16x16x32_bf16 v[16:19], v[60:63], v[40:43], v[140:143]
	v_mfma_f32_16x16x32_bf16 v[48:51], v[176:179], v[44:47], v[16:19]
	v_mfma_f32_16x16x32_bf16 v[16:19], v[192:195], v[40:43], v[152:155]
	v_mfma_f32_16x16x32_bf16 v[52:55], v[196:199], v[44:47], v[16:19]
	v_mfma_f32_16x16x32_bf16 v[16:19], v[60:63], v[212:215], v[156:159]
	v_mfma_f32_16x16x32_bf16 v[32:35], v[176:179], v[220:223], v[16:19]
	v_mfma_f32_16x16x32_bf16 v[16:19], v[192:195], v[212:215], v[160:163]
	v_mfma_f32_16x16x32_bf16 v[36:39], v[196:199], v[220:223], v[16:19]
	v_mfma_f32_16x16x32_bf16 v[16:19], v[60:63], v[224:227], v[164:167]
	v_mfma_f32_16x16x32_bf16 v[20:23], v[192:195], v[224:227], v[168:171]
	v_mfma_f32_16x16x32_bf16 v[0:3], v[60:63], v[232:235], v[0:3]
	v_mfma_f32_16x16x32_bf16 v[4:7], v[192:195], v[232:235], v[4:7]
	v_mfma_f32_16x16x32_bf16 v[16:19], v[176:179], v[228:231], v[16:19]
	v_mfma_f32_16x16x32_bf16 v[20:23], v[196:199], v[228:231], v[20:23]
	v_mfma_f32_16x16x32_bf16 v[0:3], v[176:179], v[236:239], v[0:3]
	v_mfma_f32_16x16x32_bf16 v[4:7], v[196:199], v[236:239], v[4:7]
	v_mfma_f32_16x16x32_bf16 v[8:11], v[200:203], v[40:43], v[8:11]
	v_mfma_f32_16x16x32_bf16 v[56:59], v[204:207], v[44:47], v[8:11]
	v_mfma_f32_16x16x32_bf16 v[8:11], v[208:211], v[40:43], v[12:15]
	v_mfma_f32_16x16x32_bf16 v[60:63], v[216:219], v[44:47], v[8:11]
	v_mfma_f32_16x16x32_bf16 v[8:11], v[200:203], v[212:215], v[24:27]
	v_mfma_f32_16x16x32_bf16 v[40:43], v[204:207], v[220:223], v[8:11]
	v_mfma_f32_16x16x32_bf16 v[8:11], v[208:211], v[212:215], v[28:31]
	v_mfma_f32_16x16x32_bf16 v[44:47], v[216:219], v[220:223], v[8:11]
	v_mfma_f32_16x16x32_bf16 v[8:11], v[200:203], v[224:227], v[180:183]
	v_mfma_f32_16x16x32_bf16 v[24:27], v[204:207], v[228:231], v[8:11]
	v_mfma_f32_16x16x32_bf16 v[8:11], v[208:211], v[224:227], v[184:187]
	v_mfma_f32_16x16x32_bf16 v[28:31], v[216:219], v[228:231], v[8:11]
	v_mfma_f32_16x16x32_bf16 v[8:11], v[200:203], v[232:235], v[188:191]
	v_mfma_f32_16x16x32_bf16 v[12:15], v[208:211], v[232:235], v[172:175]
	v_mfma_f32_16x16x32_bf16 v[8:11], v[204:207], v[236:239], v[8:11]
	v_mfma_f32_16x16x32_bf16 v[12:15], v[216:219], v[236:239], v[12:15]
	s_barrier
	s_andn2_b64 vcc, exec, s[14:15]
	s_cbranch_vccnz .LBB0_1260
	s_barrier

.LBB0_1269:
	v_ashrrev_i32_e32 v2, 31, v0
	v_lshrrev_b32_e32 v2, 26, v2
	v_lshlrev_b32_e32 v1, 4, v0
	v_add_u32_e32 v2, v0, v2
	v_bfe_i32 v0, v0, 27, 1
	v_lshrrev_b32_e32 v0, 22, v0
	v_add_u32_e32 v0, v1, v0
	v_and_b32_e32 v0, 0xfffffc00, v0
	v_sub_u32_e32 v0, v1, v0
	v_lshrrev_b32_e32 v3, 4, v0
	v_bitop3_b32 v0, v3, v0, 32 bitop3:0x6c
	v_ashrrev_i32_e32 v4, 31, v0
	v_ashrrev_i32_e32 v2, 6, v2
	v_lshrrev_b32_e32 v4, 26, v4
	v_lshlrev_b32_e32 v3, 3, v2
	v_add_u32_e32 v4, v0, v4
	v_and_b32_e32 v3, -16, v3
	v_ashrrev_i32_e32 v5, 6, v4
	v_and_b32_e32 v4, 0xc0, v4
	v_add_u32_e32 v3, v5, v3
	v_sub_u32_e32 v0, v0, v4
	v_mov_b32_e32 v4, 1
	s_ashr_i32 s2, s5, 3
	v_lshlrev_b32_e32 v2, 5, v2
	v_ashrrev_i16_sdwa v0, v4, sext(v0) dst_sel:DWORD dst_unused:UNUSED_PAD src0_sel:DWORD src1_sel:BYTE_0
	v_lshlrev_b32_e32 v6, 1, v3
	v_lshrrev_b32_e32 v7, 2, v3
	v_and_b32_e32 v5, 3, v5
	s_mov_b32 s5, 0x7fffe0
	v_and_b32_e32 v2, 32, v2
	v_bfe_i32 v0, v0, 0, 16
	v_and_b32_e32 v6, 24, v6
	v_and_b32_e32 v7, 4, v7
	v_and_or_b32 v5, v3, s5, v5
	v_or3_b32 v5, v5, v7, v6
	v_add_lshl_u32 v0, v2, v0, 1
	v_lshl_add_u32 v128, v3, 9, v0
	v_lshl_add_u32 v130, v5, 9, v0
	v_add_u32_e32 v0, 0x2000, v1
	v_ashrrev_i32_e32 v1, 31, v0
	v_lshrrev_b32_e32 v1, 22, v1
	v_add_u32_e32 v1, v0, v1
	v_ashrrev_i32_e32 v1, 10, v1
	v_mul_i32_i24_e32 v2, 0x400, v1
	v_sub_u32_e32 v0, v0, v2
	s_add_u32 s50, s70, 0x5580000
	v_lshrrev_b32_e32 v2, 4, v0
	s_addc_u32 s51, s71, 0
	v_bitop3_b32 v0, v2, v0, 32 bitop3:0x6c
	s_add_i32 s2, s4, s2
	v_ashrrev_i32_e32 v3, 31, v0
	s_ashr_i32 s4, s2, 31
	v_lshrrev_b32_e32 v3, 26, v3
	s_lshr_b32 s4, s4, 22
	v_lshlrev_b32_e32 v2, 3, v1
	v_add_u32_e32 v3, v0, v3
	s_add_i32 s4, s2, s4
	v_and_b32_e32 v2, -16, v2
	v_ashrrev_i32_e32 v5, 6, v3
	v_and_b32_e32 v3, 0xc0, v3
	s_ashr_i32 s4, s4, 10
	v_add_u32_e32 v2, v5, v2
	v_sub_u32_e32 v0, v0, v3
	v_and_b32_e32 v5, 3, v5
	s_lshl_b32 s6, s4, 3
	v_lshlrev_b32_e32 v1, 5, v1
	v_ashrrev_i16_sdwa v0, v4, sext(v0) dst_sel:DWORD dst_unused:UNUSED_PAD src0_sel:DWORD src1_sel:BYTE_0
	v_lshlrev_b32_e32 v3, 1, v2
	v_lshrrev_b32_e32 v4, 2, v2
	v_and_or_b32 v5, v2, s5, v5
	s_sub_i32 s5, 4, s6
	s_lshl_b32 s4, s4, 10
	v_and_b32_e32 v1, 32, v1
	v_bfe_i32 v0, v0, 0, 16
	v_and_b32_e32 v3, 24, v3
	v_and_b32_e32 v4, 4, v4
	s_min_u32 s7, s5, 8
	s_sub_i32 s9, s2, s4
	v_or3_b32 v3, v5, v4, v3
	v_add_lshl_u32 v0, v1, v0, 1
	s_sext_i32_i16 s2, s9
	v_cvt_f32_ubyte0_e32 v1, s7
	v_lshl_add_u32 v132, v2, 9, v0
	v_lshl_add_u32 v134, v3, 9, v0
	v_cvt_f32_i32_e32 v0, s2
	v_rcp_iflag_f32_e32 v2, v1
	s_ashr_i32 s8, s12, 6
	s_ashr_i32 s2, s2, 30
	s_ashr_i32 s3, s12, 8
	v_mul_f32_e32 v2, v0, v2
	v_trunc_f32_e32 v2, v2
	v_fma_f32 v0, -v2, v1, v0
	v_cvt_i32_f32_e32 v2, v2
	s_lshl_b32 s52, s8, 10
	s_or_b32 s2, s2, 1
	v_cmp_ge_f32_e64 s[4:5], |v0|, v1
	s_and_b64 s[4:5], s[4:5], exec
	s_cselect_b32 s2, s2, 0
	v_readfirstlane_b32 s4, v2
	s_add_i32 s2, s4, s2
	s_mul_i32 s4, s2, s7
	s_sub_i32 s4, s9, s4
	s_sext_i32_i16 s4, s4
	s_add_i32 s38, s6, s4
	s_ashr_i32 s39, s38, 31
	s_bfe_i64 s[6:7], s[2:3], 0x100000
	s_lshl_b64 s[4:5], s[38:39], 17
	s_lshl_b64 s[6:7], s[6:7], 17
	s_add_u32 s42, s48, s6
	s_addc_u32 s43, s49, s7
	s_add_i32 s39, s52, 0
	s_add_i32 m0, s39, 0x10000
	v_mov_b32_e32 v131, 0
	global_load_lds_dwordx4 v130, s[42:43]
	s_add_i32 m0, s39, 0x12000
	s_add_u32 s6, s42, 0x10000
	global_load_lds_dwordx4 v134, s[42:43]
	s_addc_u32 s7, s43, 0
	s_add_i32 m0, s39, 0x14000
	v_mov_b32_e32 v135, v131
	global_load_lds_dwordx4 v130, s[6:7]
	s_add_i32 m0, s39, 0x16000
	s_add_u32 s40, s50, s4
	s_addc_u32 s41, s51, s5
	s_add_i32 s53, s39, 0x2000
	global_load_lds_dwordx4 v134, s[6:7]
	s_mov_b32 m0, s39
	s_add_u32 s4, s40, 0x10000
	global_load_lds_dwordx4 v128, s[40:41]
	s_mov_b32 m0, s53
	s_addc_u32 s5, s41, 0
	s_add_i32 s54, s39, 0x4000
	global_load_lds_dwordx4 v132, s[40:41]
	s_mov_b32 m0, s54
	s_add_i32 s55, s39, 0x6000
	global_load_lds_dwordx4 v128, s[4:5]
	s_mov_b32 m0, s55
	v_mov_b32_e32 v129, v131
	global_load_lds_dwordx4 v132, s[4:5]
	v_mov_b32_e32 v133, v131
	s_cmp_eq_u32 s3, 1
	v_lshl_add_u64 v[6:7], s[42:43], 0, v[130:131]
	v_lshl_add_u64 v[4:5], s[42:43], 0, v[134:135]
	v_lshl_add_u64 v[0:1], s[40:41], 0, v[128:129]
	s_cselect_b64 s[4:5], -1, 0
	s_cmp_lg_u32 s3, 1
	v_lshl_add_u64 v[2:3], s[40:41], 0, v[132:133]
	s_cbranch_scc1 .LBB0_1271
	s_barrier
	s_setprio 1

.LBB0_1280:
	ds_read_b128 v[0:3], v161
	ds_read_b128 v[4:7], v161 offset:1024
	ds_read_b128 v[8:11], v161 offset:2048
	ds_read_b128 v[12:15], v161 offset:3072
	ds_read_b128 v[16:19], v162
	ds_read_b128 v[20:23], v162 offset:1024
	ds_read_b128 v[24:27], v162 offset:2048
	ds_read_b128 v[28:31], v162 offset:3072
	s_ashr_i32 s31, s30, 31
	s_lshl_b64 s[34:35], s[30:31], 17
	s_add_u32 s34, s50, s34
	s_addc_u32 s35, s51, s35
	s_and_b64 s[36:37], s[2:3], exec
	s_cselect_b32 s47, s35, s41
	s_cselect_b32 s46, s34, s40
	s_ashr_i32 s29, s28, 31
	s_lshl_b64 s[36:37], s[28:29], 17
	s_add_u32 s36, s48, s36
	s_addc_u32 s37, s49, s37
	s_and_b64 s[44:45], s[2:3], exec
	s_cselect_b32 s45, s37, s43
	s_cselect_b32 s44, s36, s42
	s_add_u32 s66, s40, 0x10080
	s_addc_u32 s67, s41, 0
	s_add_i32 s84, s39, 0xc000
	v_lshl_add_u64 v[64:65], s[66:67], 0, v[128:129]
	s_mov_b32 m0, s84
	s_add_i32 s29, s39, 0xe000
	ds_read_b128 v[32:35], v163
	ds_read_b128 v[36:39], v163 offset:1024
	ds_read_b128 v[40:43], v163 offset:2048
	ds_read_b128 v[44:47], v163 offset:3072
	ds_read_b128 v[48:51], v163 offset:4096
	ds_read_b128 v[52:55], v163 offset:5120
	ds_read_b128 v[56:59], v163 offset:6144
	ds_read_b128 v[60:63], v163 offset:7168
	global_load_lds_dwordx4 v[64:65], off
	v_lshl_add_u64 v[64:65], s[66:67], 0, v[132:133]
	s_mov_b32 m0, s29
	s_nop 0
	global_load_lds_dwordx4 v[64:65], off
	s_waitcnt vmcnt(8)
	s_waitcnt lgkmcnt(0)
	s_barrier
	s_waitcnt lgkmcnt(0)
	v_mfma_f32_16x16x32_bf16 v[64:67], v[0:3], v[32:35], 0
	v_mfma_f32_16x16x32_bf16 v[68:71], v[8:11], v[32:35], 0
	v_mfma_f32_16x16x32_bf16 v[72:75], v[0:3], v[40:43], 0
	v_mfma_f32_16x16x32_bf16 v[76:79], v[8:11], v[40:43], 0
	v_mfma_f32_16x16x32_bf16 v[80:83], v[0:3], v[48:51], 0
	v_mfma_f32_16x16x32_bf16 v[84:87], v[8:11], v[48:51], 0
	v_mfma_f32_16x16x32_bf16 v[88:91], v[0:3], v[56:59], 0
	v_mfma_f32_16x16x32_bf16 v[92:95], v[8:11], v[56:59], 0
	v_mfma_f32_16x16x32_bf16 v[64:67], v[4:7], v[36:39], v[64:67]
	v_mfma_f32_16x16x32_bf16 v[68:71], v[12:15], v[36:39], v[68:71]
	v_mfma_f32_16x16x32_bf16 v[72:75], v[4:7], v[44:47], v[72:75]
	v_mfma_f32_16x16x32_bf16 v[76:79], v[12:15], v[44:47], v[76:79]
	v_mfma_f32_16x16x32_bf16 v[80:83], v[4:7], v[52:55], v[80:83]
	v_mfma_f32_16x16x32_bf16 v[84:87], v[12:15], v[52:55], v[84:87]
	v_mfma_f32_16x16x32_bf16 v[88:91], v[4:7], v[60:63], v[88:91]
	v_mfma_f32_16x16x32_bf16 v[92:95], v[12:15], v[60:63], v[92:95]
	v_mfma_f32_16x16x32_bf16 v[96:99], v[16:19], v[32:35], 0
	v_mfma_f32_16x16x32_bf16 v[32:35], v[24:27], v[32:35], 0
	v_mfma_f32_16x16x32_bf16 v[96:99], v[20:23], v[36:39], v[96:99]
	v_mfma_f32_16x16x32_bf16 v[32:35], v[28:31], v[36:39], v[32:35]
	v_mfma_f32_16x16x32_bf16 v[36:39], v[16:19], v[40:43], 0
	v_mfma_f32_16x16x32_bf16 v[40:43], v[24:27], v[40:43], 0
	v_mfma_f32_16x16x32_bf16 v[36:39], v[20:23], v[44:47], v[36:39]
	v_mfma_f32_16x16x32_bf16 v[40:43], v[28:31], v[44:47], v[40:43]
	v_mfma_f32_16x16x32_bf16 v[44:47], v[16:19], v[48:51], 0
	v_mfma_f32_16x16x32_bf16 v[48:51], v[24:27], v[48:51], 0
	v_mfma_f32_16x16x32_bf16 v[44:47], v[20:23], v[52:55], v[44:47]
	v_mfma_f32_16x16x32_bf16 v[48:51], v[28:31], v[52:55], v[48:51]
	v_mfma_f32_16x16x32_bf16 v[52:55], v[16:19], v[56:59], 0
	v_mfma_f32_16x16x32_bf16 v[56:59], v[24:27], v[56:59], 0
	v_mfma_f32_16x16x32_bf16 v[52:55], v[20:23], v[60:63], v[52:55]
	v_mfma_f32_16x16x32_bf16 v[56:59], v[28:31], v[60:63], v[56:59]
	s_barrier
	s_add_i32 s68, s59, s52
	v_lshl_add_u64 v[156:157], s[42:43], 0, v[130:131]
	s_add_i32 s31, s68, 0x2000
	v_lshl_add_u64 v[140:141], v[156:157], 0, s[16:17]
	s_mov_b32 m0, s68
	v_lshl_add_u64 v[214:215], s[42:43], 0, v[134:135]
	s_add_u32 s86, s42, 0x10100
	ds_read_b128 v[60:63], v163 offset:16384
	ds_read_b128 v[100:103], v163 offset:17408
	ds_read_b128 v[104:107], v163 offset:18432
	ds_read_b128 v[108:111], v163 offset:19456
	ds_read_b128 v[112:115], v163 offset:20480
	ds_read_b128 v[116:119], v163 offset:21504
	ds_read_b128 v[120:123], v163 offset:22528
	ds_read_b128 v[124:127], v163 offset:23552
	global_load_lds_dwordx4 v[140:141], off
	v_lshl_add_u64 v[140:141], v[214:215], 0, s[16:17]
	s_mov_b32 m0, s31
	s_addc_u32 s87, s43, 0
	s_add_i32 s66, s60, s52
	global_load_lds_dwordx4 v[140:141], off
	v_lshl_add_u64 v[140:141], s[86:87], 0, v[130:131]
	s_mov_b32 m0, s66
	s_add_i32 s67, s66, 0x2000
	global_load_lds_dwordx4 v[140:141], off
	v_lshl_add_u64 v[140:141], s[86:87], 0, v[134:135]
	s_mov_b32 m0, s67
	v_lshl_add_u64 v[216:217], s[40:41], 0, v[128:129]
	global_load_lds_dwordx4 v[140:141], off
	v_lshl_add_u64 v[140:141], v[216:217], 0, s[16:17]
	s_mov_b32 m0, s39
	v_lshl_add_u64 v[218:219], s[40:41], 0, v[132:133]
	global_load_lds_dwordx4 v[140:141], off
	v_lshl_add_u64 v[140:141], v[218:219], 0, s[16:17]
	s_mov_b32 m0, s53
	s_nop 0
	global_load_lds_dwordx4 v[140:141], off
	s_waitcnt vmcnt(8)
	s_waitcnt lgkmcnt(0)
	s_barrier
	s_waitcnt lgkmcnt(0)
	v_mfma_f32_16x16x32_bf16 v[140:143], v[0:3], v[60:63], 0
	v_mfma_f32_16x16x32_bf16 v[148:151], v[0:3], v[104:107], 0
	v_mfma_f32_16x16x32_bf16 v[166:169], v[0:3], v[112:115], 0
	v_mfma_f32_16x16x32_bf16 v[0:3], v[0:3], v[120:123], 0
	v_mfma_f32_16x16x32_bf16 v[140:143], v[4:7], v[100:103], v[140:143]
	v_mfma_f32_16x16x32_bf16 v[148:151], v[4:7], v[108:111], v[148:151]
	v_mfma_f32_16x16x32_bf16 v[166:169], v[4:7], v[116:119], v[166:169]
	v_mfma_f32_16x16x32_bf16 v[0:3], v[4:7], v[124:127], v[0:3]
	v_mfma_f32_16x16x32_bf16 v[4:7], v[8:11], v[120:123], 0
	v_mfma_f32_16x16x32_bf16 v[144:147], v[8:11], v[60:63], 0
	v_mfma_f32_16x16x32_bf16 v[152:155], v[8:11], v[104:107], 0
	v_mfma_f32_16x16x32_bf16 v[170:173], v[8:11], v[112:115], 0
	v_mfma_f32_16x16x32_bf16 v[4:7], v[12:15], v[124:127], v[4:7]
	v_mfma_f32_16x16x32_bf16 v[144:147], v[12:15], v[100:103], v[144:147]
	v_mfma_f32_16x16x32_bf16 v[152:155], v[12:15], v[108:111], v[152:155]
	v_mfma_f32_16x16x32_bf16 v[170:173], v[12:15], v[116:119], v[170:173]
	v_mfma_f32_16x16x32_bf16 v[8:11], v[16:19], v[60:63], 0
	v_mfma_f32_16x16x32_bf16 v[12:15], v[24:27], v[60:63], 0
	v_mfma_f32_16x16x32_bf16 v[8:11], v[20:23], v[100:103], v[8:11]
	v_mfma_f32_16x16x32_bf16 v[12:15], v[28:31], v[100:103], v[12:15]
	v_mfma_f32_16x16x32_bf16 v[60:63], v[16:19], v[104:107], 0
	v_mfma_f32_16x16x32_bf16 v[100:103], v[24:27], v[104:107], 0
	v_mfma_f32_16x16x32_bf16 v[104:107], v[16:19], v[112:115], 0
	v_mfma_f32_16x16x32_bf16 v[16:19], v[16:19], v[120:123], 0
	v_mfma_f32_16x16x32_bf16 v[60:63], v[20:23], v[108:111], v[60:63]
	v_mfma_f32_16x16x32_bf16 v[100:103], v[28:31], v[108:111], v[100:103]
	v_mfma_f32_16x16x32_bf16 v[104:107], v[20:23], v[116:119], v[104:107]
	v_mfma_f32_16x16x32_bf16 v[108:111], v[24:27], v[112:115], 0
	v_mfma_f32_16x16x32_bf16 v[16:19], v[20:23], v[124:127], v[16:19]
	v_mfma_f32_16x16x32_bf16 v[20:23], v[24:27], v[120:123], 0
	v_mfma_f32_16x16x32_bf16 v[108:111], v[28:31], v[116:119], v[108:111]
	v_mfma_f32_16x16x32_bf16 v[20:23], v[28:31], v[124:127], v[20:23]
	s_barrier
	s_add_i32 s85, 0, 0x18000
	s_add_i32 s88, 0, 0x1c000
	v_add_u32_e32 v165, s85, v159
	v_add_u32_e32 v226, s88, v159
	ds_read_b128 v[24:27], v165
	ds_read_b128 v[28:31], v165 offset:1024
	ds_read_b128 v[112:115], v165 offset:2048
	ds_read_b128 v[116:119], v165 offset:3072
	ds_read_b128 v[120:123], v226
	ds_read_b128 v[124:127], v226 offset:1024
	ds_read_b128 v[174:177], v226 offset:2048
	ds_read_b128 v[178:181], v226 offset:3072
	s_add_u32 s86, s40, 0x10100
	s_addc_u32 s87, s41, 0
	s_mov_b32 m0, s54
	v_lshl_add_u64 v[220:221], s[86:87], 0, v[128:129]
	ds_read_b128 v[182:185], v163 offset:32768
	ds_read_b128 v[186:189], v163 offset:33792
	ds_read_b128 v[190:193], v163 offset:34816
	ds_read_b128 v[194:197], v163 offset:35840
	ds_read_b128 v[198:201], v163 offset:36864
	ds_read_b128 v[202:205], v163 offset:37888
	ds_read_b128 v[206:209], v163 offset:38912
	ds_read_b128 v[210:213], v163 offset:39936
	global_load_lds_dwordx4 v[220:221], off
	v_lshl_add_u64 v[220:221], s[86:87], 0, v[132:133]
	s_mov_b32 m0, s55
	s_nop 0
	global_load_lds_dwordx4 v[220:221], off
	s_waitcnt vmcnt(8)
	s_waitcnt lgkmcnt(0)
	s_barrier
	s_waitcnt lgkmcnt(0)
	v_mfma_f32_16x16x32_bf16 v[64:67], v[24:27], v[182:185], v[64:67]
	v_mfma_f32_16x16x32_bf16 v[68:71], v[112:115], v[182:185], v[68:71]
	v_mfma_f32_16x16x32_bf16 v[72:75], v[24:27], v[190:193], v[72:75]
	v_mfma_f32_16x16x32_bf16 v[76:79], v[112:115], v[190:193], v[76:79]
	v_mfma_f32_16x16x32_bf16 v[80:83], v[24:27], v[198:201], v[80:83]
	v_mfma_f32_16x16x32_bf16 v[84:87], v[112:115], v[198:201], v[84:87]
	v_mfma_f32_16x16x32_bf16 v[88:91], v[24:27], v[206:209], v[88:91]
	v_mfma_f32_16x16x32_bf16 v[92:95], v[112:115], v[206:209], v[92:95]
	v_mfma_f32_16x16x32_bf16 v[64:67], v[28:31], v[186:189], v[64:67]
	v_mfma_f32_16x16x32_bf16 v[68:71], v[116:119], v[186:189], v[68:71]
	v_mfma_f32_16x16x32_bf16 v[72:75], v[28:31], v[194:197], v[72:75]
	v_mfma_f32_16x16x32_bf16 v[76:79], v[116:119], v[194:197], v[76:79]
	v_mfma_f32_16x16x32_bf16 v[80:83], v[28:31], v[202:205], v[80:83]
	v_mfma_f32_16x16x32_bf16 v[84:87], v[116:119], v[202:205], v[84:87]
	v_mfma_f32_16x16x32_bf16 v[88:91], v[28:31], v[210:213], v[88:91]
	v_mfma_f32_16x16x32_bf16 v[92:95], v[116:119], v[210:213], v[92:95]
	v_mfma_f32_16x16x32_bf16 v[96:99], v[120:123], v[182:185], v[96:99]
	v_mfma_f32_16x16x32_bf16 v[32:35], v[174:177], v[182:185], v[32:35]
	v_mfma_f32_16x16x32_bf16 v[36:39], v[120:123], v[190:193], v[36:39]
	v_mfma_f32_16x16x32_bf16 v[40:43], v[174:177], v[190:193], v[40:43]
	v_mfma_f32_16x16x32_bf16 v[44:47], v[120:123], v[198:201], v[44:47]
	v_mfma_f32_16x16x32_bf16 v[48:51], v[174:177], v[198:201], v[48:51]
	v_mfma_f32_16x16x32_bf16 v[52:55], v[120:123], v[206:209], v[52:55]
	v_mfma_f32_16x16x32_bf16 v[56:59], v[174:177], v[206:209], v[56:59]
	v_mfma_f32_16x16x32_bf16 v[96:99], v[124:127], v[186:189], v[96:99]
	v_mfma_f32_16x16x32_bf16 v[32:35], v[178:181], v[186:189], v[32:35]
	v_mfma_f32_16x16x32_bf16 v[36:39], v[124:127], v[194:197], v[36:39]
	v_mfma_f32_16x16x32_bf16 v[40:43], v[178:181], v[194:197], v[40:43]
	v_mfma_f32_16x16x32_bf16 v[44:47], v[124:127], v[202:205], v[44:47]
	v_mfma_f32_16x16x32_bf16 v[48:51], v[178:181], v[202:205], v[48:51]
	v_mfma_f32_16x16x32_bf16 v[52:55], v[124:127], v[210:213], v[52:55]
	v_mfma_f32_16x16x32_bf16 v[56:59], v[178:181], v[210:213], v[56:59]
	s_barrier
	s_add_i32 s85, s85, s52
	s_add_i32 s69, s85, 0x2000
	v_lshl_add_u64 v[156:157], v[156:157], 0, s[18:19]
	s_mov_b32 m0, s85
	s_add_u32 s86, s42, 0x10180
	ds_read_b128 v[182:185], v163 offset:49152
	ds_read_b128 v[186:189], v163 offset:50176
	ds_read_b128 v[190:193], v163 offset:51200
	ds_read_b128 v[194:197], v163 offset:52224
	ds_read_b128 v[198:201], v163 offset:53248
	ds_read_b128 v[202:205], v163 offset:54272
	ds_read_b128 v[206:209], v163 offset:55296
	ds_read_b128 v[210:213], v163 offset:56320
	global_load_lds_dwordx4 v[156:157], off
	v_lshl_add_u64 v[156:157], v[214:215], 0, s[18:19]
	s_mov_b32 m0, s69
	s_addc_u32 s87, s43, 0
	s_add_i32 s42, s88, s52
	global_load_lds_dwordx4 v[156:157], off
	v_lshl_add_u64 v[156:157], s[86:87], 0, v[130:131]
	s_mov_b32 m0, s42
	s_add_i32 s43, s42, 0x2000
	global_load_lds_dwordx4 v[156:157], off
	v_lshl_add_u64 v[156:157], s[86:87], 0, v[134:135]
	s_mov_b32 m0, s43
	s_nop 0
	global_load_lds_dwordx4 v[156:157], off
	v_lshl_add_u64 v[156:157], v[216:217], 0, s[18:19]
	s_mov_b32 m0, s56
	s_nop 0
	global_load_lds_dwordx4 v[156:157], off
	v_lshl_add_u64 v[156:157], v[218:219], 0, s[18:19]
	s_mov_b32 m0, s57
	s_nop 0
	global_load_lds_dwordx4 v[156:157], off
	s_waitcnt vmcnt(8)
	s_waitcnt lgkmcnt(0)
	s_barrier
	s_waitcnt lgkmcnt(0)
	v_mfma_f32_16x16x32_bf16 v[0:3], v[24:27], v[206:209], v[0:3]
	v_mfma_f32_16x16x32_bf16 v[4:7], v[112:115], v[206:209], v[4:7]
	v_mfma_f32_16x16x32_bf16 v[140:143], v[24:27], v[182:185], v[140:143]
	v_mfma_f32_16x16x32_bf16 v[144:147], v[112:115], v[182:185], v[144:147]
	v_mfma_f32_16x16x32_bf16 v[148:151], v[24:27], v[190:193], v[148:151]
	v_mfma_f32_16x16x32_bf16 v[152:155], v[112:115], v[190:193], v[152:155]
	v_mfma_f32_16x16x32_bf16 v[166:169], v[24:27], v[198:201], v[166:169]
	v_mfma_f32_16x16x32_bf16 v[170:173], v[112:115], v[198:201], v[170:173]
	v_mfma_f32_16x16x32_bf16 v[0:3], v[28:31], v[210:213], v[0:3]
	v_mfma_f32_16x16x32_bf16 v[4:7], v[116:119], v[210:213], v[4:7]
	v_mfma_f32_16x16x32_bf16 v[140:143], v[28:31], v[186:189], v[140:143]
	v_mfma_f32_16x16x32_bf16 v[144:147], v[116:119], v[186:189], v[144:147]
	v_mfma_f32_16x16x32_bf16 v[148:151], v[28:31], v[194:197], v[148:151]
	v_mfma_f32_16x16x32_bf16 v[152:155], v[116:119], v[194:197], v[152:155]
	v_mfma_f32_16x16x32_bf16 v[166:169], v[28:31], v[202:205], v[166:169]
	v_mfma_f32_16x16x32_bf16 v[170:173], v[116:119], v[202:205], v[170:173]
	v_mfma_f32_16x16x32_bf16 v[8:11], v[120:123], v[182:185], v[8:11]
	v_mfma_f32_16x16x32_bf16 v[12:15], v[174:177], v[182:185], v[12:15]
	v_mfma_f32_16x16x32_bf16 v[24:27], v[120:123], v[190:193], v[60:63]
	v_mfma_f32_16x16x32_bf16 v[28:31], v[174:177], v[190:193], v[100:103]
	v_mfma_f32_16x16x32_bf16 v[60:63], v[120:123], v[198:201], v[104:107]
	v_mfma_f32_16x16x32_bf16 v[100:103], v[174:177], v[198:201], v[108:111]
	v_mfma_f32_16x16x32_bf16 v[16:19], v[120:123], v[206:209], v[16:19]
	v_mfma_f32_16x16x32_bf16 v[20:23], v[174:177], v[206:209], v[20:23]
	v_mfma_f32_16x16x32_bf16 v[8:11], v[124:127], v[186:189], v[8:11]
	v_mfma_f32_16x16x32_bf16 v[12:15], v[178:181], v[186:189], v[12:15]
	v_mfma_f32_16x16x32_bf16 v[24:27], v[124:127], v[194:197], v[24:27]
	v_mfma_f32_16x16x32_bf16 v[28:31], v[178:181], v[194:197], v[28:31]
	v_mfma_f32_16x16x32_bf16 v[60:63], v[124:127], v[202:205], v[60:63]
	v_mfma_f32_16x16x32_bf16 v[100:103], v[178:181], v[202:205], v[100:103]
	v_mfma_f32_16x16x32_bf16 v[16:19], v[124:127], v[210:213], v[16:19]
	v_mfma_f32_16x16x32_bf16 v[20:23], v[178:181], v[210:213], v[20:23]
	s_barrier
	ds_read_b128 v[104:107], v161
	ds_read_b128 v[108:111], v161 offset:1024
	ds_read_b128 v[112:115], v161 offset:2048
	ds_read_b128 v[116:119], v161 offset:3072
	ds_read_b128 v[120:123], v162
	ds_read_b128 v[124:127], v162 offset:1024
	ds_read_b128 v[174:177], v162 offset:2048
	ds_read_b128 v[178:181], v162 offset:3072
	s_add_u32 s40, s40, 0x10180
	s_addc_u32 s41, s41, 0
	s_mov_b32 m0, s84
	v_lshl_add_u64 v[156:157], s[40:41], 0, v[128:129]
	ds_read_b128 v[182:185], v163
	ds_read_b128 v[186:189], v163 offset:1024
	ds_read_b128 v[190:193], v163 offset:2048
	ds_read_b128 v[194:197], v163 offset:3072
	ds_read_b128 v[198:201], v163 offset:4096
	ds_read_b128 v[202:205], v163 offset:5120
	ds_read_b128 v[206:209], v163 offset:6144
	ds_read_b128 v[210:213], v163 offset:7168
	global_load_lds_dwordx4 v[156:157], off
	v_lshl_add_u64 v[156:157], s[40:41], 0, v[132:133]
	s_mov_b32 m0, s29
	s_nop 0
	global_load_lds_dwordx4 v[156:157], off
	s_waitcnt vmcnt(8)
	s_waitcnt lgkmcnt(0)
	s_barrier
	s_waitcnt lgkmcnt(0)
	v_mfma_f32_16x16x32_bf16 v[64:67], v[104:107], v[182:185], v[64:67]
	v_mfma_f32_16x16x32_bf16 v[68:71], v[112:115], v[182:185], v[68:71]
	v_mfma_f32_16x16x32_bf16 v[72:75], v[104:107], v[190:193], v[72:75]
	v_mfma_f32_16x16x32_bf16 v[76:79], v[112:115], v[190:193], v[76:79]
	v_mfma_f32_16x16x32_bf16 v[80:83], v[104:107], v[198:201], v[80:83]
	v_mfma_f32_16x16x32_bf16 v[84:87], v[112:115], v[198:201], v[84:87]
	v_mfma_f32_16x16x32_bf16 v[88:91], v[104:107], v[206:209], v[88:91]
	v_mfma_f32_16x16x32_bf16 v[64:67], v[108:111], v[186:189], v[64:67]
	v_mfma_f32_16x16x32_bf16 v[68:71], v[116:119], v[186:189], v[68:71]
	v_mfma_f32_16x16x32_bf16 v[72:75], v[108:111], v[194:197], v[72:75]
	v_mfma_f32_16x16x32_bf16 v[76:79], v[116:119], v[194:197], v[76:79]
	v_mfma_f32_16x16x32_bf16 v[80:83], v[108:111], v[202:205], v[80:83]
	v_mfma_f32_16x16x32_bf16 v[84:87], v[116:119], v[202:205], v[84:87]
	v_mfma_f32_16x16x32_bf16 v[214:217], v[108:111], v[210:213], v[88:91]
	v_mfma_f32_16x16x32_bf16 v[88:91], v[112:115], v[206:209], v[92:95]
	v_mfma_f32_16x16x32_bf16 v[218:221], v[116:119], v[210:213], v[88:91]
	v_mfma_f32_16x16x32_bf16 v[88:91], v[120:123], v[182:185], v[96:99]
	v_mfma_f32_16x16x32_bf16 v[32:35], v[174:177], v[182:185], v[32:35]
	v_mfma_f32_16x16x32_bf16 v[36:39], v[120:123], v[190:193], v[36:39]
	v_mfma_f32_16x16x32_bf16 v[40:43], v[174:177], v[190:193], v[40:43]
	v_mfma_f32_16x16x32_bf16 v[44:47], v[120:123], v[198:201], v[44:47]
	v_mfma_f32_16x16x32_bf16 v[48:51], v[174:177], v[198:201], v[48:51]
	v_mfma_f32_16x16x32_bf16 v[52:55], v[120:123], v[206:209], v[52:55]
	v_mfma_f32_16x16x32_bf16 v[56:59], v[174:177], v[206:209], v[56:59]
	v_mfma_f32_16x16x32_bf16 v[96:99], v[124:127], v[186:189], v[88:91]
	v_mfma_f32_16x16x32_bf16 v[32:35], v[178:181], v[186:189], v[32:35]
	v_mfma_f32_16x16x32_bf16 v[36:39], v[124:127], v[194:197], v[36:39]
	v_mfma_f32_16x16x32_bf16 v[40:43], v[178:181], v[194:197], v[40:43]
	v_mfma_f32_16x16x32_bf16 v[44:47], v[124:127], v[202:205], v[44:47]
	v_mfma_f32_16x16x32_bf16 v[48:51], v[178:181], v[202:205], v[48:51]
	v_mfma_f32_16x16x32_bf16 v[52:55], v[124:127], v[210:213], v[52:55]
	v_mfma_f32_16x16x32_bf16 v[56:59], v[178:181], v[210:213], v[56:59]
	s_barrier
	s_mov_b32 m0, s68
	v_lshl_add_u64 v[156:157], s[44:45], 0, v[130:131]
	s_add_u32 s40, s44, 0x10000
	ds_read_b128 v[88:91], v163 offset:16384
	ds_read_b128 v[92:95], v163 offset:17408
	ds_read_b128 v[182:185], v163 offset:18432
	ds_read_b128 v[186:189], v163 offset:19456
	ds_read_b128 v[190:193], v163 offset:20480
	ds_read_b128 v[194:197], v163 offset:21504
	ds_read_b128 v[198:201], v163 offset:22528
	ds_read_b128 v[202:205], v163 offset:23552
	global_load_lds_dwordx4 v[156:157], off
	v_lshl_add_u64 v[250:251], s[44:45], 0, v[134:135]
	s_mov_b32 m0, s31
	s_addc_u32 s41, s45, 0
	global_load_lds_dwordx4 v[250:251], off
	v_lshl_add_u64 v[206:207], s[40:41], 0, v[130:131]
	s_mov_b32 m0, s66
	v_lshl_add_u64 v[252:253], s[46:47], 0, v[128:129]
	global_load_lds_dwordx4 v[206:207], off
	v_lshl_add_u64 v[206:207], s[40:41], 0, v[134:135]
	s_mov_b32 m0, s67
	v_lshl_add_u64 v[136:137], s[46:47], 0, v[132:133]
	global_load_lds_dwordx4 v[206:207], off
	s_mov_b32 m0, s39
	s_nop 0
	global_load_lds_dwordx4 v[252:253], off
	s_mov_b32 m0, s53
	s_nop 0
	global_load_lds_dwordx4 v[136:137], off
	s_waitcnt vmcnt(8)
	s_waitcnt lgkmcnt(0)
	s_barrier
	s_waitcnt lgkmcnt(0)
	v_mfma_f32_16x16x32_bf16 v[0:3], v[104:107], v[198:201], v[0:3]
	v_mfma_f32_16x16x32_bf16 v[4:7], v[112:115], v[198:201], v[4:7]
	v_mfma_f32_16x16x32_bf16 v[140:143], v[104:107], v[88:91], v[140:143]
	v_mfma_f32_16x16x32_bf16 v[144:147], v[112:115], v[88:91], v[144:147]
	v_mfma_f32_16x16x32_bf16 v[148:151], v[104:107], v[182:185], v[148:151]
	v_mfma_f32_16x16x32_bf16 v[152:155], v[112:115], v[182:185], v[152:155]
	v_mfma_f32_16x16x32_bf16 v[166:169], v[104:107], v[190:193], v[166:169]
	v_mfma_f32_16x16x32_bf16 v[170:173], v[112:115], v[190:193], v[170:173]
	v_mfma_f32_16x16x32_bf16 v[0:3], v[108:111], v[202:205], v[0:3]
	v_mfma_f32_16x16x32_bf16 v[4:7], v[116:119], v[202:205], v[4:7]
	v_mfma_f32_16x16x32_bf16 v[140:143], v[108:111], v[92:95], v[140:143]
	v_mfma_f32_16x16x32_bf16 v[144:147], v[116:119], v[92:95], v[144:147]
	v_mfma_f32_16x16x32_bf16 v[148:151], v[108:111], v[186:189], v[148:151]
	v_mfma_f32_16x16x32_bf16 v[152:155], v[116:119], v[186:189], v[152:155]
	v_mfma_f32_16x16x32_bf16 v[166:169], v[108:111], v[194:197], v[166:169]
	v_mfma_f32_16x16x32_bf16 v[170:173], v[116:119], v[194:197], v[170:173]
	v_mfma_f32_16x16x32_bf16 v[8:11], v[120:123], v[88:91], v[8:11]
	v_mfma_f32_16x16x32_bf16 v[206:209], v[124:127], v[92:95], v[8:11]
	v_mfma_f32_16x16x32_bf16 v[8:11], v[174:177], v[88:91], v[12:15]
	v_mfma_f32_16x16x32_bf16 v[210:213], v[178:181], v[92:95], v[8:11]
	v_mfma_f32_16x16x32_bf16 v[8:11], v[120:123], v[182:185], v[24:27]
	v_mfma_f32_16x16x32_bf16 v[222:225], v[124:127], v[186:189], v[8:11]
	v_mfma_f32_16x16x32_bf16 v[8:11], v[174:177], v[182:185], v[28:31]
	v_mfma_f32_16x16x32_bf16 v[182:185], v[178:181], v[186:189], v[8:11]
	v_mfma_f32_16x16x32_bf16 v[8:11], v[120:123], v[190:193], v[60:63]
	v_mfma_f32_16x16x32_bf16 v[186:189], v[124:127], v[194:197], v[8:11]
	v_mfma_f32_16x16x32_bf16 v[8:11], v[174:177], v[190:193], v[100:103]
	v_mfma_f32_16x16x32_bf16 v[190:193], v[178:181], v[194:197], v[8:11]
	v_mfma_f32_16x16x32_bf16 v[8:11], v[120:123], v[198:201], v[16:19]
	v_mfma_f32_16x16x32_bf16 v[194:197], v[124:127], v[202:205], v[8:11]
	v_mfma_f32_16x16x32_bf16 v[8:11], v[174:177], v[198:201], v[20:23]
	v_mfma_f32_16x16x32_bf16 v[174:177], v[178:181], v[202:205], v[8:11]
	s_barrier
	s_nop 4
	ds_read_b128 v[8:11], v165
	ds_read_b128 v[12:15], v165 offset:1024
	ds_read_b128 v[16:19], v165 offset:2048
	ds_read_b128 v[20:23], v165 offset:3072
	ds_read_b128 v[178:181], v226
	ds_read_b128 v[198:201], v226 offset:1024
	ds_read_b128 v[202:205], v226 offset:2048
	ds_read_b128 v[226:229], v226 offset:3072
	s_add_u32 s40, s46, 0x10000
	s_addc_u32 s41, s47, 0
	s_mov_b32 m0, s54
	v_lshl_add_u64 v[88:89], s[40:41], 0, v[128:129]
	ds_read_b128 v[24:27], v163 offset:32768
	ds_read_b128 v[28:31], v163 offset:33792
	ds_read_b128 v[60:63], v163 offset:34816
	ds_read_b128 v[230:233], v163 offset:35840
	ds_read_b128 v[234:237], v163 offset:36864
	ds_read_b128 v[238:241], v163 offset:37888
	ds_read_b128 v[242:245], v163 offset:38912
	ds_read_b128 v[246:249], v163 offset:39936
	global_load_lds_dwordx4 v[88:89], off
	v_lshl_add_u64 v[88:89], s[40:41], 0, v[132:133]
	s_mov_b32 m0, s55
	s_nop 0
	global_load_lds_dwordx4 v[88:89], off
	s_waitcnt vmcnt(8)
	s_waitcnt lgkmcnt(0)
	s_barrier
	s_waitcnt lgkmcnt(0)
	v_mfma_f32_16x16x32_bf16 v[64:67], v[8:11], v[24:27], v[64:67]
	v_mfma_f32_16x16x32_bf16 v[124:127], v[12:15], v[28:31], v[64:67]
	v_mfma_f32_16x16x32_bf16 v[64:67], v[16:19], v[24:27], v[68:71]
	v_mfma_f32_16x16x32_bf16 v[120:123], v[20:23], v[28:31], v[64:67]
	v_mfma_f32_16x16x32_bf16 v[64:67], v[8:11], v[60:63], v[72:75]
	v_mfma_f32_16x16x32_bf16 v[108:111], v[12:15], v[230:233], v[64:67]
	v_mfma_f32_16x16x32_bf16 v[64:67], v[16:19], v[60:63], v[76:79]
	v_mfma_f32_16x16x32_bf16 v[104:107], v[20:23], v[230:233], v[64:67]
	v_mfma_f32_16x16x32_bf16 v[64:67], v[8:11], v[234:237], v[80:83]
	v_mfma_f32_16x16x32_bf16 v[92:95], v[12:15], v[238:241], v[64:67]
	v_mfma_f32_16x16x32_bf16 v[64:67], v[16:19], v[234:237], v[84:87]
	v_mfma_f32_16x16x32_bf16 v[88:91], v[20:23], v[238:241], v[64:67]
	v_mfma_f32_16x16x32_bf16 v[64:67], v[8:11], v[242:245], v[214:217]
	v_mfma_f32_16x16x32_bf16 v[68:71], v[12:15], v[246:249], v[64:67]
	v_mfma_f32_16x16x32_bf16 v[64:67], v[16:19], v[242:245], v[218:221]
	v_mfma_f32_16x16x32_bf16 v[64:67], v[20:23], v[246:249], v[64:67]
	v_mfma_f32_16x16x32_bf16 v[72:75], v[178:181], v[24:27], v[96:99]
	v_mfma_f32_16x16x32_bf16 v[24:27], v[202:205], v[24:27], v[32:35]
	v_mfma_f32_16x16x32_bf16 v[112:115], v[226:229], v[28:31], v[24:27]
	v_mfma_f32_16x16x32_bf16 v[24:27], v[178:181], v[60:63], v[36:39]
	v_mfma_f32_16x16x32_bf16 v[100:103], v[198:201], v[230:233], v[24:27]
	v_mfma_f32_16x16x32_bf16 v[24:27], v[202:205], v[60:63], v[40:43]
	v_mfma_f32_16x16x32_bf16 v[96:99], v[226:229], v[230:233], v[24:27]
	v_mfma_f32_16x16x32_bf16 v[24:27], v[178:181], v[234:237], v[44:47]
	v_mfma_f32_16x16x32_bf16 v[84:87], v[198:201], v[238:241], v[24:27]
	v_mfma_f32_16x16x32_bf16 v[24:27], v[202:205], v[234:237], v[48:51]
	v_mfma_f32_16x16x32_bf16 v[80:83], v[226:229], v[238:241], v[24:27]
	v_mfma_f32_16x16x32_bf16 v[24:27], v[178:181], v[242:245], v[52:55]
	v_mfma_f32_16x16x32_bf16 v[52:55], v[198:201], v[246:249], v[24:27]
	v_mfma_f32_16x16x32_bf16 v[24:27], v[202:205], v[242:245], v[56:59]
	v_mfma_f32_16x16x32_bf16 v[116:119], v[198:201], v[28:31], v[72:75]
	v_mfma_f32_16x16x32_bf16 v[48:51], v[226:229], v[246:249], v[24:27]
	s_barrier
	s_mov_b32 m0, s85
	s_nop 2
	v_lshl_add_u64 v[24:25], v[156:157], 0, s[8:9]
	s_add_u32 s40, s44, 0x10080
	ds_read_b128 v[32:35], v163 offset:49152
	ds_read_b128 v[36:39], v163 offset:50176
	ds_read_b128 v[214:217], v163 offset:51200
	ds_read_b128 v[218:221], v163 offset:52224
	ds_read_b128 v[230:233], v163 offset:53248
	ds_read_b128 v[234:237], v163 offset:54272
	ds_read_b128 v[238:241], v163 offset:55296
	ds_read_b128 v[242:245], v163 offset:56320
	global_load_lds_dwordx4 v[24:25], off
	v_lshl_add_u64 v[24:25], v[250:251], 0, s[8:9]
	s_mov_b32 m0, s69
	s_addc_u32 s41, s45, 0
	global_load_lds_dwordx4 v[24:25], off
	v_lshl_add_u64 v[24:25], s[40:41], 0, v[130:131]
	s_mov_b32 m0, s42
	s_nop 0
	global_load_lds_dwordx4 v[24:25], off
	v_lshl_add_u64 v[24:25], s[40:41], 0, v[134:135]
	s_mov_b32 m0, s43
	s_nop 0
	global_load_lds_dwordx4 v[24:25], off
	v_lshl_add_u64 v[24:25], v[252:253], 0, s[8:9]
	s_mov_b32 m0, s56
	s_nop 0
	global_load_lds_dwordx4 v[24:25], off
	v_lshl_add_u64 v[24:25], v[136:137], 0, s[8:9]
	s_mov_b32 m0, s57
	s_nop 0
	global_load_lds_dwordx4 v[24:25], off
	s_waitcnt vmcnt(8)
	s_waitcnt lgkmcnt(0)
	s_barrier
	s_waitcnt lgkmcnt(0)
	v_mfma_f32_16x16x32_bf16 v[24:27], v[8:11], v[32:35], v[140:143]
	v_mfma_f32_16x16x32_bf16 v[76:79], v[12:15], v[36:39], v[24:27]
	v_mfma_f32_16x16x32_bf16 v[24:27], v[16:19], v[32:35], v[144:147]
	v_mfma_f32_16x16x32_bf16 v[72:75], v[20:23], v[36:39], v[24:27]
	v_mfma_f32_16x16x32_bf16 v[24:27], v[8:11], v[214:217], v[148:151]
	v_mfma_f32_16x16x32_bf16 v[44:47], v[12:15], v[218:221], v[24:27]
	v_mfma_f32_16x16x32_bf16 v[24:27], v[16:19], v[214:217], v[152:155]
	v_mfma_f32_16x16x32_bf16 v[40:43], v[20:23], v[218:221], v[24:27]
	v_mfma_f32_16x16x32_bf16 v[24:27], v[8:11], v[230:233], v[166:169]
	v_mfma_f32_16x16x32_bf16 v[0:3], v[8:11], v[238:241], v[0:3]
	v_mfma_f32_16x16x32_bf16 v[28:31], v[12:15], v[234:237], v[24:27]
	v_mfma_f32_16x16x32_bf16 v[24:27], v[16:19], v[230:233], v[170:173]
	v_mfma_f32_16x16x32_bf16 v[12:15], v[12:15], v[242:245], v[0:3]
	v_mfma_f32_16x16x32_bf16 v[0:3], v[16:19], v[238:241], v[4:7]
	v_mfma_f32_16x16x32_bf16 v[24:27], v[20:23], v[234:237], v[24:27]
	v_mfma_f32_16x16x32_bf16 v[8:11], v[20:23], v[242:245], v[0:3]
	v_mfma_f32_16x16x32_bf16 v[0:3], v[178:181], v[32:35], v[206:209]
	v_mfma_f32_16x16x32_bf16 v[60:63], v[198:201], v[36:39], v[0:3]
	v_mfma_f32_16x16x32_bf16 v[0:3], v[202:205], v[32:35], v[210:213]
	v_mfma_f32_16x16x32_bf16 v[56:59], v[226:229], v[36:39], v[0:3]
	v_mfma_f32_16x16x32_bf16 v[0:3], v[178:181], v[214:217], v[222:225]
	v_mfma_f32_16x16x32_bf16 v[36:39], v[198:201], v[218:221], v[0:3]
	v_mfma_f32_16x16x32_bf16 v[0:3], v[202:205], v[214:217], v[182:185]
	v_mfma_f32_16x16x32_bf16 v[32:35], v[226:229], v[218:221], v[0:3]
	v_mfma_f32_16x16x32_bf16 v[0:3], v[178:181], v[230:233], v[186:189]
	v_mfma_f32_16x16x32_bf16 v[20:23], v[198:201], v[234:237], v[0:3]
	v_mfma_f32_16x16x32_bf16 v[0:3], v[202:205], v[230:233], v[190:193]
	v_mfma_f32_16x16x32_bf16 v[16:19], v[226:229], v[234:237], v[0:3]
	v_mfma_f32_16x16x32_bf16 v[0:3], v[178:181], v[238:241], v[194:197]
	v_mfma_f32_16x16x32_bf16 v[4:7], v[198:201], v[242:245], v[0:3]
	v_mfma_f32_16x16x32_bf16 v[0:3], v[202:205], v[238:241], v[174:177]
	v_mfma_f32_16x16x32_bf16 v[0:3], v[226:229], v[242:245], v[0:3]
	s_barrier
	s_andn2_b64 vcc, exec, s[12:13]
	s_cbranch_vccnz .LBB0_1282
	s_barrier

.LBB0_1286:
	s_or_b64 exec, exec, s[10:11]
	s_setprio 0
	s_load_dwordx2 s[2:3], s[0:1], 0x120
	s_waitcnt lgkmcnt(0)
	s_cmp_lt_i32 s2, 14
	s_cselect_b64 s[4:5], -1, 0
	s_cmp_gt_i32 s3, 14
	s_cselect_b64 s[6:7], -1, 0
	s_and_b64 s[4:5], s[4:5], s[6:7]
	s_andn2_b64 vcc, exec, s[4:5]
	s_cbranch_vccnz .LBB0_1317
	v_readlane_b32 s2, v254, 0
	s_waitcnt vmcnt(0) lgkmcnt(0)
	s_lshl_b32 s2, s2, 6
	s_sub_i32 s2, 0, s2
	s_waitcnt vmcnt(0)
	s_barrier
	v_mbcnt_lo_u32_b32 v0, -1, 0
	v_mbcnt_hi_u32_b32 v0, -1, v0
	s_nop 0
	v_cmp_eq_u32_e32 vcc, s2, v0
	s_and_saveexec_b64 s[82:83], vcc
	s_cbranch_execz .LBB0_1316
	s_add_i32 s2, 0, 0x20040
	v_mov_b32_e32 v0, s2
	ds_read_b32 v1, v0
	s_add_i32 s2, 0, 0x20044
	v_mov_b32_e32 v0, s2
	ds_read_b32 v0, v0
	s_waitcnt lgkmcnt(1)
	v_cmp_ne_u32_e32 vcc, 0, v1
	s_cbranch_vccnz .LBB0_1294
	s_cmp_eq_u32 s97, 0
	s_cselect_b64 s[2:3], -1, 0
	s_cmp_eq_u32 s97, 1
	s_cselect_b64 s[4:5], -1, 0
	s_cmp_eq_u32 s97, 2
	s_cselect_b64 s[6:7], -1, 0
	s_cmp_eq_u32 s97, 3
	s_cselect_b64 s[8:9], -1, 0
	s_cmp_eq_u32 s97, 4
	s_cselect_b64 s[10:11], -1, 0
	s_cmp_eq_u32 s97, 5
	s_cselect_b64 s[12:13], -1, 0
	s_cmp_eq_u32 s97, 6
	s_cselect_b64 s[14:15], -1, 0
	s_cmp_eq_u32 s97, 7
	s_cselect_b64 s[16:17], -1, 0
	s_cmp_eq_u32 s97, 8
	s_cselect_b64 s[18:19], -1, 0
	s_cmp_eq_u32 s97, 9
	s_cselect_b64 s[20:21], -1, 0
	s_cmp_eq_u32 s97, 10
	s_cselect_b64 s[22:23], -1, 0
	s_cmp_eq_u32 s97, 11
	s_cselect_b64 s[24:25], -1, 0
	s_add_u32 s84, s70, 0x1000
	s_addc_u32 s85, s71, 0
	s_cmp_eq_u32 s97, 12
	s_cselect_b64 s[26:27], -1, 0
	s_add_u32 s86, s70, 0x1100
	s_addc_u32 s87, s71, 0
	s_cmp_eq_u32 s97, 13
	s_cselect_b64 s[28:29], -1, 0
	s_add_u32 s88, s70, 0x1200
	s_addc_u32 s89, s71, 0
	s_cmp_eq_u32 s97, 14
	s_cselect_b64 s[30:31], -1, 0
	s_add_u32 s90, s70, 0x1300
	s_addc_u32 s91, s71, 0
	s_cmp_eq_u32 s97, 15
	s_cselect_b64 s[34:35], -1, 0
	v_mov_b32_e32 v2, 0
	v_mov_b32_e32 v1, 0
	s_branch .LBB0_1291

.LBB0_1324:
	s_andn2_b64 vcc, exec, s[4:5]
	s_cbranch_vccnz .LBB0_1360
	v_ashrrev_i32_e32 v2, 31, v0
	v_lshrrev_b32_e32 v2, 26, v2
	v_lshlrev_b32_e32 v1, 4, v0
	v_add_u32_e32 v2, v0, v2
	v_bfe_i32 v0, v0, 27, 1
	v_lshrrev_b32_e32 v0, 22, v0
	v_add_u32_e32 v0, v1, v0
	v_and_b32_e32 v0, 0xfffffc00, v0
	v_sub_u32_e32 v0, v1, v0
	v_ashrrev_i32_e32 v9, 6, v2
	v_lshrrev_b32_e32 v2, 4, v0
	v_bitop3_b32 v0, v2, v0, 32 bitop3:0x6c
	v_ashrrev_i32_e32 v3, 31, v0
	v_lshrrev_b32_e32 v3, 26, v3
	v_add_u32_e32 v3, v0, v3
	v_lshlrev_b32_e32 v2, 3, v9
	v_ashrrev_i32_e32 v10, 6, v3
	v_and_b32_e32 v3, 0xc0, v3
	v_and_b32_e32 v2, -16, v2
	v_sub_u32_e32 v0, v0, v3
	v_mov_b32_e32 v3, 1
	v_add_u32_e32 v2, v10, v2
	v_ashrrev_i16_sdwa v0, v3, sext(v0) dst_sel:DWORD dst_unused:UNUSED_PAD src0_sel:DWORD src1_sel:BYTE_0
	v_lshlrev_b32_e32 v4, 5, v9
	v_bfe_i32 v11, v0, 0, 16
	v_lshlrev_b32_e32 v0, 1, v2
	v_lshrrev_b32_e32 v5, 2, v2
	v_and_b32_e32 v6, 3, v10
	s_mov_b32 s3, 0x1fffe0
	v_and_b32_e32 v4, 32, v4
	v_and_b32_e32 v0, 24, v0
	v_and_b32_e32 v5, 4, v5
	v_and_or_b32 v6, v2, s3, v6
	v_or3_b32 v0, v6, v5, v0
	v_add_lshl_u32 v4, v4, v11, 1
	v_lshl_add_u32 v130, v0, 11, v4
	v_add_u32_e32 v0, 0x2000, v1
	v_ashrrev_i32_e32 v1, 31, v0
	v_lshrrev_b32_e32 v1, 22, v1
	v_add_u32_e32 v1, v0, v1
	v_ashrrev_i32_e32 v12, 10, v1
	v_mul_i32_i24_e32 v1, 0x400, v12
	v_sub_u32_e32 v0, v0, v1
	v_lshrrev_b32_e32 v1, 4, v0
	v_bitop3_b32 v0, v1, v0, 32 bitop3:0x6c
	v_lshl_add_u32 v128, v2, 11, v4
	v_ashrrev_i32_e32 v2, 31, v0
	v_lshrrev_b32_e32 v2, 26, v2
	v_add_u32_e32 v2, v0, v2
	v_lshlrev_b32_e32 v1, 3, v12
	v_ashrrev_i32_e32 v13, 6, v2
	v_and_b32_e32 v2, 0xc0, v2
	s_add_u32 s30, s70, 0x5600000
	v_and_b32_e32 v1, -16, v1
	v_sub_u32_e32 v0, v0, v2
	s_addc_u32 s31, s71, 0
	s_ashr_i32 s2, s12, 6
	v_add_u32_e32 v1, v13, v1
	v_ashrrev_i16_sdwa v0, v3, sext(v0) dst_sel:DWORD dst_unused:UNUSED_PAD src0_sel:DWORD src1_sel:BYTE_0
	v_and_b32_e32 v3, 3, v13
	s_ashr_i32 s23, s22, 31
	s_ashr_i32 s7, s6, 31
	v_and_or_b32 v3, v1, s3, v3
	s_ashr_i32 s3, s12, 8
	s_lshl_b32 s34, s2, 10
	s_lshl_b64 s[4:5], s[22:23], 19
	s_lshl_b64 s[8:9], s[6:7], 19
	s_add_u32 s26, s30, s8
	v_lshlrev_b32_e32 v4, 5, v12
	v_bfe_i32 v14, v0, 0, 16
	v_lshlrev_b32_e32 v0, 1, v1
	v_lshrrev_b32_e32 v2, 2, v1
	s_addc_u32 s27, s31, s9
	s_add_i32 s35, s34, 0
	v_and_b32_e32 v4, 32, v4
	v_and_b32_e32 v0, 24, v0
	v_and_b32_e32 v2, 4, v2
	s_add_i32 m0, s35, 0x10000
	v_or3_b32 v0, v3, v2, v0
	v_add_lshl_u32 v2, v4, v14, 1
	global_load_lds_dwordx4 v130, s[26:27]
	s_add_i32 m0, s35, 0x12000
	v_lshl_add_u32 v134, v0, 11, v2
	s_add_u32 s8, s26, 0x40000
	global_load_lds_dwordx4 v134, s[26:27]
	s_addc_u32 s9, s27, 0
	s_add_i32 m0, s35, 0x14000
	v_lshl_add_u32 v132, v1, 11, v2
	global_load_lds_dwordx4 v130, s[8:9]
	s_add_i32 m0, s35, 0x16000
	s_add_u32 s24, s76, s4
	s_addc_u32 s25, s77, s5
	s_add_i32 s36, s35, 0x2000
	global_load_lds_dwordx4 v134, s[8:9]
	s_mov_b32 m0, s35
	s_add_u32 s4, s24, 0x40000
	global_load_lds_dwordx4 v128, s[24:25]
	s_mov_b32 m0, s36
	s_addc_u32 s5, s25, 0
	s_add_i32 s37, s35, 0x4000
	global_load_lds_dwordx4 v132, s[24:25]
	s_mov_b32 m0, s37
	s_add_i32 s38, s35, 0x6000
	global_load_lds_dwordx4 v128, s[4:5]
	s_mov_b32 m0, s38
	v_mov_b32_e32 v131, 0
	global_load_lds_dwordx4 v132, s[4:5]
	v_mov_b32_e32 v135, v131
	v_mov_b32_e32 v129, v131
	v_mov_b32_e32 v133, v131
	s_cmp_eq_u32 s3, 1
	s_mov_b32 s7, 0
	v_lshl_add_u64 v[6:7], s[26:27], 0, v[130:131]
	v_lshl_add_u64 v[4:5], s[26:27], 0, v[134:135]
	v_lshl_add_u64 v[0:1], s[24:25], 0, v[128:129]
	s_cselect_b64 s[8:9], -1, 0
	s_cmp_lg_u32 s3, 1
	v_lshl_add_u64 v[2:3], s[24:25], 0, v[132:133]
	s_cbranch_scc1 .LBB0_1327
	s_barrier
	s_setprio 1

.LBB0_1337:
	ds_read_b128 v[144:147], v151
	ds_read_b128 v[156:159], v151 offset:1024
	ds_read_b128 v[160:163], v151 offset:2048
	ds_read_b128 v[164:167], v151 offset:3072
	ds_read_b128 v[168:171], v152
	ds_read_b128 v[172:175], v152 offset:1024
	ds_read_b128 v[176:179], v152 offset:2048
	ds_read_b128 v[180:183], v152 offset:3072
	s_add_u32 s26, s24, 0xfffc0080
	s_addc_u32 s27, s25, -1
	s_cmp_eq_u32 s50, 12
	s_cselect_b32 s29, s17, s27
	s_cselect_b32 s28, s23, s26
	s_cselect_b32 s27, s15, s49
	s_cselect_b32 s26, s47, s48
	v_lshl_add_u64 v[216:217], s[24:25], 0, v[136:137]
	s_add_i32 m0, s35, 0xc000
	ds_read_b128 v[184:187], v153
	ds_read_b128 v[188:191], v153 offset:1024
	ds_read_b128 v[192:195], v153 offset:2048
	ds_read_b128 v[196:199], v153 offset:3072
	ds_read_b128 v[200:203], v153 offset:4096
	ds_read_b128 v[204:207], v153 offset:5120
	ds_read_b128 v[208:211], v153 offset:6144
	ds_read_b128 v[212:215], v153 offset:7168
	global_load_lds_dwordx4 v[216:217], off
	v_lshl_add_u64 v[216:217], s[24:25], 0, v[138:139]
	s_add_i32 m0, s35, 0xe000
	s_nop 0
	global_load_lds_dwordx4 v[216:217], off
	s_waitcnt vmcnt(8)
	s_waitcnt lgkmcnt(0)
	s_barrier
	s_waitcnt lgkmcnt(0)
	v_mfma_f32_16x16x32_bf16 v[124:127], v[144:147], v[184:187], v[124:127]
	v_mfma_f32_16x16x32_bf16 v[120:123], v[160:163], v[184:187], v[120:123]
	v_mfma_f32_16x16x32_bf16 v[108:111], v[144:147], v[192:195], v[108:111]
	v_mfma_f32_16x16x32_bf16 v[104:107], v[160:163], v[192:195], v[104:107]
	v_mfma_f32_16x16x32_bf16 v[92:95], v[144:147], v[200:203], v[92:95]
	v_mfma_f32_16x16x32_bf16 v[88:91], v[160:163], v[200:203], v[88:91]
	v_mfma_f32_16x16x32_bf16 v[76:79], v[144:147], v[208:211], v[76:79]
	v_mfma_f32_16x16x32_bf16 v[72:75], v[160:163], v[208:211], v[72:75]
	v_mfma_f32_16x16x32_bf16 v[124:127], v[156:159], v[188:191], v[124:127]
	v_mfma_f32_16x16x32_bf16 v[120:123], v[164:167], v[188:191], v[120:123]
	v_mfma_f32_16x16x32_bf16 v[108:111], v[156:159], v[196:199], v[108:111]
	v_mfma_f32_16x16x32_bf16 v[104:107], v[164:167], v[196:199], v[104:107]
	v_mfma_f32_16x16x32_bf16 v[92:95], v[156:159], v[204:207], v[92:95]
	v_mfma_f32_16x16x32_bf16 v[88:91], v[164:167], v[204:207], v[88:91]
	v_mfma_f32_16x16x32_bf16 v[76:79], v[156:159], v[212:215], v[76:79]
	v_mfma_f32_16x16x32_bf16 v[72:75], v[164:167], v[212:215], v[72:75]
	v_mfma_f32_16x16x32_bf16 v[116:119], v[168:171], v[184:187], v[116:119]
	v_mfma_f32_16x16x32_bf16 v[112:115], v[176:179], v[184:187], v[112:115]
	v_mfma_f32_16x16x32_bf16 v[100:103], v[168:171], v[192:195], v[100:103]
	v_mfma_f32_16x16x32_bf16 v[96:99], v[176:179], v[192:195], v[96:99]
	v_mfma_f32_16x16x32_bf16 v[84:87], v[168:171], v[200:203], v[84:87]
	v_mfma_f32_16x16x32_bf16 v[80:83], v[176:179], v[200:203], v[80:83]
	v_mfma_f32_16x16x32_bf16 v[68:71], v[168:171], v[208:211], v[68:71]
	v_mfma_f32_16x16x32_bf16 v[64:67], v[176:179], v[208:211], v[64:67]
	v_mfma_f32_16x16x32_bf16 v[116:119], v[172:175], v[188:191], v[116:119]
	v_mfma_f32_16x16x32_bf16 v[112:115], v[180:183], v[188:191], v[112:115]
	v_mfma_f32_16x16x32_bf16 v[100:103], v[172:175], v[196:199], v[100:103]
	v_mfma_f32_16x16x32_bf16 v[96:99], v[180:183], v[196:199], v[96:99]
	v_mfma_f32_16x16x32_bf16 v[84:87], v[172:175], v[204:207], v[84:87]
	v_mfma_f32_16x16x32_bf16 v[80:83], v[180:183], v[204:207], v[80:83]
	v_mfma_f32_16x16x32_bf16 v[68:71], v[172:175], v[212:215], v[68:71]
	v_mfma_f32_16x16x32_bf16 v[64:67], v[180:183], v[212:215], v[64:67]
	s_barrier
	s_add_i32 s51, s44, s34
	v_lshl_add_u64 v[216:217], s[26:27], 0, v[130:131]
	s_mov_b32 m0, s51
	ds_read_b128 v[184:187], v153 offset:16384
	ds_read_b128 v[188:191], v153 offset:17408
	ds_read_b128 v[192:195], v153 offset:18432
	ds_read_b128 v[196:199], v153 offset:19456
	ds_read_b128 v[200:203], v153 offset:20480
	ds_read_b128 v[204:207], v153 offset:21504
	ds_read_b128 v[208:211], v153 offset:22528
	ds_read_b128 v[212:215], v153 offset:23552
	global_load_lds_dwordx4 v[216:217], off
	s_add_i32 m0, s51, 0x2000
	s_add_u32 s52, s26, 0x40000
	v_lshl_add_u64 v[218:219], s[26:27], 0, v[134:135]
	s_addc_u32 s53, s27, 0
	s_add_i32 s51, s45, s34
	global_load_lds_dwordx4 v[218:219], off
	v_lshl_add_u64 v[220:221], s[52:53], 0, v[130:131]
	s_mov_b32 m0, s51
	v_lshl_add_u64 v[222:223], s[28:29], 0, v[132:133]
	global_load_lds_dwordx4 v[220:221], off
	v_lshl_add_u64 v[220:221], s[52:53], 0, v[134:135]
	s_add_i32 m0, s51, 0x2000
	s_nop 0
	global_load_lds_dwordx4 v[220:221], off
	v_lshl_add_u64 v[220:221], s[28:29], 0, v[128:129]
	s_mov_b32 m0, s35
	s_nop 0
	global_load_lds_dwordx4 v[220:221], off
	s_mov_b32 m0, s36
	s_nop 0
	global_load_lds_dwordx4 v[222:223], off
	s_waitcnt vmcnt(8)
	s_waitcnt lgkmcnt(0)
	s_barrier
	s_waitcnt lgkmcnt(0)
	v_mfma_f32_16x16x32_bf16 v[60:63], v[144:147], v[184:187], v[60:63]
	v_mfma_f32_16x16x32_bf16 v[56:59], v[160:163], v[184:187], v[56:59]
	v_mfma_f32_16x16x32_bf16 v[44:47], v[144:147], v[192:195], v[44:47]
	v_mfma_f32_16x16x32_bf16 v[40:43], v[160:163], v[192:195], v[40:43]
	v_mfma_f32_16x16x32_bf16 v[28:31], v[144:147], v[200:203], v[28:31]
	v_mfma_f32_16x16x32_bf16 v[24:27], v[160:163], v[200:203], v[24:27]
	v_mfma_f32_16x16x32_bf16 v[12:15], v[144:147], v[208:211], v[12:15]
	v_mfma_f32_16x16x32_bf16 v[8:11], v[160:163], v[208:211], v[8:11]
	v_mfma_f32_16x16x32_bf16 v[60:63], v[156:159], v[188:191], v[60:63]
	v_mfma_f32_16x16x32_bf16 v[56:59], v[164:167], v[188:191], v[56:59]
	v_mfma_f32_16x16x32_bf16 v[44:47], v[156:159], v[196:199], v[44:47]
	v_mfma_f32_16x16x32_bf16 v[40:43], v[164:167], v[196:199], v[40:43]
	v_mfma_f32_16x16x32_bf16 v[28:31], v[156:159], v[204:207], v[28:31]
	v_mfma_f32_16x16x32_bf16 v[24:27], v[164:167], v[204:207], v[24:27]
	v_mfma_f32_16x16x32_bf16 v[12:15], v[156:159], v[212:215], v[12:15]
	v_mfma_f32_16x16x32_bf16 v[8:11], v[164:167], v[212:215], v[8:11]
	v_mfma_f32_16x16x32_bf16 v[52:55], v[168:171], v[184:187], v[52:55]
	v_mfma_f32_16x16x32_bf16 v[48:51], v[176:179], v[184:187], v[48:51]
	v_mfma_f32_16x16x32_bf16 v[36:39], v[168:171], v[192:195], v[36:39]
	v_mfma_f32_16x16x32_bf16 v[32:35], v[176:179], v[192:195], v[32:35]
	v_mfma_f32_16x16x32_bf16 v[20:23], v[168:171], v[200:203], v[20:23]
	v_mfma_f32_16x16x32_bf16 v[16:19], v[176:179], v[200:203], v[16:19]
	v_mfma_f32_16x16x32_bf16 v[4:7], v[168:171], v[208:211], v[4:7]
	v_mfma_f32_16x16x32_bf16 v[0:3], v[176:179], v[208:211], v[0:3]
	v_mfma_f32_16x16x32_bf16 v[52:55], v[172:175], v[188:191], v[52:55]
	v_mfma_f32_16x16x32_bf16 v[48:51], v[180:183], v[188:191], v[48:51]
	v_mfma_f32_16x16x32_bf16 v[36:39], v[172:175], v[196:199], v[36:39]
	v_mfma_f32_16x16x32_bf16 v[32:35], v[180:183], v[196:199], v[32:35]
	v_mfma_f32_16x16x32_bf16 v[20:23], v[172:175], v[204:207], v[20:23]
	v_mfma_f32_16x16x32_bf16 v[16:19], v[180:183], v[204:207], v[16:19]
	v_mfma_f32_16x16x32_bf16 v[4:7], v[172:175], v[212:215], v[4:7]
	v_mfma_f32_16x16x32_bf16 v[0:3], v[180:183], v[212:215], v[0:3]
	s_barrier
	s_add_i32 s51, 0, 0x18000
	s_add_i32 s52, 0, 0x1c000
	v_add_u32_e32 v164, s51, v149
	v_add_u32_e32 v180, s52, v149
	ds_read_b128 v[144:147], v164
	ds_read_b128 v[156:159], v164 offset:1024
	ds_read_b128 v[160:163], v164 offset:2048
	ds_read_b128 v[164:167], v164 offset:3072
	ds_read_b128 v[168:171], v180
	ds_read_b128 v[172:175], v180 offset:1024
	ds_read_b128 v[176:179], v180 offset:2048
	ds_read_b128 v[180:183], v180 offset:3072
	s_add_u32 s28, s28, 0x40000
	s_addc_u32 s29, s29, 0
	s_mov_b32 m0, s37
	v_lshl_add_u64 v[224:225], s[28:29], 0, v[128:129]
	ds_read_b128 v[184:187], v153 offset:32768
	ds_read_b128 v[188:191], v153 offset:33792
	ds_read_b128 v[192:195], v153 offset:34816
	ds_read_b128 v[196:199], v153 offset:35840
	ds_read_b128 v[200:203], v153 offset:36864
	ds_read_b128 v[204:207], v153 offset:37888
	ds_read_b128 v[208:211], v153 offset:38912
	ds_read_b128 v[212:215], v153 offset:39936
	global_load_lds_dwordx4 v[224:225], off
	v_lshl_add_u64 v[224:225], s[28:29], 0, v[132:133]
	s_mov_b32 m0, s38
	s_nop 0
	global_load_lds_dwordx4 v[224:225], off
	s_waitcnt vmcnt(8)
	s_waitcnt lgkmcnt(0)
	s_barrier
	s_waitcnt lgkmcnt(0)
	v_mfma_f32_16x16x32_bf16 v[124:127], v[144:147], v[184:187], v[124:127]
	v_mfma_f32_16x16x32_bf16 v[120:123], v[160:163], v[184:187], v[120:123]
	v_mfma_f32_16x16x32_bf16 v[108:111], v[144:147], v[192:195], v[108:111]
	v_mfma_f32_16x16x32_bf16 v[104:107], v[160:163], v[192:195], v[104:107]
	v_mfma_f32_16x16x32_bf16 v[92:95], v[144:147], v[200:203], v[92:95]
	v_mfma_f32_16x16x32_bf16 v[88:91], v[160:163], v[200:203], v[88:91]
	v_mfma_f32_16x16x32_bf16 v[76:79], v[144:147], v[208:211], v[76:79]
	v_mfma_f32_16x16x32_bf16 v[72:75], v[160:163], v[208:211], v[72:75]
	v_mfma_f32_16x16x32_bf16 v[124:127], v[156:159], v[188:191], v[124:127]
	v_mfma_f32_16x16x32_bf16 v[120:123], v[164:167], v[188:191], v[120:123]
	v_mfma_f32_16x16x32_bf16 v[108:111], v[156:159], v[196:199], v[108:111]
	v_mfma_f32_16x16x32_bf16 v[104:107], v[164:167], v[196:199], v[104:107]
	v_mfma_f32_16x16x32_bf16 v[92:95], v[156:159], v[204:207], v[92:95]
	v_mfma_f32_16x16x32_bf16 v[88:91], v[164:167], v[204:207], v[88:91]
	v_mfma_f32_16x16x32_bf16 v[76:79], v[156:159], v[212:215], v[76:79]
	v_mfma_f32_16x16x32_bf16 v[72:75], v[164:167], v[212:215], v[72:75]
	v_mfma_f32_16x16x32_bf16 v[116:119], v[168:171], v[184:187], v[116:119]
	v_mfma_f32_16x16x32_bf16 v[112:115], v[176:179], v[184:187], v[112:115]
	v_mfma_f32_16x16x32_bf16 v[100:103], v[168:171], v[192:195], v[100:103]
	v_mfma_f32_16x16x32_bf16 v[96:99], v[176:179], v[192:195], v[96:99]
	v_mfma_f32_16x16x32_bf16 v[84:87], v[168:171], v[200:203], v[84:87]
	v_mfma_f32_16x16x32_bf16 v[80:83], v[176:179], v[200:203], v[80:83]
	v_mfma_f32_16x16x32_bf16 v[68:71], v[168:171], v[208:211], v[68:71]
	v_mfma_f32_16x16x32_bf16 v[64:67], v[176:179], v[208:211], v[64:67]
	v_mfma_f32_16x16x32_bf16 v[116:119], v[172:175], v[188:191], v[116:119]
	v_mfma_f32_16x16x32_bf16 v[112:115], v[180:183], v[188:191], v[112:115]
	v_mfma_f32_16x16x32_bf16 v[100:103], v[172:175], v[196:199], v[100:103]
	v_mfma_f32_16x16x32_bf16 v[96:99], v[180:183], v[196:199], v[96:99]
	v_mfma_f32_16x16x32_bf16 v[84:87], v[172:175], v[204:207], v[84:87]
	v_mfma_f32_16x16x32_bf16 v[80:83], v[180:183], v[204:207], v[80:83]
	v_mfma_f32_16x16x32_bf16 v[68:71], v[172:175], v[212:215], v[68:71]
	v_mfma_f32_16x16x32_bf16 v[64:67], v[180:183], v[212:215], v[64:67]
	s_barrier
	s_add_i32 s28, s51, s34
	v_lshl_add_u64 v[216:217], v[216:217], 0, s[10:11]
	s_mov_b32 m0, s28
	ds_read_b128 v[184:187], v153 offset:49152
	ds_read_b128 v[188:191], v153 offset:50176
	ds_read_b128 v[192:195], v153 offset:51200
	ds_read_b128 v[196:199], v153 offset:52224
	ds_read_b128 v[200:203], v153 offset:53248
	ds_read_b128 v[204:207], v153 offset:54272
	ds_read_b128 v[208:211], v153 offset:55296
	ds_read_b128 v[212:215], v153 offset:56320
	global_load_lds_dwordx4 v[216:217], off
	s_add_i32 m0, s28, 0x2000
	s_add_u32 s26, s26, 0x40080
	v_lshl_add_u64 v[216:217], v[218:219], 0, s[10:11]
	s_addc_u32 s27, s27, 0
	s_add_i32 s28, s52, s34
	global_load_lds_dwordx4 v[216:217], off
	v_lshl_add_u64 v[216:217], s[26:27], 0, v[130:131]
	s_mov_b32 m0, s28
	s_nop 0
	global_load_lds_dwordx4 v[216:217], off
	v_lshl_add_u64 v[216:217], s[26:27], 0, v[134:135]
	s_add_i32 m0, s28, 0x2000
	s_nop 0
	global_load_lds_dwordx4 v[216:217], off
	v_lshl_add_u64 v[216:217], v[220:221], 0, s[10:11]
	s_mov_b32 m0, s40
	s_nop 0
	global_load_lds_dwordx4 v[216:217], off
	v_lshl_add_u64 v[216:217], v[222:223], 0, s[10:11]
	s_mov_b32 m0, s41
	s_nop 0
	global_load_lds_dwordx4 v[216:217], off
	s_waitcnt vmcnt(8)
	s_waitcnt lgkmcnt(0)
	s_barrier
	s_waitcnt lgkmcnt(0)
	v_mfma_f32_16x16x32_bf16 v[60:63], v[144:147], v[184:187], v[60:63]
	v_mfma_f32_16x16x32_bf16 v[56:59], v[160:163], v[184:187], v[56:59]
	v_mfma_f32_16x16x32_bf16 v[44:47], v[144:147], v[192:195], v[44:47]
	v_mfma_f32_16x16x32_bf16 v[40:43], v[160:163], v[192:195], v[40:43]
	v_mfma_f32_16x16x32_bf16 v[28:31], v[144:147], v[200:203], v[28:31]
	v_mfma_f32_16x16x32_bf16 v[24:27], v[160:163], v[200:203], v[24:27]
	v_mfma_f32_16x16x32_bf16 v[12:15], v[144:147], v[208:211], v[12:15]
	v_mfma_f32_16x16x32_bf16 v[8:11], v[160:163], v[208:211], v[8:11]
	v_mfma_f32_16x16x32_bf16 v[60:63], v[156:159], v[188:191], v[60:63]
	v_mfma_f32_16x16x32_bf16 v[56:59], v[164:167], v[188:191], v[56:59]
	v_mfma_f32_16x16x32_bf16 v[44:47], v[156:159], v[196:199], v[44:47]
	v_mfma_f32_16x16x32_bf16 v[40:43], v[164:167], v[196:199], v[40:43]
	v_mfma_f32_16x16x32_bf16 v[28:31], v[156:159], v[204:207], v[28:31]
	v_mfma_f32_16x16x32_bf16 v[24:27], v[164:167], v[204:207], v[24:27]
	v_mfma_f32_16x16x32_bf16 v[12:15], v[156:159], v[212:215], v[12:15]
	v_mfma_f32_16x16x32_bf16 v[8:11], v[164:167], v[212:215], v[8:11]
	v_mfma_f32_16x16x32_bf16 v[52:55], v[168:171], v[184:187], v[52:55]
	v_mfma_f32_16x16x32_bf16 v[48:51], v[176:179], v[184:187], v[48:51]
	v_mfma_f32_16x16x32_bf16 v[36:39], v[168:171], v[192:195], v[36:39]
	v_mfma_f32_16x16x32_bf16 v[32:35], v[176:179], v[192:195], v[32:35]
	v_mfma_f32_16x16x32_bf16 v[20:23], v[168:171], v[200:203], v[20:23]
	v_mfma_f32_16x16x32_bf16 v[16:19], v[176:179], v[200:203], v[16:19]
	v_mfma_f32_16x16x32_bf16 v[4:7], v[168:171], v[208:211], v[4:7]
	v_mfma_f32_16x16x32_bf16 v[0:3], v[176:179], v[208:211], v[0:3]
	v_mfma_f32_16x16x32_bf16 v[52:55], v[172:175], v[188:191], v[52:55]
	v_mfma_f32_16x16x32_bf16 v[48:51], v[180:183], v[188:191], v[48:51]
	v_mfma_f32_16x16x32_bf16 v[36:39], v[172:175], v[196:199], v[36:39]
	v_mfma_f32_16x16x32_bf16 v[32:35], v[180:183], v[196:199], v[32:35]
	v_mfma_f32_16x16x32_bf16 v[20:23], v[172:175], v[204:207], v[20:23]
	v_mfma_f32_16x16x32_bf16 v[16:19], v[180:183], v[204:207], v[16:19]
	v_mfma_f32_16x16x32_bf16 v[4:7], v[172:175], v[212:215], v[4:7]
	v_mfma_f32_16x16x32_bf16 v[0:3], v[180:183], v[212:215], v[0:3]
	s_barrier
	s_add_i32 s50, s50, 2
	s_add_u32 s24, s24, 0x100
	s_addc_u32 s25, s25, 0
	s_add_u32 s48, s48, 0x100
	s_addc_u32 s49, s49, 0
	s_cmp_gt_u32 s50, 13
	s_cbranch_scc0 .LBB0_1337
	s_and_b64 vcc, exec, s[12:13]
	s_cbranch_vccz .LBB0_1340
	s_barrier

.LBB0_1394:
	s_andn2_b64 vcc, exec, s[8:9]
	s_cbranch_vccnz .LBB0_1442
	v_ashrrev_i32_e32 v2, 31, v0
	v_lshrrev_b32_e32 v2, 26, v2
	v_lshlrev_b32_e32 v1, 4, v0
	v_add_u32_e32 v2, v0, v2
	v_bfe_i32 v0, v0, 27, 1
	v_lshrrev_b32_e32 v0, 22, v0
	v_add_u32_e32 v0, v1, v0
	v_and_b32_e32 v0, 0xfffffc00, v0
	v_sub_u32_e32 v0, v1, v0
	v_ashrrev_i32_e32 v9, 6, v2
	v_lshrrev_b32_e32 v2, 4, v0
	v_bitop3_b32 v0, v2, v0, 32 bitop3:0x6c
	v_ashrrev_i32_e32 v3, 31, v0
	v_lshrrev_b32_e32 v3, 26, v3
	v_add_u32_e32 v3, v0, v3
	v_lshlrev_b32_e32 v2, 3, v9
	v_ashrrev_i32_e32 v10, 6, v3
	v_and_b32_e32 v3, 0xc0, v3
	v_and_b32_e32 v2, -16, v2
	v_sub_u32_e32 v0, v0, v3
	v_mov_b32_e32 v3, 1
	v_add_u32_e32 v2, v10, v2
	v_ashrrev_i16_sdwa v0, v3, sext(v0) dst_sel:DWORD dst_unused:UNUSED_PAD src0_sel:DWORD src1_sel:BYTE_0
	v_lshlrev_b32_e32 v4, 5, v9
	v_bfe_i32 v11, v0, 0, 16
	v_lshlrev_b32_e32 v0, 1, v2
	v_lshrrev_b32_e32 v5, 2, v2
	v_and_b32_e32 v6, 3, v10
	s_mov_b32 s3, 0x3fffe0
	v_and_b32_e32 v4, 32, v4
	v_and_b32_e32 v0, 24, v0
	v_and_b32_e32 v5, 4, v5
	v_and_or_b32 v6, v2, s3, v6
	v_or3_b32 v0, v6, v5, v0
	v_add_lshl_u32 v4, v4, v11, 1
	v_lshl_add_u32 v134, v0, 10, v4
	v_add_u32_e32 v0, 0x2000, v1
	v_ashrrev_i32_e32 v1, 31, v0
	v_lshrrev_b32_e32 v1, 22, v1
	v_add_u32_e32 v1, v0, v1
	v_ashrrev_i32_e32 v12, 10, v1
	v_mul_i32_i24_e32 v1, 0x400, v12
	v_sub_u32_e32 v0, v0, v1
	v_lshrrev_b32_e32 v1, 4, v0
	v_bitop3_b32 v0, v1, v0, 32 bitop3:0x6c
	v_lshl_add_u32 v132, v2, 10, v4
	v_ashrrev_i32_e32 v2, 31, v0
	v_lshrrev_b32_e32 v2, 26, v2
	v_add_u32_e32 v2, v0, v2
	v_lshlrev_b32_e32 v1, 3, v12
	v_ashrrev_i32_e32 v13, 6, v2
	v_and_b32_e32 v2, 0xc0, v2
	s_add_u32 s36, s70, 0x5700000
	v_and_b32_e32 v1, -16, v1
	v_sub_u32_e32 v0, v0, v2
	s_addc_u32 s37, s71, 0
	s_ashr_i32 s2, s16, 6
	v_add_u32_e32 v1, v13, v1
	v_ashrrev_i16_sdwa v0, v3, sext(v0) dst_sel:DWORD dst_unused:UNUSED_PAD src0_sel:DWORD src1_sel:BYTE_0
	v_and_b32_e32 v3, 3, v13
	s_ashr_i32 s7, s6, 31
	s_ashr_i32 s5, s4, 31
	v_and_or_b32 v3, v1, s3, v3
	s_ashr_i32 s3, s16, 8
	s_lshl_b32 s38, s2, 10
	s_lshl_b64 s[8:9], s[6:7], 18
	s_lshl_b64 s[10:11], s[4:5], 18
	s_add_u32 s30, s36, s10
	v_lshlrev_b32_e32 v4, 5, v12
	v_bfe_i32 v14, v0, 0, 16
	v_lshlrev_b32_e32 v0, 1, v1
	v_lshrrev_b32_e32 v2, 2, v1
	s_addc_u32 s31, s37, s11
	s_add_i32 s39, s38, 0
	v_and_b32_e32 v4, 32, v4
	v_and_b32_e32 v0, 24, v0
	v_and_b32_e32 v2, 4, v2
	s_add_i32 m0, s39, 0x10000
	v_or3_b32 v0, v3, v2, v0
	v_add_lshl_u32 v2, v4, v14, 1
	global_load_lds_dwordx4 v134, s[30:31]
	s_add_i32 m0, s39, 0x12000
	v_lshl_add_u32 v138, v0, 10, v2
	s_add_u32 s10, s30, 0x20000
	global_load_lds_dwordx4 v138, s[30:31]
	s_addc_u32 s11, s31, 0
	s_add_i32 m0, s39, 0x14000
	v_lshl_add_u32 v136, v1, 10, v2
	global_load_lds_dwordx4 v134, s[10:11]
	s_add_i32 m0, s39, 0x16000
	s_add_u32 s28, s72, s8
	s_addc_u32 s29, s73, s9
	s_add_i32 s40, s39, 0x2000
	global_load_lds_dwordx4 v138, s[10:11]
	s_mov_b32 m0, s39
	s_add_u32 s8, s28, 0x20000
	global_load_lds_dwordx4 v132, s[28:29]
	s_mov_b32 m0, s40
	s_addc_u32 s9, s29, 0
	s_add_i32 s41, s39, 0x4000
	global_load_lds_dwordx4 v136, s[28:29]
	s_mov_b32 m0, s41
	s_add_i32 s42, s39, 0x6000
	global_load_lds_dwordx4 v132, s[8:9]
	s_mov_b32 m0, s42
	v_mov_b32_e32 v141, 0
	global_load_lds_dwordx4 v136, s[8:9]
	v_mov_b32_e32 v135, v141
	v_mov_b32_e32 v139, v141
	v_mov_b32_e32 v133, v141
	v_mov_b32_e32 v137, v141
	s_cmp_eq_u32 s3, 1
	s_mov_b32 s7, 0
	v_lshl_add_u64 v[6:7], s[30:31], 0, v[134:135]
	v_lshl_add_u64 v[4:5], s[30:31], 0, v[138:139]
	v_lshl_add_u64 v[0:1], s[28:29], 0, v[132:133]
	s_cselect_b64 s[8:9], -1, 0
	s_cmp_lg_u32 s3, 1
	v_lshl_add_u64 v[2:3], s[28:29], 0, v[136:137]
	s_cbranch_scc1 .LBB0_1397
	s_barrier
	s_setprio 1

.LBB0_1403:
	ds_read_b128 v[128:131], v164
	ds_read_b128 v[160:163], v164 offset:1024
	ds_read_b128 v[168:171], v164 offset:2048
	ds_read_b128 v[172:175], v164 offset:3072
	ds_read_b128 v[176:179], v165
	ds_read_b128 v[180:183], v165 offset:1024
	ds_read_b128 v[184:187], v165 offset:2048
	ds_read_b128 v[188:191], v165 offset:3072
	s_add_u32 s30, s28, 0xfffe0080
	s_addc_u32 s31, s29, -1
	s_cmp_eq_u32 s56, 4
	s_cselect_b32 s35, s5, s31
	s_cselect_b32 s34, s23, s30
	s_cselect_b32 s31, s21, s55
	s_cselect_b32 s30, s53, s54
	v_lshl_add_u64 v[156:157], s[28:29], 0, v[148:149]
	s_add_i32 m0, s39, 0xc000
	ds_read_b128 v[192:195], v166
	ds_read_b128 v[196:199], v166 offset:1024
	ds_read_b128 v[200:203], v166 offset:2048
	ds_read_b128 v[204:207], v166 offset:3072
	ds_read_b128 v[208:211], v166 offset:4096
	ds_read_b128 v[212:215], v166 offset:5120
	ds_read_b128 v[216:219], v166 offset:6144
	ds_read_b128 v[220:223], v166 offset:7168
	global_load_lds_dwordx4 v[156:157], off
	v_lshl_add_u64 v[156:157], s[28:29], 0, v[150:151]
	s_add_i32 m0, s39, 0xe000
	s_nop 0
	global_load_lds_dwordx4 v[156:157], off
	s_waitcnt vmcnt(8)
	s_waitcnt lgkmcnt(0)
	s_barrier
	s_waitcnt lgkmcnt(0)
	v_mfma_f32_16x16x32_bf16 v[124:127], v[128:131], v[192:195], v[124:127]
	v_mfma_f32_16x16x32_bf16 v[120:123], v[168:171], v[192:195], v[120:123]
	v_mfma_f32_16x16x32_bf16 v[108:111], v[128:131], v[200:203], v[108:111]
	v_mfma_f32_16x16x32_bf16 v[104:107], v[168:171], v[200:203], v[104:107]
	v_mfma_f32_16x16x32_bf16 v[92:95], v[128:131], v[208:211], v[92:95]
	v_mfma_f32_16x16x32_bf16 v[88:91], v[168:171], v[208:211], v[88:91]
	v_mfma_f32_16x16x32_bf16 v[76:79], v[128:131], v[216:219], v[76:79]
	v_mfma_f32_16x16x32_bf16 v[72:75], v[168:171], v[216:219], v[72:75]
	v_mfma_f32_16x16x32_bf16 v[124:127], v[160:163], v[196:199], v[124:127]
	v_mfma_f32_16x16x32_bf16 v[120:123], v[172:175], v[196:199], v[120:123]
	v_mfma_f32_16x16x32_bf16 v[108:111], v[160:163], v[204:207], v[108:111]
	v_mfma_f32_16x16x32_bf16 v[104:107], v[172:175], v[204:207], v[104:107]
	v_mfma_f32_16x16x32_bf16 v[92:95], v[160:163], v[212:215], v[92:95]
	v_mfma_f32_16x16x32_bf16 v[88:91], v[172:175], v[212:215], v[88:91]
	v_mfma_f32_16x16x32_bf16 v[76:79], v[160:163], v[220:223], v[76:79]
	v_mfma_f32_16x16x32_bf16 v[72:75], v[172:175], v[220:223], v[72:75]
	v_mfma_f32_16x16x32_bf16 v[116:119], v[176:179], v[192:195], v[116:119]
	v_mfma_f32_16x16x32_bf16 v[112:115], v[184:187], v[192:195], v[112:115]
	v_mfma_f32_16x16x32_bf16 v[100:103], v[176:179], v[200:203], v[100:103]
	v_mfma_f32_16x16x32_bf16 v[96:99], v[184:187], v[200:203], v[96:99]
	v_mfma_f32_16x16x32_bf16 v[84:87], v[176:179], v[208:211], v[84:87]
	v_mfma_f32_16x16x32_bf16 v[80:83], v[184:187], v[208:211], v[80:83]
	v_mfma_f32_16x16x32_bf16 v[68:71], v[176:179], v[216:219], v[68:71]
	v_mfma_f32_16x16x32_bf16 v[64:67], v[184:187], v[216:219], v[64:67]
	v_mfma_f32_16x16x32_bf16 v[116:119], v[180:183], v[196:199], v[116:119]
	v_mfma_f32_16x16x32_bf16 v[112:115], v[188:191], v[196:199], v[112:115]
	v_mfma_f32_16x16x32_bf16 v[100:103], v[180:183], v[204:207], v[100:103]
	v_mfma_f32_16x16x32_bf16 v[96:99], v[188:191], v[204:207], v[96:99]
	v_mfma_f32_16x16x32_bf16 v[84:87], v[180:183], v[212:215], v[84:87]
	v_mfma_f32_16x16x32_bf16 v[80:83], v[188:191], v[212:215], v[80:83]
	v_mfma_f32_16x16x32_bf16 v[68:71], v[180:183], v[220:223], v[68:71]
	v_mfma_f32_16x16x32_bf16 v[64:67], v[188:191], v[220:223], v[64:67]
	s_barrier
	s_add_i32 s57, s50, s38
	v_lshl_add_u64 v[156:157], s[30:31], 0, v[134:135]
	s_mov_b32 m0, s57
	ds_read_b128 v[192:195], v166 offset:16384
	ds_read_b128 v[196:199], v166 offset:17408
	ds_read_b128 v[200:203], v166 offset:18432
	ds_read_b128 v[204:207], v166 offset:19456
	ds_read_b128 v[208:211], v166 offset:20480
	ds_read_b128 v[212:215], v166 offset:21504
	ds_read_b128 v[216:219], v166 offset:22528
	ds_read_b128 v[220:223], v166 offset:23552
	global_load_lds_dwordx4 v[156:157], off
	s_add_i32 m0, s57, 0x2000
	s_add_u32 s58, s30, 0x20000
	v_lshl_add_u64 v[224:225], s[30:31], 0, v[138:139]
	s_addc_u32 s59, s31, 0
	s_add_i32 s57, s51, s38
	global_load_lds_dwordx4 v[224:225], off
	v_lshl_add_u64 v[226:227], s[58:59], 0, v[134:135]
	s_mov_b32 m0, s57
	v_lshl_add_u64 v[228:229], s[34:35], 0, v[136:137]
	global_load_lds_dwordx4 v[226:227], off
	v_lshl_add_u64 v[226:227], s[58:59], 0, v[138:139]
	s_add_i32 m0, s57, 0x2000
	s_nop 0
	global_load_lds_dwordx4 v[226:227], off
	v_lshl_add_u64 v[226:227], s[34:35], 0, v[132:133]
	s_mov_b32 m0, s39
	s_nop 0
	global_load_lds_dwordx4 v[226:227], off
	s_mov_b32 m0, s40
	s_nop 0
	global_load_lds_dwordx4 v[228:229], off
	s_waitcnt vmcnt(8)
	s_waitcnt lgkmcnt(0)
	s_barrier
	s_waitcnt lgkmcnt(0)
	v_mfma_f32_16x16x32_bf16 v[60:63], v[128:131], v[192:195], v[60:63]
	v_mfma_f32_16x16x32_bf16 v[56:59], v[168:171], v[192:195], v[56:59]
	v_mfma_f32_16x16x32_bf16 v[44:47], v[128:131], v[200:203], v[44:47]
	v_mfma_f32_16x16x32_bf16 v[40:43], v[168:171], v[200:203], v[40:43]
	v_mfma_f32_16x16x32_bf16 v[28:31], v[128:131], v[208:211], v[28:31]
	v_mfma_f32_16x16x32_bf16 v[24:27], v[168:171], v[208:211], v[24:27]
	v_mfma_f32_16x16x32_bf16 v[12:15], v[128:131], v[216:219], v[12:15]
	v_mfma_f32_16x16x32_bf16 v[8:11], v[168:171], v[216:219], v[8:11]
	v_mfma_f32_16x16x32_bf16 v[60:63], v[160:163], v[196:199], v[60:63]
	v_mfma_f32_16x16x32_bf16 v[56:59], v[172:175], v[196:199], v[56:59]
	v_mfma_f32_16x16x32_bf16 v[44:47], v[160:163], v[204:207], v[44:47]
	v_mfma_f32_16x16x32_bf16 v[40:43], v[172:175], v[204:207], v[40:43]
	v_mfma_f32_16x16x32_bf16 v[28:31], v[160:163], v[212:215], v[28:31]
	v_mfma_f32_16x16x32_bf16 v[24:27], v[172:175], v[212:215], v[24:27]
	v_mfma_f32_16x16x32_bf16 v[12:15], v[160:163], v[220:223], v[12:15]
	v_mfma_f32_16x16x32_bf16 v[8:11], v[172:175], v[220:223], v[8:11]
	v_mfma_f32_16x16x32_bf16 v[52:55], v[176:179], v[192:195], v[52:55]
	v_mfma_f32_16x16x32_bf16 v[48:51], v[184:187], v[192:195], v[48:51]
	v_mfma_f32_16x16x32_bf16 v[36:39], v[176:179], v[200:203], v[36:39]
	v_mfma_f32_16x16x32_bf16 v[32:35], v[184:187], v[200:203], v[32:35]
	v_mfma_f32_16x16x32_bf16 v[20:23], v[176:179], v[208:211], v[20:23]
	v_mfma_f32_16x16x32_bf16 v[16:19], v[184:187], v[208:211], v[16:19]
	v_mfma_f32_16x16x32_bf16 v[4:7], v[176:179], v[216:219], v[4:7]
	v_mfma_f32_16x16x32_bf16 v[0:3], v[184:187], v[216:219], v[0:3]
	v_mfma_f32_16x16x32_bf16 v[52:55], v[180:183], v[196:199], v[52:55]
	v_mfma_f32_16x16x32_bf16 v[48:51], v[188:191], v[196:199], v[48:51]
	v_mfma_f32_16x16x32_bf16 v[36:39], v[180:183], v[204:207], v[36:39]
	v_mfma_f32_16x16x32_bf16 v[32:35], v[188:191], v[204:207], v[32:35]
	v_mfma_f32_16x16x32_bf16 v[20:23], v[180:183], v[212:215], v[20:23]
	v_mfma_f32_16x16x32_bf16 v[16:19], v[188:191], v[212:215], v[16:19]
	v_mfma_f32_16x16x32_bf16 v[4:7], v[180:183], v[220:223], v[4:7]
	v_mfma_f32_16x16x32_bf16 v[0:3], v[188:191], v[220:223], v[0:3]
	s_barrier
	s_add_i32 s57, 0, 0x18000
	v_add_u32_e32 v140, s57, v159
	s_add_i32 s58, 0, 0x1c000
	ds_read_b128 v[128:131], v140
	ds_read_b128 v[160:163], v140 offset:1024
	ds_read_b128 v[168:171], v140 offset:2048
	ds_read_b128 v[172:175], v140 offset:3072
	v_add_u32_e32 v140, s58, v159
	ds_read_b128 v[176:179], v140
	ds_read_b128 v[180:183], v140 offset:1024
	ds_read_b128 v[184:187], v140 offset:2048
	ds_read_b128 v[188:191], v140 offset:3072
	s_add_u32 s34, s34, 0x20000
	s_addc_u32 s35, s35, 0
	s_mov_b32 m0, s41
	v_lshl_add_u64 v[230:231], s[34:35], 0, v[132:133]
	ds_read_b128 v[192:195], v166 offset:32768
	ds_read_b128 v[196:199], v166 offset:33792
	ds_read_b128 v[200:203], v166 offset:34816
	ds_read_b128 v[204:207], v166 offset:35840
	ds_read_b128 v[208:211], v166 offset:36864
	ds_read_b128 v[212:215], v166 offset:37888
	ds_read_b128 v[216:219], v166 offset:38912
	ds_read_b128 v[220:223], v166 offset:39936
	global_load_lds_dwordx4 v[230:231], off
	v_lshl_add_u64 v[230:231], s[34:35], 0, v[136:137]
	s_mov_b32 m0, s42
	s_nop 0
	global_load_lds_dwordx4 v[230:231], off
	s_waitcnt vmcnt(8)
	s_waitcnt lgkmcnt(0)
	s_barrier
	s_waitcnt lgkmcnt(0)
	v_mfma_f32_16x16x32_bf16 v[124:127], v[128:131], v[192:195], v[124:127]
	v_mfma_f32_16x16x32_bf16 v[120:123], v[168:171], v[192:195], v[120:123]
	v_mfma_f32_16x16x32_bf16 v[108:111], v[128:131], v[200:203], v[108:111]
	v_mfma_f32_16x16x32_bf16 v[104:107], v[168:171], v[200:203], v[104:107]
	v_mfma_f32_16x16x32_bf16 v[92:95], v[128:131], v[208:211], v[92:95]
	v_mfma_f32_16x16x32_bf16 v[88:91], v[168:171], v[208:211], v[88:91]
	v_mfma_f32_16x16x32_bf16 v[76:79], v[128:131], v[216:219], v[76:79]
	v_mfma_f32_16x16x32_bf16 v[72:75], v[168:171], v[216:219], v[72:75]
	v_mfma_f32_16x16x32_bf16 v[124:127], v[160:163], v[196:199], v[124:127]
	v_mfma_f32_16x16x32_bf16 v[120:123], v[172:175], v[196:199], v[120:123]
	v_mfma_f32_16x16x32_bf16 v[108:111], v[160:163], v[204:207], v[108:111]
	v_mfma_f32_16x16x32_bf16 v[104:107], v[172:175], v[204:207], v[104:107]
	v_mfma_f32_16x16x32_bf16 v[92:95], v[160:163], v[212:215], v[92:95]
	v_mfma_f32_16x16x32_bf16 v[88:91], v[172:175], v[212:215], v[88:91]
	v_mfma_f32_16x16x32_bf16 v[76:79], v[160:163], v[220:223], v[76:79]
	v_mfma_f32_16x16x32_bf16 v[72:75], v[172:175], v[220:223], v[72:75]
	v_mfma_f32_16x16x32_bf16 v[116:119], v[176:179], v[192:195], v[116:119]
	v_mfma_f32_16x16x32_bf16 v[112:115], v[184:187], v[192:195], v[112:115]
	v_mfma_f32_16x16x32_bf16 v[100:103], v[176:179], v[200:203], v[100:103]
	v_mfma_f32_16x16x32_bf16 v[96:99], v[184:187], v[200:203], v[96:99]
	v_mfma_f32_16x16x32_bf16 v[84:87], v[176:179], v[208:211], v[84:87]
	v_mfma_f32_16x16x32_bf16 v[80:83], v[184:187], v[208:211], v[80:83]
	v_mfma_f32_16x16x32_bf16 v[68:71], v[176:179], v[216:219], v[68:71]
	v_mfma_f32_16x16x32_bf16 v[64:67], v[184:187], v[216:219], v[64:67]
	v_mfma_f32_16x16x32_bf16 v[116:119], v[180:183], v[196:199], v[116:119]
	v_mfma_f32_16x16x32_bf16 v[112:115], v[188:191], v[196:199], v[112:115]
	v_mfma_f32_16x16x32_bf16 v[100:103], v[180:183], v[204:207], v[100:103]
	v_mfma_f32_16x16x32_bf16 v[96:99], v[188:191], v[204:207], v[96:99]
	v_mfma_f32_16x16x32_bf16 v[84:87], v[180:183], v[212:215], v[84:87]
	v_mfma_f32_16x16x32_bf16 v[80:83], v[188:191], v[212:215], v[80:83]
	v_mfma_f32_16x16x32_bf16 v[68:71], v[180:183], v[220:223], v[68:71]
	v_mfma_f32_16x16x32_bf16 v[64:67], v[188:191], v[220:223], v[64:67]
	s_barrier
	s_add_i32 s34, s57, s38
	v_lshl_add_u64 v[156:157], v[156:157], 0, s[14:15]
	s_mov_b32 m0, s34
	ds_read_b128 v[192:195], v166 offset:49152
	ds_read_b128 v[196:199], v166 offset:50176
	ds_read_b128 v[200:203], v166 offset:51200
	ds_read_b128 v[204:207], v166 offset:52224
	ds_read_b128 v[208:211], v166 offset:53248
	ds_read_b128 v[212:215], v166 offset:54272
	ds_read_b128 v[216:219], v166 offset:55296
	ds_read_b128 v[220:223], v166 offset:56320
	global_load_lds_dwordx4 v[156:157], off
	s_add_i32 m0, s34, 0x2000
	s_add_u32 s30, s30, 0x20080
	v_lshl_add_u64 v[156:157], v[224:225], 0, s[14:15]
	s_addc_u32 s31, s31, 0
	s_add_i32 s34, s58, s38
	global_load_lds_dwordx4 v[156:157], off
	v_lshl_add_u64 v[156:157], s[30:31], 0, v[134:135]
	s_mov_b32 m0, s34
	s_nop 0
	global_load_lds_dwordx4 v[156:157], off
	v_lshl_add_u64 v[156:157], s[30:31], 0, v[138:139]
	s_add_i32 m0, s34, 0x2000
	s_nop 0
	global_load_lds_dwordx4 v[156:157], off
	v_lshl_add_u64 v[156:157], v[226:227], 0, s[14:15]
	s_mov_b32 m0, s44
	s_nop 0
	global_load_lds_dwordx4 v[156:157], off
	v_lshl_add_u64 v[156:157], v[228:229], 0, s[14:15]
	s_mov_b32 m0, s45
	s_nop 0
	global_load_lds_dwordx4 v[156:157], off
	s_waitcnt vmcnt(8)
	s_waitcnt lgkmcnt(0)
	s_barrier
	s_waitcnt lgkmcnt(0)
	v_mfma_f32_16x16x32_bf16 v[60:63], v[128:131], v[192:195], v[60:63]
	v_mfma_f32_16x16x32_bf16 v[56:59], v[168:171], v[192:195], v[56:59]
	v_mfma_f32_16x16x32_bf16 v[44:47], v[128:131], v[200:203], v[44:47]
	v_mfma_f32_16x16x32_bf16 v[40:43], v[168:171], v[200:203], v[40:43]
	v_mfma_f32_16x16x32_bf16 v[28:31], v[128:131], v[208:211], v[28:31]
	v_mfma_f32_16x16x32_bf16 v[24:27], v[168:171], v[208:211], v[24:27]
	v_mfma_f32_16x16x32_bf16 v[12:15], v[128:131], v[216:219], v[12:15]
	v_mfma_f32_16x16x32_bf16 v[8:11], v[168:171], v[216:219], v[8:11]
	v_mfma_f32_16x16x32_bf16 v[60:63], v[160:163], v[196:199], v[60:63]
	v_mfma_f32_16x16x32_bf16 v[56:59], v[172:175], v[196:199], v[56:59]
	v_mfma_f32_16x16x32_bf16 v[44:47], v[160:163], v[204:207], v[44:47]
	v_mfma_f32_16x16x32_bf16 v[40:43], v[172:175], v[204:207], v[40:43]
	v_mfma_f32_16x16x32_bf16 v[28:31], v[160:163], v[212:215], v[28:31]
	v_mfma_f32_16x16x32_bf16 v[24:27], v[172:175], v[212:215], v[24:27]
	v_mfma_f32_16x16x32_bf16 v[12:15], v[160:163], v[220:223], v[12:15]
	v_mfma_f32_16x16x32_bf16 v[8:11], v[172:175], v[220:223], v[8:11]
	v_mfma_f32_16x16x32_bf16 v[52:55], v[176:179], v[192:195], v[52:55]
	v_mfma_f32_16x16x32_bf16 v[48:51], v[184:187], v[192:195], v[48:51]
	v_mfma_f32_16x16x32_bf16 v[36:39], v[176:179], v[200:203], v[36:39]
	v_mfma_f32_16x16x32_bf16 v[32:35], v[184:187], v[200:203], v[32:35]
	v_mfma_f32_16x16x32_bf16 v[20:23], v[176:179], v[208:211], v[20:23]
	v_mfma_f32_16x16x32_bf16 v[16:19], v[184:187], v[208:211], v[16:19]
	v_mfma_f32_16x16x32_bf16 v[4:7], v[176:179], v[216:219], v[4:7]
	v_mfma_f32_16x16x32_bf16 v[0:3], v[184:187], v[216:219], v[0:3]
	v_mfma_f32_16x16x32_bf16 v[52:55], v[180:183], v[196:199], v[52:55]
	v_mfma_f32_16x16x32_bf16 v[48:51], v[188:191], v[196:199], v[48:51]
	v_mfma_f32_16x16x32_bf16 v[36:39], v[180:183], v[204:207], v[36:39]
	v_mfma_f32_16x16x32_bf16 v[32:35], v[188:191], v[204:207], v[32:35]
	v_mfma_f32_16x16x32_bf16 v[20:23], v[180:183], v[212:215], v[20:23]
	v_mfma_f32_16x16x32_bf16 v[16:19], v[188:191], v[212:215], v[16:19]
	v_mfma_f32_16x16x32_bf16 v[4:7], v[180:183], v[220:223], v[4:7]
	v_mfma_f32_16x16x32_bf16 v[0:3], v[188:191], v[220:223], v[0:3]
	s_barrier
	s_add_i32 s56, s56, 2
	s_add_u32 s28, s28, 0x100
	s_addc_u32 s29, s29, 0
	s_add_u32 s54, s54, 0x100
	s_addc_u32 s55, s55, 0
	s_cmp_gt_u32 s56, 5
	s_cbranch_scc0 .LBB0_1403
	s_and_b64 vcc, exec, s[16:17]
	s_cbranch_vccz .LBB0_1406
	s_barrier

.LBB0_1540:
	s_andn2_b64 vcc, exec, s[4:5]
	s_cbranch_vccnz .LBB0_1576
	v_ashrrev_i32_e32 v2, 31, v0
	v_lshrrev_b32_e32 v2, 26, v2
	v_lshlrev_b32_e32 v1, 4, v0
	v_add_u32_e32 v2, v0, v2
	v_bfe_i32 v0, v0, 27, 1
	v_lshrrev_b32_e32 v0, 22, v0
	v_add_u32_e32 v0, v1, v0
	v_and_b32_e32 v0, 0xfffffc00, v0
	v_sub_u32_e32 v0, v1, v0
	v_ashrrev_i32_e32 v9, 6, v2
	v_lshrrev_b32_e32 v2, 4, v0
	v_bitop3_b32 v0, v2, v0, 32 bitop3:0x6c
	v_ashrrev_i32_e32 v3, 31, v0
	v_lshrrev_b32_e32 v3, 26, v3
	v_add_u32_e32 v3, v0, v3
	v_ashrrev_i32_e32 v10, 6, v3
	v_and_b32_e32 v3, 0xc0, v3
	v_sub_u32_e32 v0, v0, v3
	v_mov_b32_e32 v3, 1
	v_lshlrev_b32_e32 v2, 3, v9
	v_lshlrev_b32_e32 v4, 5, v9
	v_ashrrev_i16_sdwa v0, v3, sext(v0) dst_sel:DWORD dst_unused:UNUSED_PAD src0_sel:DWORD src1_sel:BYTE_0
	v_and_b32_e32 v2, 0x1ffff0, v2
	v_and_b32_e32 v4, 32, v4
	v_bfe_i32 v11, v0, 0, 16
	v_add_u32_e32 v0, v4, v11
	v_add_lshl_u32 v2, v10, v2, 11
	s_waitcnt vmcnt(0)
	v_lshl_add_u32 v128, v0, 1, v2
	v_add_u32_e32 v0, 0x2000, v1
	v_ashrrev_i32_e32 v1, 31, v0
	v_lshrrev_b32_e32 v1, 22, v1
	v_add_u32_e32 v1, v0, v1
	v_ashrrev_i32_e32 v12, 10, v1
	v_mul_i32_i24_e32 v1, 0x400, v12
	v_sub_u32_e32 v0, v0, v1
	v_lshrrev_b32_e32 v1, 4, v0
	s_add_u32 s34, s70, 0xbc00000
	v_bitop3_b32 v0, v1, v0, 32 bitop3:0x6c
	s_addc_u32 s35, s71, 0
	v_ashrrev_i32_e32 v2, 31, v0
	s_add_u32 s36, s70, 0x5900000
	v_lshrrev_b32_e32 v2, 26, v2
	s_addc_u32 s37, s71, 0
	s_ashr_i32 s2, s14, 6
	v_add_u32_e32 v2, v0, v2
	s_ashr_i32 s25, s24, 31
	s_ashr_i32 s9, s8, 31
	v_ashrrev_i32_e32 v13, 6, v2
	v_and_b32_e32 v2, 0xc0, v2
	s_ashr_i32 s3, s14, 8
	s_lshl_b32 s38, s2, 10
	s_lshl_b64 s[4:5], s[24:25], 19
	s_lshl_b64 s[10:11], s[8:9], 19
	v_sub_u32_e32 v0, v0, v2
	s_add_u32 s28, s36, s10
	v_lshlrev_b32_e32 v1, 3, v12
	v_lshlrev_b32_e32 v4, 5, v12
	v_ashrrev_i16_sdwa v0, v3, sext(v0) dst_sel:DWORD dst_unused:UNUSED_PAD src0_sel:DWORD src1_sel:BYTE_0
	s_addc_u32 s29, s37, s11
	s_add_i32 s39, s38, 0
	v_and_b32_e32 v1, 0x1ffff0, v1
	v_and_b32_e32 v4, 32, v4
	v_bfe_i32 v14, v0, 0, 16
	s_add_i32 m0, s39, 0x10000
	v_add_u32_e32 v0, v4, v14
	v_add_lshl_u32 v1, v13, v1, 11
	global_load_lds_dwordx4 v128, s[28:29]
	s_add_i32 m0, s39, 0x12000
	v_lshl_add_u32 v130, v0, 1, v1
	s_add_u32 s10, s28, 0x40000
	global_load_lds_dwordx4 v130, s[28:29]
	s_addc_u32 s11, s29, 0
	s_add_i32 m0, s39, 0x14000
	v_mov_b32_e32 v129, 0
	global_load_lds_dwordx4 v128, s[10:11]
	s_add_i32 m0, s39, 0x16000
	s_add_u32 s26, s34, s4
	s_addc_u32 s27, s35, s5
	s_add_i32 s40, s39, 0x2000
	global_load_lds_dwordx4 v130, s[10:11]
	s_mov_b32 m0, s39
	s_add_u32 s4, s26, 0x40000
	global_load_lds_dwordx4 v128, s[26:27]
	s_mov_b32 m0, s40
	s_addc_u32 s5, s27, 0
	s_add_i32 s41, s39, 0x4000
	global_load_lds_dwordx4 v130, s[26:27]
	s_mov_b32 m0, s41
	s_add_i32 s42, s39, 0x6000
	global_load_lds_dwordx4 v128, s[4:5]
	s_mov_b32 m0, s42
	v_mov_b32_e32 v131, v129
	global_load_lds_dwordx4 v130, s[4:5]
	s_cmp_eq_u32 s3, 1
	s_mov_b32 s9, 0
	v_lshl_add_u64 v[6:7], s[28:29], 0, v[128:129]
	v_lshl_add_u64 v[4:5], s[28:29], 0, v[130:131]
	v_lshl_add_u64 v[0:1], s[26:27], 0, v[128:129]
	s_cselect_b64 s[10:11], -1, 0
	s_cmp_lg_u32 s3, 1
	v_lshl_add_u64 v[2:3], s[26:27], 0, v[130:131]
	s_cbranch_scc1 .LBB0_1543
	s_barrier
	s_setprio 1

.LBB0_1553:
	ds_read_b128 v[140:143], v147
	ds_read_b128 v[152:155], v147 offset:1024
	ds_read_b128 v[156:159], v147 offset:2048
	ds_read_b128 v[160:163], v147 offset:3072
	ds_read_b128 v[164:167], v148
	ds_read_b128 v[168:171], v148 offset:1024
	ds_read_b128 v[172:175], v148 offset:2048
	ds_read_b128 v[176:179], v148 offset:3072
	s_add_u32 s28, s26, 0xfffc0080
	s_addc_u32 s29, s27, -1
	s_cmp_eq_u32 s54, 12
	s_cselect_b32 s31, s19, s29
	s_cselect_b32 s30, s25, s28
	s_cselect_b32 s29, s17, s53
	s_cselect_b32 s28, s51, s52
	v_lshl_add_u64 v[212:213], s[26:27], 0, v[132:133]
	s_add_i32 m0, s39, 0xc000
	ds_read_b128 v[180:183], v149
	ds_read_b128 v[184:187], v149 offset:1024
	ds_read_b128 v[188:191], v149 offset:2048
	ds_read_b128 v[192:195], v149 offset:3072
	ds_read_b128 v[196:199], v149 offset:4096
	ds_read_b128 v[200:203], v149 offset:5120
	ds_read_b128 v[204:207], v149 offset:6144
	ds_read_b128 v[208:211], v149 offset:7168
	global_load_lds_dwordx4 v[212:213], off
	v_lshl_add_u64 v[212:213], s[26:27], 0, v[134:135]
	s_add_i32 m0, s39, 0xe000
	s_nop 0
	global_load_lds_dwordx4 v[212:213], off
	s_waitcnt vmcnt(8)
	s_waitcnt lgkmcnt(0)
	s_barrier
	s_waitcnt lgkmcnt(0)
	v_mfma_f32_16x16x32_bf16 v[124:127], v[140:143], v[180:183], v[124:127]
	v_mfma_f32_16x16x32_bf16 v[120:123], v[156:159], v[180:183], v[120:123]
	v_mfma_f32_16x16x32_bf16 v[108:111], v[140:143], v[188:191], v[108:111]
	v_mfma_f32_16x16x32_bf16 v[104:107], v[156:159], v[188:191], v[104:107]
	v_mfma_f32_16x16x32_bf16 v[92:95], v[140:143], v[196:199], v[92:95]
	v_mfma_f32_16x16x32_bf16 v[88:91], v[156:159], v[196:199], v[88:91]
	v_mfma_f32_16x16x32_bf16 v[76:79], v[140:143], v[204:207], v[76:79]
	v_mfma_f32_16x16x32_bf16 v[72:75], v[156:159], v[204:207], v[72:75]
	v_mfma_f32_16x16x32_bf16 v[124:127], v[152:155], v[184:187], v[124:127]
	v_mfma_f32_16x16x32_bf16 v[120:123], v[160:163], v[184:187], v[120:123]
	v_mfma_f32_16x16x32_bf16 v[108:111], v[152:155], v[192:195], v[108:111]
	v_mfma_f32_16x16x32_bf16 v[104:107], v[160:163], v[192:195], v[104:107]
	v_mfma_f32_16x16x32_bf16 v[92:95], v[152:155], v[200:203], v[92:95]
	v_mfma_f32_16x16x32_bf16 v[88:91], v[160:163], v[200:203], v[88:91]
	v_mfma_f32_16x16x32_bf16 v[76:79], v[152:155], v[208:211], v[76:79]
	v_mfma_f32_16x16x32_bf16 v[72:75], v[160:163], v[208:211], v[72:75]
	v_mfma_f32_16x16x32_bf16 v[116:119], v[164:167], v[180:183], v[116:119]
	v_mfma_f32_16x16x32_bf16 v[112:115], v[172:175], v[180:183], v[112:115]
	v_mfma_f32_16x16x32_bf16 v[100:103], v[164:167], v[188:191], v[100:103]
	v_mfma_f32_16x16x32_bf16 v[96:99], v[172:175], v[188:191], v[96:99]
	v_mfma_f32_16x16x32_bf16 v[84:87], v[164:167], v[196:199], v[84:87]
	v_mfma_f32_16x16x32_bf16 v[80:83], v[172:175], v[196:199], v[80:83]
	v_mfma_f32_16x16x32_bf16 v[68:71], v[164:167], v[204:207], v[68:71]
	v_mfma_f32_16x16x32_bf16 v[64:67], v[172:175], v[204:207], v[64:67]
	v_mfma_f32_16x16x32_bf16 v[116:119], v[168:171], v[184:187], v[116:119]
	v_mfma_f32_16x16x32_bf16 v[112:115], v[176:179], v[184:187], v[112:115]
	v_mfma_f32_16x16x32_bf16 v[100:103], v[168:171], v[192:195], v[100:103]
	v_mfma_f32_16x16x32_bf16 v[96:99], v[176:179], v[192:195], v[96:99]
	v_mfma_f32_16x16x32_bf16 v[84:87], v[168:171], v[200:203], v[84:87]
	v_mfma_f32_16x16x32_bf16 v[80:83], v[176:179], v[200:203], v[80:83]
	v_mfma_f32_16x16x32_bf16 v[68:71], v[168:171], v[208:211], v[68:71]
	v_mfma_f32_16x16x32_bf16 v[64:67], v[176:179], v[208:211], v[64:67]
	s_barrier
	s_add_i32 s55, s48, s38
	v_lshl_add_u64 v[212:213], s[28:29], 0, v[128:129]
	s_mov_b32 m0, s55
	ds_read_b128 v[180:183], v149 offset:16384
	ds_read_b128 v[184:187], v149 offset:17408
	ds_read_b128 v[188:191], v149 offset:18432
	ds_read_b128 v[192:195], v149 offset:19456
	ds_read_b128 v[196:199], v149 offset:20480
	ds_read_b128 v[200:203], v149 offset:21504
	ds_read_b128 v[204:207], v149 offset:22528
	ds_read_b128 v[208:211], v149 offset:23552
	global_load_lds_dwordx4 v[212:213], off
	s_add_i32 m0, s55, 0x2000
	s_add_u32 s56, s28, 0x40000
	v_lshl_add_u64 v[214:215], s[28:29], 0, v[130:131]
	s_addc_u32 s57, s29, 0
	s_add_i32 s55, s49, s38
	global_load_lds_dwordx4 v[214:215], off
	v_lshl_add_u64 v[216:217], s[56:57], 0, v[128:129]
	s_mov_b32 m0, s55
	v_lshl_add_u64 v[218:219], s[30:31], 0, v[130:131]
	global_load_lds_dwordx4 v[216:217], off
	v_lshl_add_u64 v[216:217], s[56:57], 0, v[130:131]
	s_add_i32 m0, s55, 0x2000
	s_nop 0
	global_load_lds_dwordx4 v[216:217], off
	v_lshl_add_u64 v[216:217], s[30:31], 0, v[128:129]
	s_mov_b32 m0, s39
	s_nop 0
	global_load_lds_dwordx4 v[216:217], off
	s_mov_b32 m0, s40
	s_nop 0
	global_load_lds_dwordx4 v[218:219], off
	s_waitcnt vmcnt(8)
	s_waitcnt lgkmcnt(0)
	s_barrier
	s_waitcnt lgkmcnt(0)
	v_mfma_f32_16x16x32_bf16 v[60:63], v[140:143], v[180:183], v[60:63]
	v_mfma_f32_16x16x32_bf16 v[56:59], v[156:159], v[180:183], v[56:59]
	v_mfma_f32_16x16x32_bf16 v[44:47], v[140:143], v[188:191], v[44:47]
	v_mfma_f32_16x16x32_bf16 v[40:43], v[156:159], v[188:191], v[40:43]
	v_mfma_f32_16x16x32_bf16 v[28:31], v[140:143], v[196:199], v[28:31]
	v_mfma_f32_16x16x32_bf16 v[24:27], v[156:159], v[196:199], v[24:27]
	v_mfma_f32_16x16x32_bf16 v[12:15], v[140:143], v[204:207], v[12:15]
	v_mfma_f32_16x16x32_bf16 v[8:11], v[156:159], v[204:207], v[8:11]
	v_mfma_f32_16x16x32_bf16 v[60:63], v[152:155], v[184:187], v[60:63]
	v_mfma_f32_16x16x32_bf16 v[56:59], v[160:163], v[184:187], v[56:59]
	v_mfma_f32_16x16x32_bf16 v[44:47], v[152:155], v[192:195], v[44:47]
	v_mfma_f32_16x16x32_bf16 v[40:43], v[160:163], v[192:195], v[40:43]
	v_mfma_f32_16x16x32_bf16 v[28:31], v[152:155], v[200:203], v[28:31]
	v_mfma_f32_16x16x32_bf16 v[24:27], v[160:163], v[200:203], v[24:27]
	v_mfma_f32_16x16x32_bf16 v[12:15], v[152:155], v[208:211], v[12:15]
	v_mfma_f32_16x16x32_bf16 v[8:11], v[160:163], v[208:211], v[8:11]
	v_mfma_f32_16x16x32_bf16 v[52:55], v[164:167], v[180:183], v[52:55]
	v_mfma_f32_16x16x32_bf16 v[48:51], v[172:175], v[180:183], v[48:51]
	v_mfma_f32_16x16x32_bf16 v[36:39], v[164:167], v[188:191], v[36:39]
	v_mfma_f32_16x16x32_bf16 v[32:35], v[172:175], v[188:191], v[32:35]
	v_mfma_f32_16x16x32_bf16 v[20:23], v[164:167], v[196:199], v[20:23]
	v_mfma_f32_16x16x32_bf16 v[16:19], v[172:175], v[196:199], v[16:19]
	v_mfma_f32_16x16x32_bf16 v[4:7], v[164:167], v[204:207], v[4:7]
	v_mfma_f32_16x16x32_bf16 v[0:3], v[172:175], v[204:207], v[0:3]
	v_mfma_f32_16x16x32_bf16 v[52:55], v[168:171], v[184:187], v[52:55]
	v_mfma_f32_16x16x32_bf16 v[48:51], v[176:179], v[184:187], v[48:51]
	v_mfma_f32_16x16x32_bf16 v[36:39], v[168:171], v[192:195], v[36:39]
	v_mfma_f32_16x16x32_bf16 v[32:35], v[176:179], v[192:195], v[32:35]
	v_mfma_f32_16x16x32_bf16 v[20:23], v[168:171], v[200:203], v[20:23]
	v_mfma_f32_16x16x32_bf16 v[16:19], v[176:179], v[200:203], v[16:19]
	v_mfma_f32_16x16x32_bf16 v[4:7], v[168:171], v[208:211], v[4:7]
	v_mfma_f32_16x16x32_bf16 v[0:3], v[176:179], v[208:211], v[0:3]
	s_barrier
	s_add_i32 s55, 0, 0x18000
	v_add_u32_e32 v151, s55, v145
	s_add_i32 s56, 0, 0x1c000
	ds_read_b128 v[140:143], v151
	ds_read_b128 v[152:155], v151 offset:1024
	ds_read_b128 v[156:159], v151 offset:2048
	ds_read_b128 v[160:163], v151 offset:3072
	v_add_u32_e32 v151, s56, v145
	ds_read_b128 v[164:167], v151
	ds_read_b128 v[168:171], v151 offset:1024
	ds_read_b128 v[172:175], v151 offset:2048
	ds_read_b128 v[176:179], v151 offset:3072
	s_add_u32 s30, s30, 0x40000
	s_addc_u32 s31, s31, 0
	s_mov_b32 m0, s41
	v_lshl_add_u64 v[220:221], s[30:31], 0, v[128:129]
	ds_read_b128 v[180:183], v149 offset:32768
	ds_read_b128 v[184:187], v149 offset:33792
	ds_read_b128 v[188:191], v149 offset:34816
	ds_read_b128 v[192:195], v149 offset:35840
	ds_read_b128 v[196:199], v149 offset:36864
	ds_read_b128 v[200:203], v149 offset:37888
	ds_read_b128 v[204:207], v149 offset:38912
	ds_read_b128 v[208:211], v149 offset:39936
	global_load_lds_dwordx4 v[220:221], off
	v_lshl_add_u64 v[220:221], s[30:31], 0, v[130:131]
	s_mov_b32 m0, s42
	s_nop 0
	global_load_lds_dwordx4 v[220:221], off
	s_waitcnt vmcnt(8)
	s_waitcnt lgkmcnt(0)
	s_barrier
	s_waitcnt lgkmcnt(0)
	v_mfma_f32_16x16x32_bf16 v[124:127], v[140:143], v[180:183], v[124:127]
	v_mfma_f32_16x16x32_bf16 v[120:123], v[156:159], v[180:183], v[120:123]
	v_mfma_f32_16x16x32_bf16 v[108:111], v[140:143], v[188:191], v[108:111]
	v_mfma_f32_16x16x32_bf16 v[104:107], v[156:159], v[188:191], v[104:107]
	v_mfma_f32_16x16x32_bf16 v[92:95], v[140:143], v[196:199], v[92:95]
	v_mfma_f32_16x16x32_bf16 v[88:91], v[156:159], v[196:199], v[88:91]
	v_mfma_f32_16x16x32_bf16 v[76:79], v[140:143], v[204:207], v[76:79]
	v_mfma_f32_16x16x32_bf16 v[72:75], v[156:159], v[204:207], v[72:75]
	v_mfma_f32_16x16x32_bf16 v[124:127], v[152:155], v[184:187], v[124:127]
	v_mfma_f32_16x16x32_bf16 v[120:123], v[160:163], v[184:187], v[120:123]
	v_mfma_f32_16x16x32_bf16 v[108:111], v[152:155], v[192:195], v[108:111]
	v_mfma_f32_16x16x32_bf16 v[104:107], v[160:163], v[192:195], v[104:107]
	v_mfma_f32_16x16x32_bf16 v[92:95], v[152:155], v[200:203], v[92:95]
	v_mfma_f32_16x16x32_bf16 v[88:91], v[160:163], v[200:203], v[88:91]
	v_mfma_f32_16x16x32_bf16 v[76:79], v[152:155], v[208:211], v[76:79]
	v_mfma_f32_16x16x32_bf16 v[72:75], v[160:163], v[208:211], v[72:75]
	v_mfma_f32_16x16x32_bf16 v[116:119], v[164:167], v[180:183], v[116:119]
	v_mfma_f32_16x16x32_bf16 v[112:115], v[172:175], v[180:183], v[112:115]
	v_mfma_f32_16x16x32_bf16 v[100:103], v[164:167], v[188:191], v[100:103]
	v_mfma_f32_16x16x32_bf16 v[96:99], v[172:175], v[188:191], v[96:99]
	v_mfma_f32_16x16x32_bf16 v[84:87], v[164:167], v[196:199], v[84:87]
	v_mfma_f32_16x16x32_bf16 v[80:83], v[172:175], v[196:199], v[80:83]
	v_mfma_f32_16x16x32_bf16 v[68:71], v[164:167], v[204:207], v[68:71]
	v_mfma_f32_16x16x32_bf16 v[64:67], v[172:175], v[204:207], v[64:67]
	v_mfma_f32_16x16x32_bf16 v[116:119], v[168:171], v[184:187], v[116:119]
	v_mfma_f32_16x16x32_bf16 v[112:115], v[176:179], v[184:187], v[112:115]
	v_mfma_f32_16x16x32_bf16 v[100:103], v[168:171], v[192:195], v[100:103]
	v_mfma_f32_16x16x32_bf16 v[96:99], v[176:179], v[192:195], v[96:99]
	v_mfma_f32_16x16x32_bf16 v[84:87], v[168:171], v[200:203], v[84:87]
	v_mfma_f32_16x16x32_bf16 v[80:83], v[176:179], v[200:203], v[80:83]
	v_mfma_f32_16x16x32_bf16 v[68:71], v[168:171], v[208:211], v[68:71]
	v_mfma_f32_16x16x32_bf16 v[64:67], v[176:179], v[208:211], v[64:67]
	s_barrier
	s_add_i32 s30, s55, s38
	v_lshl_add_u64 v[212:213], v[212:213], 0, s[12:13]
	s_mov_b32 m0, s30
	ds_read_b128 v[180:183], v149 offset:49152
	ds_read_b128 v[184:187], v149 offset:50176
	ds_read_b128 v[188:191], v149 offset:51200
	ds_read_b128 v[192:195], v149 offset:52224
	ds_read_b128 v[196:199], v149 offset:53248
	ds_read_b128 v[200:203], v149 offset:54272
	ds_read_b128 v[204:207], v149 offset:55296
	ds_read_b128 v[208:211], v149 offset:56320
	global_load_lds_dwordx4 v[212:213], off
	s_add_i32 m0, s30, 0x2000
	s_add_u32 s28, s28, 0x40080
	v_lshl_add_u64 v[212:213], v[214:215], 0, s[12:13]
	s_addc_u32 s29, s29, 0
	s_add_i32 s30, s56, s38
	global_load_lds_dwordx4 v[212:213], off
	v_lshl_add_u64 v[212:213], s[28:29], 0, v[128:129]
	s_mov_b32 m0, s30
	s_nop 0
	global_load_lds_dwordx4 v[212:213], off
	v_lshl_add_u64 v[212:213], s[28:29], 0, v[130:131]
	s_add_i32 m0, s30, 0x2000
	s_nop 0
	global_load_lds_dwordx4 v[212:213], off
	v_lshl_add_u64 v[212:213], v[216:217], 0, s[12:13]
	s_mov_b32 m0, s44
	s_nop 0
	global_load_lds_dwordx4 v[212:213], off
	v_lshl_add_u64 v[212:213], v[218:219], 0, s[12:13]
	s_mov_b32 m0, s45
	s_nop 0
	global_load_lds_dwordx4 v[212:213], off
	s_waitcnt vmcnt(8)
	s_waitcnt lgkmcnt(0)
	s_barrier
	s_waitcnt lgkmcnt(0)
	v_mfma_f32_16x16x32_bf16 v[60:63], v[140:143], v[180:183], v[60:63]
	v_mfma_f32_16x16x32_bf16 v[56:59], v[156:159], v[180:183], v[56:59]
	v_mfma_f32_16x16x32_bf16 v[44:47], v[140:143], v[188:191], v[44:47]
	v_mfma_f32_16x16x32_bf16 v[40:43], v[156:159], v[188:191], v[40:43]
	v_mfma_f32_16x16x32_bf16 v[28:31], v[140:143], v[196:199], v[28:31]
	v_mfma_f32_16x16x32_bf16 v[24:27], v[156:159], v[196:199], v[24:27]
	v_mfma_f32_16x16x32_bf16 v[12:15], v[140:143], v[204:207], v[12:15]
	v_mfma_f32_16x16x32_bf16 v[8:11], v[156:159], v[204:207], v[8:11]
	v_mfma_f32_16x16x32_bf16 v[60:63], v[152:155], v[184:187], v[60:63]
	v_mfma_f32_16x16x32_bf16 v[56:59], v[160:163], v[184:187], v[56:59]
	v_mfma_f32_16x16x32_bf16 v[44:47], v[152:155], v[192:195], v[44:47]
	v_mfma_f32_16x16x32_bf16 v[40:43], v[160:163], v[192:195], v[40:43]
	v_mfma_f32_16x16x32_bf16 v[28:31], v[152:155], v[200:203], v[28:31]
	v_mfma_f32_16x16x32_bf16 v[24:27], v[160:163], v[200:203], v[24:27]
	v_mfma_f32_16x16x32_bf16 v[12:15], v[152:155], v[208:211], v[12:15]
	v_mfma_f32_16x16x32_bf16 v[8:11], v[160:163], v[208:211], v[8:11]
	v_mfma_f32_16x16x32_bf16 v[52:55], v[164:167], v[180:183], v[52:55]
	v_mfma_f32_16x16x32_bf16 v[48:51], v[172:175], v[180:183], v[48:51]
	v_mfma_f32_16x16x32_bf16 v[36:39], v[164:167], v[188:191], v[36:39]
	v_mfma_f32_16x16x32_bf16 v[32:35], v[172:175], v[188:191], v[32:35]
	v_mfma_f32_16x16x32_bf16 v[20:23], v[164:167], v[196:199], v[20:23]
	v_mfma_f32_16x16x32_bf16 v[16:19], v[172:175], v[196:199], v[16:19]
	v_mfma_f32_16x16x32_bf16 v[4:7], v[164:167], v[204:207], v[4:7]
	v_mfma_f32_16x16x32_bf16 v[0:3], v[172:175], v[204:207], v[0:3]
	v_mfma_f32_16x16x32_bf16 v[52:55], v[168:171], v[184:187], v[52:55]
	v_mfma_f32_16x16x32_bf16 v[48:51], v[176:179], v[184:187], v[48:51]
	v_mfma_f32_16x16x32_bf16 v[36:39], v[168:171], v[192:195], v[36:39]
	v_mfma_f32_16x16x32_bf16 v[32:35], v[176:179], v[192:195], v[32:35]
	v_mfma_f32_16x16x32_bf16 v[20:23], v[168:171], v[200:203], v[20:23]
	v_mfma_f32_16x16x32_bf16 v[16:19], v[176:179], v[200:203], v[16:19]
	v_mfma_f32_16x16x32_bf16 v[4:7], v[168:171], v[208:211], v[4:7]
	v_mfma_f32_16x16x32_bf16 v[0:3], v[176:179], v[208:211], v[0:3]
	s_barrier
	s_add_i32 s54, s54, 2
	s_add_u32 s26, s26, 0x100
	s_addc_u32 s27, s27, 0
	s_add_u32 s52, s52, 0x100
	s_addc_u32 s53, s53, 0
	s_cmp_gt_u32 s54, 13
	s_cbranch_scc0 .LBB0_1553
	s_and_b64 vcc, exec, s[14:15]
	s_cbranch_vccz .LBB0_1556
	s_barrier

.LBB0_1610:
	s_andn2_b64 vcc, exec, s[4:5]
	s_cbranch_vccnz .LBB0_1652
	v_ashrrev_i32_e32 v2, 31, v0
	v_lshrrev_b32_e32 v2, 26, v2
	v_lshlrev_b32_e32 v1, 4, v0
	v_add_u32_e32 v2, v0, v2
	v_bfe_i32 v0, v0, 27, 1
	v_lshrrev_b32_e32 v0, 22, v0
	v_add_u32_e32 v0, v1, v0
	v_and_b32_e32 v0, 0xfffffc00, v0
	v_sub_u32_e32 v0, v1, v0
	v_ashrrev_i32_e32 v9, 6, v2
	v_lshrrev_b32_e32 v2, 4, v0
	v_bitop3_b32 v0, v2, v0, 32 bitop3:0x6c
	v_ashrrev_i32_e32 v3, 31, v0
	v_lshrrev_b32_e32 v3, 26, v3
	v_add_u32_e32 v3, v0, v3
	v_lshlrev_b32_e32 v2, 3, v9
	v_ashrrev_i32_e32 v10, 6, v3
	v_and_b32_e32 v3, 0xc0, v3
	v_and_b32_e32 v2, -16, v2
	v_sub_u32_e32 v0, v0, v3
	v_mov_b32_e32 v3, 1
	v_add_u32_e32 v2, v10, v2
	v_ashrrev_i16_sdwa v0, v3, sext(v0) dst_sel:DWORD dst_unused:UNUSED_PAD src0_sel:DWORD src1_sel:BYTE_0
	v_lshlrev_b32_e32 v4, 5, v9
	v_bfe_i32 v11, v0, 0, 16
	v_lshlrev_b32_e32 v0, 1, v2
	v_lshrrev_b32_e32 v5, 2, v2
	v_and_b32_e32 v6, 3, v10
	s_mov_b32 s3, 0x1fffe0
	v_and_b32_e32 v4, 32, v4
	v_and_b32_e32 v0, 24, v0
	v_and_b32_e32 v5, 4, v5
	v_and_or_b32 v6, v2, s3, v6
	v_or3_b32 v0, v6, v5, v0
	v_add_lshl_u32 v4, v4, v11, 1
	s_waitcnt vmcnt(0)
	v_lshl_add_u32 v130, v0, 11, v4
	v_add_u32_e32 v0, 0x2000, v1
	v_ashrrev_i32_e32 v1, 31, v0
	v_lshrrev_b32_e32 v1, 22, v1
	v_add_u32_e32 v1, v0, v1
	v_ashrrev_i32_e32 v12, 10, v1
	v_mul_i32_i24_e32 v1, 0x400, v12
	v_sub_u32_e32 v0, v0, v1
	v_lshrrev_b32_e32 v1, 4, v0
	v_bitop3_b32 v0, v1, v0, 32 bitop3:0x6c
	v_lshl_add_u32 v128, v2, 11, v4
	v_ashrrev_i32_e32 v2, 31, v0
	v_lshrrev_b32_e32 v2, 26, v2
	v_add_u32_e32 v2, v0, v2
	v_lshlrev_b32_e32 v1, 3, v12
	v_ashrrev_i32_e32 v13, 6, v2
	v_and_b32_e32 v2, 0xc0, v2
	s_add_u32 s36, s70, 0x2800000
	v_and_b32_e32 v1, -16, v1
	v_sub_u32_e32 v0, v0, v2
	s_addc_u32 s37, s71, 0
	s_ashr_i32 s2, s6, 6
	v_add_u32_e32 v1, v13, v1
	v_ashrrev_i16_sdwa v0, v3, sext(v0) dst_sel:DWORD dst_unused:UNUSED_PAD src0_sel:DWORD src1_sel:BYTE_0
	v_and_b32_e32 v3, 3, v13
	s_ashr_i32 s27, s26, 31
	s_ashr_i32 s25, s24, 31
	v_and_or_b32 v3, v1, s3, v3
	s_ashr_i32 s3, s6, 8
	s_lshl_b32 s38, s2, 10
	s_lshl_b64 s[4:5], s[26:27], 19
	s_lshl_b64 s[8:9], s[24:25], 19
	s_add_u32 s30, s36, s8
	v_lshlrev_b32_e32 v4, 5, v12
	v_bfe_i32 v14, v0, 0, 16
	v_lshlrev_b32_e32 v0, 1, v1
	v_lshrrev_b32_e32 v2, 2, v1
	s_addc_u32 s31, s37, s9
	s_add_i32 s39, s38, 0
	v_and_b32_e32 v4, 32, v4
	v_and_b32_e32 v0, 24, v0
	v_and_b32_e32 v2, 4, v2
	s_add_i32 m0, s39, 0x10000
	v_or3_b32 v0, v3, v2, v0
	v_add_lshl_u32 v2, v4, v14, 1
	global_load_lds_dwordx4 v130, s[30:31]
	s_add_i32 m0, s39, 0x12000
	v_lshl_add_u32 v134, v0, 11, v2
	s_add_u32 s8, s30, 0x40000
	global_load_lds_dwordx4 v134, s[30:31]
	s_addc_u32 s9, s31, 0
	s_add_i32 m0, s39, 0x14000
	v_lshl_add_u32 v132, v1, 11, v2
	global_load_lds_dwordx4 v130, s[8:9]
	s_add_i32 m0, s39, 0x16000
	s_add_u32 s28, s76, s4
	s_addc_u32 s29, s77, s5
	s_add_i32 s40, s39, 0x2000
	global_load_lds_dwordx4 v134, s[8:9]
	s_mov_b32 m0, s39
	s_add_u32 s4, s28, 0x40000
	global_load_lds_dwordx4 v128, s[28:29]
	s_mov_b32 m0, s40
	s_addc_u32 s5, s29, 0
	s_add_i32 s41, s39, 0x4000
	global_load_lds_dwordx4 v132, s[28:29]
	s_mov_b32 m0, s41
	s_add_i32 s42, s39, 0x6000
	global_load_lds_dwordx4 v128, s[4:5]
	s_mov_b32 m0, s42
	v_mov_b32_e32 v137, 0
	global_load_lds_dwordx4 v132, s[4:5]
	v_mov_b32_e32 v131, v137
	v_mov_b32_e32 v135, v137
	v_mov_b32_e32 v129, v137
	v_mov_b32_e32 v133, v137
	s_cmp_eq_u32 s3, 1
	s_mov_b32 s7, 0
	v_lshl_add_u64 v[6:7], s[30:31], 0, v[130:131]
	v_lshl_add_u64 v[4:5], s[30:31], 0, v[134:135]
	v_lshl_add_u64 v[0:1], s[28:29], 0, v[128:129]
	s_cselect_b64 s[8:9], -1, 0
	s_cmp_lg_u32 s3, 1
	v_lshl_add_u64 v[2:3], s[28:29], 0, v[132:133]
	s_cbranch_scc1 .LBB0_1613
	s_barrier
	s_setprio 1

.LBB0_1619:
	ds_read_b128 v[152:155], v143
	ds_read_b128 v[162:165], v143 offset:1024
	ds_read_b128 v[166:169], v143 offset:2048
	ds_read_b128 v[170:173], v143 offset:3072
	ds_read_b128 v[174:177], v158
	ds_read_b128 v[178:181], v158 offset:1024
	ds_read_b128 v[182:185], v158 offset:2048
	ds_read_b128 v[186:189], v158 offset:3072
	s_add_u32 s30, s28, 0xfffc0080
	s_addc_u32 s31, s29, -1
	s_cmp_eq_u32 s55, 12
	s_cselect_b32 s35, s19, s31
	s_cselect_b32 s34, s25, s30
	s_cselect_b32 s31, s17, s54
	s_cselect_b32 s30, s27, s53
	s_waitcnt lgkmcnt(0)
	v_lshl_add_u64 v[156:157], s[28:29], 0, v[144:145]
	s_add_i32 m0, s39, 0xc000
	ds_read_b128 v[190:193], v159
	ds_read_b128 v[194:197], v159 offset:1024
	ds_read_b128 v[198:201], v159 offset:2048
	ds_read_b128 v[202:205], v159 offset:3072
	ds_read_b128 v[206:209], v159 offset:4096
	ds_read_b128 v[210:213], v159 offset:5120
	ds_read_b128 v[214:217], v159 offset:6144
	ds_read_b128 v[218:221], v159 offset:7168
	global_load_lds_dwordx4 v[156:157], off
	v_lshl_add_u64 v[156:157], s[28:29], 0, v[146:147]
	s_add_i32 m0, s39, 0xe000
	s_nop 0
	global_load_lds_dwordx4 v[156:157], off
	s_waitcnt vmcnt(8)
	s_waitcnt lgkmcnt(0)
	s_barrier
	s_waitcnt lgkmcnt(0)
	v_mfma_f32_16x16x32_bf16 v[116:119], v[152:155], v[190:193], v[116:119]
	v_mfma_f32_16x16x32_bf16 v[112:115], v[166:169], v[190:193], v[112:115]
	v_mfma_f32_16x16x32_bf16 v[100:103], v[152:155], v[198:201], v[100:103]
	v_mfma_f32_16x16x32_bf16 v[96:99], v[166:169], v[198:201], v[96:99]
	v_mfma_f32_16x16x32_bf16 v[88:91], v[152:155], v[206:209], v[88:91]
	v_mfma_f32_16x16x32_bf16 v[84:87], v[166:169], v[206:209], v[84:87]
	v_mfma_f32_16x16x32_bf16 v[72:75], v[152:155], v[214:217], v[72:75]
	v_mfma_f32_16x16x32_bf16 v[68:71], v[166:169], v[214:217], v[68:71]
	v_mfma_f32_16x16x32_bf16 v[116:119], v[162:165], v[194:197], v[116:119]
	v_mfma_f32_16x16x32_bf16 v[112:115], v[170:173], v[194:197], v[112:115]
	v_mfma_f32_16x16x32_bf16 v[100:103], v[162:165], v[202:205], v[100:103]
	v_mfma_f32_16x16x32_bf16 v[96:99], v[170:173], v[202:205], v[96:99]
	v_mfma_f32_16x16x32_bf16 v[88:91], v[162:165], v[210:213], v[88:91]
	v_mfma_f32_16x16x32_bf16 v[84:87], v[170:173], v[210:213], v[84:87]
	v_mfma_f32_16x16x32_bf16 v[72:75], v[162:165], v[218:221], v[72:75]
	v_mfma_f32_16x16x32_bf16 v[68:71], v[170:173], v[218:221], v[68:71]
	v_mfma_f32_16x16x32_bf16 v[124:127], v[174:177], v[190:193], v[124:127]
	v_mfma_f32_16x16x32_bf16 v[120:123], v[182:185], v[190:193], v[120:123]
	v_mfma_f32_16x16x32_bf16 v[108:111], v[174:177], v[198:201], v[108:111]
	v_mfma_f32_16x16x32_bf16 v[104:107], v[182:185], v[198:201], v[104:107]
	v_mfma_f32_16x16x32_bf16 v[92:95], v[174:177], v[206:209], v[92:95]
	v_mfma_f32_16x16x32_bf16 v[80:83], v[182:185], v[206:209], v[80:83]
	v_mfma_f32_16x16x32_bf16 v[76:79], v[174:177], v[214:217], v[76:79]
	v_mfma_f32_16x16x32_bf16 v[64:67], v[182:185], v[214:217], v[64:67]
	v_mfma_f32_16x16x32_bf16 v[124:127], v[178:181], v[194:197], v[124:127]
	v_mfma_f32_16x16x32_bf16 v[120:123], v[186:189], v[194:197], v[120:123]
	v_mfma_f32_16x16x32_bf16 v[108:111], v[178:181], v[202:205], v[108:111]
	v_mfma_f32_16x16x32_bf16 v[104:107], v[186:189], v[202:205], v[104:107]
	v_mfma_f32_16x16x32_bf16 v[92:95], v[178:181], v[210:213], v[92:95]
	v_mfma_f32_16x16x32_bf16 v[80:83], v[186:189], v[210:213], v[80:83]
	v_mfma_f32_16x16x32_bf16 v[76:79], v[178:181], v[218:221], v[76:79]
	v_mfma_f32_16x16x32_bf16 v[64:67], v[186:189], v[218:221], v[64:67]
	s_barrier
	s_add_i32 s56, s49, s38
	v_lshl_add_u64 v[156:157], s[30:31], 0, v[130:131]
	s_mov_b32 m0, s56
	ds_read_b128 v[190:193], v159 offset:16384
	ds_read_b128 v[194:197], v159 offset:17408
	ds_read_b128 v[198:201], v159 offset:18432
	ds_read_b128 v[202:205], v159 offset:19456
	ds_read_b128 v[206:209], v159 offset:20480
	ds_read_b128 v[210:213], v159 offset:21504
	ds_read_b128 v[214:217], v159 offset:22528
	ds_read_b128 v[218:221], v159 offset:23552
	global_load_lds_dwordx4 v[156:157], off
	s_add_i32 m0, s56, 0x2000
	s_add_u32 s56, s30, 0x40000
	v_lshl_add_u64 v[222:223], s[30:31], 0, v[134:135]
	s_addc_u32 s57, s31, 0
	s_add_i32 s58, s50, s38
	global_load_lds_dwordx4 v[222:223], off
	v_lshl_add_u64 v[224:225], s[56:57], 0, v[130:131]
	s_mov_b32 m0, s58
	v_lshl_add_u64 v[226:227], s[34:35], 0, v[132:133]
	global_load_lds_dwordx4 v[224:225], off
	v_lshl_add_u64 v[224:225], s[56:57], 0, v[134:135]
	s_add_i32 m0, s58, 0x2000
	s_nop 0
	global_load_lds_dwordx4 v[224:225], off
	v_lshl_add_u64 v[224:225], s[34:35], 0, v[128:129]
	s_mov_b32 m0, s39
	s_nop 0
	global_load_lds_dwordx4 v[224:225], off
	s_mov_b32 m0, s40
	s_nop 0
	global_load_lds_dwordx4 v[226:227], off
	s_waitcnt vmcnt(8)
	s_waitcnt lgkmcnt(0)
	s_barrier
	s_waitcnt lgkmcnt(0)
	v_mfma_f32_16x16x32_bf16 v[56:59], v[152:155], v[190:193], v[56:59]
	v_mfma_f32_16x16x32_bf16 v[52:55], v[166:169], v[190:193], v[52:55]
	v_mfma_f32_16x16x32_bf16 v[40:43], v[152:155], v[198:201], v[40:43]
	v_mfma_f32_16x16x32_bf16 v[36:39], v[166:169], v[198:201], v[36:39]
	v_mfma_f32_16x16x32_bf16 v[24:27], v[152:155], v[206:209], v[24:27]
	v_mfma_f32_16x16x32_bf16 v[20:23], v[166:169], v[206:209], v[20:23]
	v_mfma_f32_16x16x32_bf16 v[8:11], v[152:155], v[214:217], v[8:11]
	v_mfma_f32_16x16x32_bf16 v[4:7], v[166:169], v[214:217], v[4:7]
	v_mfma_f32_16x16x32_bf16 v[56:59], v[162:165], v[194:197], v[56:59]
	v_mfma_f32_16x16x32_bf16 v[52:55], v[170:173], v[194:197], v[52:55]
	v_mfma_f32_16x16x32_bf16 v[40:43], v[162:165], v[202:205], v[40:43]
	v_mfma_f32_16x16x32_bf16 v[36:39], v[170:173], v[202:205], v[36:39]
	v_mfma_f32_16x16x32_bf16 v[24:27], v[162:165], v[210:213], v[24:27]
	v_mfma_f32_16x16x32_bf16 v[20:23], v[170:173], v[210:213], v[20:23]
	v_mfma_f32_16x16x32_bf16 v[8:11], v[162:165], v[218:221], v[8:11]
	v_mfma_f32_16x16x32_bf16 v[4:7], v[170:173], v[218:221], v[4:7]
	v_mfma_f32_16x16x32_bf16 v[60:63], v[174:177], v[190:193], v[60:63]
	v_mfma_f32_16x16x32_bf16 v[48:51], v[182:185], v[190:193], v[48:51]
	v_mfma_f32_16x16x32_bf16 v[44:47], v[174:177], v[198:201], v[44:47]
	v_mfma_f32_16x16x32_bf16 v[32:35], v[182:185], v[198:201], v[32:35]
	v_mfma_f32_16x16x32_bf16 v[28:31], v[174:177], v[206:209], v[28:31]
	v_mfma_f32_16x16x32_bf16 v[16:19], v[182:185], v[206:209], v[16:19]
	v_mfma_f32_16x16x32_bf16 v[12:15], v[174:177], v[214:217], v[12:15]
	v_mfma_f32_16x16x32_bf16 v[0:3], v[182:185], v[214:217], v[0:3]
	v_mfma_f32_16x16x32_bf16 v[60:63], v[178:181], v[194:197], v[60:63]
	v_mfma_f32_16x16x32_bf16 v[48:51], v[186:189], v[194:197], v[48:51]
	v_mfma_f32_16x16x32_bf16 v[44:47], v[178:181], v[202:205], v[44:47]
	v_mfma_f32_16x16x32_bf16 v[32:35], v[186:189], v[202:205], v[32:35]
	v_mfma_f32_16x16x32_bf16 v[28:31], v[178:181], v[210:213], v[28:31]
	v_mfma_f32_16x16x32_bf16 v[16:19], v[186:189], v[210:213], v[16:19]
	v_mfma_f32_16x16x32_bf16 v[12:15], v[178:181], v[218:221], v[12:15]
	v_mfma_f32_16x16x32_bf16 v[0:3], v[186:189], v[218:221], v[0:3]
	s_barrier
	s_add_i32 s56, 0, 0x18000
	s_add_i32 s57, 0, 0x1c000
	v_add_u32_e32 v170, s56, v141
	v_add_u32_e32 v186, s57, v141
	ds_read_b128 v[152:155], v170
	ds_read_b128 v[162:165], v170 offset:1024
	ds_read_b128 v[166:169], v170 offset:2048
	ds_read_b128 v[170:173], v170 offset:3072
	ds_read_b128 v[174:177], v186
	ds_read_b128 v[178:181], v186 offset:1024
	ds_read_b128 v[182:185], v186 offset:2048
	ds_read_b128 v[186:189], v186 offset:3072
	s_add_u32 s34, s34, 0x40000
	s_addc_u32 s35, s35, 0
	s_mov_b32 m0, s41
	v_lshl_add_u64 v[228:229], s[34:35], 0, v[128:129]
	ds_read_b128 v[190:193], v159 offset:32768
	ds_read_b128 v[194:197], v159 offset:33792
	ds_read_b128 v[198:201], v159 offset:34816
	ds_read_b128 v[202:205], v159 offset:35840
	ds_read_b128 v[206:209], v159 offset:36864
	ds_read_b128 v[210:213], v159 offset:37888
	ds_read_b128 v[214:217], v159 offset:38912
	ds_read_b128 v[218:221], v159 offset:39936
	global_load_lds_dwordx4 v[228:229], off
	v_lshl_add_u64 v[228:229], s[34:35], 0, v[132:133]
	s_mov_b32 m0, s42
	s_nop 0
	global_load_lds_dwordx4 v[228:229], off
	s_waitcnt vmcnt(8)
	s_waitcnt lgkmcnt(0)
	s_barrier
	s_waitcnt lgkmcnt(0)
	v_mfma_f32_16x16x32_bf16 v[116:119], v[152:155], v[190:193], v[116:119]
	v_mfma_f32_16x16x32_bf16 v[112:115], v[166:169], v[190:193], v[112:115]
	v_mfma_f32_16x16x32_bf16 v[100:103], v[152:155], v[198:201], v[100:103]
	v_mfma_f32_16x16x32_bf16 v[96:99], v[166:169], v[198:201], v[96:99]
	v_mfma_f32_16x16x32_bf16 v[88:91], v[152:155], v[206:209], v[88:91]
	v_mfma_f32_16x16x32_bf16 v[84:87], v[166:169], v[206:209], v[84:87]
	v_mfma_f32_16x16x32_bf16 v[72:75], v[152:155], v[214:217], v[72:75]
	v_mfma_f32_16x16x32_bf16 v[68:71], v[166:169], v[214:217], v[68:71]
	v_mfma_f32_16x16x32_bf16 v[116:119], v[162:165], v[194:197], v[116:119]
	v_mfma_f32_16x16x32_bf16 v[112:115], v[170:173], v[194:197], v[112:115]
	v_mfma_f32_16x16x32_bf16 v[100:103], v[162:165], v[202:205], v[100:103]
	v_mfma_f32_16x16x32_bf16 v[96:99], v[170:173], v[202:205], v[96:99]
	v_mfma_f32_16x16x32_bf16 v[88:91], v[162:165], v[210:213], v[88:91]
	v_mfma_f32_16x16x32_bf16 v[84:87], v[170:173], v[210:213], v[84:87]
	v_mfma_f32_16x16x32_bf16 v[72:75], v[162:165], v[218:221], v[72:75]
	v_mfma_f32_16x16x32_bf16 v[68:71], v[170:173], v[218:221], v[68:71]
	v_mfma_f32_16x16x32_bf16 v[124:127], v[174:177], v[190:193], v[124:127]
	v_mfma_f32_16x16x32_bf16 v[120:123], v[182:185], v[190:193], v[120:123]
	v_mfma_f32_16x16x32_bf16 v[108:111], v[174:177], v[198:201], v[108:111]
	v_mfma_f32_16x16x32_bf16 v[104:107], v[182:185], v[198:201], v[104:107]
	v_mfma_f32_16x16x32_bf16 v[92:95], v[174:177], v[206:209], v[92:95]
	v_mfma_f32_16x16x32_bf16 v[80:83], v[182:185], v[206:209], v[80:83]
	v_mfma_f32_16x16x32_bf16 v[76:79], v[174:177], v[214:217], v[76:79]
	v_mfma_f32_16x16x32_bf16 v[64:67], v[182:185], v[214:217], v[64:67]
	v_mfma_f32_16x16x32_bf16 v[124:127], v[178:181], v[194:197], v[124:127]
	v_mfma_f32_16x16x32_bf16 v[120:123], v[186:189], v[194:197], v[120:123]
	v_mfma_f32_16x16x32_bf16 v[108:111], v[178:181], v[202:205], v[108:111]
	v_mfma_f32_16x16x32_bf16 v[104:107], v[186:189], v[202:205], v[104:107]
	v_mfma_f32_16x16x32_bf16 v[92:95], v[178:181], v[210:213], v[92:95]
	v_mfma_f32_16x16x32_bf16 v[80:83], v[186:189], v[210:213], v[80:83]
	v_mfma_f32_16x16x32_bf16 v[76:79], v[178:181], v[218:221], v[76:79]
	v_mfma_f32_16x16x32_bf16 v[64:67], v[186:189], v[218:221], v[64:67]
	s_barrier
	s_add_i32 s34, s56, s38
	v_lshl_add_u64 v[156:157], v[156:157], 0, s[10:11]
	s_mov_b32 m0, s34
	ds_read_b128 v[190:193], v159 offset:49152
	ds_read_b128 v[194:197], v159 offset:50176
	ds_read_b128 v[198:201], v159 offset:51200
	ds_read_b128 v[202:205], v159 offset:52224
	ds_read_b128 v[206:209], v159 offset:53248
	ds_read_b128 v[210:213], v159 offset:54272
	ds_read_b128 v[214:217], v159 offset:55296
	ds_read_b128 v[218:221], v159 offset:56320
	global_load_lds_dwordx4 v[156:157], off
	s_add_i32 m0, s34, 0x2000
	s_add_u32 s30, s30, 0x40080
	v_lshl_add_u64 v[156:157], v[222:223], 0, s[10:11]
	s_addc_u32 s31, s31, 0
	s_add_i32 s34, s57, s38
	global_load_lds_dwordx4 v[156:157], off
	v_lshl_add_u64 v[156:157], s[30:31], 0, v[130:131]
	s_mov_b32 m0, s34
	s_nop 0
	global_load_lds_dwordx4 v[156:157], off
	v_lshl_add_u64 v[156:157], s[30:31], 0, v[134:135]
	s_add_i32 m0, s34, 0x2000
	s_nop 0
	global_load_lds_dwordx4 v[156:157], off
	v_lshl_add_u64 v[156:157], v[224:225], 0, s[10:11]
	s_mov_b32 m0, s43
	s_nop 0
	global_load_lds_dwordx4 v[156:157], off
	v_lshl_add_u64 v[156:157], v[226:227], 0, s[10:11]
	s_mov_b32 m0, s44
	s_nop 0
	global_load_lds_dwordx4 v[156:157], off
	s_waitcnt vmcnt(8)
	s_waitcnt lgkmcnt(0)
	s_barrier
	s_waitcnt lgkmcnt(0)
	v_mfma_f32_16x16x32_bf16 v[56:59], v[152:155], v[190:193], v[56:59]
	v_mfma_f32_16x16x32_bf16 v[52:55], v[166:169], v[190:193], v[52:55]
	v_mfma_f32_16x16x32_bf16 v[40:43], v[152:155], v[198:201], v[40:43]
	v_mfma_f32_16x16x32_bf16 v[36:39], v[166:169], v[198:201], v[36:39]
	v_mfma_f32_16x16x32_bf16 v[24:27], v[152:155], v[206:209], v[24:27]
	v_mfma_f32_16x16x32_bf16 v[20:23], v[166:169], v[206:209], v[20:23]
	v_mfma_f32_16x16x32_bf16 v[8:11], v[152:155], v[214:217], v[8:11]
	v_mfma_f32_16x16x32_bf16 v[4:7], v[166:169], v[214:217], v[4:7]
	v_mfma_f32_16x16x32_bf16 v[56:59], v[162:165], v[194:197], v[56:59]
	v_mfma_f32_16x16x32_bf16 v[52:55], v[170:173], v[194:197], v[52:55]
	v_mfma_f32_16x16x32_bf16 v[40:43], v[162:165], v[202:205], v[40:43]
	v_mfma_f32_16x16x32_bf16 v[36:39], v[170:173], v[202:205], v[36:39]
	v_mfma_f32_16x16x32_bf16 v[24:27], v[162:165], v[210:213], v[24:27]
	v_mfma_f32_16x16x32_bf16 v[20:23], v[170:173], v[210:213], v[20:23]
	v_mfma_f32_16x16x32_bf16 v[8:11], v[162:165], v[218:221], v[8:11]
	v_mfma_f32_16x16x32_bf16 v[4:7], v[170:173], v[218:221], v[4:7]
	v_mfma_f32_16x16x32_bf16 v[60:63], v[174:177], v[190:193], v[60:63]
	v_mfma_f32_16x16x32_bf16 v[48:51], v[182:185], v[190:193], v[48:51]
	v_mfma_f32_16x16x32_bf16 v[44:47], v[174:177], v[198:201], v[44:47]
	v_mfma_f32_16x16x32_bf16 v[32:35], v[182:185], v[198:201], v[32:35]
	v_mfma_f32_16x16x32_bf16 v[28:31], v[174:177], v[206:209], v[28:31]
	v_mfma_f32_16x16x32_bf16 v[16:19], v[182:185], v[206:209], v[16:19]
	v_mfma_f32_16x16x32_bf16 v[12:15], v[174:177], v[214:217], v[12:15]
	v_mfma_f32_16x16x32_bf16 v[0:3], v[182:185], v[214:217], v[0:3]
	v_mfma_f32_16x16x32_bf16 v[60:63], v[178:181], v[194:197], v[60:63]
	v_mfma_f32_16x16x32_bf16 v[48:51], v[186:189], v[194:197], v[48:51]
	v_mfma_f32_16x16x32_bf16 v[44:47], v[178:181], v[202:205], v[44:47]
	v_mfma_f32_16x16x32_bf16 v[32:35], v[186:189], v[202:205], v[32:35]
	v_mfma_f32_16x16x32_bf16 v[28:31], v[178:181], v[210:213], v[28:31]
	v_mfma_f32_16x16x32_bf16 v[16:19], v[186:189], v[210:213], v[16:19]
	v_mfma_f32_16x16x32_bf16 v[12:15], v[178:181], v[218:221], v[12:15]
	v_mfma_f32_16x16x32_bf16 v[0:3], v[186:189], v[218:221], v[0:3]
	s_barrier
	s_add_i32 s55, s55, 2
	s_add_u32 s28, s28, 0x100
	s_addc_u32 s29, s29, 0
	s_add_u32 s53, s53, 0x100
	s_addc_u32 s54, s54, 0
	s_cmp_gt_u32 s55, 13
	s_cbranch_scc0 .LBB0_1619
	s_and_b64 vcc, exec, s[12:13]
	s_cbranch_vccz .LBB0_1624
	s_barrier
	v_lshl_add_u32 v152, s26, 8, v139
	s_cmp_gt_i32 s24, 21
	s_mov_b64 s[26:27], -1
	s_cbranch_scc1 .LBB0_1625

.LBB0_1689:
	v_ashrrev_i32_e32 v2, 31, v0
	v_lshrrev_b32_e32 v2, 26, v2
	v_lshlrev_b32_e32 v1, 4, v0
	v_add_u32_e32 v2, v0, v2
	v_bfe_i32 v0, v0, 27, 1
	v_lshrrev_b32_e32 v0, 22, v0
	v_add_u32_e32 v0, v1, v0
	v_and_b32_e32 v0, 0xfffffc00, v0
	v_sub_u32_e32 v0, v1, v0
	v_ashrrev_i32_e32 v9, 6, v2
	v_lshrrev_b32_e32 v2, 4, v0
	v_bitop3_b32 v0, v2, v0, 32 bitop3:0x6c
	v_ashrrev_i32_e32 v3, 31, v0
	v_lshrrev_b32_e32 v3, 26, v3
	v_add_u32_e32 v3, v0, v3
	v_lshlrev_b32_e32 v2, 3, v9
	v_ashrrev_i32_e32 v11, 6, v3
	v_and_b32_e32 v3, 0xc0, v3
	v_and_b32_e32 v2, 0xfffff0, v2
	v_sub_u32_e32 v0, v0, v3
	v_mov_b32_e32 v3, 1
	v_add_u32_e32 v2, v11, v2
	v_lshlrev_b32_e32 v4, 5, v9
	v_ashrrev_i16_sdwa v0, v3, sext(v0) dst_sel:DWORD dst_unused:UNUSED_PAD src0_sel:DWORD src1_sel:BYTE_0
	s_movk_i32 s2, 0xb00
	s_add_u32 s35, s70, 0x4480000
	v_and_b32_e32 v10, 32, v4
	v_bfe_i32 v12, v0, 0, 16
	v_mul_lo_u32 v0, v2, s2
	s_addc_u32 s36, s71, 0
	v_or_b32_e32 v0, v0, v10
	s_add_i32 s6, s6, s7
	s_waitcnt vmcnt(0)
	v_add_lshl_u32 v128, v0, v12, 1
	v_add_u32_e32 v0, 0x2000, v1
	s_ashr_i32 s7, s6, 31
	v_ashrrev_i32_e32 v1, 31, v0
	s_lshr_b32 s7, s7, 27
	v_lshrrev_b32_e32 v1, 22, v1
	s_add_i32 s7, s6, s7
	v_add_u32_e32 v1, v0, v1
	s_ashr_i32 s8, s7, 5
	s_and_b32 s7, s7, 0xffe0
	v_ashrrev_i32_e32 v13, 10, v1
	s_sub_i32 s6, s6, s7
	v_mul_i32_i24_e32 v1, 0x400, v13
	s_bfe_i32 s7, s6, 0x80000
	v_sub_u32_e32 v0, v0, v1
	s_bfe_u32 s7, s7, 0x3000c
	v_lshrrev_b32_e32 v1, 4, v0
	s_add_i32 s7, s6, s7
	v_bitop3_b32 v0, v1, v0, 32 bitop3:0x6c
	s_bfe_i32 s9, s7, 0x80000
	s_and_b32 s7, s7, 0xf8
	v_ashrrev_i32_e32 v2, 31, v0
	s_sub_i32 s6, s6, s7
	v_lshrrev_b32_e32 v2, 26, v2
	s_lshl_b32 s8, s8, 3
	s_sext_i32_i16 s9, s9
	s_sext_i32_i8 s6, s6
	s_ashr_i32 s3, s4, 6
	v_add_u32_e32 v2, v0, v2
	s_add_i32 s54, s8, s6
	s_ashr_i32 s6, s9, 3
	v_lshlrev_b32_e32 v1, 3, v13
	v_ashrrev_i32_e32 v14, 6, v2
	v_and_b32_e32 v2, 0xc0, v2
	s_ashr_i32 s5, s4, 8
	s_lshl_b32 s37, s3, 10
	s_lshr_b32 s14, s9, 3
	s_mul_hi_i32 s7, s6, 0x160000
	s_mul_i32 s6, s6, 0x160000
	v_and_b32_e32 v1, 0xfffff0, v1
	v_sub_u32_e32 v0, v0, v2
	s_add_u32 s26, s35, s6
	v_add_u32_e32 v1, v14, v1
	v_lshlrev_b32_e32 v4, 5, v13
	v_ashrrev_i16_sdwa v0, v3, sext(v0) dst_sel:DWORD dst_unused:UNUSED_PAD src0_sel:DWORD src1_sel:BYTE_0
	s_addc_u32 s27, s36, s7
	s_add_i32 s38, s37, 0
	v_and_b32_e32 v15, 32, v4
	v_bfe_i32 v16, v0, 0, 16
	v_mul_lo_u32 v0, v1, s2
	s_add_i32 m0, s38, 0x10000
	v_or_b32_e32 v0, v0, v15
	global_load_lds_dwordx4 v128, s[26:27]
	s_add_i32 m0, s38, 0x12000
	v_add_lshl_u32 v130, v0, v16, 1
	s_add_u32 s6, s26, 0xb0000
	global_load_lds_dwordx4 v130, s[26:27]
	s_addc_u32 s7, s27, 0
	s_add_i32 m0, s38, 0x14000
	s_mul_i32 s10, s54, 0x160000
	global_load_lds_dwordx4 v128, s[6:7]
	s_add_i32 m0, s38, 0x16000
	s_mul_hi_i32 s8, s54, 0x160000
	s_add_u32 s24, s72, s10
	s_addc_u32 s25, s73, s8
	s_add_i32 s39, s38, 0x2000
	global_load_lds_dwordx4 v130, s[6:7]
	s_mov_b32 m0, s38
	s_add_u32 s6, s24, 0xb0000
	global_load_lds_dwordx4 v128, s[24:25]
	s_mov_b32 m0, s39
	s_addc_u32 s7, s25, 0
	s_add_i32 s40, s38, 0x4000
	global_load_lds_dwordx4 v130, s[24:25]
	s_mov_b32 m0, s40
	s_add_i32 s41, s38, 0x6000
	global_load_lds_dwordx4 v128, s[6:7]
	s_mov_b32 m0, s41
	v_mov_b32_e32 v129, 0
	global_load_lds_dwordx4 v130, s[6:7]
	s_load_dwordx2 s[6:7], s[0:1], 0x110
	v_mov_b32_e32 v131, v129
	s_cmp_eq_u32 s5, 1
	s_mov_b32 s42, 0
	v_lshl_add_u64 v[6:7], s[26:27], 0, v[128:129]
	v_lshl_add_u64 v[4:5], s[26:27], 0, v[130:131]
	s_mov_b64 s[8:9], 0xb0000
	v_lshl_add_u64 v[0:1], s[24:25], 0, v[128:129]
	s_cselect_b64 s[10:11], -1, 0
	s_cmp_lg_u32 s5, 1
	v_lshl_add_u64 v[2:3], s[24:25], 0, v[130:131]
	s_cbranch_scc1 .LBB0_1691
	s_barrier
	s_setprio 1

.LBB0_1705:
	ds_read_b128 v[148:151], v145
	ds_read_b128 v[152:155], v145 offset:1024
	ds_read_b128 v[156:159], v145 offset:2048
	ds_read_b128 v[160:163], v145 offset:3072
	ds_read_b128 v[164:167], v146
	ds_read_b128 v[168:171], v146 offset:1024
	ds_read_b128 v[172:175], v146 offset:2048
	ds_read_b128 v[176:179], v146 offset:3072
	s_add_u32 s26, s24, 0x100
	s_addc_u32 s27, s25, 0
	s_cmp_eq_u32 s58, 40
	s_cselect_b32 s31, s5, s27
	s_cselect_b32 s30, s4, s26
	s_cselect_b32 s29, s23, s57
	s_cselect_b32 s28, s22, s56
	v_lshl_add_u64 v[140:141], s[24:25], 0, v[132:133]
	s_add_i32 m0, s38, 0xc000
	ds_read_b128 v[180:183], v147
	ds_read_b128 v[184:187], v147 offset:1024
	ds_read_b128 v[188:191], v147 offset:2048
	ds_read_b128 v[192:195], v147 offset:3072
	ds_read_b128 v[196:199], v147 offset:4096
	ds_read_b128 v[200:203], v147 offset:5120
	ds_read_b128 v[204:207], v147 offset:6144
	ds_read_b128 v[208:211], v147 offset:7168
	global_load_lds_dwordx4 v[140:141], off
	v_lshl_add_u64 v[140:141], s[24:25], 0, v[134:135]
	s_add_i32 m0, s38, 0xe000
	s_nop 0
	global_load_lds_dwordx4 v[140:141], off
	s_waitcnt vmcnt(8)
	s_waitcnt lgkmcnt(0)
	s_barrier
	s_waitcnt lgkmcnt(0)
	v_mfma_f32_16x16x32_bf16 v[124:127], v[148:151], v[180:183], v[124:127]
	v_mfma_f32_16x16x32_bf16 v[120:123], v[156:159], v[180:183], v[120:123]
	v_mfma_f32_16x16x32_bf16 v[116:119], v[148:151], v[188:191], v[116:119]
	v_mfma_f32_16x16x32_bf16 v[112:115], v[156:159], v[188:191], v[112:115]
	v_mfma_f32_16x16x32_bf16 v[92:95], v[148:151], v[196:199], v[92:95]
	v_mfma_f32_16x16x32_bf16 v[88:91], v[156:159], v[196:199], v[88:91]
	v_mfma_f32_16x16x32_bf16 v[84:87], v[148:151], v[204:207], v[84:87]
	v_mfma_f32_16x16x32_bf16 v[80:83], v[156:159], v[204:207], v[80:83]
	v_mfma_f32_16x16x32_bf16 v[124:127], v[152:155], v[184:187], v[124:127]
	v_mfma_f32_16x16x32_bf16 v[120:123], v[160:163], v[184:187], v[120:123]
	v_mfma_f32_16x16x32_bf16 v[116:119], v[152:155], v[192:195], v[116:119]
	v_mfma_f32_16x16x32_bf16 v[112:115], v[160:163], v[192:195], v[112:115]
	v_mfma_f32_16x16x32_bf16 v[92:95], v[152:155], v[200:203], v[92:95]
	v_mfma_f32_16x16x32_bf16 v[88:91], v[160:163], v[200:203], v[88:91]
	v_mfma_f32_16x16x32_bf16 v[84:87], v[152:155], v[208:211], v[84:87]
	v_mfma_f32_16x16x32_bf16 v[80:83], v[160:163], v[208:211], v[80:83]
	v_mfma_f32_16x16x32_bf16 v[108:111], v[164:167], v[180:183], v[108:111]
	v_mfma_f32_16x16x32_bf16 v[104:107], v[172:175], v[180:183], v[104:107]
	v_mfma_f32_16x16x32_bf16 v[100:103], v[164:167], v[188:191], v[100:103]
	v_mfma_f32_16x16x32_bf16 v[96:99], v[172:175], v[188:191], v[96:99]
	v_mfma_f32_16x16x32_bf16 v[76:79], v[164:167], v[196:199], v[76:79]
	v_mfma_f32_16x16x32_bf16 v[72:75], v[172:175], v[196:199], v[72:75]
	v_mfma_f32_16x16x32_bf16 v[68:71], v[164:167], v[204:207], v[68:71]
	v_mfma_f32_16x16x32_bf16 v[64:67], v[172:175], v[204:207], v[64:67]
	v_mfma_f32_16x16x32_bf16 v[108:111], v[168:171], v[184:187], v[108:111]
	v_mfma_f32_16x16x32_bf16 v[104:107], v[176:179], v[184:187], v[104:107]
	v_mfma_f32_16x16x32_bf16 v[100:103], v[168:171], v[192:195], v[100:103]
	v_mfma_f32_16x16x32_bf16 v[96:99], v[176:179], v[192:195], v[96:99]
	v_mfma_f32_16x16x32_bf16 v[76:79], v[168:171], v[200:203], v[76:79]
	v_mfma_f32_16x16x32_bf16 v[72:75], v[176:179], v[200:203], v[72:75]
	v_mfma_f32_16x16x32_bf16 v[68:71], v[168:171], v[208:211], v[68:71]
	v_mfma_f32_16x16x32_bf16 v[64:67], v[176:179], v[208:211], v[64:67]
	s_barrier
	s_add_i32 s24, s46, s37
	v_lshl_add_u64 v[140:141], s[28:29], 0, v[128:129]
	s_mov_b32 m0, s24
	ds_read_b128 v[180:183], v147 offset:16384
	ds_read_b128 v[184:187], v147 offset:17408
	ds_read_b128 v[188:191], v147 offset:18432
	ds_read_b128 v[192:195], v147 offset:19456
	ds_read_b128 v[196:199], v147 offset:20480
	ds_read_b128 v[200:203], v147 offset:21504
	ds_read_b128 v[204:207], v147 offset:22528
	ds_read_b128 v[208:211], v147 offset:23552
	global_load_lds_dwordx4 v[140:141], off
	s_add_i32 m0, s24, 0x2000
	s_add_u32 s24, s28, 0xb0000
	v_lshl_add_u64 v[212:213], s[28:29], 0, v[130:131]
	s_addc_u32 s25, s29, 0
	s_add_i32 s59, s47, s37
	global_load_lds_dwordx4 v[212:213], off
	v_lshl_add_u64 v[214:215], s[24:25], 0, v[128:129]
	s_mov_b32 m0, s59
	v_lshl_add_u64 v[216:217], s[30:31], 0, v[130:131]
	global_load_lds_dwordx4 v[214:215], off
	v_lshl_add_u64 v[214:215], s[24:25], 0, v[130:131]
	s_add_i32 m0, s59, 0x2000
	s_nop 0
	global_load_lds_dwordx4 v[214:215], off
	v_lshl_add_u64 v[214:215], s[30:31], 0, v[128:129]
	s_mov_b32 m0, s38
	s_nop 0
	global_load_lds_dwordx4 v[214:215], off
	s_mov_b32 m0, s39
	s_nop 0
	global_load_lds_dwordx4 v[216:217], off
	s_waitcnt vmcnt(8)
	s_waitcnt lgkmcnt(0)
	s_barrier
	s_waitcnt lgkmcnt(0)
	v_mfma_f32_16x16x32_bf16 v[60:63], v[148:151], v[180:183], v[60:63]
	v_mfma_f32_16x16x32_bf16 v[56:59], v[156:159], v[180:183], v[56:59]
	v_mfma_f32_16x16x32_bf16 v[52:55], v[148:151], v[188:191], v[52:55]
	v_mfma_f32_16x16x32_bf16 v[48:51], v[156:159], v[188:191], v[48:51]
	v_mfma_f32_16x16x32_bf16 v[28:31], v[148:151], v[196:199], v[28:31]
	v_mfma_f32_16x16x32_bf16 v[24:27], v[156:159], v[196:199], v[24:27]
	v_mfma_f32_16x16x32_bf16 v[20:23], v[148:151], v[204:207], v[20:23]
	v_mfma_f32_16x16x32_bf16 v[16:19], v[156:159], v[204:207], v[16:19]
	v_mfma_f32_16x16x32_bf16 v[60:63], v[152:155], v[184:187], v[60:63]
	v_mfma_f32_16x16x32_bf16 v[56:59], v[160:163], v[184:187], v[56:59]
	v_mfma_f32_16x16x32_bf16 v[52:55], v[152:155], v[192:195], v[52:55]
	v_mfma_f32_16x16x32_bf16 v[48:51], v[160:163], v[192:195], v[48:51]
	v_mfma_f32_16x16x32_bf16 v[28:31], v[152:155], v[200:203], v[28:31]
	v_mfma_f32_16x16x32_bf16 v[24:27], v[160:163], v[200:203], v[24:27]
	v_mfma_f32_16x16x32_bf16 v[20:23], v[152:155], v[208:211], v[20:23]
	v_mfma_f32_16x16x32_bf16 v[16:19], v[160:163], v[208:211], v[16:19]
	v_mfma_f32_16x16x32_bf16 v[44:47], v[164:167], v[180:183], v[44:47]
	v_mfma_f32_16x16x32_bf16 v[40:43], v[172:175], v[180:183], v[40:43]
	v_mfma_f32_16x16x32_bf16 v[36:39], v[164:167], v[188:191], v[36:39]
	v_mfma_f32_16x16x32_bf16 v[32:35], v[172:175], v[188:191], v[32:35]
	v_mfma_f32_16x16x32_bf16 v[12:15], v[164:167], v[196:199], v[12:15]
	v_mfma_f32_16x16x32_bf16 v[8:11], v[172:175], v[196:199], v[8:11]
	v_mfma_f32_16x16x32_bf16 v[4:7], v[164:167], v[204:207], v[4:7]
	v_mfma_f32_16x16x32_bf16 v[0:3], v[172:175], v[204:207], v[0:3]
	v_mfma_f32_16x16x32_bf16 v[44:47], v[168:171], v[184:187], v[44:47]
	v_mfma_f32_16x16x32_bf16 v[40:43], v[176:179], v[184:187], v[40:43]
	v_mfma_f32_16x16x32_bf16 v[36:39], v[168:171], v[192:195], v[36:39]
	v_mfma_f32_16x16x32_bf16 v[32:35], v[176:179], v[192:195], v[32:35]
	v_mfma_f32_16x16x32_bf16 v[12:15], v[168:171], v[200:203], v[12:15]
	v_mfma_f32_16x16x32_bf16 v[8:11], v[176:179], v[200:203], v[8:11]
	v_mfma_f32_16x16x32_bf16 v[4:7], v[168:171], v[208:211], v[4:7]
	v_mfma_f32_16x16x32_bf16 v[0:3], v[176:179], v[208:211], v[0:3]
	s_barrier
	s_add_i32 s59, 0, 0x18000
	s_add_i32 s60, 0, 0x1c000
	v_add_u32_e32 v160, s59, v143
	v_add_u32_e32 v176, s60, v143
	ds_read_b128 v[148:151], v160
	ds_read_b128 v[152:155], v160 offset:1024
	ds_read_b128 v[156:159], v160 offset:2048
	ds_read_b128 v[160:163], v160 offset:3072
	ds_read_b128 v[164:167], v176
	ds_read_b128 v[168:171], v176 offset:1024
	ds_read_b128 v[172:175], v176 offset:2048
	ds_read_b128 v[176:179], v176 offset:3072
	s_add_u32 s24, s30, 0xb0000
	s_addc_u32 s25, s31, 0
	s_mov_b32 m0, s40
	v_lshl_add_u64 v[218:219], s[24:25], 0, v[128:129]
	ds_read_b128 v[180:183], v147 offset:32768
	ds_read_b128 v[184:187], v147 offset:33792
	ds_read_b128 v[188:191], v147 offset:34816
	ds_read_b128 v[192:195], v147 offset:35840
	ds_read_b128 v[196:199], v147 offset:36864
	ds_read_b128 v[200:203], v147 offset:37888
	ds_read_b128 v[204:207], v147 offset:38912
	ds_read_b128 v[208:211], v147 offset:39936
	global_load_lds_dwordx4 v[218:219], off
	v_lshl_add_u64 v[218:219], s[24:25], 0, v[130:131]
	s_mov_b32 m0, s41
	s_nop 0
	global_load_lds_dwordx4 v[218:219], off
	s_waitcnt vmcnt(8)
	s_waitcnt lgkmcnt(0)
	s_barrier
	s_waitcnt lgkmcnt(0)
	v_mfma_f32_16x16x32_bf16 v[124:127], v[148:151], v[180:183], v[124:127]
	v_mfma_f32_16x16x32_bf16 v[120:123], v[156:159], v[180:183], v[120:123]
	v_mfma_f32_16x16x32_bf16 v[116:119], v[148:151], v[188:191], v[116:119]
	v_mfma_f32_16x16x32_bf16 v[112:115], v[156:159], v[188:191], v[112:115]
	v_mfma_f32_16x16x32_bf16 v[92:95], v[148:151], v[196:199], v[92:95]
	v_mfma_f32_16x16x32_bf16 v[88:91], v[156:159], v[196:199], v[88:91]
	v_mfma_f32_16x16x32_bf16 v[84:87], v[148:151], v[204:207], v[84:87]
	v_mfma_f32_16x16x32_bf16 v[80:83], v[156:159], v[204:207], v[80:83]
	v_mfma_f32_16x16x32_bf16 v[124:127], v[152:155], v[184:187], v[124:127]
	v_mfma_f32_16x16x32_bf16 v[120:123], v[160:163], v[184:187], v[120:123]
	v_mfma_f32_16x16x32_bf16 v[116:119], v[152:155], v[192:195], v[116:119]
	v_mfma_f32_16x16x32_bf16 v[112:115], v[160:163], v[192:195], v[112:115]
	v_mfma_f32_16x16x32_bf16 v[92:95], v[152:155], v[200:203], v[92:95]
	v_mfma_f32_16x16x32_bf16 v[88:91], v[160:163], v[200:203], v[88:91]
	v_mfma_f32_16x16x32_bf16 v[84:87], v[152:155], v[208:211], v[84:87]
	v_mfma_f32_16x16x32_bf16 v[80:83], v[160:163], v[208:211], v[80:83]
	v_mfma_f32_16x16x32_bf16 v[108:111], v[164:167], v[180:183], v[108:111]
	v_mfma_f32_16x16x32_bf16 v[104:107], v[172:175], v[180:183], v[104:107]
	v_mfma_f32_16x16x32_bf16 v[100:103], v[164:167], v[188:191], v[100:103]
	v_mfma_f32_16x16x32_bf16 v[96:99], v[172:175], v[188:191], v[96:99]
	v_mfma_f32_16x16x32_bf16 v[76:79], v[164:167], v[196:199], v[76:79]
	v_mfma_f32_16x16x32_bf16 v[72:75], v[172:175], v[196:199], v[72:75]
	v_mfma_f32_16x16x32_bf16 v[68:71], v[164:167], v[204:207], v[68:71]
	v_mfma_f32_16x16x32_bf16 v[64:67], v[172:175], v[204:207], v[64:67]
	v_mfma_f32_16x16x32_bf16 v[108:111], v[168:171], v[184:187], v[108:111]
	v_mfma_f32_16x16x32_bf16 v[104:107], v[176:179], v[184:187], v[104:107]
	v_mfma_f32_16x16x32_bf16 v[100:103], v[168:171], v[192:195], v[100:103]
	v_mfma_f32_16x16x32_bf16 v[96:99], v[176:179], v[192:195], v[96:99]
	v_mfma_f32_16x16x32_bf16 v[76:79], v[168:171], v[200:203], v[76:79]
	v_mfma_f32_16x16x32_bf16 v[72:75], v[176:179], v[200:203], v[72:75]
	v_mfma_f32_16x16x32_bf16 v[68:71], v[168:171], v[208:211], v[68:71]
	v_mfma_f32_16x16x32_bf16 v[64:67], v[176:179], v[208:211], v[64:67]
	s_barrier
	s_add_i32 s24, s59, s37
	v_lshl_add_u64 v[140:141], v[140:141], 0, s[12:13]
	s_mov_b32 m0, s24
	ds_read_b128 v[180:183], v147 offset:49152
	ds_read_b128 v[184:187], v147 offset:50176
	ds_read_b128 v[188:191], v147 offset:51200
	ds_read_b128 v[192:195], v147 offset:52224
	ds_read_b128 v[196:199], v147 offset:53248
	ds_read_b128 v[200:203], v147 offset:54272
	ds_read_b128 v[204:207], v147 offset:55296
	ds_read_b128 v[208:211], v147 offset:56320
	global_load_lds_dwordx4 v[140:141], off
	s_add_i32 m0, s24, 0x2000
	s_add_u32 s24, s28, 0xb0080
	v_lshl_add_u64 v[140:141], v[212:213], 0, s[12:13]
	s_addc_u32 s25, s29, 0
	s_add_i32 s28, s60, s37
	global_load_lds_dwordx4 v[140:141], off
	v_lshl_add_u64 v[140:141], s[24:25], 0, v[128:129]
	s_mov_b32 m0, s28
	s_nop 0
	global_load_lds_dwordx4 v[140:141], off
	v_lshl_add_u64 v[140:141], s[24:25], 0, v[130:131]
	s_add_i32 m0, s28, 0x2000
	s_nop 0
	global_load_lds_dwordx4 v[140:141], off
	v_lshl_add_u64 v[140:141], v[214:215], 0, s[12:13]
	s_mov_b32 m0, s43
	s_nop 0
	global_load_lds_dwordx4 v[140:141], off
	v_lshl_add_u64 v[140:141], v[216:217], 0, s[12:13]
	s_mov_b32 m0, s44
	s_nop 0
	global_load_lds_dwordx4 v[140:141], off
	s_waitcnt vmcnt(8)
	s_waitcnt lgkmcnt(0)
	s_barrier
	s_waitcnt lgkmcnt(0)
	v_mfma_f32_16x16x32_bf16 v[60:63], v[148:151], v[180:183], v[60:63]
	v_mfma_f32_16x16x32_bf16 v[56:59], v[156:159], v[180:183], v[56:59]
	v_mfma_f32_16x16x32_bf16 v[52:55], v[148:151], v[188:191], v[52:55]
	v_mfma_f32_16x16x32_bf16 v[48:51], v[156:159], v[188:191], v[48:51]
	v_mfma_f32_16x16x32_bf16 v[28:31], v[148:151], v[196:199], v[28:31]
	v_mfma_f32_16x16x32_bf16 v[24:27], v[156:159], v[196:199], v[24:27]
	v_mfma_f32_16x16x32_bf16 v[20:23], v[148:151], v[204:207], v[20:23]
	v_mfma_f32_16x16x32_bf16 v[16:19], v[156:159], v[204:207], v[16:19]
	v_mfma_f32_16x16x32_bf16 v[60:63], v[152:155], v[184:187], v[60:63]
	v_mfma_f32_16x16x32_bf16 v[56:59], v[160:163], v[184:187], v[56:59]
	v_mfma_f32_16x16x32_bf16 v[52:55], v[152:155], v[192:195], v[52:55]
	v_mfma_f32_16x16x32_bf16 v[48:51], v[160:163], v[192:195], v[48:51]
	v_mfma_f32_16x16x32_bf16 v[28:31], v[152:155], v[200:203], v[28:31]
	v_mfma_f32_16x16x32_bf16 v[24:27], v[160:163], v[200:203], v[24:27]
	v_mfma_f32_16x16x32_bf16 v[20:23], v[152:155], v[208:211], v[20:23]
	v_mfma_f32_16x16x32_bf16 v[16:19], v[160:163], v[208:211], v[16:19]
	v_mfma_f32_16x16x32_bf16 v[44:47], v[164:167], v[180:183], v[44:47]
	v_mfma_f32_16x16x32_bf16 v[40:43], v[172:175], v[180:183], v[40:43]
	v_mfma_f32_16x16x32_bf16 v[36:39], v[164:167], v[188:191], v[36:39]
	v_mfma_f32_16x16x32_bf16 v[32:35], v[172:175], v[188:191], v[32:35]
	v_mfma_f32_16x16x32_bf16 v[12:15], v[164:167], v[196:199], v[12:15]
	v_mfma_f32_16x16x32_bf16 v[8:11], v[172:175], v[196:199], v[8:11]
	v_mfma_f32_16x16x32_bf16 v[4:7], v[164:167], v[204:207], v[4:7]
	v_mfma_f32_16x16x32_bf16 v[0:3], v[172:175], v[204:207], v[0:3]
	v_mfma_f32_16x16x32_bf16 v[44:47], v[168:171], v[184:187], v[44:47]
	v_mfma_f32_16x16x32_bf16 v[40:43], v[176:179], v[184:187], v[40:43]
	v_mfma_f32_16x16x32_bf16 v[36:39], v[168:171], v[192:195], v[36:39]
	v_mfma_f32_16x16x32_bf16 v[32:35], v[176:179], v[192:195], v[32:35]
	v_mfma_f32_16x16x32_bf16 v[12:15], v[168:171], v[200:203], v[12:15]
	v_mfma_f32_16x16x32_bf16 v[8:11], v[176:179], v[200:203], v[8:11]
	v_mfma_f32_16x16x32_bf16 v[4:7], v[168:171], v[208:211], v[4:7]
	v_mfma_f32_16x16x32_bf16 v[0:3], v[176:179], v[208:211], v[0:3]
	s_barrier
	s_add_i32 s58, s58, 2
	s_add_u32 s56, s56, 0x100
	s_addc_u32 s57, s57, 0
	s_cmp_gt_u32 s58, 41
	s_mov_b64 s[24:25], s[26:27]
	s_cbranch_scc0 .LBB0_1705
	s_and_b64 vcc, exec, s[14:15]
	s_cbranch_vccz .LBB0_1708
	s_barrier
